# streaming (nt) loads for all read-once / last-use data: x rows and f32 weights in PRO, q rows in top-k, x8 / expert ids / gate weights in the gather, query fragments in attention
# speedup vs baseline: 1.0213x; 1.0121x over previous
.LBB0_23:
	s_ashr_i32 s27, s33, 31
	s_lshr_b32 s27, s27, 21
	s_add_i32 s27, s33, s27
	s_and_b32 s27, s27, 0xfffff800
	s_add_i32 s26, s33, 0xffffe000
	s_sub_i32 s27, s33, s27
	s_and_b64 s[24:25], s[24:25], exec
	s_cselect_b32 s24, s1, s44
	s_cselect_b32 s25, s3, s45
	s_cmpk_eq_i32 s35, 0x1000
	s_cselect_b32 s25, s51, s25
	s_cselect_b32 s24, s50, s24
	s_cmpk_lt_i32 s33, 0x2000
	s_cselect_b32 s28, s27, s26
	s_and_b64 s[16:17], s[16:17], exec
	s_cselect_b32 s16, s46, s24
	s_cselect_b32 s17, s47, s25
	s_and_b64 s[14:15], exec, s[14:15]
	s_cselect_b32 s14, s43, s17
	s_cselect_b32 s15, s42, s16
	v_mov_b32_e32 v3, s14
	s_lshr_b32 s14, s34, 5
	v_cvt_f32_ubyte0_e32 v1, s14
	v_rcp_iflag_f32_e32 v1, v1
	s_add_u32 s4, s54, s4
	s_addc_u32 s5, s55, s5
	s_sub_i32 s24, 0, s14
	v_mul_f32_e32 v1, 0x4f7ffffe, v1
	v_cvt_u32_f32_e32 v1, v1
	s_abs_i32 s17, s28
	s_ashr_i32 s16, s28, 31
	v_mov_b32_e32 v2, s15
	v_readfirstlane_b32 s25, v1
	s_mul_i32 s24, s24, s25
	s_mul_hi_u32 s24, s25, s24
	s_add_i32 s25, s25, s24
	s_mul_hi_u32 s24, s17, s25
	s_mul_i32 s25, s24, s14
	s_sub_i32 s17, s17, s25
	s_add_i32 s25, s24, 1
	s_sub_i32 s26, s17, s14
	s_cmp_ge_u32 s17, s14
	s_cselect_b32 s24, s25, s24
	s_cselect_b32 s17, s26, s17
	s_add_i32 s25, s24, 1
	s_cmp_ge_u32 s17, s14
	s_cselect_b32 s17, s25, s24
	s_xor_b32 s17, s17, s16
	s_sub_i32 s16, s17, s16
	s_mul_i32 s14, s16, s14
	s_lshl_b32 s16, s16, 6
	v_ashrrev_i32_e32 v1, 5, v80
	s_sub_i32 s14, s28, s14
	v_add_u32_e32 v1, s16, v1
	s_lshl_b32 s24, s14, 5
	v_mad_i64_i32 v[4:5], s[26:27], v1, s34, 0
	v_lshl_add_u64 v[2:3], v[4:5], 2, v[2:3]
	s_ashr_i32 s25, s24, 31
	v_and_b32_e32 v1, 31, v80
	v_lshl_add_u64 v[2:3], s[24:25], 2, v[2:3]
	v_lshlrev_b32_e32 v4, 2, v1
	v_mov_b32_e32 v5, 0
	s_mov_b32 s15, 0
	v_lshl_add_u64 v[26:27], v[2:3], 0, v[4:5]
	s_lshl_b32 s14, s34, 3
	v_lshl_add_u64 v[4:5], v[26:27], 0, s[14:15]
	s_lshl_b32 s14, s34, 4
	v_lshl_add_u64 v[6:7], v[26:27], 0, s[14:15]
	s_mul_i32 s14, s34, 24
	v_lshl_add_u64 v[8:9], v[26:27], 0, s[14:15]
	s_lshl_b32 s14, s34, 5
	v_lshl_add_u64 v[10:11], v[26:27], 0, s[14:15]
	s_mul_i32 s14, s34, 40
	v_lshl_add_u64 v[12:13], v[26:27], 0, s[14:15]
	s_mul_i32 s14, s34, 48
	v_lshl_add_u64 v[14:15], v[26:27], 0, s[14:15]
	s_mul_i32 s14, s34, 56
	v_lshl_add_u64 v[16:17], v[26:27], 0, s[14:15]
	s_lshl_b32 s14, s34, 6
	global_load_dword v2, v[26:27], off nt
	global_load_dword v3, v[4:5], off nt
	s_nop 0
	global_load_dword v4, v[6:7], off nt
	global_load_dword v5, v[8:9], off nt
	s_nop 0
	global_load_dword v6, v[10:11], off nt
	global_load_dword v7, v[12:13], off nt
	global_load_dword v8, v[14:15], off nt
	global_load_dword v9, v[16:17], off nt
	v_lshl_add_u64 v[10:11], v[26:27], 0, s[14:15]
	s_mul_i32 s14, s34, 0x48
	v_lshl_add_u64 v[12:13], v[26:27], 0, s[14:15]
	s_mul_i32 s14, s34, 0x50
	v_lshl_add_u64 v[14:15], v[26:27], 0, s[14:15]
	s_mul_i32 s14, s34, 0x58
	v_lshl_add_u64 v[16:17], v[26:27], 0, s[14:15]
	s_mul_i32 s14, s34, 0x60
	v_lshl_add_u64 v[18:19], v[26:27], 0, s[14:15]
	s_mul_i32 s14, s34, 0x68
	v_lshl_add_u64 v[20:21], v[26:27], 0, s[14:15]
	s_mul_i32 s14, s34, 0x70
	v_lshl_add_u64 v[22:23], v[26:27], 0, s[14:15]
	s_mul_i32 s14, s34, 0x78
	v_lshl_add_u64 v[24:25], v[26:27], 0, s[14:15]
	s_lshl_b32 s14, s34, 7
	global_load_dword v10, v[10:11], off nt
	s_nop 0
	global_load_dword v11, v[12:13], off nt
	s_nop 0
	global_load_dword v12, v[14:15], off nt
	global_load_dword v13, v[16:17], off nt
	s_nop 0
	global_load_dword v14, v[18:19], off nt
	global_load_dword v15, v[20:21], off nt
	global_load_dword v16, v[22:23], off nt
	global_load_dword v17, v[24:25], off nt
	v_lshl_add_u64 v[18:19], v[26:27], 0, s[14:15]
	s_mul_i32 s14, s34, 0x88
	v_lshl_add_u64 v[20:21], v[26:27], 0, s[14:15]
	s_mul_i32 s14, s34, 0x90
	v_lshl_add_u64 v[22:23], v[26:27], 0, s[14:15]
	s_mul_i32 s14, s34, 0x98
	v_lshl_add_u64 v[24:25], v[26:27], 0, s[14:15]
	s_mul_i32 s14, s34, 0xa0
	v_lshl_add_u64 v[28:29], v[26:27], 0, s[14:15]
	s_mul_i32 s14, s34, 0xa8
	v_lshl_add_u64 v[30:31], v[26:27], 0, s[14:15]
	s_mul_i32 s14, s34, 0xb0
	v_lshl_add_u64 v[32:33], v[26:27], 0, s[14:15]
	s_mul_i32 s14, s34, 0xb8
	v_lshl_add_u64 v[34:35], v[26:27], 0, s[14:15]
	s_mul_i32 s14, s34, 0xc0
	global_load_dword v18, v[18:19], off nt
	s_nop 0
	global_load_dword v19, v[20:21], off nt
	s_nop 0
	global_load_dword v20, v[22:23], off nt
	global_load_dword v21, v[24:25], off nt
	s_nop 0
	global_load_dword v22, v[28:29], off nt
	global_load_dword v23, v[30:31], off nt
	global_load_dword v24, v[32:33], off nt
	global_load_dword v25, v[34:35], off nt
	v_lshl_add_u64 v[28:29], v[26:27], 0, s[14:15]
	s_mul_i32 s14, s34, 0xc8
	v_lshl_add_u64 v[30:31], v[26:27], 0, s[14:15]
	s_mul_i32 s14, s34, 0xd0
	v_lshl_add_u64 v[32:33], v[26:27], 0, s[14:15]
	s_mul_i32 s14, s34, 0xd8
	v_lshl_add_u64 v[34:35], v[26:27], 0, s[14:15]
	s_mul_i32 s14, s34, 0xe0
	v_lshl_add_u64 v[36:37], v[26:27], 0, s[14:15]
	s_mul_i32 s14, s34, 0xe8
	v_lshl_add_u64 v[38:39], v[26:27], 0, s[14:15]
	s_mul_i32 s14, s34, 0xf0
	v_lshl_add_u64 v[40:41], v[26:27], 0, s[14:15]
	s_mul_i32 s14, s34, 0xf8
	v_lshl_add_u64 v[42:43], v[26:27], 0, s[14:15]
	global_load_dword v26, v[28:29], off nt
	global_load_dword v27, v[30:31], off nt
	s_nop 0
	global_load_dword v28, v[32:33], off nt
	global_load_dword v29, v[34:35], off nt
	global_load_dword v30, v[36:37], off nt
	global_load_dword v31, v[38:39], off nt
	s_nop 0
	global_load_dword v32, v[40:41], off nt
	global_load_dword v33, v[42:43], off nt
	s_cmp_eq_u64 s[12:13], 0
	s_cbranch_scc1 .LBB0_25
	s_ashr_i32 s17, s16, 31
	s_lshl_b64 s[14:15], s[16:17], 2
	s_add_u32 s12, s12, s14
	v_lshlrev_b32_e32 v1, 5, v80
	s_addc_u32 s13, s13, s15
	v_and_b32_e32 v1, 0xe0, v1
	global_load_dwordx4 v[64:67], v1, s[12:13] offset:16
	global_load_dwordx4 v[68:71], v1, s[12:13]
	s_waitcnt vmcnt(1)
	v_mov_b32_e32 v83, v66
	v_mov_b32_e32 v66, v65
	v_mov_b32_e32 v82, v64
	s_waitcnt vmcnt(0)
	v_mov_b32_e32 v85, v70
	v_mov_b32_e32 v70, v69
	v_mov_b32_e32 v84, v68
	s_andn2_b64 vcc, exec, s[10:11]
	v_and_b32_e32 v68, 31, v80
	s_cbranch_vccz .LBB0_26
	s_branch .LBB0_64

.LBB0_52:
	s_add_u32 s14, s54, s14
	s_addc_u32 s15, s55, s15
	s_cmpk_gt_i32 s78, 0x1fff
	s_cselect_b64 s[16:17], -1, 0
	s_and_b64 s[24:25], s[16:17], exec
	s_cselect_b32 s80, s70, 0x800
	s_lshr_b32 s10, s80, 5
	s_sext_i32_i16 s24, s79
	v_cvt_f32_ubyte0_e32 v35, s10
	v_cvt_f32_i32_e32 v34, s24
	v_rcp_iflag_f32_e32 v36, v35
	s_ashr_i32 s24, s24, 30
	s_or_b32 s81, s24, 1
	v_mov_b32_e32 v91, v87
	v_mul_f32_e32 v36, v34, v36
	v_trunc_f32_e32 v36, v36
	v_fma_f32 v34, -v36, v35, v34
	v_cvt_i32_f32_e32 v36, v36
	v_cmp_ge_f32_e64 s[24:25], |v34|, v35
	s_and_b64 s[24:25], s[24:25], exec
	s_cselect_b32 s24, s81, 0
	v_readfirstlane_b32 s25, v36
	s_add_i32 s25, s25, s24
	s_sext_i32_i16 s24, s25
	s_mul_i32 s10, s10, s24
	s_lshl_b32 s24, s24, 6
	s_sub_i32 s10, s79, s10
	v_add_u32_e32 v34, s24, v1
	s_lshl_b32 s82, s10, 5
	v_mad_i64_i32 v[34:35], s[84:85], v34, s80, 0
	v_lshl_add_u64 v[34:35], v[34:35], 2, s[26:27]
	s_ashr_i32 s83, s82, 31
	v_lshl_add_u64 v[34:35], s[82:83], 2, v[34:35]
	v_lshl_add_u64 v[58:59], v[34:35], 0, v[90:91]
	s_lshl_b32 s10, s80, 3
	v_lshl_add_u64 v[36:37], v[58:59], 0, s[10:11]
	s_lshl_b32 s10, s80, 4
	v_lshl_add_u64 v[38:39], v[58:59], 0, s[10:11]
	s_mul_i32 s10, s80, 24
	v_lshl_add_u64 v[40:41], v[58:59], 0, s[10:11]
	s_lshl_b32 s10, s80, 5
	v_lshl_add_u64 v[42:43], v[58:59], 0, s[10:11]
	s_mul_i32 s10, s80, 40
	v_lshl_add_u64 v[44:45], v[58:59], 0, s[10:11]
	s_mul_i32 s10, s80, 48
	v_lshl_add_u64 v[46:47], v[58:59], 0, s[10:11]
	s_mul_i32 s10, s80, 56
	v_lshl_add_u64 v[48:49], v[58:59], 0, s[10:11]
	s_lshl_b32 s10, s80, 6
	global_load_dword v34, v[58:59], off nt
	global_load_dword v35, v[36:37], off nt
	s_nop 0
	global_load_dword v36, v[38:39], off nt
	global_load_dword v37, v[40:41], off nt
	s_nop 0
	global_load_dword v38, v[42:43], off nt
	global_load_dword v39, v[44:45], off nt
	global_load_dword v40, v[46:47], off nt
	global_load_dword v41, v[48:49], off nt
	v_lshl_add_u64 v[42:43], v[58:59], 0, s[10:11]
	s_mul_i32 s10, s80, 0x48
	v_lshl_add_u64 v[44:45], v[58:59], 0, s[10:11]
	s_mul_i32 s10, s80, 0x50
	v_lshl_add_u64 v[46:47], v[58:59], 0, s[10:11]
	s_mul_i32 s10, s80, 0x58
	v_lshl_add_u64 v[48:49], v[58:59], 0, s[10:11]
	s_mul_i32 s10, s80, 0x60
	v_lshl_add_u64 v[50:51], v[58:59], 0, s[10:11]
	s_mul_i32 s10, s80, 0x68
	v_lshl_add_u64 v[52:53], v[58:59], 0, s[10:11]
	s_mul_i32 s10, s80, 0x70
	v_lshl_add_u64 v[54:55], v[58:59], 0, s[10:11]
	s_mul_i32 s10, s80, 0x78
	v_lshl_add_u64 v[56:57], v[58:59], 0, s[10:11]
	s_lshl_b32 s10, s80, 7
	global_load_dword v42, v[42:43], off nt
	s_nop 0
	global_load_dword v43, v[44:45], off nt
	s_nop 0
	global_load_dword v44, v[46:47], off nt
	global_load_dword v45, v[48:49], off nt
	s_nop 0
	global_load_dword v46, v[50:51], off nt
	global_load_dword v47, v[52:53], off nt
	global_load_dword v48, v[54:55], off nt
	global_load_dword v49, v[56:57], off nt
	v_lshl_add_u64 v[50:51], v[58:59], 0, s[10:11]
	s_mul_i32 s10, s80, 0x88
	v_lshl_add_u64 v[52:53], v[58:59], 0, s[10:11]
	s_mul_i32 s10, s80, 0x90
	v_lshl_add_u64 v[54:55], v[58:59], 0, s[10:11]
	s_mul_i32 s10, s80, 0x98
	v_lshl_add_u64 v[56:57], v[58:59], 0, s[10:11]
	s_mul_i32 s10, s80, 0xa0
	v_lshl_add_u64 v[60:61], v[58:59], 0, s[10:11]
	s_mul_i32 s10, s80, 0xa8
	v_lshl_add_u64 v[62:63], v[58:59], 0, s[10:11]
	s_mul_i32 s10, s80, 0xb0
	v_lshl_add_u64 v[64:65], v[58:59], 0, s[10:11]
	s_mul_i32 s10, s80, 0xb8
	v_lshl_add_u64 v[72:73], v[58:59], 0, s[10:11]
	s_mul_i32 s10, s80, 0xc0
	global_load_dword v50, v[50:51], off nt
	s_nop 0
	global_load_dword v51, v[52:53], off nt
	s_nop 0
	global_load_dword v52, v[54:55], off nt
	global_load_dword v53, v[56:57], off nt
	s_nop 0
	global_load_dword v54, v[60:61], off nt
	global_load_dword v55, v[62:63], off nt
	global_load_dword v56, v[64:65], off nt
	global_load_dword v57, v[72:73], off nt
	v_lshl_add_u64 v[60:61], v[58:59], 0, s[10:11]
	s_mul_i32 s10, s80, 0xc8
	v_lshl_add_u64 v[62:63], v[58:59], 0, s[10:11]
	s_mul_i32 s10, s80, 0xd0
	v_lshl_add_u64 v[64:65], v[58:59], 0, s[10:11]
	s_mul_i32 s10, s80, 0xd8
	v_lshl_add_u64 v[72:73], v[58:59], 0, s[10:11]
	s_mul_i32 s10, s80, 0xe0
	v_lshl_add_u64 v[74:75], v[58:59], 0, s[10:11]
	s_mul_i32 s10, s80, 0xe8
	v_lshl_add_u64 v[76:77], v[58:59], 0, s[10:11]
	s_mul_i32 s10, s80, 0xf0
	v_lshl_add_u64 v[78:79], v[58:59], 0, s[10:11]
	s_mul_i32 s10, s80, 0xf8
	v_lshl_add_u64 v[94:95], v[58:59], 0, s[10:11]
	global_load_dword v58, v[60:61], off nt
	global_load_dword v59, v[62:63], off nt
	s_nop 0
	global_load_dword v60, v[64:65], off nt
	global_load_dword v61, v[72:73], off nt
	global_load_dword v62, v[74:75], off nt
	global_load_dword v63, v[76:77], off nt
	s_nop 0
	global_load_dword v64, v[78:79], off nt
	global_load_dword v65, v[94:95], off nt
	s_cmp_eq_u64 s[6:7], 0
	s_cbranch_scc1 .LBB0_54
	s_ashr_i32 s25, s24, 31
	s_lshl_b64 s[24:25], s[24:25], 2
	s_add_u32 s6, s6, s24
	s_addc_u32 s7, s7, s25
	v_lshlrev_b32_e32 v72, 2, v88
	global_load_dwordx4 v[76:79], v72, s[6:7]
	s_nop 0
	global_load_dwordx4 v[72:75], v72, s[6:7] offset:16
	s_branch .LBB0_55

.LBB0_64:
	s_andn2_b64 vcc, exec, s[18:19]
	v_lshlrev_b32_e32 v72, 2, v80
	s_cbranch_vccnz .LBB0_67
	s_and_b64 s[4:5], s[18:19], exec
	s_cselect_b32 s4, s33, 0
	s_ashr_i32 s5, s4, 31
	s_lshl_b64 s[4:5], s[4:5], 13
	v_ashrrev_i32_e32 v81, 31, v80
	s_add_u32 s4, s36, s4
	v_lshlrev_b64 v[34:35], 4, v[80:81]
	s_addc_u32 s5, s37, s5
	s_waitcnt vmcnt(2)
	v_lshl_add_u64 v[30:31], s[4:5], 0, v[34:35]
	v_add_co_u32_e32 v14, vcc, 0x1000, v30
	v_mbcnt_lo_u32_b32 v1, -1, 0
	s_nop 0
	v_addc_co_u32_e32 v15, vcc, 0, v31, vcc
	global_load_dwordx4 v[2:5], v[14:15], off offset:3072 nt
	global_load_dwordx4 v[6:9], v[14:15], off offset:2048 nt
	global_load_dwordx4 v[10:13], v[14:15], off offset:1024 nt
	s_nop 0
	global_load_dwordx4 v[14:17], v[14:15], off nt
	s_nop 0
	global_load_dwordx4 v[18:21], v[30:31], off offset:3072 nt
	global_load_dwordx4 v[22:25], v[30:31], off offset:2048 nt
	global_load_dwordx4 v[26:29], v[30:31], off offset:1024 nt
	s_nop 0
	global_load_dwordx4 v[30:33], v[30:31], off nt
	v_lshl_add_u64 v[66:67], s[36:37], 0, v[34:35]
	v_lshl_add_u64 v[70:71], s[38:39], 0, v[34:35]
	v_mbcnt_hi_u32_b32 v34, -1, v1
	v_and_b32_e32 v1, 64, v34
	v_add_u32_e32 v35, 64, v1
	v_xor_b32_e32 v1, 1, v34
	v_cmp_lt_i32_e32 vcc, v1, v35
	v_xor_b32_e32 v36, 2, v34
	s_mov_b64 s[4:5], 0x1000
	v_cndmask_b32_e32 v1, v34, v1, vcc
	v_cmp_lt_i32_e32 vcc, v36, v35
	v_lshl_add_u64 v[76:77], v[70:71], 0, s[4:5]
	s_mov_b64 s[4:5], 0x1400
	v_cndmask_b32_e32 v36, v34, v36, vcc
	v_lshlrev_b32_e32 v69, 2, v36
	v_xor_b32_e32 v36, 4, v34
	v_cmp_lt_i32_e32 vcc, v36, v35
	v_lshl_add_u64 v[78:79], v[70:71], 0, s[4:5]
	s_mov_b64 s[4:5], 0x1800
	v_cndmask_b32_e32 v36, v34, v36, vcc
	v_lshlrev_b32_e32 v81, 2, v36
	v_xor_b32_e32 v36, 8, v34
	v_cmp_lt_i32_e32 vcc, v36, v35
	v_ashrrev_i32_e32 v73, 31, v72
	v_lshl_add_u64 v[82:83], v[70:71], 0, s[4:5]
	v_cndmask_b32_e32 v36, v34, v36, vcc
	v_lshlrev_b32_e32 v86, 2, v36
	v_xor_b32_e32 v36, 16, v34
	v_cmp_lt_i32_e32 vcc, v36, v35
	s_mov_b64 s[4:5], 0x1c00
	s_movk_i32 s1, 0x1000
	v_cndmask_b32_e32 v36, v34, v36, vcc
	v_lshlrev_b32_e32 v87, 2, v36
	v_xor_b32_e32 v36, 32, v34
	v_cmp_lt_i32_e32 vcc, v36, v35
	v_lshlrev_b32_e32 v1, 2, v1
	v_lshl_add_u64 v[74:75], v[72:73], 1, s[68:69]
	v_cndmask_b32_e32 v34, v34, v36, vcc
	v_lshlrev_b32_e32 v88, 2, v34
	v_lshl_add_u64 v[84:85], v[70:71], 0, s[4:5]
	v_mov_b32_e32 v73, 0x358637bd
	s_mov_b32 s3, 0x800000
	s_movk_i32 s6, 0x7fff
	v_mov_b32_e32 v89, 1
	s_mov_b32 s5, s33
.LBB0_66:
	global_load_dwordx4 v[90:93], v[70:71], off
	s_waitcnt vmcnt(1)
	v_mov_b32_e32 v36, v31
	v_mov_b32_e32 v37, v27
	v_mov_b32_e32 v40, v33
	v_mov_b32_e32 v41, v29
	v_mov_b32_e32 v34, v30
	v_mov_b32_e32 v35, v26
	v_mov_b32_e32 v38, v32
	v_mov_b32_e32 v39, v28
	v_pk_mul_f32 v[42:43], v[24:25], v[24:25]
	v_pk_mul_f32 v[44:45], v[22:23], v[22:23]
	v_mul_f32_e32 v55, v14, v14
	v_mul_f32_e32 v57, v15, v15
	v_mul_f32_e32 v46, v19, v19
	v_mul_f32_e32 v48, v21, v21
	v_pk_mul_f32 v[50:51], v[12:13], v[12:13]
	v_pk_mul_f32 v[52:53], v[10:11], v[10:11]
	v_mul_f32_e32 v54, v7, v7
	v_mul_f32_e32 v56, v9, v9
	v_pk_mul_f32 v[36:37], v[36:37], v[36:37]
	v_pk_mul_f32 v[40:41], v[40:41], v[40:41]
	v_mul_f32_e32 v61, v4, v4
	v_mul_f32_e32 v62, v5, v5
	v_mov_b32_e32 v94, v30
	v_mov_b32_e32 v95, v32
	v_mov_b32_e32 v32, v31
	v_mov_b32_e32 v96, v26
	v_mov_b32_e32 v97, v28
	v_mov_b32_e32 v28, v27
	v_pk_mov_b32 v[26:27], v[44:45], v[42:43] op_sel:[1,0]
	v_mov_b32_e32 v45, v43
	v_pk_mov_b32 v[30:31], v[52:53], v[50:51] op_sel:[1,0]
	v_mov_b32_e32 v53, v51
	v_pk_fma_f32 v[42:43], v[18:19], v[18:19], v[46:47] op_sel_hi:[1,1,0]
	v_pk_fma_f32 v[46:47], v[20:21], v[20:21], v[48:49] op_sel_hi:[1,1,0]
	v_pk_fma_f32 v[48:49], v[6:7], v[6:7], v[54:55] op_sel_hi:[1,1,0]
	v_pk_fma_f32 v[50:51], v[8:9], v[8:9], v[56:57] op_sel_hi:[1,1,0]
	v_pk_fma_f32 v[34:35], v[34:35], v[34:35], v[36:37]
	v_pk_fma_f32 v[36:37], v[38:39], v[38:39], v[40:41]
	v_pk_add_f32 v[26:27], v[26:27], v[44:45]
	v_mov_b32_e32 v49, v61
	v_mov_b32_e32 v51, v62
	v_pk_add_f32 v[34:35], v[34:35], v[36:37]
	v_mul_f32_e32 v58, v16, v16
	v_mul_f32_e32 v59, v17, v17
	v_pk_add_f32 v[26:27], v[26:27], v[26:27] op_sel:[0,1] op_sel_hi:[1,0]
	v_pk_add_f32 v[98:99], v[48:49], v[50:51]
	v_pk_add_f32 v[50:51], v[34:35], v[34:35] op_sel:[0,1] op_sel_hi:[1,0]
	v_mov_b32_e32 v43, v58
	v_mov_b32_e32 v47, v59
	v_mov_b32_e32 v27, v57
	v_mov_b32_e32 v51, v55
	v_pk_add_f32 v[30:31], v[30:31], v[52:53]
	v_pk_add_f32 v[52:53], v[42:43], v[46:47]
	v_pk_add_f32 v[26:27], v[50:51], v[26:27]
	v_mul_f32_e32 v104, v2, v2
	v_pk_add_f32 v[26:27], v[26:27], v[52:53]
	v_mul_f32_e32 v60, v3, v3
	v_pk_add_f32 v[30:31], v[30:31], v[30:31] op_sel:[0,1] op_sel_hi:[1,0]
	v_pk_add_f32 v[26:27], v[26:27], v[26:27] op_sel:[0,1] op_sel_hi:[1,0]
	v_mov_b32_e32 v31, v60
	v_mov_b32_e32 v27, v104
	v_pk_add_f32 v[26:27], v[26:27], v[30:31]
	s_add_i32 s7, s5, s90
	v_pk_add_f32 v[26:27], v[26:27], v[98:99]
	s_cmpk_lt_i32 s7, 0x4000
	v_add_f32_e32 v26, v26, v27
	ds_bpermute_b32 v27, v1, v26
	s_cselect_b32 s4, s7, s5
	s_and_b32 s10, s5, 0xfff
	s_lshl_b32 s8, s5, 3
	s_ashr_i32 s5, s4, 31
	s_waitcnt lgkmcnt(0)
	v_add_f32_e32 v26, v26, v27
	ds_bpermute_b32 v27, v69, v26
	s_and_b32 s11, s8, 0xffff8000
	s_lshl_b64 s[8:9], s[4:5], 13
	v_lshl_add_u64 v[46:47], v[66:67], 0, s[8:9]
	v_add_co_u32_e32 v62, vcc, s1, v46
	s_waitcnt lgkmcnt(0)
	v_add_f32_e32 v26, v26, v27
	ds_bpermute_b32 v27, v81, v26
	v_addc_co_u32_e32 v63, vcc, 0, v47, vcc
	s_or_b32 s4, s11, s10
	s_ashr_i32 s5, s4, 31
	s_waitcnt lgkmcnt(0)
	v_add_f32_e32 v26, v26, v27
	ds_bpermute_b32 v27, v86, v26
	s_lshl_b64 s[8:9], s[4:5], 9
	v_lshl_add_u64 v[100:101], v[74:75], 0, s[8:9]
	global_load_dwordx4 v[34:37], v[46:47], off nt
	global_load_dwordx4 v[38:41], v[46:47], off offset:1024 nt
	global_load_dwordx4 v[42:45], v[46:47], off offset:2048 nt
	s_nop 0
	global_load_dwordx4 v[46:49], v[46:47], off offset:3072 nt
	s_waitcnt lgkmcnt(0)
	v_add_f32_e32 v26, v26, v27
	ds_bpermute_b32 v27, v87, v26
	global_load_dwordx4 v[50:53], v[62:63], off nt
	global_load_dwordx4 v[54:57], v[62:63], off offset:1024 nt
	global_load_dwordx4 v[58:61], v[62:63], off offset:2048 nt
	s_nop 0
	global_load_dwordx4 v[62:65], v[62:63], off offset:3072 nt
	s_or_b32 s10, s4, 0x1000
	s_ashr_i32 s11, s10, 31
	s_lshl_b64 s[10:11], s[10:11], 9
	s_waitcnt lgkmcnt(0)
	v_add_f32_e32 v26, v26, v27
	ds_bpermute_b32 v27, v88, v26
	v_lshl_add_u64 v[102:103], v[74:75], 0, s[10:11]
	s_or_b32 s8, s4, 0x2000
	s_ashr_i32 s9, s8, 31
	s_lshl_b64 s[8:9], s[8:9], 9
	s_waitcnt lgkmcnt(0)
	v_add_f32_e32 v26, v26, v27
	v_fmamk_f32 v26, v26, 0x3a000000, v73
	v_mul_f32_e32 v27, 0x4b800000, v26
	v_cmp_gt_f32_e32 vcc, s3, v26
	s_mov_b32 s5, s7
	s_nop 0
	v_cndmask_b32_e32 v26, v26, v27, vcc
	v_rsq_f32_e32 v26, v26
	s_nop 0
	v_mul_f32_e32 v27, 0x45800000, v26
	v_cndmask_b32_e32 v26, v26, v27, vcc
	v_pk_mul_f32 v[30:31], v[26:27], v[32:33] op_sel_hi:[0,1]
	v_pk_mul_f32 v[32:33], v[26:27], v[94:95] op_sel_hi:[0,1]
	s_waitcnt vmcnt(8)
	v_mov_b32_e32 v95, v92
	v_mov_b32_e32 v92, v91
	v_mov_b32_e32 v94, v90
	v_pk_mul_f32 v[30:31], v[92:93], v[30:31]
	v_pk_mul_f32 v[32:33], v[94:95], v[32:33]
	v_and_b32_sdwa v91, v31, v89 dst_sel:DWORD dst_unused:UNUSED_PAD src0_sel:WORD_1 src1_sel:DWORD
	v_and_b32_sdwa v92, v30, v89 dst_sel:DWORD dst_unused:UNUSED_PAD src0_sel:WORD_1 src1_sel:DWORD
	v_and_b32_sdwa v27, v33, v89 dst_sel:DWORD dst_unused:UNUSED_PAD src0_sel:WORD_1 src1_sel:DWORD
	v_and_b32_sdwa v90, v32, v89 dst_sel:DWORD dst_unused:UNUSED_PAD src0_sel:WORD_1 src1_sel:DWORD
	v_add3_u32 v31, v31, v91, s6
	v_add3_u32 v30, v30, v92, s6
	v_add3_u32 v32, v32, v90, s6
	v_add3_u32 v27, v33, v27, s6
	v_and_b32_e32 v31, 0xffff0000, v31
	v_and_b32_e32 v30, 0xffff0000, v30
	v_or_b32_sdwa v31, v31, v27 dst_sel:DWORD dst_unused:UNUSED_PAD src0_sel:DWORD src1_sel:WORD_1
	v_or_b32_sdwa v30, v30, v32 dst_sel:DWORD dst_unused:UNUSED_PAD src0_sel:DWORD src1_sel:WORD_1
	global_store_dwordx2 v[100:101], v[30:31], off
	global_load_dwordx4 v[30:33], v[70:71], off offset:1024
	v_pk_mul_f32 v[28:29], v[26:27], v[28:29] op_sel_hi:[0,1]
	v_pk_mul_f32 v[90:91], v[26:27], v[96:97] op_sel_hi:[0,1]
	s_waitcnt vmcnt(0)
	v_mov_b32_e32 v93, v32
	v_mov_b32_e32 v32, v31
	v_mov_b32_e32 v92, v30
	v_pk_mul_f32 v[28:29], v[32:33], v[28:29]
	v_pk_mul_f32 v[30:31], v[92:93], v[90:91]
	v_and_b32_sdwa v33, v29, v89 dst_sel:DWORD dst_unused:UNUSED_PAD src0_sel:WORD_1 src1_sel:DWORD
	v_and_b32_sdwa v90, v28, v89 dst_sel:DWORD dst_unused:UNUSED_PAD src0_sel:WORD_1 src1_sel:DWORD
	v_and_b32_sdwa v27, v31, v89 dst_sel:DWORD dst_unused:UNUSED_PAD src0_sel:WORD_1 src1_sel:DWORD
	v_and_b32_sdwa v32, v30, v89 dst_sel:DWORD dst_unused:UNUSED_PAD src0_sel:WORD_1 src1_sel:DWORD
	v_add3_u32 v29, v29, v33, s6
	v_add3_u32 v28, v28, v90, s6
	v_add3_u32 v30, v30, v32, s6
	v_add3_u32 v27, v31, v27, s6
	v_and_b32_e32 v29, 0xffff0000, v29
	v_and_b32_e32 v28, 0xffff0000, v28
	v_or_b32_sdwa v29, v29, v27 dst_sel:DWORD dst_unused:UNUSED_PAD src0_sel:DWORD src1_sel:WORD_1
	v_or_b32_sdwa v28, v28, v30 dst_sel:DWORD dst_unused:UNUSED_PAD src0_sel:DWORD src1_sel:WORD_1
	global_store_dwordx2 v[102:103], v[28:29], off
	global_load_dwordx4 v[28:31], v[70:71], off offset:2048
	v_mov_b32_e32 v33, v24
	v_mov_b32_e32 v24, v23
	v_mov_b32_e32 v32, v22
	v_pk_mul_f32 v[24:25], v[26:27], v[24:25] op_sel_hi:[0,1]
	v_pk_mul_f32 v[32:33], v[26:27], v[32:33] op_sel_hi:[0,1]
	v_lshl_add_u64 v[22:23], v[74:75], 0, s[8:9]
	s_or_b32 s8, s4, 0x3000
	s_ashr_i32 s9, s8, 31
	s_lshl_b64 s[8:9], s[8:9], 9
	s_waitcnt vmcnt(0)
	v_mov_b32_e32 v91, v30
	v_mov_b32_e32 v30, v29
	v_mov_b32_e32 v90, v28
	v_pk_mul_f32 v[24:25], v[30:31], v[24:25]
	v_pk_mul_f32 v[28:29], v[90:91], v[32:33]
	v_and_b32_sdwa v31, v25, v89 dst_sel:DWORD dst_unused:UNUSED_PAD src0_sel:WORD_1 src1_sel:DWORD
	v_and_b32_sdwa v32, v24, v89 dst_sel:DWORD dst_unused:UNUSED_PAD src0_sel:WORD_1 src1_sel:DWORD
	v_and_b32_sdwa v27, v29, v89 dst_sel:DWORD dst_unused:UNUSED_PAD src0_sel:WORD_1 src1_sel:DWORD
	v_and_b32_sdwa v30, v28, v89 dst_sel:DWORD dst_unused:UNUSED_PAD src0_sel:WORD_1 src1_sel:DWORD
	v_add3_u32 v25, v25, v31, s6
	v_add3_u32 v24, v24, v32, s6
	v_add3_u32 v28, v28, v30, s6
	v_add3_u32 v27, v29, v27, s6
	v_and_b32_e32 v25, 0xffff0000, v25
	v_and_b32_e32 v24, 0xffff0000, v24
	v_or_b32_sdwa v25, v25, v27 dst_sel:DWORD dst_unused:UNUSED_PAD src0_sel:DWORD src1_sel:WORD_1
	v_or_b32_sdwa v24, v24, v28 dst_sel:DWORD dst_unused:UNUSED_PAD src0_sel:DWORD src1_sel:WORD_1
	global_store_dwordx2 v[22:23], v[24:25], off
	global_load_dwordx4 v[22:25], v[70:71], off offset:3072
	v_mov_b32_e32 v29, v20
	v_mov_b32_e32 v20, v19
	v_mov_b32_e32 v28, v18
	v_pk_mul_f32 v[20:21], v[26:27], v[20:21] op_sel_hi:[0,1]
	v_pk_mul_f32 v[28:29], v[26:27], v[28:29] op_sel_hi:[0,1]
	v_lshl_add_u64 v[18:19], v[74:75], 0, s[8:9]
	s_or_b32 s8, s4, 0x4000
	s_ashr_i32 s9, s8, 31
	s_lshl_b64 s[8:9], s[8:9], 9
	s_waitcnt vmcnt(0)
	v_mov_b32_e32 v31, v24
	v_mov_b32_e32 v24, v23
	v_mov_b32_e32 v30, v22
	v_pk_mul_f32 v[20:21], v[24:25], v[20:21]
	v_pk_mul_f32 v[22:23], v[30:31], v[28:29]
	v_and_b32_sdwa v27, v21, v89 dst_sel:DWORD dst_unused:UNUSED_PAD src0_sel:WORD_1 src1_sel:DWORD
	v_and_b32_sdwa v28, v20, v89 dst_sel:DWORD dst_unused:UNUSED_PAD src0_sel:WORD_1 src1_sel:DWORD
	v_and_b32_sdwa v24, v23, v89 dst_sel:DWORD dst_unused:UNUSED_PAD src0_sel:WORD_1 src1_sel:DWORD
	v_and_b32_sdwa v25, v22, v89 dst_sel:DWORD dst_unused:UNUSED_PAD src0_sel:WORD_1 src1_sel:DWORD
	v_add3_u32 v21, v21, v27, s6
	v_add3_u32 v20, v20, v28, s6
	v_add3_u32 v22, v22, v25, s6
	v_add3_u32 v23, v23, v24, s6
	v_and_b32_e32 v21, 0xffff0000, v21
	v_and_b32_e32 v20, 0xffff0000, v20
	v_or_b32_sdwa v21, v21, v23 dst_sel:DWORD dst_unused:UNUSED_PAD src0_sel:DWORD src1_sel:WORD_1
	v_or_b32_sdwa v20, v20, v22 dst_sel:DWORD dst_unused:UNUSED_PAD src0_sel:DWORD src1_sel:WORD_1
	global_store_dwordx2 v[18:19], v[20:21], off
	global_load_dwordx4 v[18:21], v[76:77], off
	v_mov_b32_e32 v23, v16
	v_mov_b32_e32 v16, v15
	v_mov_b32_e32 v22, v14
	v_pk_mul_f32 v[16:17], v[26:27], v[16:17] op_sel_hi:[0,1]
	v_pk_mul_f32 v[22:23], v[26:27], v[22:23] op_sel_hi:[0,1]
	v_lshl_add_u64 v[14:15], v[74:75], 0, s[8:9]
	s_or_b32 s8, s4, 0x5000
	s_ashr_i32 s9, s8, 31
	s_lshl_b64 s[8:9], s[8:9], 9
	v_mov_b64_e32 v[30:31], v[34:35]
	v_mov_b64_e32 v[32:33], v[36:37]
	s_waitcnt vmcnt(0)
	v_mov_b32_e32 v25, v20
	v_mov_b32_e32 v20, v19
	v_mov_b32_e32 v24, v18
	v_pk_mul_f32 v[16:17], v[20:21], v[16:17]
	v_pk_mul_f32 v[18:19], v[24:25], v[22:23]
	v_and_b32_sdwa v22, v17, v89 dst_sel:DWORD dst_unused:UNUSED_PAD src0_sel:WORD_1 src1_sel:DWORD
	v_and_b32_sdwa v23, v16, v89 dst_sel:DWORD dst_unused:UNUSED_PAD src0_sel:WORD_1 src1_sel:DWORD
	v_and_b32_sdwa v20, v19, v89 dst_sel:DWORD dst_unused:UNUSED_PAD src0_sel:WORD_1 src1_sel:DWORD
	v_and_b32_sdwa v21, v18, v89 dst_sel:DWORD dst_unused:UNUSED_PAD src0_sel:WORD_1 src1_sel:DWORD
	v_add3_u32 v17, v17, v22, s6
	v_add3_u32 v16, v16, v23, s6
	v_add3_u32 v18, v18, v21, s6
	v_add3_u32 v19, v19, v20, s6
	v_and_b32_e32 v17, 0xffff0000, v17
	v_and_b32_e32 v16, 0xffff0000, v16
	v_or_b32_sdwa v17, v17, v19 dst_sel:DWORD dst_unused:UNUSED_PAD src0_sel:DWORD src1_sel:WORD_1
	v_or_b32_sdwa v16, v16, v18 dst_sel:DWORD dst_unused:UNUSED_PAD src0_sel:DWORD src1_sel:WORD_1
	global_store_dwordx2 v[14:15], v[16:17], off
	global_load_dwordx4 v[14:17], v[78:79], off
	v_mov_b32_e32 v19, v12
	v_mov_b32_e32 v12, v11
	v_mov_b32_e32 v18, v10
	v_pk_mul_f32 v[12:13], v[26:27], v[12:13] op_sel_hi:[0,1]
	v_pk_mul_f32 v[18:19], v[26:27], v[18:19] op_sel_hi:[0,1]
	v_lshl_add_u64 v[10:11], v[74:75], 0, s[8:9]
	s_or_b32 s8, s4, 0x6000
	s_ashr_i32 s9, s8, 31
	s_lshl_b64 s[8:9], s[8:9], 9
	v_mov_b64_e32 v[22:23], v[42:43]
	v_mov_b64_e32 v[24:25], v[44:45]
	s_waitcnt vmcnt(0)
	v_mov_b32_e32 v21, v16
	v_mov_b32_e32 v16, v15
	v_mov_b32_e32 v20, v14
	v_pk_mul_f32 v[12:13], v[16:17], v[12:13]
	v_pk_mul_f32 v[14:15], v[20:21], v[18:19]
	v_and_b32_sdwa v18, v13, v89 dst_sel:DWORD dst_unused:UNUSED_PAD src0_sel:WORD_1 src1_sel:DWORD
	v_and_b32_sdwa v19, v12, v89 dst_sel:DWORD dst_unused:UNUSED_PAD src0_sel:WORD_1 src1_sel:DWORD
	v_and_b32_sdwa v16, v15, v89 dst_sel:DWORD dst_unused:UNUSED_PAD src0_sel:WORD_1 src1_sel:DWORD
	v_and_b32_sdwa v17, v14, v89 dst_sel:DWORD dst_unused:UNUSED_PAD src0_sel:WORD_1 src1_sel:DWORD
	v_add3_u32 v13, v13, v18, s6
	v_add3_u32 v12, v12, v19, s6
	v_add3_u32 v14, v14, v17, s6
	v_add3_u32 v15, v15, v16, s6
	v_and_b32_e32 v13, 0xffff0000, v13
	v_and_b32_e32 v12, 0xffff0000, v12
	v_or_b32_sdwa v13, v13, v15 dst_sel:DWORD dst_unused:UNUSED_PAD src0_sel:DWORD src1_sel:WORD_1
	v_or_b32_sdwa v12, v12, v14 dst_sel:DWORD dst_unused:UNUSED_PAD src0_sel:DWORD src1_sel:WORD_1
	global_store_dwordx2 v[10:11], v[12:13], off
	global_load_dwordx4 v[10:13], v[82:83], off
	v_mov_b32_e32 v15, v8
	v_mov_b32_e32 v8, v7
	v_mov_b32_e32 v14, v6
	v_pk_mul_f32 v[8:9], v[26:27], v[8:9] op_sel_hi:[0,1]
	v_pk_mul_f32 v[14:15], v[26:27], v[14:15] op_sel_hi:[0,1]
	v_lshl_add_u64 v[6:7], v[74:75], 0, s[8:9]
	s_or_b32 s8, s4, 0x7000
	s_ashr_i32 s9, s8, 31
	s_lshl_b64 s[8:9], s[8:9], 9
	v_mov_b64_e32 v[18:19], v[46:47]
	s_cmpk_gt_i32 s7, 0x3fff
	v_lshl_add_u64 v[94:95], v[74:75], 0, s[8:9]
	v_mov_b64_e32 v[20:21], v[48:49]
	s_waitcnt vmcnt(0)
	v_mov_b32_e32 v17, v12
	v_mov_b32_e32 v12, v11
	v_mov_b32_e32 v16, v10
	v_pk_mul_f32 v[8:9], v[12:13], v[8:9]
	v_pk_mul_f32 v[10:11], v[16:17], v[14:15]
	v_and_b32_sdwa v14, v9, v89 dst_sel:DWORD dst_unused:UNUSED_PAD src0_sel:WORD_1 src1_sel:DWORD
	v_and_b32_sdwa v15, v8, v89 dst_sel:DWORD dst_unused:UNUSED_PAD src0_sel:WORD_1 src1_sel:DWORD
	v_and_b32_sdwa v12, v11, v89 dst_sel:DWORD dst_unused:UNUSED_PAD src0_sel:WORD_1 src1_sel:DWORD
	v_and_b32_sdwa v13, v10, v89 dst_sel:DWORD dst_unused:UNUSED_PAD src0_sel:WORD_1 src1_sel:DWORD
	v_add3_u32 v9, v9, v14, s6
	v_add3_u32 v8, v8, v15, s6
	v_add3_u32 v10, v10, v13, s6
	v_add3_u32 v11, v11, v12, s6
	v_and_b32_e32 v9, 0xffff0000, v9
	v_and_b32_e32 v8, 0xffff0000, v8
	v_or_b32_sdwa v9, v9, v11 dst_sel:DWORD dst_unused:UNUSED_PAD src0_sel:DWORD src1_sel:WORD_1
	v_or_b32_sdwa v8, v8, v10 dst_sel:DWORD dst_unused:UNUSED_PAD src0_sel:DWORD src1_sel:WORD_1
	global_store_dwordx2 v[6:7], v[8:9], off
	global_load_dwordx4 v[90:93], v[84:85], off
	v_mov_b32_e32 v7, v4
	v_mov_b32_e32 v4, v3
	v_mov_b32_e32 v6, v2
	v_pk_mul_f32 v[98:99], v[26:27], v[4:5] op_sel_hi:[0,1]
	v_pk_mul_f32 v[96:97], v[26:27], v[6:7] op_sel_hi:[0,1]
	v_mov_b64_e32 v[26:27], v[38:39]
	v_mov_b64_e32 v[28:29], v[40:41]
	v_mov_b64_e32 v[14:15], v[50:51]
	v_mov_b64_e32 v[10:11], v[54:55]
	v_mov_b64_e32 v[6:7], v[58:59]
	v_mov_b64_e32 v[2:3], v[62:63]
	v_mov_b64_e32 v[16:17], v[52:53]
	v_mov_b64_e32 v[12:13], v[56:57]
	v_mov_b64_e32 v[8:9], v[60:61]
	v_mov_b64_e32 v[4:5], v[64:65]
	s_waitcnt vmcnt(0)
	v_mov_b32_e32 v35, v92
	v_mov_b32_e32 v92, v91
	v_mov_b32_e32 v34, v90
	v_pk_mul_f32 v[36:37], v[92:93], v[98:99]
	v_pk_mul_f32 v[34:35], v[34:35], v[96:97]
	v_and_b32_sdwa v40, v37, v89 dst_sel:DWORD dst_unused:UNUSED_PAD src0_sel:WORD_1 src1_sel:DWORD
	v_and_b32_sdwa v41, v36, v89 dst_sel:DWORD dst_unused:UNUSED_PAD src0_sel:WORD_1 src1_sel:DWORD
	v_and_b32_sdwa v38, v35, v89 dst_sel:DWORD dst_unused:UNUSED_PAD src0_sel:WORD_1 src1_sel:DWORD
	v_and_b32_sdwa v39, v34, v89 dst_sel:DWORD dst_unused:UNUSED_PAD src0_sel:WORD_1 src1_sel:DWORD
	v_add3_u32 v37, v37, v40, s6
	v_add3_u32 v36, v36, v41, s6
	v_add3_u32 v34, v34, v39, s6
	v_add3_u32 v35, v35, v38, s6
	v_and_b32_e32 v37, 0xffff0000, v37
	v_and_b32_e32 v36, 0xffff0000, v36
	v_or_b32_sdwa v35, v37, v35 dst_sel:DWORD dst_unused:UNUSED_PAD src0_sel:DWORD src1_sel:WORD_1
	v_or_b32_sdwa v34, v36, v34 dst_sel:DWORD dst_unused:UNUSED_PAD src0_sel:DWORD src1_sel:WORD_1
	global_store_dwordx2 v[94:95], v[34:35], off
	s_cbranch_scc0 .LBB0_66

.Ltk0_unit:
	s_lshl_b32 s26, s24, 9
	s_lshl_b32 s20, s23, 12
	s_add_i32 s26, s26, s20
	s_add_i32 s26, s26, 0x1c000000
	s_add_u32 s16, s54, s26
	s_addc_u32 s17, s55, 0
	s_lshl_b32 s26, s24, 16
	s_add_i32 s26, s26, 0x300000
	s_add_u32 s18, s54, s26
	s_addc_u32 s19, s55, 0
	s_lshl_b32 s20, s23, 9
	s_lshl_b32 s26, s24, 6
	s_add_i32 s20, s20, s26
	s_add_i32 s26, s20, 0x28000000
	s_add_u32 s28, s54, s26
	s_addc_u32 s29, s55, 0
	s_add_i32 s26, s20, 0x28800000
	s_add_u32 s30, s54, s26
	s_addc_u32 s31, s55, 0
	s_barrier
	global_load_dwordx4 v[0:3], v242, s[18:19]
	v_add_u32_e32 v247, 0x2000, v242
	global_load_dwordx4 v[4:7], v247, s[18:19]
	v_add_u32_e32 v247, 0x4000, v242
	global_load_dwordx4 v[8:11], v247, s[18:19]
	v_add_u32_e32 v247, 0x6000, v242
	global_load_dwordx4 v[12:15], v247, s[18:19]
	v_add_u32_e32 v247, 0x8000, v242
	global_load_dwordx4 v[16:19], v247, s[18:19]
	v_add_u32_e32 v247, 0xa000, v242
	global_load_dwordx4 v[20:23], v247, s[18:19]
	v_add_u32_e32 v247, 0xc000, v242
	global_load_dwordx4 v[24:27], v247, s[18:19]
	v_add_u32_e32 v247, 0xe000, v242
	global_load_dwordx4 v[28:31], v247, s[18:19]
	global_load_dwordx4 v[64:67], v239, s[16:17] offset:0 nt
	global_load_dwordx4 v[68:71], v239, s[16:17] offset:32 nt
	global_load_dwordx4 v[72:75], v239, s[16:17] offset:64 nt
	global_load_dwordx4 v[76:79], v239, s[16:17] offset:96 nt
	global_load_dwordx4 v[80:83], v239, s[16:17] offset:128 nt
	global_load_dwordx4 v[84:87], v239, s[16:17] offset:160 nt
	global_load_dwordx4 v[88:91], v239, s[16:17] offset:192 nt
	global_load_dwordx4 v[92:95], v239, s[16:17] offset:224 nt
	s_waitcnt vmcnt(15)
	ds_write_b128 v243, v[0:3] offset:0
	s_waitcnt vmcnt(14)
	ds_write_b128 v243, v[4:7] offset:8192
	s_waitcnt vmcnt(13)
	ds_write_b128 v243, v[8:11] offset:16384
	s_waitcnt vmcnt(12)
	ds_write_b128 v243, v[12:15] offset:24576
	s_waitcnt vmcnt(11)
	ds_write_b128 v243, v[16:19] offset:32768
	s_waitcnt vmcnt(10)
	ds_write_b128 v243, v[20:23] offset:40960
	s_waitcnt vmcnt(9)
	ds_write_b128 v243, v[24:27] offset:49152
	s_waitcnt vmcnt(8)
	ds_write_b128 v243, v[28:31] offset:57344
	s_waitcnt lgkmcnt(0)
	s_barrier
	ds_read_b128 v[96:99], v215 offset:0
	ds_read_b128 v[100:103], v232 offset:0
	ds_read_b128 v[104:107], v233 offset:0
	ds_read_b128 v[108:111], v234 offset:0
	ds_read_b128 v[112:115], v235 offset:0
	ds_read_b128 v[116:119], v236 offset:0
	ds_read_b128 v[120:123], v237 offset:0
	ds_read_b128 v[124:127], v238 offset:0
	s_waitcnt vmcnt(0)
	s_waitcnt lgkmcnt(4)
	v_mfma_f32_32x32x16_bf16 v[0:15], v[96:99], v[64:67], 0
	v_mfma_f32_32x32x16_bf16 v[0:15], v[100:103], v[68:71], v[0:15]
	v_mfma_f32_32x32x16_bf16 v[0:15], v[104:107], v[72:75], v[0:15]
	v_mfma_f32_32x32x16_bf16 v[0:15], v[108:111], v[76:79], v[0:15]
	ds_read_b128 v[96:99], v215 offset:8192
	ds_read_b128 v[100:103], v232 offset:8192
	ds_read_b128 v[104:107], v233 offset:8192
	ds_read_b128 v[108:111], v234 offset:8192
	s_waitcnt lgkmcnt(4)
	v_mfma_f32_32x32x16_bf16 v[0:15], v[112:115], v[80:83], v[0:15]
	v_mfma_f32_32x32x16_bf16 v[0:15], v[116:119], v[84:87], v[0:15]
	v_mfma_f32_32x32x16_bf16 v[0:15], v[120:123], v[88:91], v[0:15]
	v_mfma_f32_32x32x16_bf16 v[0:15], v[124:127], v[92:95], v[0:15]
	ds_read_b128 v[112:115], v235 offset:8192
	ds_read_b128 v[116:119], v236 offset:8192
	ds_read_b128 v[120:123], v237 offset:8192
	ds_read_b128 v[124:127], v238 offset:8192
	s_waitcnt lgkmcnt(4)
	v_mfma_f32_32x32x16_bf16 v[16:31], v[96:99], v[64:67], 0
	v_mfma_f32_32x32x16_bf16 v[16:31], v[100:103], v[68:71], v[16:31]
	v_mfma_f32_32x32x16_bf16 v[16:31], v[104:107], v[72:75], v[16:31]
	v_mfma_f32_32x32x16_bf16 v[16:31], v[108:111], v[76:79], v[16:31]
	ds_read_b128 v[96:99], v215 offset:16384
	ds_read_b128 v[100:103], v232 offset:16384
	ds_read_b128 v[104:107], v233 offset:16384
	ds_read_b128 v[108:111], v234 offset:16384
	s_waitcnt lgkmcnt(4)
	v_mfma_f32_32x32x16_bf16 v[16:31], v[112:115], v[80:83], v[16:31]
	v_mfma_f32_32x32x16_bf16 v[16:31], v[116:119], v[84:87], v[16:31]
	v_mfma_f32_32x32x16_bf16 v[16:31], v[120:123], v[88:91], v[16:31]
	v_mfma_f32_32x32x16_bf16 v[16:31], v[124:127], v[92:95], v[16:31]
	ds_read_b128 v[112:115], v235 offset:16384
	ds_read_b128 v[116:119], v236 offset:16384
	ds_read_b128 v[120:123], v237 offset:16384
	ds_read_b128 v[124:127], v238 offset:16384
	s_waitcnt lgkmcnt(4)
	v_mfma_f32_32x32x16_bf16 v[32:47], v[96:99], v[64:67], 0
	v_mfma_f32_32x32x16_bf16 v[32:47], v[100:103], v[68:71], v[32:47]
	v_mfma_f32_32x32x16_bf16 v[32:47], v[104:107], v[72:75], v[32:47]
	v_mfma_f32_32x32x16_bf16 v[32:47], v[108:111], v[76:79], v[32:47]
	ds_read_b128 v[96:99], v215 offset:24576
	ds_read_b128 v[100:103], v232 offset:24576
	ds_read_b128 v[104:107], v233 offset:24576
	ds_read_b128 v[108:111], v234 offset:24576
	s_waitcnt lgkmcnt(4)
	v_mfma_f32_32x32x16_bf16 v[32:47], v[112:115], v[80:83], v[32:47]
	v_mfma_f32_32x32x16_bf16 v[32:47], v[116:119], v[84:87], v[32:47]
	v_mfma_f32_32x32x16_bf16 v[32:47], v[120:123], v[88:91], v[32:47]
	v_mfma_f32_32x32x16_bf16 v[32:47], v[124:127], v[92:95], v[32:47]
	ds_read_b128 v[112:115], v235 offset:24576
	ds_read_b128 v[116:119], v236 offset:24576
	ds_read_b128 v[120:123], v237 offset:24576
	ds_read_b128 v[124:127], v238 offset:24576
	s_waitcnt lgkmcnt(4)
	v_mfma_f32_32x32x16_bf16 v[48:63], v[96:99], v[64:67], 0
	v_mfma_f32_32x32x16_bf16 v[48:63], v[100:103], v[68:71], v[48:63]
	v_mfma_f32_32x32x16_bf16 v[48:63], v[104:107], v[72:75], v[48:63]
	v_mfma_f32_32x32x16_bf16 v[48:63], v[108:111], v[76:79], v[48:63]
	s_waitcnt lgkmcnt(0)
	v_mfma_f32_32x32x16_bf16 v[48:63], v[112:115], v[80:83], v[48:63]
	v_mfma_f32_32x32x16_bf16 v[48:63], v[116:119], v[84:87], v[48:63]
	v_mfma_f32_32x32x16_bf16 v[48:63], v[120:123], v[88:91], v[48:63]
	v_mfma_f32_32x32x16_bf16 v[48:63], v[124:127], v[92:95], v[48:63]
	global_load_dwordx4 v[64:67], v239, s[16:17] offset:256 nt
	global_load_dwordx4 v[68:71], v239, s[16:17] offset:288 nt
	global_load_dwordx4 v[72:75], v239, s[16:17] offset:320 nt
	global_load_dwordx4 v[76:79], v239, s[16:17] offset:352 nt
	global_load_dwordx4 v[80:83], v239, s[16:17] offset:384 nt
	global_load_dwordx4 v[84:87], v239, s[16:17] offset:416 nt
	global_load_dwordx4 v[88:91], v239, s[16:17] offset:448 nt
	global_load_dwordx4 v[92:95], v239, s[16:17] offset:480 nt
	s_nop 11
	v_and_or_b32 v0, v0, s6, v211
	v_or_b32_e32 v0, 0x7b, v0
	v_and_or_b32 v1, v1, s6, v211
	v_or_b32_e32 v1, 0x7a, v1
	v_and_or_b32 v2, v2, s6, v211
	v_or_b32_e32 v2, 0x79, v2
	v_and_or_b32 v3, v3, s6, v211
	v_or_b32_e32 v3, 0x78, v3
	v_and_or_b32 v4, v4, s6, v211
	v_or_b32_e32 v4, 0x73, v4
	v_and_or_b32 v5, v5, s6, v211
	v_or_b32_e32 v5, 0x72, v5
	v_and_or_b32 v6, v6, s6, v211
	v_or_b32_e32 v6, 0x71, v6
	v_and_or_b32 v7, v7, s6, v211
	v_or_b32_e32 v7, 0x70, v7
	v_and_or_b32 v8, v8, s6, v211
	v_or_b32_e32 v8, 0x6b, v8
	v_and_or_b32 v9, v9, s6, v211
	v_or_b32_e32 v9, 0x6a, v9
	v_and_or_b32 v10, v10, s6, v211
	v_or_b32_e32 v10, 0x69, v10
	v_and_or_b32 v11, v11, s6, v211
	v_or_b32_e32 v11, 0x68, v11
	v_and_or_b32 v12, v12, s6, v211
	v_or_b32_e32 v12, 0x63, v12
	v_and_or_b32 v13, v13, s6, v211
	v_or_b32_e32 v13, 0x62, v13
	v_and_or_b32 v14, v14, s6, v211
	v_or_b32_e32 v14, 0x61, v14
	v_and_or_b32 v15, v15, s6, v211
	v_or_b32_e32 v15, 0x60, v15
	v_and_or_b32 v16, v16, s6, v211
	v_or_b32_e32 v16, 0x5b, v16
	v_and_or_b32 v17, v17, s6, v211
	v_or_b32_e32 v17, 0x5a, v17
	v_and_or_b32 v18, v18, s6, v211
	v_or_b32_e32 v18, 0x59, v18
	v_and_or_b32 v19, v19, s6, v211
	v_or_b32_e32 v19, 0x58, v19
	v_and_or_b32 v20, v20, s6, v211
	v_or_b32_e32 v20, 0x53, v20
	v_and_or_b32 v21, v21, s6, v211
	v_or_b32_e32 v21, 0x52, v21
	v_and_or_b32 v22, v22, s6, v211
	v_or_b32_e32 v22, 0x51, v22
	v_and_or_b32 v23, v23, s6, v211
	v_or_b32_e32 v23, 0x50, v23
	v_and_or_b32 v24, v24, s6, v211
	v_or_b32_e32 v24, 0x4b, v24
	v_and_or_b32 v25, v25, s6, v211
	v_or_b32_e32 v25, 0x4a, v25
	v_and_or_b32 v26, v26, s6, v211
	v_or_b32_e32 v26, 0x49, v26
	v_and_or_b32 v27, v27, s6, v211
	v_or_b32_e32 v27, 0x48, v27
	v_and_or_b32 v28, v28, s6, v211
	v_or_b32_e32 v28, 0x43, v28
	v_and_or_b32 v29, v29, s6, v211
	v_or_b32_e32 v29, 0x42, v29
	v_and_or_b32 v30, v30, s6, v211
	v_or_b32_e32 v30, 0x41, v30
	v_and_or_b32 v31, v31, s6, v211
	v_or_b32_e32 v31, 64, v31
	v_and_or_b32 v32, v32, s6, v211
	v_or_b32_e32 v32, 59, v32
	v_and_or_b32 v33, v33, s6, v211
	v_or_b32_e32 v33, 58, v33
	v_and_or_b32 v34, v34, s6, v211
	v_or_b32_e32 v34, 57, v34
	v_and_or_b32 v35, v35, s6, v211
	v_or_b32_e32 v35, 56, v35
	v_and_or_b32 v36, v36, s6, v211
	v_or_b32_e32 v36, 51, v36
	v_and_or_b32 v37, v37, s6, v211
	v_or_b32_e32 v37, 50, v37
	v_and_or_b32 v38, v38, s6, v211
	v_or_b32_e32 v38, 49, v38
	v_and_or_b32 v39, v39, s6, v211
	v_or_b32_e32 v39, 48, v39
	v_and_or_b32 v40, v40, s6, v211
	v_or_b32_e32 v40, 43, v40
	v_and_or_b32 v41, v41, s6, v211
	v_or_b32_e32 v41, 42, v41
	v_and_or_b32 v42, v42, s6, v211
	v_or_b32_e32 v42, 41, v42
	v_and_or_b32 v43, v43, s6, v211
	v_or_b32_e32 v43, 40, v43
	v_and_or_b32 v44, v44, s6, v211
	v_or_b32_e32 v44, 35, v44
	v_and_or_b32 v45, v45, s6, v211
	v_or_b32_e32 v45, 34, v45
	v_and_or_b32 v46, v46, s6, v211
	v_or_b32_e32 v46, 33, v46
	v_and_or_b32 v47, v47, s6, v211
	v_or_b32_e32 v47, 32, v47
	v_and_or_b32 v48, v48, s6, v211
	v_or_b32_e32 v48, 27, v48
	v_and_or_b32 v49, v49, s6, v211
	v_or_b32_e32 v49, 26, v49
	v_and_or_b32 v50, v50, s6, v211
	v_or_b32_e32 v50, 25, v50
	v_and_or_b32 v51, v51, s6, v211
	v_or_b32_e32 v51, 24, v51
	v_and_or_b32 v52, v52, s6, v211
	v_or_b32_e32 v52, 19, v52
	v_and_or_b32 v53, v53, s6, v211
	v_or_b32_e32 v53, 18, v53
	v_and_or_b32 v54, v54, s6, v211
	v_or_b32_e32 v54, 17, v54
	v_and_or_b32 v55, v55, s6, v211
	v_or_b32_e32 v55, 16, v55
	v_and_or_b32 v56, v56, s6, v211
	v_or_b32_e32 v56, 11, v56
	v_and_or_b32 v57, v57, s6, v211
	v_or_b32_e32 v57, 10, v57
	v_and_or_b32 v58, v58, s6, v211
	v_or_b32_e32 v58, 9, v58
	v_and_or_b32 v59, v59, s6, v211
	v_or_b32_e32 v59, 8, v59
	v_and_or_b32 v60, v60, s6, v211
	v_or_b32_e32 v60, 3, v60
	v_and_or_b32 v61, v61, s6, v211
	v_or_b32_e32 v61, 2, v61
	v_and_or_b32 v62, v62, s6, v211
	v_or_b32_e32 v62, 1, v62
	v_and_or_b32 v63, v63, s6, v211
	v_or_b32_e32 v63, 0, v63
	v_max_f32_e32 v144, v0, v13
	v_min_f32_e32 v13, v0, v13
	v_max_f32_e32 v145, v1, v12
	v_min_f32_e32 v12, v1, v12
	v_max_f32_e32 v146, v2, v15
	v_min_f32_e32 v15, v2, v15
	v_max_f32_e32 v147, v3, v14
	v_min_f32_e32 v14, v3, v14
	v_max_f32_e32 v148, v4, v8
	v_min_f32_e32 v8, v4, v8
	v_max_f32_e32 v149, v5, v6
	v_min_f32_e32 v6, v5, v6
	v_max_f32_e32 v150, v7, v11
	v_min_f32_e32 v11, v7, v11
	v_max_f32_e32 v151, v9, v10
	v_min_f32_e32 v10, v9, v10
	v_max_f32_e32 v249, v144, v149
	v_min_f32_e32 v149, v144, v149
	v_max_f32_e32 v250, v145, v150
	v_min_f32_e32 v150, v145, v150
	v_max_f32_e32 v251, v146, v151
	v_min_f32_e32 v151, v146, v151
	v_max_f32_e32 v252, v147, v148
	v_min_f32_e32 v148, v147, v148
	v_max_f32_e32 v253, v6, v13
	v_min_f32_e32 v13, v6, v13
	v_max_f32_e32 v254, v8, v14
	v_min_f32_e32 v14, v8, v14
	v_max_f32_e32 v255, v10, v15
	v_min_f32_e32 v15, v10, v15
	v_max_f32_e32 v96, v11, v12
	v_min_f32_e32 v12, v11, v12
	v_max_f32_e32 v97, v249, v250
	v_min_f32_e32 v250, v249, v250
	v_max_f32_e32 v98, v251, v252
	v_min_f32_e32 v252, v251, v252
	v_max_f32_e32 v99, v148, v149
	v_min_f32_e32 v149, v148, v149
	v_max_f32_e32 v100, v253, v254
	v_min_f32_e32 v254, v253, v254
	v_max_f32_e32 v101, v150, v151
	v_min_f32_e32 v151, v150, v151
	v_max_f32_e32 v102, v255, v96
	v_min_f32_e32 v96, v255, v96
	v_max_f32_e32 v103, v12, v13
	v_min_f32_e32 v13, v12, v13
	v_max_f32_e32 v104, v14, v15
	v_min_f32_e32 v15, v14, v15
	v_max_f32_e32 v105, v97, v98
	v_min_f32_e32 v98, v97, v98
	v_max_f32_e32 v106, v250, v252
	v_min_f32_e32 v252, v250, v252
	v_max_f32_e32 v107, v99, v102
	v_min_f32_e32 v102, v99, v102
	v_max_f32_e32 v108, v149, v96
	v_min_f32_e32 v96, v149, v96
	v_max_f32_e32 v109, v100, v101
	v_min_f32_e32 v101, v100, v101
	v_max_f32_e32 v110, v254, v151
	v_min_f32_e32 v151, v254, v151
	v_max_f32_e32 v111, v103, v104
	v_min_f32_e32 v104, v103, v104
	v_max_f32_e32 v112, v13, v15
	v_min_f32_e32 v15, v13, v15
	v_max_f32_e32 v113, v106, v98
	v_min_f32_e32 v98, v106, v98
	v_max_f32_e32 v114, v252, v111
	v_min_f32_e32 v111, v252, v111
	v_max_f32_e32 v115, v107, v109
	v_min_f32_e32 v109, v107, v109
	v_max_f32_e32 v116, v108, v101
	v_min_f32_e32 v101, v108, v101
	v_max_f32_e32 v117, v110, v102
	v_min_f32_e32 v102, v110, v102
	v_max_f32_e32 v118, v151, v96
	v_min_f32_e32 v96, v151, v96
	v_max_f32_e32 v119, v112, v104
	v_min_f32_e32 v104, v112, v104
	v_max_f32_e32 v120, v113, v115
	v_min_f32_e32 v115, v113, v115
	v_max_f32_e32 v121, v98, v109
	v_min_f32_e32 v109, v98, v109
	v_max_f32_e32 v122, v116, v117
	v_min_f32_e32 v117, v116, v117
	v_max_f32_e32 v123, v101, v102
	v_min_f32_e32 v102, v101, v102
	v_max_f32_e32 v124, v118, v119
	v_min_f32_e32 v119, v118, v119
	v_max_f32_e32 v125, v96, v104
	v_min_f32_e32 v104, v96, v104
	v_max_f32_e32 v126, v121, v115
	v_min_f32_e32 v115, v121, v115
	v_max_f32_e32 v127, v114, v109
	v_min_f32_e32 v109, v114, v109
	v_max_f32_e32 v0, v124, v111
	v_min_f32_e32 v111, v124, v111
	v_max_f32_e32 v1, v125, v119
	v_min_f32_e32 v119, v125, v119
	v_max_f32_e32 v2, v127, v122
	v_min_f32_e32 v122, v127, v122
	v_max_f32_e32 v3, v109, v117
	v_min_f32_e32 v117, v109, v117
	v_max_f32_e32 v4, v123, v0
	v_min_f32_e32 v0, v123, v0
	v_max_f32_e32 v5, v102, v111
	v_min_f32_e32 v111, v102, v111
	v_max_f32_e32 v7, v2, v115
	v_min_f32_e32 v115, v2, v115
	v_max_f32_e32 v9, v122, v3
	v_min_f32_e32 v3, v122, v3
	v_max_f32_e32 v144, v4, v117
	v_min_f32_e32 v117, v4, v117
	v_max_f32_e32 v145, v0, v5
	v_min_f32_e32 v5, v0, v5
	v_max_f32_e32 v146, v1, v111
	v_min_f32_e32 v111, v1, v111
	v_max_f32_e32 v147, v3, v144
	v_min_f32_e32 v144, v3, v144
	v_max_f32_e32 v6, v117, v145
	v_min_f32_e32 v145, v117, v145
	v_max_f32_e32 v8, v16, v29
	v_min_f32_e32 v29, v16, v29
	v_max_f32_e32 v10, v17, v28
	v_min_f32_e32 v28, v17, v28
	v_max_f32_e32 v11, v18, v31
	v_min_f32_e32 v31, v18, v31
	v_max_f32_e32 v249, v19, v30
	v_min_f32_e32 v30, v19, v30
	v_max_f32_e32 v251, v20, v24
	v_min_f32_e32 v24, v20, v24
	v_max_f32_e32 v148, v21, v22
	v_min_f32_e32 v22, v21, v22
	v_max_f32_e32 v253, v23, v27
	v_min_f32_e32 v27, v23, v27
	v_max_f32_e32 v150, v25, v26
	v_min_f32_e32 v26, v25, v26
	v_max_f32_e32 v255, v8, v148
	v_min_f32_e32 v148, v8, v148
	v_max_f32_e32 v12, v10, v253
	v_min_f32_e32 v253, v10, v253
	v_max_f32_e32 v14, v11, v150
	v_min_f32_e32 v150, v11, v150
	v_max_f32_e32 v97, v249, v251
	v_min_f32_e32 v251, v249, v251
	v_max_f32_e32 v250, v22, v29
	v_min_f32_e32 v29, v22, v29
	v_max_f32_e32 v99, v24, v30
	v_min_f32_e32 v30, v24, v30
	v_max_f32_e32 v149, v26, v31
	v_min_f32_e32 v31, v26, v31
	v_max_f32_e32 v100, v27, v28
	v_min_f32_e32 v28, v27, v28
	v_max_f32_e32 v254, v255, v12
	v_min_f32_e32 v12, v255, v12
	v_max_f32_e32 v103, v14, v97
	v_min_f32_e32 v97, v14, v97
	v_max_f32_e32 v13, v251, v148
	v_min_f32_e32 v148, v251, v148
	v_max_f32_e32 v106, v250, v99
	v_min_f32_e32 v99, v250, v99
	v_max_f32_e32 v252, v253, v150
	v_min_f32_e32 v150, v253, v150
	v_max_f32_e32 v107, v149, v100
	v_min_f32_e32 v100, v149, v100
	v_max_f32_e32 v108, v28, v29
	v_min_f32_e32 v29, v28, v29
	v_max_f32_e32 v110, v30, v31
	v_min_f32_e32 v31, v30, v31
	v_max_f32_e32 v151, v254, v103
	v_min_f32_e32 v103, v254, v103
	v_max_f32_e32 v112, v12, v97
	v_min_f32_e32 v97, v12, v97
	v_max_f32_e32 v113, v13, v107
	v_min_f32_e32 v107, v13, v107
	v_max_f32_e32 v98, v148, v100
	v_min_f32_e32 v100, v148, v100
	v_max_f32_e32 v116, v106, v252
	v_min_f32_e32 v252, v106, v252
	v_max_f32_e32 v101, v99, v150
	v_min_f32_e32 v150, v99, v150
	v_max_f32_e32 v118, v108, v110
	v_min_f32_e32 v110, v108, v110
	v_max_f32_e32 v96, v29, v31
	v_min_f32_e32 v31, v29, v31
	v_max_f32_e32 v121, v112, v103
	v_min_f32_e32 v103, v112, v103
	v_max_f32_e32 v114, v97, v118
	v_min_f32_e32 v118, v97, v118
	v_max_f32_e32 v124, v113, v116
	v_min_f32_e32 v116, v113, v116
	v_max_f32_e32 v125, v98, v252
	v_min_f32_e32 v252, v98, v252
	v_max_f32_e32 v127, v101, v107
	v_min_f32_e32 v107, v101, v107
	v_max_f32_e32 v109, v150, v100
	v_min_f32_e32 v100, v150, v100
	v_max_f32_e32 v123, v96, v110
	v_min_f32_e32 v110, v96, v110
	v_max_f32_e32 v102, v121, v124
	v_min_f32_e32 v124, v121, v124
	v_max_f32_e32 v2, v103, v116
	v_min_f32_e32 v116, v103, v116
	v_max_f32_e32 v122, v125, v127
	v_min_f32_e32 v127, v125, v127
	v_max_f32_e32 v4, v252, v107
	v_min_f32_e32 v107, v252, v107
	v_max_f32_e32 v0, v109, v123
	v_min_f32_e32 v123, v109, v123
	v_max_f32_e32 v1, v100, v110
	v_min_f32_e32 v110, v100, v110
	v_max_f32_e32 v3, v2, v124
	v_min_f32_e32 v124, v2, v124
	v_max_f32_e32 v117, v114, v116
	v_min_f32_e32 v116, v114, v116
	v_max_f32_e32 v16, v0, v118
	v_min_f32_e32 v118, v0, v118
	v_max_f32_e32 v17, v1, v123
	v_min_f32_e32 v123, v1, v123
	v_max_f32_e32 v18, v117, v122
	v_min_f32_e32 v122, v117, v122
	v_max_f32_e32 v19, v116, v127
	v_min_f32_e32 v127, v116, v127
	v_max_f32_e32 v20, v4, v16
	v_min_f32_e32 v16, v4, v16
	v_max_f32_e32 v21, v107, v118
	v_min_f32_e32 v118, v107, v118
	v_max_f32_e32 v23, v18, v124
	v_min_f32_e32 v124, v18, v124
	v_max_f32_e32 v25, v122, v19
	v_min_f32_e32 v19, v122, v19
	v_max_f32_e32 v8, v20, v127
	v_min_f32_e32 v127, v20, v127
	v_max_f32_e32 v10, v16, v21
	v_min_f32_e32 v21, v16, v21
	v_max_f32_e32 v11, v17, v118
	v_min_f32_e32 v118, v17, v118
	v_max_f32_e32 v249, v19, v8
	v_min_f32_e32 v8, v19, v8
	v_max_f32_e32 v22, v127, v10
	v_min_f32_e32 v10, v127, v10
	s_waitcnt vmcnt(24)
	v_pk_mul_f32 v[160:161], v[160:161], v[176:177]
	v_pk_mul_f32 v[162:163], v[162:163], v[178:179]
	v_pk_mul_f32 v[164:165], v[164:165], v[180:181]
	v_pk_mul_f32 v[166:167], v[166:167], v[182:183]
	v_pk_mul_f32 v[168:169], v[168:169], v[184:185]
	v_pk_mul_f32 v[170:171], v[170:171], v[186:187]
	v_pk_mul_f32 v[172:173], v[172:173], v[188:189]
	v_pk_mul_f32 v[174:175], v[174:175], v[190:191]
	v_max3_f32 v192, |v160|, |v161|, |v162|
	v_max3_f32 v192, |v163|, |v164|, v192
	v_max3_f32 v192, |v165|, |v166|, v192
	v_max3_f32 v192, |v167|, |v168|, v192
	v_max3_f32 v192, |v169|, |v170|, v192
	v_max3_f32 v192, |v171|, |v172|, v192
	v_max3_f32 v192, |v173|, |v174|, v192
	v_max_f32_e64 v192, |v175|, v192
	s_nop 1
	v_mov_b32_dpp v193, v192 quad_perm:[1,0,3,2] row_mask:0xf bank_mask:0xf bound_ctrl:1
	v_max_f32_e32 v192, v192, v193
	s_nop 1
	v_mov_b32_dpp v193, v192 quad_perm:[2,3,0,1] row_mask:0xf bank_mask:0xf bound_ctrl:1
	v_max_f32_e32 v192, v192, v193
	s_nop 1
	v_mov_b32_dpp v193, v192 row_half_mirror row_mask:0xf bank_mask:0xf bound_ctrl:1
	v_max_f32_e32 v192, v192, v193
	s_nop 1
	v_mov_b32_dpp v193, v192 row_mirror row_mask:0xf bank_mask:0xf bound_ctrl:1
	v_max_f32_e32 v192, v192, v193
	v_mov_b32_e32 v193, v192
	s_nop 1
	v_permlane16_swap_b32_e32 v192, v193
	s_nop 1
	v_max_f32_e32 v192, v192, v193
	v_mov_b32_e32 v193, v192
	s_nop 1
	v_permlane32_swap_b32_e32 v192, v193
	s_nop 1
	v_max_f32_e32 v192, v192, v193
	v_max_f32_e32 v192, 0xda24260, v192
	v_mul_f32_e32 v194, 0x3e2aaaab, v192
	global_store_dword v214, v194, s[12:13]
	v_div_scale_f32 v195, s[26:27], v194, v194, 1.0
	v_rcp_f32_e32 v196, v195
	v_div_scale_f32 v204, vcc, 1.0, v194, 1.0
	v_fma_f32 v205, -v195, v196, 1.0
	v_fmac_f32_e32 v196, v205, v196
	v_mul_f32_e32 v205, v204, v196
	v_fma_f32 v206, -v195, v205, v204
	v_fmac_f32_e32 v205, v206, v196
	v_fma_f32 v195, -v195, v205, v204
	s_nop 0
	v_div_fmas_f32 v195, v195, v196, v205
	v_div_fixup_f32 v207, v195, v194, 1.0
	v_mul_f32_e32 v160, v207, v160
	v_mul_f32_e32 v161, v207, v161
	v_mul_f32_e32 v162, v207, v162
	v_mul_f32_e32 v163, v207, v163
	v_mul_f32_e32 v164, v207, v164
	v_mul_f32_e32 v165, v207, v165
	v_mul_f32_e32 v166, v207, v166
	v_mul_f32_e32 v167, v207, v167
	v_mul_f32_e32 v168, v207, v168
	v_mul_f32_e32 v169, v207, v169
	v_mul_f32_e32 v170, v207, v170
	v_mul_f32_e32 v171, v207, v171
	v_mul_f32_e32 v172, v207, v172
	v_mul_f32_e32 v173, v207, v173
	v_mul_f32_e32 v174, v207, v174
	v_mul_f32_e32 v175, v207, v175
	v_mov_b32_e32 v208, 0
	v_mov_b32_e32 v209, 0
	v_mov_b32_e32 v210, 0
	v_mov_b32_e32 v193, 0
	v_cvt_scalef32_pk_fp4_f32 v208, v160, v161, 1.0
	v_cvt_scalef32_pk_fp4_f32 v209, v164, v165, 1.0
	v_cvt_scalef32_pk_fp4_f32 v210, v168, v169, 1.0
	v_cvt_scalef32_pk_fp4_f32 v193, v172, v173, 1.0
	v_cvt_scalef32_pk_fp4_f32 v208, v162, v163, 1.0 op_sel:[0,0,1,0]
	v_cvt_scalef32_pk_fp4_f32 v209, v166, v167, 1.0 op_sel:[0,0,1,0]
	v_cvt_scalef32_pk_fp4_f32 v210, v170, v171, 1.0 op_sel:[0,0,1,0]
	v_cvt_scalef32_pk_fp4_f32 v193, v174, v175, 1.0 op_sel:[0,0,1,0]
	global_store_short v213, v208, s[10:11] nt
	s_add_u32 s14, s10, 0x200000
	s_addc_u32 s15, s11, 0
	global_store_short v213, v209, s[14:15] nt
	s_add_u32 s14, s10, 0x400000
	s_addc_u32 s15, s11, 0
	global_store_short v213, v210, s[14:15] nt
	s_add_u32 s14, s10, 0x600000
	s_addc_u32 s15, s11, 0
	global_store_short v213, v193, s[14:15] nt
	s_add_u32 s10, s10, 0x20000
	s_addc_u32 s11, s11, 0
	s_add_u32 s12, s12, 0x2000
	s_addc_u32 s13, s13, 0
	global_load_dwordx4 v[160:163], v212, s[8:9] offset:0 nt
	global_load_dwordx4 v[164:167], v212, s[8:9] offset:1024 nt
	global_load_dwordx4 v[168:171], v212, s[8:9] offset:2048 nt
	global_load_dwordx4 v[172:175], v212, s[8:9] offset:3072 nt
	s_add_u32 s8, s8, 0x800000
	s_addc_u32 s9, s9, 0
	v_max_f32_e32 v24, v32, v45
	v_min_f32_e32 v45, v32, v45
	v_max_f32_e32 v26, v33, v44
	v_min_f32_e32 v44, v33, v44
	v_max_f32_e32 v27, v34, v47
	v_min_f32_e32 v47, v34, v47
	v_max_f32_e32 v255, v35, v46
	v_min_f32_e32 v46, v35, v46
	v_max_f32_e32 v14, v36, v40
	v_min_f32_e32 v40, v36, v40
	v_max_f32_e32 v251, v37, v38
	v_min_f32_e32 v38, v37, v38
	v_max_f32_e32 v250, v39, v43
	v_min_f32_e32 v43, v39, v43
	v_max_f32_e32 v253, v41, v42
	v_min_f32_e32 v42, v41, v42
	v_max_f32_e32 v149, v24, v251
	v_min_f32_e32 v251, v24, v251
	v_max_f32_e32 v28, v26, v250
	v_min_f32_e32 v250, v26, v250
	v_max_f32_e32 v30, v27, v253
	v_min_f32_e32 v253, v27, v253
	v_max_f32_e32 v254, v255, v14
	v_min_f32_e32 v14, v255, v14
	v_max_f32_e32 v12, v38, v45
	v_min_f32_e32 v45, v38, v45
	v_max_f32_e32 v13, v40, v46
	v_min_f32_e32 v46, v40, v46
	v_max_f32_e32 v148, v42, v47
	v_min_f32_e32 v47, v42, v47
	v_max_f32_e32 v106, v43, v44
	v_min_f32_e32 v44, v43, v44
	v_max_f32_e32 v99, v149, v28
	v_min_f32_e32 v28, v149, v28
	v_max_f32_e32 v108, v30, v254
	v_min_f32_e32 v254, v30, v254
	v_max_f32_e32 v29, v14, v251
	v_min_f32_e32 v251, v14, v251
	v_max_f32_e32 v112, v12, v13
	v_min_f32_e32 v13, v12, v13
	v_max_f32_e32 v97, v250, v253
	v_min_f32_e32 v253, v250, v253
	v_max_f32_e32 v113, v148, v106
	v_min_f32_e32 v106, v148, v106
	v_max_f32_e32 v98, v44, v45
	v_min_f32_e32 v45, v44, v45
	v_max_f32_e32 v101, v46, v47
	v_min_f32_e32 v47, v46, v47
	v_max_f32_e32 v150, v99, v108
	v_min_f32_e32 v108, v99, v108
	v_max_f32_e32 v96, v28, v254
	v_min_f32_e32 v254, v28, v254
	v_max_f32_e32 v121, v29, v113
	v_min_f32_e32 v113, v29, v113
	v_max_f32_e32 v103, v251, v106
	v_min_f32_e32 v106, v251, v106
	v_max_f32_e32 v125, v112, v97
	v_min_f32_e32 v97, v112, v97
	v_max_f32_e32 v252, v13, v253
	v_min_f32_e32 v253, v13, v253
	v_max_f32_e32 v109, v98, v101
	v_min_f32_e32 v101, v98, v101
	v_max_f32_e32 v100, v45, v47
	v_min_f32_e32 v47, v45, v47
	v_max_f32_e32 v2, v96, v108
	v_min_f32_e32 v108, v96, v108
	v_max_f32_e32 v114, v254, v109
	v_min_f32_e32 v109, v254, v109
	v_max_f32_e32 v0, v121, v125
	v_min_f32_e32 v125, v121, v125
	v_max_f32_e32 v1, v103, v97
	v_min_f32_e32 v97, v103, v97
	v_max_f32_e32 v117, v252, v113
	v_min_f32_e32 v113, v252, v113
	v_max_f32_e32 v116, v253, v106
	v_min_f32_e32 v106, v253, v106
	v_max_f32_e32 v4, v100, v101
	v_min_f32_e32 v101, v100, v101
	v_max_f32_e32 v107, v2, v0
	v_min_f32_e32 v0, v2, v0
	v_max_f32_e32 v18, v108, v125
	v_min_f32_e32 v125, v108, v125
	v_max_f32_e32 v122, v1, v117
	v_min_f32_e32 v117, v1, v117
	v_max_f32_e32 v20, v97, v113
	v_min_f32_e32 v113, v97, v113
	v_max_f32_e32 v16, v116, v4
	v_min_f32_e32 v4, v116, v4
	v_max_f32_e32 v17, v106, v101
	v_min_f32_e32 v101, v106, v101
	v_max_f32_e32 v19, v18, v0
	v_min_f32_e32 v0, v18, v0
	v_max_f32_e32 v127, v114, v125
	v_min_f32_e32 v125, v114, v125
	v_max_f32_e32 v32, v16, v109
	v_min_f32_e32 v109, v16, v109
	v_max_f32_e32 v33, v17, v4
	v_min_f32_e32 v4, v17, v4
	v_max_f32_e32 v34, v127, v122
	v_min_f32_e32 v122, v127, v122
	v_max_f32_e32 v35, v125, v117
	v_min_f32_e32 v117, v125, v117
	v_max_f32_e32 v36, v20, v32
	v_min_f32_e32 v32, v20, v32
	v_max_f32_e32 v37, v113, v109
	v_min_f32_e32 v109, v113, v109
	v_max_f32_e32 v39, v34, v0
	v_min_f32_e32 v0, v34, v0
	v_max_f32_e32 v41, v122, v35
	v_min_f32_e32 v35, v122, v35
	v_max_f32_e32 v24, v36, v117
	v_min_f32_e32 v117, v36, v117
	v_max_f32_e32 v26, v32, v37
	v_min_f32_e32 v37, v32, v37
	v_max_f32_e32 v27, v33, v109
	v_min_f32_e32 v109, v33, v109
	v_max_f32_e32 v255, v35, v24
	v_min_f32_e32 v24, v35, v24
	v_max_f32_e32 v38, v117, v26
	v_min_f32_e32 v26, v117, v26
	v_max_f32_e32 v40, v48, v61
	v_min_f32_e32 v61, v48, v61
	v_max_f32_e32 v42, v49, v60
	v_min_f32_e32 v60, v49, v60
	v_max_f32_e32 v43, v50, v63
	v_min_f32_e32 v63, v50, v63
	v_max_f32_e32 v149, v51, v62
	v_min_f32_e32 v62, v51, v62
	v_max_f32_e32 v30, v52, v56
	v_min_f32_e32 v56, v52, v56
	v_max_f32_e32 v14, v53, v54
	v_min_f32_e32 v54, v53, v54
	v_max_f32_e32 v12, v55, v59
	v_min_f32_e32 v59, v55, v59
	v_max_f32_e32 v250, v57, v58
	v_min_f32_e32 v58, v57, v58
	v_max_f32_e32 v148, v40, v14
	v_min_f32_e32 v14, v40, v14
	v_max_f32_e32 v44, v42, v12
	v_min_f32_e32 v12, v42, v12
	v_max_f32_e32 v46, v43, v250
	v_min_f32_e32 v250, v43, v250
	v_max_f32_e32 v99, v149, v30
	v_min_f32_e32 v30, v149, v30
	v_max_f32_e32 v28, v54, v61
	v_min_f32_e32 v61, v54, v61
	v_max_f32_e32 v29, v56, v62
	v_min_f32_e32 v62, v56, v62
	v_max_f32_e32 v251, v58, v63
	v_min_f32_e32 v63, v58, v63
	v_max_f32_e32 v112, v59, v60
	v_min_f32_e32 v60, v59, v60
	v_max_f32_e32 v13, v148, v44
	v_min_f32_e32 v44, v148, v44
	v_max_f32_e32 v98, v46, v99
	v_min_f32_e32 v99, v46, v99
	v_max_f32_e32 v45, v30, v14
	v_min_f32_e32 v14, v30, v14
	v_max_f32_e32 v96, v28, v29
	v_min_f32_e32 v29, v28, v29
	v_max_f32_e32 v254, v12, v250
	v_min_f32_e32 v250, v12, v250
	v_max_f32_e32 v121, v251, v112
	v_min_f32_e32 v112, v251, v112
	v_max_f32_e32 v103, v60, v61
	v_min_f32_e32 v61, v60, v61
	v_max_f32_e32 v252, v62, v63
	v_min_f32_e32 v63, v62, v63
	v_max_f32_e32 v253, v13, v98
	v_min_f32_e32 v98, v13, v98
	v_max_f32_e32 v100, v44, v99
	v_min_f32_e32 v99, v44, v99
	v_max_f32_e32 v2, v45, v121
	v_min_f32_e32 v121, v45, v121
	v_max_f32_e32 v108, v14, v112
	v_min_f32_e32 v112, v14, v112
	v_max_f32_e32 v1, v96, v254
	v_min_f32_e32 v254, v96, v254
	v_max_f32_e32 v97, v29, v250
	v_min_f32_e32 v250, v29, v250
	v_max_f32_e32 v116, v103, v252
	v_min_f32_e32 v252, v103, v252
	v_max_f32_e32 v106, v61, v63
	v_min_f32_e32 v63, v61, v63
	v_max_f32_e32 v18, v100, v98
	v_min_f32_e32 v98, v100, v98
	v_max_f32_e32 v114, v99, v116
	v_min_f32_e32 v116, v99, v116
	v_max_f32_e32 v16, v2, v1
	v_min_f32_e32 v1, v2, v1
	v_max_f32_e32 v17, v108, v254
	v_min_f32_e32 v254, v108, v254
	v_max_f32_e32 v127, v97, v121
	v_min_f32_e32 v121, v97, v121
	v_max_f32_e32 v125, v250, v112
	v_min_f32_e32 v112, v250, v112
	v_max_f32_e32 v20, v106, v252
	v_min_f32_e32 v252, v106, v252
	v_max_f32_e32 v113, v18, v16
	v_min_f32_e32 v16, v18, v16
	v_max_f32_e32 v34, v98, v1
	v_min_f32_e32 v1, v98, v1
	v_max_f32_e32 v122, v17, v127
	v_min_f32_e32 v127, v17, v127
	v_max_f32_e32 v36, v254, v121
	v_min_f32_e32 v121, v254, v121
	v_max_f32_e32 v32, v125, v20
	v_min_f32_e32 v20, v125, v20
	v_max_f32_e32 v33, v112, v252
	v_min_f32_e32 v252, v112, v252
	v_max_f32_e32 v35, v34, v16
	v_min_f32_e32 v16, v34, v16
	v_max_f32_e32 v117, v114, v1
	v_min_f32_e32 v1, v114, v1
	v_max_f32_e32 v48, v32, v116
	v_min_f32_e32 v116, v32, v116
	v_max_f32_e32 v49, v33, v20
	v_min_f32_e32 v20, v33, v20
	v_max_f32_e32 v50, v117, v122
	v_min_f32_e32 v122, v117, v122
	v_max_f32_e32 v51, v1, v127
	v_min_f32_e32 v127, v1, v127
	v_max_f32_e32 v52, v36, v48
	v_min_f32_e32 v48, v36, v48
	v_max_f32_e32 v53, v121, v116
	v_min_f32_e32 v116, v121, v116
	v_max_f32_e32 v55, v50, v16
	v_min_f32_e32 v16, v50, v16
	v_max_f32_e32 v57, v122, v51
	v_min_f32_e32 v51, v122, v51
	v_max_f32_e32 v40, v52, v127
	v_min_f32_e32 v127, v52, v127
	v_max_f32_e32 v42, v48, v53
	v_min_f32_e32 v53, v48, v53
	v_max_f32_e32 v43, v49, v116
	v_min_f32_e32 v116, v49, v116
	v_max_f32_e32 v149, v51, v40
	v_min_f32_e32 v40, v51, v40
	v_max_f32_e32 v54, v127, v42
	v_min_f32_e32 v42, v127, v42
	s_waitcnt vmcnt(0)
	v_pk_mul_f32 v[160:161], v[160:161], v[176:177]
	v_pk_mul_f32 v[162:163], v[162:163], v[178:179]
	v_pk_mul_f32 v[164:165], v[164:165], v[180:181]
	v_pk_mul_f32 v[166:167], v[166:167], v[182:183]
	v_pk_mul_f32 v[168:169], v[168:169], v[184:185]
	v_pk_mul_f32 v[170:171], v[170:171], v[186:187]
	v_pk_mul_f32 v[172:173], v[172:173], v[188:189]
	v_pk_mul_f32 v[174:175], v[174:175], v[190:191]
	v_max3_f32 v192, |v160|, |v161|, |v162|
	v_max3_f32 v192, |v163|, |v164|, v192
	v_max3_f32 v192, |v165|, |v166|, v192
	v_max3_f32 v192, |v167|, |v168|, v192
	v_max3_f32 v192, |v169|, |v170|, v192
	v_max3_f32 v192, |v171|, |v172|, v192
	v_max3_f32 v192, |v173|, |v174|, v192
	v_max_f32_e64 v192, |v175|, v192
	s_nop 1
	v_mov_b32_dpp v193, v192 quad_perm:[1,0,3,2] row_mask:0xf bank_mask:0xf bound_ctrl:1
	v_max_f32_e32 v192, v192, v193
	s_nop 1
	v_mov_b32_dpp v193, v192 quad_perm:[2,3,0,1] row_mask:0xf bank_mask:0xf bound_ctrl:1
	v_max_f32_e32 v192, v192, v193
	s_nop 1
	v_mov_b32_dpp v193, v192 row_half_mirror row_mask:0xf bank_mask:0xf bound_ctrl:1
	v_max_f32_e32 v192, v192, v193
	s_nop 1
	v_mov_b32_dpp v193, v192 row_mirror row_mask:0xf bank_mask:0xf bound_ctrl:1
	v_max_f32_e32 v192, v192, v193
	v_mov_b32_e32 v193, v192
	s_nop 1
	v_permlane16_swap_b32_e32 v192, v193
	s_nop 1
	v_max_f32_e32 v192, v192, v193
	v_mov_b32_e32 v193, v192
	s_nop 1
	v_permlane32_swap_b32_e32 v192, v193
	s_nop 1
	v_max_f32_e32 v192, v192, v193
	v_max_f32_e32 v192, 0xda24260, v192
	v_mul_f32_e32 v194, 0x3e2aaaab, v192
	global_store_dword v214, v194, s[12:13]
	v_div_scale_f32 v195, s[26:27], v194, v194, 1.0
	v_rcp_f32_e32 v196, v195
	v_div_scale_f32 v204, vcc, 1.0, v194, 1.0
	v_fma_f32 v205, -v195, v196, 1.0
	v_fmac_f32_e32 v196, v205, v196
	v_mul_f32_e32 v205, v204, v196
	v_fma_f32 v206, -v195, v205, v204
	v_fmac_f32_e32 v205, v206, v196
	v_fma_f32 v195, -v195, v205, v204
	s_nop 0
	v_div_fmas_f32 v195, v195, v196, v205
	v_div_fixup_f32 v207, v195, v194, 1.0
	v_mul_f32_e32 v160, v207, v160
	v_mul_f32_e32 v161, v207, v161
	v_mul_f32_e32 v162, v207, v162
	v_mul_f32_e32 v163, v207, v163
	v_mul_f32_e32 v164, v207, v164
	v_mul_f32_e32 v165, v207, v165
	v_mul_f32_e32 v166, v207, v166
	v_mul_f32_e32 v167, v207, v167
	v_mul_f32_e32 v168, v207, v168
	v_mul_f32_e32 v169, v207, v169
	v_mul_f32_e32 v170, v207, v170
	v_mul_f32_e32 v171, v207, v171
	v_mul_f32_e32 v172, v207, v172
	v_mul_f32_e32 v173, v207, v173
	v_mul_f32_e32 v174, v207, v174
	v_mul_f32_e32 v175, v207, v175
	v_mov_b32_e32 v208, 0
	v_mov_b32_e32 v209, 0
	v_mov_b32_e32 v210, 0
	v_mov_b32_e32 v193, 0
	v_cvt_scalef32_pk_fp4_f32 v208, v160, v161, 1.0
	v_cvt_scalef32_pk_fp4_f32 v209, v164, v165, 1.0
	v_cvt_scalef32_pk_fp4_f32 v210, v168, v169, 1.0
	v_cvt_scalef32_pk_fp4_f32 v193, v172, v173, 1.0
	v_cvt_scalef32_pk_fp4_f32 v208, v162, v163, 1.0 op_sel:[0,0,1,0]
	v_cvt_scalef32_pk_fp4_f32 v209, v166, v167, 1.0 op_sel:[0,0,1,0]
	v_cvt_scalef32_pk_fp4_f32 v210, v170, v171, 1.0 op_sel:[0,0,1,0]
	v_cvt_scalef32_pk_fp4_f32 v193, v174, v175, 1.0 op_sel:[0,0,1,0]
	global_store_short v213, v208, s[10:11] nt
	s_add_u32 s14, s10, 0x200000
	s_addc_u32 s15, s11, 0
	global_store_short v213, v209, s[14:15] nt
	s_add_u32 s14, s10, 0x400000
	s_addc_u32 s15, s11, 0
	global_store_short v213, v210, s[14:15] nt
	s_add_u32 s14, s10, 0x600000
	s_addc_u32 s15, s11, 0
	global_store_short v213, v193, s[14:15] nt
	s_add_u32 s10, s10, 0x20000
	s_addc_u32 s11, s11, 0
	s_add_u32 s12, s12, 0x2000
	s_addc_u32 s13, s13, 0
	global_load_dwordx4 v[160:163], v212, s[8:9] offset:0 nt
	global_load_dwordx4 v[164:167], v212, s[8:9] offset:1024 nt
	global_load_dwordx4 v[168:171], v212, s[8:9] offset:2048 nt
	global_load_dwordx4 v[172:175], v212, s[8:9] offset:3072 nt
	s_add_u32 s8, s8, 0x800000
	s_addc_u32 s9, s9, 0
	v_max_f32_e32 v105, v105, v31
	v_max_f32_e32 v120, v120, v110
	v_max_f32_e32 v126, v126, v123
	v_max_f32_e32 v7, v7, v118
	v_max_f32_e32 v115, v115, v11
	v_max_f32_e32 v9, v9, v21
	v_max_f32_e32 v147, v147, v10
	v_max_f32_e32 v144, v144, v22
	v_max_f32_e32 v6, v6, v8
	v_max_f32_e32 v145, v145, v249
	v_max_f32_e32 v5, v5, v25
	v_max_f32_e32 v146, v146, v124
	v_max_f32_e32 v111, v111, v23
	v_max_f32_e32 v119, v119, v3
	v_max_f32_e32 v104, v104, v102
	v_max_f32_e32 v15, v15, v151
	v_max_f32_e32 v56, v105, v6
	v_min_f32_e32 v6, v105, v6
	v_max_f32_e32 v58, v120, v145
	v_min_f32_e32 v145, v120, v145
	v_max_f32_e32 v59, v126, v5
	v_min_f32_e32 v5, v126, v5
	v_max_f32_e32 v148, v7, v146
	v_min_f32_e32 v146, v7, v146
	v_max_f32_e32 v46, v115, v111
	v_min_f32_e32 v111, v115, v111
	v_max_f32_e32 v30, v9, v119
	v_min_f32_e32 v119, v9, v119
	v_max_f32_e32 v28, v147, v104
	v_min_f32_e32 v104, v147, v104
	v_max_f32_e32 v12, v144, v15
	v_min_f32_e32 v15, v144, v15
	v_max_f32_e32 v251, v56, v46
	v_min_f32_e32 v46, v56, v46
	v_max_f32_e32 v60, v58, v30
	v_min_f32_e32 v30, v58, v30
	v_max_f32_e32 v62, v59, v28
	v_min_f32_e32 v28, v59, v28
	v_max_f32_e32 v13, v148, v12
	v_min_f32_e32 v12, v148, v12
	v_max_f32_e32 v44, v6, v111
	v_min_f32_e32 v111, v6, v111
	v_max_f32_e32 v45, v145, v119
	v_min_f32_e32 v119, v145, v119
	v_max_f32_e32 v14, v5, v104
	v_min_f32_e32 v104, v5, v104
	v_max_f32_e32 v96, v146, v15
	v_min_f32_e32 v15, v146, v15
	v_max_f32_e32 v29, v251, v62
	v_min_f32_e32 v62, v251, v62
	v_max_f32_e32 v103, v60, v13
	v_min_f32_e32 v13, v60, v13
	v_max_f32_e32 v61, v46, v28
	v_min_f32_e32 v28, v46, v28
	v_max_f32_e32 v100, v30, v12
	v_min_f32_e32 v12, v30, v12
	v_max_f32_e32 v99, v44, v14
	v_min_f32_e32 v14, v44, v14
	v_max_f32_e32 v2, v45, v96
	v_min_f32_e32 v96, v45, v96
	v_max_f32_e32 v108, v111, v104
	v_min_f32_e32 v104, v111, v104
	v_max_f32_e32 v97, v119, v15
	v_min_f32_e32 v15, v119, v15
	v_max_f32_e32 v250, v29, v103
	v_min_f32_e32 v103, v29, v103
	v_max_f32_e32 v106, v62, v13
	v_min_f32_e32 v13, v62, v13
	v_max_f32_e32 v18, v61, v100
	v_min_f32_e32 v100, v61, v100
	v_max_f32_e32 v98, v28, v12
	v_min_f32_e32 v12, v28, v12
	v_max_f32_e32 v17, v99, v2
	v_min_f32_e32 v2, v99, v2
	v_max_f32_e32 v254, v14, v96
	v_min_f32_e32 v96, v14, v96
	v_max_f32_e32 v125, v108, v97
	v_min_f32_e32 v97, v108, v97
	v_max_f32_e32 v112, v104, v15
	v_min_f32_e32 v15, v104, v15
	v_max_f32_e32 v150, v150, v63
	v_max_f32_e32 v107, v107, v252
	v_max_f32_e32 v19, v19, v20
	v_max_f32_e32 v39, v39, v116
	v_max_f32_e32 v0, v0, v43
	v_max_f32_e32 v41, v41, v53
	v_max_f32_e32 v255, v255, v42
	v_max_f32_e32 v24, v24, v54
	v_max_f32_e32 v38, v38, v40
	v_max_f32_e32 v26, v26, v149
	v_max_f32_e32 v37, v37, v57
	v_max_f32_e32 v27, v27, v16
	v_max_f32_e32 v109, v109, v55
	v_max_f32_e32 v4, v4, v35
	v_max_f32_e32 v101, v101, v113
	v_max_f32_e32 v47, v47, v253
	v_max_f32_e32 v34, v150, v38
	v_min_f32_e32 v38, v150, v38
	v_max_f32_e32 v114, v107, v26
	v_min_f32_e32 v26, v107, v26
	v_max_f32_e32 v32, v19, v37
	v_min_f32_e32 v37, v19, v37
	v_max_f32_e32 v33, v39, v27
	v_min_f32_e32 v27, v39, v27
	v_max_f32_e32 v117, v0, v109
	v_min_f32_e32 v109, v0, v109
	v_max_f32_e32 v1, v41, v4
	v_min_f32_e32 v4, v41, v4
	v_max_f32_e32 v36, v255, v101
	v_min_f32_e32 v101, v255, v101
	v_max_f32_e32 v121, v24, v47
	v_min_f32_e32 v47, v24, v47
	v_max_f32_e32 v50, v34, v117
	v_min_f32_e32 v117, v34, v117
	v_max_f32_e32 v122, v114, v1
	v_min_f32_e32 v1, v114, v1
	v_max_f32_e32 v52, v32, v36
	v_min_f32_e32 v36, v32, v36
	v_max_f32_e32 v48, v33, v121
	v_min_f32_e32 v121, v33, v121
	v_max_f32_e32 v49, v38, v109
	v_min_f32_e32 v109, v38, v109
	v_max_f32_e32 v51, v26, v4
	v_min_f32_e32 v4, v26, v4
	v_max_f32_e32 v127, v37, v101
	v_min_f32_e32 v101, v37, v101
	v_max_f32_e32 v151, v27, v47
	v_min_f32_e32 v47, v27, v47
	v_max_f32_e32 v102, v50, v52
	v_min_f32_e32 v52, v50, v52
	v_max_f32_e32 v3, v122, v48
	v_min_f32_e32 v48, v122, v48
	v_max_f32_e32 v23, v117, v36
	v_min_f32_e32 v36, v117, v36
	v_max_f32_e32 v124, v1, v121
	v_min_f32_e32 v121, v1, v121
	v_max_f32_e32 v25, v49, v127
	v_min_f32_e32 v127, v49, v127
	v_max_f32_e32 v249, v51, v151
	v_min_f32_e32 v151, v51, v151
	v_max_f32_e32 v8, v109, v101
	v_min_f32_e32 v101, v109, v101
	v_max_f32_e32 v22, v4, v47
	v_min_f32_e32 v47, v4, v47
	v_max_f32_e32 v10, v102, v3
	v_min_f32_e32 v3, v102, v3
	v_max_f32_e32 v21, v52, v48
	v_min_f32_e32 v48, v52, v48
	v_max_f32_e32 v11, v23, v124
	v_min_f32_e32 v124, v23, v124
	v_max_f32_e32 v118, v36, v121
	v_min_f32_e32 v121, v36, v121
	v_max_f32_e32 v123, v25, v249
	v_min_f32_e32 v249, v25, v249
	v_max_f32_e32 v110, v127, v151
	v_min_f32_e32 v151, v127, v151
	v_max_f32_e32 v31, v8, v22
	v_min_f32_e32 v22, v8, v22
	v_max_f32_e32 v105, v101, v47
	v_min_f32_e32 v47, v101, v47
	v_max_f32_e32 v250, v250, v47
	v_max_f32_e32 v103, v103, v105
	v_max_f32_e32 v106, v106, v22
	v_max_f32_e32 v13, v13, v31
	v_max_f32_e32 v18, v18, v151
	v_max_f32_e32 v100, v100, v110
	v_max_f32_e32 v98, v98, v249
	v_max_f32_e32 v12, v12, v123
	v_max_f32_e32 v17, v17, v121
	v_max_f32_e32 v2, v2, v118
	v_max_f32_e32 v254, v254, v124
	v_max_f32_e32 v96, v96, v11
	v_max_f32_e32 v125, v125, v48
	v_max_f32_e32 v97, v97, v21
	v_max_f32_e32 v112, v112, v3
	v_max_f32_e32 v15, v15, v10
	v_max_f32_e32 v120, v250, v17
	v_min_f32_e32 v17, v250, v17
	v_max_f32_e32 v126, v103, v2
	v_min_f32_e32 v2, v103, v2
	v_max_f32_e32 v7, v106, v254
	v_min_f32_e32 v254, v106, v254
	v_max_f32_e32 v115, v13, v96
	v_min_f32_e32 v96, v13, v96
	v_max_f32_e32 v9, v18, v125
	v_min_f32_e32 v125, v18, v125
	v_max_f32_e32 v147, v100, v97
	v_min_f32_e32 v97, v100, v97
	v_max_f32_e32 v144, v98, v112
	v_min_f32_e32 v112, v98, v112
	v_max_f32_e32 v56, v12, v15
	v_min_f32_e32 v15, v12, v15
	v_max_f32_e32 v58, v120, v9
	v_min_f32_e32 v9, v120, v9
	v_max_f32_e32 v59, v126, v147
	v_min_f32_e32 v147, v126, v147
	v_max_f32_e32 v148, v7, v144
	v_min_f32_e32 v144, v7, v144
	v_max_f32_e32 v6, v115, v56
	v_min_f32_e32 v56, v115, v56
	v_max_f32_e32 v145, v17, v125
	v_min_f32_e32 v125, v17, v125
	v_max_f32_e32 v5, v2, v97
	v_min_f32_e32 v97, v2, v97
	v_max_f32_e32 v146, v254, v112
	v_min_f32_e32 v112, v254, v112
	v_max_f32_e32 v251, v96, v15
	v_min_f32_e32 v15, v96, v15
	v_max_f32_e32 v60, v58, v148
	v_min_f32_e32 v148, v58, v148
	v_max_f32_e32 v46, v59, v6
	v_min_f32_e32 v6, v59, v6
	v_max_f32_e32 v30, v9, v144
	v_min_f32_e32 v144, v9, v144
	v_max_f32_e32 v44, v147, v56
	v_min_f32_e32 v56, v147, v56
	v_max_f32_e32 v45, v145, v146
	v_min_f32_e32 v146, v145, v146
	v_max_f32_e32 v111, v5, v251
	v_min_f32_e32 v251, v5, v251
	v_max_f32_e32 v119, v125, v112
	v_min_f32_e32 v112, v125, v112
	v_max_f32_e32 v29, v97, v15
	v_min_f32_e32 v15, v97, v15
	v_max_f32_e32 v62, v60, v46
	v_min_f32_e32 v46, v60, v46
	v_max_f32_e32 v61, v148, v6
	v_min_f32_e32 v6, v148, v6
	v_max_f32_e32 v28, v30, v44
	v_min_f32_e32 v44, v30, v44
	v_max_f32_e32 v99, v144, v56
	v_min_f32_e32 v56, v144, v56
	v_max_f32_e32 v14, v45, v111
	v_min_f32_e32 v111, v45, v111
	v_max_f32_e32 v108, v146, v251
	v_min_f32_e32 v251, v146, v251
	v_max_f32_e32 v104, v119, v29
	v_min_f32_e32 v29, v119, v29
	v_max_f32_e32 v253, v112, v15
	v_min_f32_e32 v15, v112, v15
	v_mov_b32_e32 v113, v62
	v_mov_b32_e32 v35, v46
	v_mov_b32_e32 v55, v61
	v_mov_b32_e32 v16, v6
	v_mov_b32_e32 v57, v28
	v_mov_b32_e32 v149, v44
	v_mov_b32_e32 v40, v99
	v_mov_b32_e32 v54, v56
	v_mov_b32_e32 v42, v14
	v_mov_b32_e32 v53, v111
	v_mov_b32_e32 v43, v108
	v_mov_b32_e32 v116, v251
	v_mov_b32_e32 v20, v104
	v_mov_b32_e32 v252, v29
	v_mov_b32_e32 v63, v253
	v_mov_b32_e32 v150, v15
	s_nop 1
	v_permlane32_swap_b32_e32 v62, v113
	v_permlane32_swap_b32_e32 v46, v35
	v_permlane32_swap_b32_e32 v61, v55
	v_permlane32_swap_b32_e32 v6, v16
	v_permlane32_swap_b32_e32 v28, v57
	v_permlane32_swap_b32_e32 v44, v149
	v_permlane32_swap_b32_e32 v99, v40
	v_permlane32_swap_b32_e32 v56, v54
	v_permlane32_swap_b32_e32 v14, v42
	v_permlane32_swap_b32_e32 v111, v53
	v_permlane32_swap_b32_e32 v108, v43
	v_permlane32_swap_b32_e32 v251, v116
	v_permlane32_swap_b32_e32 v104, v20
	v_permlane32_swap_b32_e32 v29, v252
	v_permlane32_swap_b32_e32 v253, v63
	v_permlane32_swap_b32_e32 v15, v150
	s_nop 1
	v_max_f32_e32 v62, v62, v150
	v_max_f32_e32 v46, v46, v63
	v_max_f32_e32 v61, v61, v252
	v_max_f32_e32 v6, v6, v20
	v_max_f32_e32 v28, v28, v116
	v_max_f32_e32 v44, v44, v43
	v_max_f32_e32 v99, v99, v53
	v_max_f32_e32 v56, v56, v42
	v_max_f32_e32 v14, v14, v54
	v_max_f32_e32 v111, v111, v40
	v_max_f32_e32 v108, v108, v149
	v_max_f32_e32 v251, v251, v57
	v_max_f32_e32 v104, v104, v16
	v_max_f32_e32 v29, v29, v55
	v_max_f32_e32 v253, v253, v35
	v_max_f32_e32 v15, v15, v113
	v_max_f32_e32 v107, v62, v14
	v_min_f32_e32 v14, v62, v14
	v_max_f32_e32 v19, v46, v111
	v_min_f32_e32 v111, v46, v111
	v_max_f32_e32 v39, v61, v108
	v_min_f32_e32 v108, v61, v108
	v_max_f32_e32 v0, v6, v251
	v_min_f32_e32 v251, v6, v251
	v_max_f32_e32 v41, v28, v104
	v_min_f32_e32 v104, v28, v104
	v_max_f32_e32 v255, v44, v29
	v_min_f32_e32 v29, v44, v29
	v_max_f32_e32 v24, v99, v253
	v_min_f32_e32 v253, v99, v253
	v_max_f32_e32 v34, v56, v15
	v_min_f32_e32 v15, v56, v15
	v_max_f32_e32 v114, v107, v41
	v_min_f32_e32 v41, v107, v41
	v_max_f32_e32 v32, v19, v255
	v_min_f32_e32 v255, v19, v255
	v_max_f32_e32 v33, v39, v24
	v_min_f32_e32 v24, v39, v24
	v_max_f32_e32 v38, v0, v34
	v_min_f32_e32 v34, v0, v34
	v_max_f32_e32 v26, v14, v104
	v_min_f32_e32 v104, v14, v104
	v_max_f32_e32 v37, v111, v29
	v_min_f32_e32 v29, v111, v29
	v_max_f32_e32 v27, v108, v253
	v_min_f32_e32 v253, v108, v253
	v_max_f32_e32 v50, v251, v15
	v_min_f32_e32 v15, v251, v15
	v_max_f32_e32 v122, v114, v33
	v_min_f32_e32 v33, v114, v33
	v_max_f32_e32 v117, v32, v38
	v_min_f32_e32 v38, v32, v38
	v_max_f32_e32 v1, v41, v24
	v_min_f32_e32 v24, v41, v24
	v_max_f32_e32 v49, v255, v34
	v_min_f32_e32 v34, v255, v34
	v_max_f32_e32 v51, v26, v27
	v_min_f32_e32 v27, v26, v27
	v_max_f32_e32 v109, v37, v50
	v_min_f32_e32 v50, v37, v50
	v_max_f32_e32 v4, v104, v253
	v_min_f32_e32 v253, v104, v253
	v_max_f32_e32 v102, v29, v15
	v_min_f32_e32 v15, v29, v15
	v_max_f32_e32 v128, v122, v117
	v_min_f32_e32 v129, v122, v117
	v_max_f32_e32 v130, v33, v38
	v_min_f32_e32 v131, v33, v38
	v_max_f32_e32 v132, v1, v49
	v_min_f32_e32 v133, v1, v49
	v_max_f32_e32 v134, v24, v34
	v_min_f32_e32 v135, v24, v34
	v_max_f32_e32 v136, v51, v109
	v_min_f32_e32 v137, v51, v109
	v_max_f32_e32 v138, v27, v50
	v_min_f32_e32 v139, v27, v50
	v_max_f32_e32 v140, v4, v102
	v_min_f32_e32 v141, v4, v102
	v_max_f32_e32 v142, v253, v15
	v_min_f32_e32 v143, v253, v15
	s_waitcnt vmcnt(0)
	v_pk_mul_f32 v[160:161], v[160:161], v[176:177]
	v_pk_mul_f32 v[162:163], v[162:163], v[178:179]
	v_pk_mul_f32 v[164:165], v[164:165], v[180:181]
	v_pk_mul_f32 v[166:167], v[166:167], v[182:183]
	v_pk_mul_f32 v[168:169], v[168:169], v[184:185]
	v_pk_mul_f32 v[170:171], v[170:171], v[186:187]
	v_pk_mul_f32 v[172:173], v[172:173], v[188:189]
	v_pk_mul_f32 v[174:175], v[174:175], v[190:191]
	v_max3_f32 v192, |v160|, |v161|, |v162|
	v_max3_f32 v192, |v163|, |v164|, v192
	v_max3_f32 v192, |v165|, |v166|, v192
	v_max3_f32 v192, |v167|, |v168|, v192
	v_max3_f32 v192, |v169|, |v170|, v192
	v_max3_f32 v192, |v171|, |v172|, v192
	v_max3_f32 v192, |v173|, |v174|, v192
	v_max_f32_e64 v192, |v175|, v192
	s_nop 1
	v_mov_b32_dpp v193, v192 quad_perm:[1,0,3,2] row_mask:0xf bank_mask:0xf bound_ctrl:1
	v_max_f32_e32 v192, v192, v193
	s_nop 1
	v_mov_b32_dpp v193, v192 quad_perm:[2,3,0,1] row_mask:0xf bank_mask:0xf bound_ctrl:1
	v_max_f32_e32 v192, v192, v193
	s_nop 1
	v_mov_b32_dpp v193, v192 row_half_mirror row_mask:0xf bank_mask:0xf bound_ctrl:1
	v_max_f32_e32 v192, v192, v193
	s_nop 1
	v_mov_b32_dpp v193, v192 row_mirror row_mask:0xf bank_mask:0xf bound_ctrl:1
	v_max_f32_e32 v192, v192, v193
	v_mov_b32_e32 v193, v192
	s_nop 1
	v_permlane16_swap_b32_e32 v192, v193
	s_nop 1
	v_max_f32_e32 v192, v192, v193
	v_mov_b32_e32 v193, v192
	s_nop 1
	v_permlane32_swap_b32_e32 v192, v193
	s_nop 1
	v_max_f32_e32 v192, v192, v193
	v_max_f32_e32 v192, 0xda24260, v192
	v_mul_f32_e32 v194, 0x3e2aaaab, v192
	global_store_dword v214, v194, s[12:13]
	v_div_scale_f32 v195, s[26:27], v194, v194, 1.0
	v_rcp_f32_e32 v196, v195
	v_div_scale_f32 v204, vcc, 1.0, v194, 1.0
	v_fma_f32 v205, -v195, v196, 1.0
	v_fmac_f32_e32 v196, v205, v196
	v_mul_f32_e32 v205, v204, v196
	v_fma_f32 v206, -v195, v205, v204
	v_fmac_f32_e32 v205, v206, v196
	v_fma_f32 v195, -v195, v205, v204
	s_nop 0
	v_div_fmas_f32 v195, v195, v196, v205
	v_div_fixup_f32 v207, v195, v194, 1.0
	v_mul_f32_e32 v160, v207, v160
	v_mul_f32_e32 v161, v207, v161
	v_mul_f32_e32 v162, v207, v162
	v_mul_f32_e32 v163, v207, v163
	v_mul_f32_e32 v164, v207, v164
	v_mul_f32_e32 v165, v207, v165
	v_mul_f32_e32 v166, v207, v166
	v_mul_f32_e32 v167, v207, v167
	v_mul_f32_e32 v168, v207, v168
	v_mul_f32_e32 v169, v207, v169
	v_mul_f32_e32 v170, v207, v170
	v_mul_f32_e32 v171, v207, v171
	v_mul_f32_e32 v172, v207, v172
	v_mul_f32_e32 v173, v207, v173
	v_mul_f32_e32 v174, v207, v174
	v_mul_f32_e32 v175, v207, v175
	v_mov_b32_e32 v208, 0
	v_mov_b32_e32 v209, 0
	v_mov_b32_e32 v210, 0
	v_mov_b32_e32 v193, 0
	v_cvt_scalef32_pk_fp4_f32 v208, v160, v161, 1.0
	v_cvt_scalef32_pk_fp4_f32 v209, v164, v165, 1.0
	v_cvt_scalef32_pk_fp4_f32 v210, v168, v169, 1.0
	v_cvt_scalef32_pk_fp4_f32 v193, v172, v173, 1.0
	v_cvt_scalef32_pk_fp4_f32 v208, v162, v163, 1.0 op_sel:[0,0,1,0]
	v_cvt_scalef32_pk_fp4_f32 v209, v166, v167, 1.0 op_sel:[0,0,1,0]
	v_cvt_scalef32_pk_fp4_f32 v210, v170, v171, 1.0 op_sel:[0,0,1,0]
	v_cvt_scalef32_pk_fp4_f32 v193, v174, v175, 1.0 op_sel:[0,0,1,0]
	global_store_short v213, v208, s[10:11] nt
	s_add_u32 s14, s10, 0x200000
	s_addc_u32 s15, s11, 0
	global_store_short v213, v209, s[14:15] nt
	s_add_u32 s14, s10, 0x400000
	s_addc_u32 s15, s11, 0
	global_store_short v213, v210, s[14:15] nt
	s_add_u32 s14, s10, 0x600000
	s_addc_u32 s15, s11, 0
	global_store_short v213, v193, s[14:15] nt
	s_add_u32 s10, s10, 0x20000
	s_addc_u32 s11, s11, 0
	s_add_u32 s12, s12, 0x2000
	s_addc_u32 s13, s13, 0
	global_load_dwordx4 v[160:163], v212, s[8:9] offset:0 nt
	global_load_dwordx4 v[164:167], v212, s[8:9] offset:1024 nt
	global_load_dwordx4 v[168:171], v212, s[8:9] offset:2048 nt
	global_load_dwordx4 v[172:175], v212, s[8:9] offset:3072 nt
	s_add_u32 s8, s8, 0x800000
	s_addc_u32 s9, s9, 0
	ds_write_b8 v240, v128 offset:0
	ds_write_b8 v240, v129 offset:1
	ds_write_b8 v240, v130 offset:2
	ds_write_b8 v240, v131 offset:3
	ds_write_b8 v240, v132 offset:4
	ds_write_b8 v240, v133 offset:5
	ds_write_b8 v240, v134 offset:6
	ds_write_b8 v240, v135 offset:7
	ds_write_b8 v240, v136 offset:8
	ds_write_b8 v240, v137 offset:9
	ds_write_b8 v240, v138 offset:10
	ds_write_b8 v240, v139 offset:11
	ds_write_b8 v240, v140 offset:12
	ds_write_b8 v240, v141 offset:13
	ds_write_b8 v240, v142 offset:14
	ds_write_b8 v240, v143 offset:15
	ds_read_b128 v[96:99], v215 offset:32768
	ds_read_b128 v[100:103], v232 offset:32768
	ds_read_b128 v[104:107], v233 offset:32768
	ds_read_b128 v[108:111], v234 offset:32768
	ds_read_b128 v[112:115], v235 offset:32768
	ds_read_b128 v[116:119], v236 offset:32768
	ds_read_b128 v[120:123], v237 offset:32768
	ds_read_b128 v[124:127], v238 offset:32768
	s_waitcnt vmcnt(27)
	s_waitcnt lgkmcnt(4)
	v_mfma_f32_32x32x16_bf16 v[0:15], v[96:99], v[64:67], 0
	v_mfma_f32_32x32x16_bf16 v[0:15], v[100:103], v[68:71], v[0:15]
	v_mfma_f32_32x32x16_bf16 v[0:15], v[104:107], v[72:75], v[0:15]
	v_mfma_f32_32x32x16_bf16 v[0:15], v[108:111], v[76:79], v[0:15]
	ds_read_b128 v[96:99], v215 offset:40960
	ds_read_b128 v[100:103], v232 offset:40960
	ds_read_b128 v[104:107], v233 offset:40960
	ds_read_b128 v[108:111], v234 offset:40960
	s_waitcnt lgkmcnt(4)
	v_mfma_f32_32x32x16_bf16 v[0:15], v[112:115], v[80:83], v[0:15]
	v_mfma_f32_32x32x16_bf16 v[0:15], v[116:119], v[84:87], v[0:15]
	v_mfma_f32_32x32x16_bf16 v[0:15], v[120:123], v[88:91], v[0:15]
	v_mfma_f32_32x32x16_bf16 v[0:15], v[124:127], v[92:95], v[0:15]
	ds_read_b128 v[112:115], v235 offset:40960
	ds_read_b128 v[116:119], v236 offset:40960
	ds_read_b128 v[120:123], v237 offset:40960
	ds_read_b128 v[124:127], v238 offset:40960
	s_waitcnt lgkmcnt(4)
	v_mfma_f32_32x32x16_bf16 v[16:31], v[96:99], v[64:67], 0
	v_mfma_f32_32x32x16_bf16 v[16:31], v[100:103], v[68:71], v[16:31]
	v_mfma_f32_32x32x16_bf16 v[16:31], v[104:107], v[72:75], v[16:31]
	v_mfma_f32_32x32x16_bf16 v[16:31], v[108:111], v[76:79], v[16:31]
	ds_read_b128 v[96:99], v215 offset:49152
	ds_read_b128 v[100:103], v232 offset:49152
	ds_read_b128 v[104:107], v233 offset:49152
	ds_read_b128 v[108:111], v234 offset:49152
	s_waitcnt lgkmcnt(4)
	v_mfma_f32_32x32x16_bf16 v[16:31], v[112:115], v[80:83], v[16:31]
	v_mfma_f32_32x32x16_bf16 v[16:31], v[116:119], v[84:87], v[16:31]
	v_mfma_f32_32x32x16_bf16 v[16:31], v[120:123], v[88:91], v[16:31]
	v_mfma_f32_32x32x16_bf16 v[16:31], v[124:127], v[92:95], v[16:31]
	ds_read_b128 v[112:115], v235 offset:49152
	ds_read_b128 v[116:119], v236 offset:49152
	ds_read_b128 v[120:123], v237 offset:49152
	ds_read_b128 v[124:127], v238 offset:49152
	s_waitcnt lgkmcnt(4)
	v_mfma_f32_32x32x16_bf16 v[32:47], v[96:99], v[64:67], 0
	v_mfma_f32_32x32x16_bf16 v[32:47], v[100:103], v[68:71], v[32:47]
	v_mfma_f32_32x32x16_bf16 v[32:47], v[104:107], v[72:75], v[32:47]
	v_mfma_f32_32x32x16_bf16 v[32:47], v[108:111], v[76:79], v[32:47]
	ds_read_b128 v[96:99], v215 offset:57344
	ds_read_b128 v[100:103], v232 offset:57344
	ds_read_b128 v[104:107], v233 offset:57344
	ds_read_b128 v[108:111], v234 offset:57344
	s_waitcnt lgkmcnt(4)
	v_mfma_f32_32x32x16_bf16 v[32:47], v[112:115], v[80:83], v[32:47]
	v_mfma_f32_32x32x16_bf16 v[32:47], v[116:119], v[84:87], v[32:47]
	v_mfma_f32_32x32x16_bf16 v[32:47], v[120:123], v[88:91], v[32:47]
	v_mfma_f32_32x32x16_bf16 v[32:47], v[124:127], v[92:95], v[32:47]
	ds_read_b128 v[112:115], v235 offset:57344
	ds_read_b128 v[116:119], v236 offset:57344
	ds_read_b128 v[120:123], v237 offset:57344
	ds_read_b128 v[124:127], v238 offset:57344
	s_waitcnt lgkmcnt(4)
	v_mfma_f32_32x32x16_bf16 v[48:63], v[96:99], v[64:67], 0
	v_mfma_f32_32x32x16_bf16 v[48:63], v[100:103], v[68:71], v[48:63]
	v_mfma_f32_32x32x16_bf16 v[48:63], v[104:107], v[72:75], v[48:63]
	v_mfma_f32_32x32x16_bf16 v[48:63], v[108:111], v[76:79], v[48:63]
	s_waitcnt lgkmcnt(0)
	v_mfma_f32_32x32x16_bf16 v[48:63], v[112:115], v[80:83], v[48:63]
	v_mfma_f32_32x32x16_bf16 v[48:63], v[116:119], v[84:87], v[48:63]
	v_mfma_f32_32x32x16_bf16 v[48:63], v[120:123], v[88:91], v[48:63]
	v_mfma_f32_32x32x16_bf16 v[48:63], v[124:127], v[92:95], v[48:63]
	s_nop 11
	v_and_or_b32 v0, v0, s6, v211
	v_or_b32_e32 v0, 0x7b, v0
	v_and_or_b32 v1, v1, s6, v211
	v_or_b32_e32 v1, 0x7a, v1
	v_and_or_b32 v2, v2, s6, v211
	v_or_b32_e32 v2, 0x79, v2
	v_and_or_b32 v3, v3, s6, v211
	v_or_b32_e32 v3, 0x78, v3
	v_and_or_b32 v4, v4, s6, v211
	v_or_b32_e32 v4, 0x73, v4
	v_and_or_b32 v5, v5, s6, v211
	v_or_b32_e32 v5, 0x72, v5
	v_and_or_b32 v6, v6, s6, v211
	v_or_b32_e32 v6, 0x71, v6
	v_and_or_b32 v7, v7, s6, v211
	v_or_b32_e32 v7, 0x70, v7
	v_and_or_b32 v8, v8, s6, v211
	v_or_b32_e32 v8, 0x6b, v8
	v_and_or_b32 v9, v9, s6, v211
	v_or_b32_e32 v9, 0x6a, v9
	v_and_or_b32 v10, v10, s6, v211
	v_or_b32_e32 v10, 0x69, v10
	v_and_or_b32 v11, v11, s6, v211
	v_or_b32_e32 v11, 0x68, v11
	v_and_or_b32 v12, v12, s6, v211
	v_or_b32_e32 v12, 0x63, v12
	v_and_or_b32 v13, v13, s6, v211
	v_or_b32_e32 v13, 0x62, v13
	v_and_or_b32 v14, v14, s6, v211
	v_or_b32_e32 v14, 0x61, v14
	v_and_or_b32 v15, v15, s6, v211
	v_or_b32_e32 v15, 0x60, v15
	v_and_or_b32 v16, v16, s6, v211
	v_or_b32_e32 v16, 0x5b, v16
	v_and_or_b32 v17, v17, s6, v211
	v_or_b32_e32 v17, 0x5a, v17
	v_and_or_b32 v18, v18, s6, v211
	v_or_b32_e32 v18, 0x59, v18
	v_and_or_b32 v19, v19, s6, v211
	v_or_b32_e32 v19, 0x58, v19
	v_and_or_b32 v20, v20, s6, v211
	v_or_b32_e32 v20, 0x53, v20
	v_and_or_b32 v21, v21, s6, v211
	v_or_b32_e32 v21, 0x52, v21
	v_and_or_b32 v22, v22, s6, v211
	v_or_b32_e32 v22, 0x51, v22
	v_and_or_b32 v23, v23, s6, v211
	v_or_b32_e32 v23, 0x50, v23
	v_and_or_b32 v24, v24, s6, v211
	v_or_b32_e32 v24, 0x4b, v24
	v_and_or_b32 v25, v25, s6, v211
	v_or_b32_e32 v25, 0x4a, v25
	v_and_or_b32 v26, v26, s6, v211
	v_or_b32_e32 v26, 0x49, v26
	v_and_or_b32 v27, v27, s6, v211
	v_or_b32_e32 v27, 0x48, v27
	v_and_or_b32 v28, v28, s6, v211
	v_or_b32_e32 v28, 0x43, v28
	v_and_or_b32 v29, v29, s6, v211
	v_or_b32_e32 v29, 0x42, v29
	v_and_or_b32 v30, v30, s6, v211
	v_or_b32_e32 v30, 0x41, v30
	v_and_or_b32 v31, v31, s6, v211
	v_or_b32_e32 v31, 64, v31
	v_and_or_b32 v32, v32, s6, v211
	v_or_b32_e32 v32, 59, v32
	v_and_or_b32 v33, v33, s6, v211
	v_or_b32_e32 v33, 58, v33
	v_and_or_b32 v34, v34, s6, v211
	v_or_b32_e32 v34, 57, v34
	v_and_or_b32 v35, v35, s6, v211
	v_or_b32_e32 v35, 56, v35
	v_and_or_b32 v36, v36, s6, v211
	v_or_b32_e32 v36, 51, v36
	v_and_or_b32 v37, v37, s6, v211
	v_or_b32_e32 v37, 50, v37
	v_and_or_b32 v38, v38, s6, v211
	v_or_b32_e32 v38, 49, v38
	v_and_or_b32 v39, v39, s6, v211
	v_or_b32_e32 v39, 48, v39
	v_and_or_b32 v40, v40, s6, v211
	v_or_b32_e32 v40, 43, v40
	v_and_or_b32 v41, v41, s6, v211
	v_or_b32_e32 v41, 42, v41
	v_and_or_b32 v42, v42, s6, v211
	v_or_b32_e32 v42, 41, v42
	v_and_or_b32 v43, v43, s6, v211
	v_or_b32_e32 v43, 40, v43
	v_and_or_b32 v44, v44, s6, v211
	v_or_b32_e32 v44, 35, v44
	v_and_or_b32 v45, v45, s6, v211
	v_or_b32_e32 v45, 34, v45
	v_and_or_b32 v46, v46, s6, v211
	v_or_b32_e32 v46, 33, v46
	v_and_or_b32 v47, v47, s6, v211
	v_or_b32_e32 v47, 32, v47
	v_and_or_b32 v48, v48, s6, v211
	v_or_b32_e32 v48, 27, v48
	v_and_or_b32 v49, v49, s6, v211
	v_or_b32_e32 v49, 26, v49
	v_and_or_b32 v50, v50, s6, v211
	v_or_b32_e32 v50, 25, v50
	v_and_or_b32 v51, v51, s6, v211
	v_or_b32_e32 v51, 24, v51
	v_and_or_b32 v52, v52, s6, v211
	v_or_b32_e32 v52, 19, v52
	v_and_or_b32 v53, v53, s6, v211
	v_or_b32_e32 v53, 18, v53
	v_and_or_b32 v54, v54, s6, v211
	v_or_b32_e32 v54, 17, v54
	v_and_or_b32 v55, v55, s6, v211
	v_or_b32_e32 v55, 16, v55
	v_and_or_b32 v56, v56, s6, v211
	v_or_b32_e32 v56, 11, v56
	v_and_or_b32 v57, v57, s6, v211
	v_or_b32_e32 v57, 10, v57
	v_and_or_b32 v58, v58, s6, v211
	v_or_b32_e32 v58, 9, v58
	v_and_or_b32 v59, v59, s6, v211
	v_or_b32_e32 v59, 8, v59
	v_and_or_b32 v60, v60, s6, v211
	v_or_b32_e32 v60, 3, v60
	v_and_or_b32 v61, v61, s6, v211
	v_or_b32_e32 v61, 2, v61
	v_and_or_b32 v62, v62, s6, v211
	v_or_b32_e32 v62, 1, v62
	v_and_or_b32 v63, v63, s6, v211
	v_or_b32_e32 v63, 0, v63
	v_max_f32_e32 v144, v0, v13
	v_min_f32_e32 v13, v0, v13
	v_max_f32_e32 v145, v1, v12
	v_min_f32_e32 v12, v1, v12
	v_max_f32_e32 v146, v2, v15
	v_min_f32_e32 v15, v2, v15
	v_max_f32_e32 v147, v3, v14
	v_min_f32_e32 v14, v3, v14
	v_max_f32_e32 v148, v4, v8
	v_min_f32_e32 v8, v4, v8
	v_max_f32_e32 v149, v5, v6
	v_min_f32_e32 v6, v5, v6
	v_max_f32_e32 v150, v7, v11
	v_min_f32_e32 v11, v7, v11
	v_max_f32_e32 v151, v9, v10
	v_min_f32_e32 v10, v9, v10
	v_max_f32_e32 v249, v144, v149
	v_min_f32_e32 v149, v144, v149
	v_max_f32_e32 v250, v145, v150
	v_min_f32_e32 v150, v145, v150
	v_max_f32_e32 v251, v146, v151
	v_min_f32_e32 v151, v146, v151
	v_max_f32_e32 v252, v147, v148
	v_min_f32_e32 v148, v147, v148
	v_max_f32_e32 v253, v6, v13
	v_min_f32_e32 v13, v6, v13
	v_max_f32_e32 v254, v8, v14
	v_min_f32_e32 v14, v8, v14
	v_max_f32_e32 v255, v10, v15
	v_min_f32_e32 v15, v10, v15
	v_max_f32_e32 v96, v11, v12
	v_min_f32_e32 v12, v11, v12
	v_max_f32_e32 v97, v249, v250
	v_min_f32_e32 v250, v249, v250
	v_max_f32_e32 v98, v251, v252
	v_min_f32_e32 v252, v251, v252
	v_max_f32_e32 v99, v148, v149
	v_min_f32_e32 v149, v148, v149
	v_max_f32_e32 v100, v253, v254
	v_min_f32_e32 v254, v253, v254
	v_max_f32_e32 v101, v150, v151
	v_min_f32_e32 v151, v150, v151
	v_max_f32_e32 v102, v255, v96
	v_min_f32_e32 v96, v255, v96
	v_max_f32_e32 v103, v12, v13
	v_min_f32_e32 v13, v12, v13
	v_max_f32_e32 v104, v14, v15
	v_min_f32_e32 v15, v14, v15
	v_max_f32_e32 v105, v97, v98
	v_min_f32_e32 v98, v97, v98
	v_max_f32_e32 v106, v250, v252
	v_min_f32_e32 v252, v250, v252
	v_max_f32_e32 v107, v99, v102
	v_min_f32_e32 v102, v99, v102
	v_max_f32_e32 v108, v149, v96
	v_min_f32_e32 v96, v149, v96
	v_max_f32_e32 v109, v100, v101
	v_min_f32_e32 v101, v100, v101
	v_max_f32_e32 v110, v254, v151
	v_min_f32_e32 v151, v254, v151
	v_max_f32_e32 v111, v103, v104
	v_min_f32_e32 v104, v103, v104
	v_max_f32_e32 v112, v13, v15
	v_min_f32_e32 v15, v13, v15
	v_max_f32_e32 v113, v106, v98
	v_min_f32_e32 v98, v106, v98
	v_max_f32_e32 v114, v252, v111
	v_min_f32_e32 v111, v252, v111
	v_max_f32_e32 v115, v107, v109
	v_min_f32_e32 v109, v107, v109
	v_max_f32_e32 v116, v108, v101
	v_min_f32_e32 v101, v108, v101
	v_max_f32_e32 v117, v110, v102
	v_min_f32_e32 v102, v110, v102
	v_max_f32_e32 v118, v151, v96
	v_min_f32_e32 v96, v151, v96
	v_max_f32_e32 v119, v112, v104
	v_min_f32_e32 v104, v112, v104
	v_max_f32_e32 v120, v113, v115
	v_min_f32_e32 v115, v113, v115
	v_max_f32_e32 v121, v98, v109
	v_min_f32_e32 v109, v98, v109
	v_max_f32_e32 v122, v116, v117
	v_min_f32_e32 v117, v116, v117
	v_max_f32_e32 v123, v101, v102
	v_min_f32_e32 v102, v101, v102
	v_max_f32_e32 v124, v118, v119
	v_min_f32_e32 v119, v118, v119
	v_max_f32_e32 v125, v96, v104
	v_min_f32_e32 v104, v96, v104
	v_max_f32_e32 v126, v121, v115
	v_min_f32_e32 v115, v121, v115
	v_max_f32_e32 v127, v114, v109
	v_min_f32_e32 v109, v114, v109
	v_max_f32_e32 v64, v124, v111
	v_min_f32_e32 v111, v124, v111
	v_max_f32_e32 v65, v125, v119
	v_min_f32_e32 v119, v125, v119
	v_max_f32_e32 v66, v127, v122
	v_min_f32_e32 v122, v127, v122
	v_max_f32_e32 v67, v109, v117
	v_min_f32_e32 v117, v109, v117
	v_max_f32_e32 v68, v123, v64
	v_min_f32_e32 v64, v123, v64
	v_max_f32_e32 v69, v102, v111
	v_min_f32_e32 v111, v102, v111
	v_max_f32_e32 v70, v66, v115
	v_min_f32_e32 v115, v66, v115
	v_max_f32_e32 v71, v122, v67
	v_min_f32_e32 v67, v122, v67
	v_max_f32_e32 v72, v68, v117
	v_min_f32_e32 v117, v68, v117
	v_max_f32_e32 v73, v64, v69
	v_min_f32_e32 v69, v64, v69
	v_max_f32_e32 v74, v65, v111
	v_min_f32_e32 v111, v65, v111
	v_max_f32_e32 v75, v67, v72
	v_min_f32_e32 v72, v67, v72
	v_max_f32_e32 v76, v117, v73
	v_min_f32_e32 v73, v117, v73
	v_max_f32_e32 v77, v16, v29
	v_min_f32_e32 v29, v16, v29
	v_max_f32_e32 v78, v17, v28
	v_min_f32_e32 v28, v17, v28
	v_max_f32_e32 v79, v18, v31
	v_min_f32_e32 v31, v18, v31
	v_max_f32_e32 v80, v19, v30
	v_min_f32_e32 v30, v19, v30
	v_max_f32_e32 v81, v20, v24
	v_min_f32_e32 v24, v20, v24
	v_max_f32_e32 v82, v21, v22
	v_min_f32_e32 v22, v21, v22
	v_max_f32_e32 v83, v23, v27
	v_min_f32_e32 v27, v23, v27
	v_max_f32_e32 v84, v25, v26
	v_min_f32_e32 v26, v25, v26
	v_max_f32_e32 v85, v77, v82
	v_min_f32_e32 v82, v77, v82
	v_max_f32_e32 v86, v78, v83
	v_min_f32_e32 v83, v78, v83
	v_max_f32_e32 v87, v79, v84
	v_min_f32_e32 v84, v79, v84
	v_max_f32_e32 v88, v80, v81
	v_min_f32_e32 v81, v80, v81
	v_max_f32_e32 v89, v22, v29
	v_min_f32_e32 v29, v22, v29
	v_max_f32_e32 v90, v24, v30
	v_min_f32_e32 v30, v24, v30
	v_max_f32_e32 v91, v26, v31
	v_min_f32_e32 v31, v26, v31
	v_max_f32_e32 v92, v27, v28
	v_min_f32_e32 v28, v27, v28
	v_max_f32_e32 v93, v85, v86
	v_min_f32_e32 v86, v85, v86
	v_max_f32_e32 v94, v87, v88
	v_min_f32_e32 v88, v87, v88
	v_max_f32_e32 v95, v81, v82
	v_min_f32_e32 v82, v81, v82
	v_max_f32_e32 v0, v89, v90
	v_min_f32_e32 v90, v89, v90
	v_max_f32_e32 v1, v83, v84
	v_min_f32_e32 v84, v83, v84
	v_max_f32_e32 v2, v91, v92
	v_min_f32_e32 v92, v91, v92
	v_max_f32_e32 v3, v28, v29
	v_min_f32_e32 v29, v28, v29
	v_max_f32_e32 v4, v30, v31
	v_min_f32_e32 v31, v30, v31
	v_max_f32_e32 v5, v93, v94
	v_min_f32_e32 v94, v93, v94
	v_max_f32_e32 v7, v86, v88
	v_min_f32_e32 v88, v86, v88
	v_max_f32_e32 v9, v95, v2
	v_min_f32_e32 v2, v95, v2
	v_max_f32_e32 v144, v82, v92
	v_min_f32_e32 v92, v82, v92
	v_max_f32_e32 v145, v0, v1
	v_min_f32_e32 v1, v0, v1
	v_max_f32_e32 v146, v90, v84
	v_min_f32_e32 v84, v90, v84
	v_max_f32_e32 v147, v3, v4
	v_min_f32_e32 v4, v3, v4
	v_max_f32_e32 v6, v29, v31
	v_min_f32_e32 v31, v29, v31
	v_max_f32_e32 v8, v7, v94
	v_min_f32_e32 v94, v7, v94
	v_max_f32_e32 v10, v88, v147
	v_min_f32_e32 v147, v88, v147
	v_max_f32_e32 v11, v9, v145
	v_min_f32_e32 v145, v9, v145
	v_max_f32_e32 v249, v144, v1
	v_min_f32_e32 v1, v144, v1
	v_max_f32_e32 v251, v146, v2
	v_min_f32_e32 v2, v146, v2
	v_max_f32_e32 v148, v84, v92
	v_min_f32_e32 v92, v84, v92
	v_max_f32_e32 v253, v6, v4
	v_min_f32_e32 v4, v6, v4
	v_max_f32_e32 v150, v8, v11
	v_min_f32_e32 v11, v8, v11
	v_max_f32_e32 v255, v94, v145
	v_min_f32_e32 v145, v94, v145
	v_max_f32_e32 v12, v249, v251
	v_min_f32_e32 v251, v249, v251
	v_max_f32_e32 v14, v1, v2
	v_min_f32_e32 v2, v1, v2
	v_max_f32_e32 v97, v148, v253
	v_min_f32_e32 v253, v148, v253
	v_max_f32_e32 v250, v92, v4
	v_min_f32_e32 v4, v92, v4
	v_max_f32_e32 v99, v255, v11
	v_min_f32_e32 v11, v255, v11
	v_max_f32_e32 v149, v10, v145
	v_min_f32_e32 v145, v10, v145
	v_max_f32_e32 v100, v97, v147
	v_min_f32_e32 v147, v97, v147
	v_max_f32_e32 v254, v250, v253
	v_min_f32_e32 v253, v250, v253
	v_max_f32_e32 v103, v149, v12
	v_min_f32_e32 v12, v149, v12
	v_max_f32_e32 v13, v145, v251
	v_min_f32_e32 v251, v145, v251
	v_max_f32_e32 v106, v14, v100
	v_min_f32_e32 v100, v14, v100
	v_max_f32_e32 v252, v2, v147
	v_min_f32_e32 v147, v2, v147
	v_max_f32_e32 v107, v103, v11
	v_min_f32_e32 v11, v103, v11
	v_max_f32_e32 v108, v12, v13
	v_min_f32_e32 v13, v12, v13
	v_max_f32_e32 v110, v106, v251
	v_min_f32_e32 v251, v106, v251
	v_max_f32_e32 v151, v100, v252
	v_min_f32_e32 v252, v100, v252
	v_max_f32_e32 v112, v254, v147
	v_min_f32_e32 v147, v254, v147
	v_max_f32_e32 v113, v13, v110
	v_min_f32_e32 v110, v13, v110
	v_max_f32_e32 v98, v251, v151
	v_min_f32_e32 v151, v251, v151
	s_waitcnt vmcnt(0)
	v_pk_mul_f32 v[160:161], v[160:161], v[176:177]
	v_pk_mul_f32 v[162:163], v[162:163], v[178:179]
	v_pk_mul_f32 v[164:165], v[164:165], v[180:181]
	v_pk_mul_f32 v[166:167], v[166:167], v[182:183]
	v_pk_mul_f32 v[168:169], v[168:169], v[184:185]
	v_pk_mul_f32 v[170:171], v[170:171], v[186:187]
	v_pk_mul_f32 v[172:173], v[172:173], v[188:189]
	v_pk_mul_f32 v[174:175], v[174:175], v[190:191]
	v_max3_f32 v192, |v160|, |v161|, |v162|
	v_max3_f32 v192, |v163|, |v164|, v192
	v_max3_f32 v192, |v165|, |v166|, v192
	v_max3_f32 v192, |v167|, |v168|, v192
	v_max3_f32 v192, |v169|, |v170|, v192
	v_max3_f32 v192, |v171|, |v172|, v192
	v_max3_f32 v192, |v173|, |v174|, v192
	v_max_f32_e64 v192, |v175|, v192
	s_nop 1
	v_mov_b32_dpp v193, v192 quad_perm:[1,0,3,2] row_mask:0xf bank_mask:0xf bound_ctrl:1
	v_max_f32_e32 v192, v192, v193
	s_nop 1
	v_mov_b32_dpp v193, v192 quad_perm:[2,3,0,1] row_mask:0xf bank_mask:0xf bound_ctrl:1
	v_max_f32_e32 v192, v192, v193
	s_nop 1
	v_mov_b32_dpp v193, v192 row_half_mirror row_mask:0xf bank_mask:0xf bound_ctrl:1
	v_max_f32_e32 v192, v192, v193
	s_nop 1
	v_mov_b32_dpp v193, v192 row_mirror row_mask:0xf bank_mask:0xf bound_ctrl:1
	v_max_f32_e32 v192, v192, v193
	v_mov_b32_e32 v193, v192
	s_nop 1
	v_permlane16_swap_b32_e32 v192, v193
	s_nop 1
	v_max_f32_e32 v192, v192, v193
	v_mov_b32_e32 v193, v192
	s_nop 1
	v_permlane32_swap_b32_e32 v192, v193
	s_nop 1
	v_max_f32_e32 v192, v192, v193
	v_max_f32_e32 v192, 0xda24260, v192
	v_mul_f32_e32 v194, 0x3e2aaaab, v192
	global_store_dword v214, v194, s[12:13]
	v_div_scale_f32 v195, s[26:27], v194, v194, 1.0
	v_rcp_f32_e32 v196, v195
	v_div_scale_f32 v204, vcc, 1.0, v194, 1.0
	v_fma_f32 v205, -v195, v196, 1.0
	v_fmac_f32_e32 v196, v205, v196
	v_mul_f32_e32 v205, v204, v196
	v_fma_f32 v206, -v195, v205, v204
	v_fmac_f32_e32 v205, v206, v196
	v_fma_f32 v195, -v195, v205, v204
	s_nop 0
	v_div_fmas_f32 v195, v195, v196, v205
	v_div_fixup_f32 v207, v195, v194, 1.0
	v_mul_f32_e32 v160, v207, v160
	v_mul_f32_e32 v161, v207, v161
	v_mul_f32_e32 v162, v207, v162
	v_mul_f32_e32 v163, v207, v163
	v_mul_f32_e32 v164, v207, v164
	v_mul_f32_e32 v165, v207, v165
	v_mul_f32_e32 v166, v207, v166
	v_mul_f32_e32 v167, v207, v167
	v_mul_f32_e32 v168, v207, v168
	v_mul_f32_e32 v169, v207, v169
	v_mul_f32_e32 v170, v207, v170
	v_mul_f32_e32 v171, v207, v171
	v_mul_f32_e32 v172, v207, v172
	v_mul_f32_e32 v173, v207, v173
	v_mul_f32_e32 v174, v207, v174
	v_mul_f32_e32 v175, v207, v175
	v_mov_b32_e32 v208, 0
	v_mov_b32_e32 v209, 0
	v_mov_b32_e32 v210, 0
	v_mov_b32_e32 v193, 0
	v_cvt_scalef32_pk_fp4_f32 v208, v160, v161, 1.0
	v_cvt_scalef32_pk_fp4_f32 v209, v164, v165, 1.0
	v_cvt_scalef32_pk_fp4_f32 v210, v168, v169, 1.0
	v_cvt_scalef32_pk_fp4_f32 v193, v172, v173, 1.0
	v_cvt_scalef32_pk_fp4_f32 v208, v162, v163, 1.0 op_sel:[0,0,1,0]
	v_cvt_scalef32_pk_fp4_f32 v209, v166, v167, 1.0 op_sel:[0,0,1,0]
	v_cvt_scalef32_pk_fp4_f32 v210, v170, v171, 1.0 op_sel:[0,0,1,0]
	v_cvt_scalef32_pk_fp4_f32 v193, v174, v175, 1.0 op_sel:[0,0,1,0]
	global_store_short v213, v208, s[10:11] nt
	s_add_u32 s14, s10, 0x200000
	s_addc_u32 s15, s11, 0
	global_store_short v213, v209, s[14:15] nt
	s_add_u32 s14, s10, 0x400000
	s_addc_u32 s15, s11, 0
	global_store_short v213, v210, s[14:15] nt
	s_add_u32 s14, s10, 0x600000
	s_addc_u32 s15, s11, 0
	global_store_short v213, v193, s[14:15] nt
	s_add_u32 s10, s10, 0x20000
	s_addc_u32 s11, s11, 0
	s_add_u32 s12, s12, 0x2000
	s_addc_u32 s13, s13, 0
	global_load_dwordx4 v[160:163], v212, s[8:9] offset:0 nt
	global_load_dwordx4 v[164:167], v212, s[8:9] offset:1024 nt
	global_load_dwordx4 v[168:171], v212, s[8:9] offset:2048 nt
	global_load_dwordx4 v[172:175], v212, s[8:9] offset:3072 nt
	s_add_u32 s8, s8, 0x800000
	s_addc_u32 s9, s9, 0
	v_max_f32_e32 v116, v32, v45
	v_min_f32_e32 v45, v32, v45
	v_max_f32_e32 v101, v33, v44
	v_min_f32_e32 v44, v33, v44
	v_max_f32_e32 v118, v34, v47
	v_min_f32_e32 v47, v34, v47
	v_max_f32_e32 v96, v35, v46
	v_min_f32_e32 v46, v35, v46
	v_max_f32_e32 v121, v36, v40
	v_min_f32_e32 v40, v36, v40
	v_max_f32_e32 v114, v37, v38
	v_min_f32_e32 v38, v37, v38
	v_max_f32_e32 v124, v39, v43
	v_min_f32_e32 v43, v39, v43
	v_max_f32_e32 v125, v41, v42
	v_min_f32_e32 v42, v41, v42
	v_max_f32_e32 v127, v116, v114
	v_min_f32_e32 v114, v116, v114
	v_max_f32_e32 v109, v101, v124
	v_min_f32_e32 v124, v101, v124
	v_max_f32_e32 v123, v118, v125
	v_min_f32_e32 v125, v118, v125
	v_max_f32_e32 v102, v96, v121
	v_min_f32_e32 v121, v96, v121
	v_max_f32_e32 v66, v38, v45
	v_min_f32_e32 v45, v38, v45
	v_max_f32_e32 v122, v40, v46
	v_min_f32_e32 v46, v40, v46
	v_max_f32_e32 v68, v42, v47
	v_min_f32_e32 v47, v42, v47
	v_max_f32_e32 v64, v43, v44
	v_min_f32_e32 v44, v43, v44
	v_max_f32_e32 v65, v127, v109
	v_min_f32_e32 v109, v127, v109
	v_max_f32_e32 v67, v123, v102
	v_min_f32_e32 v102, v123, v102
	v_max_f32_e32 v117, v121, v114
	v_min_f32_e32 v114, v121, v114
	v_max_f32_e32 v16, v66, v122
	v_min_f32_e32 v122, v66, v122
	v_max_f32_e32 v17, v124, v125
	v_min_f32_e32 v125, v124, v125
	v_max_f32_e32 v18, v68, v64
	v_min_f32_e32 v64, v68, v64
	v_max_f32_e32 v19, v44, v45
	v_min_f32_e32 v45, v44, v45
	v_max_f32_e32 v20, v46, v47
	v_min_f32_e32 v47, v46, v47
	v_max_f32_e32 v21, v65, v67
	v_min_f32_e32 v67, v65, v67
	v_max_f32_e32 v23, v109, v102
	v_min_f32_e32 v102, v109, v102
	v_max_f32_e32 v25, v117, v18
	v_min_f32_e32 v18, v117, v18
	v_max_f32_e32 v77, v114, v64
	v_min_f32_e32 v64, v114, v64
	v_max_f32_e32 v78, v16, v17
	v_min_f32_e32 v17, v16, v17
	v_max_f32_e32 v79, v122, v125
	v_min_f32_e32 v125, v122, v125
	v_max_f32_e32 v80, v19, v20
	v_min_f32_e32 v20, v19, v20
	v_max_f32_e32 v22, v45, v47
	v_min_f32_e32 v47, v45, v47
	v_max_f32_e32 v24, v23, v67
	v_min_f32_e32 v67, v23, v67
	v_max_f32_e32 v26, v102, v80
	v_min_f32_e32 v80, v102, v80
	v_max_f32_e32 v27, v25, v78
	v_min_f32_e32 v78, v25, v78
	v_max_f32_e32 v85, v77, v17
	v_min_f32_e32 v17, v77, v17
	v_max_f32_e32 v87, v79, v18
	v_min_f32_e32 v18, v79, v18
	v_max_f32_e32 v81, v125, v64
	v_min_f32_e32 v64, v125, v64
	v_max_f32_e32 v89, v22, v20
	v_min_f32_e32 v20, v22, v20
	v_max_f32_e32 v83, v24, v27
	v_min_f32_e32 v27, v24, v27
	v_max_f32_e32 v91, v67, v78
	v_min_f32_e32 v78, v67, v78
	v_max_f32_e32 v28, v85, v87
	v_min_f32_e32 v87, v85, v87
	v_max_f32_e32 v30, v17, v18
	v_min_f32_e32 v18, v17, v18
	v_max_f32_e32 v93, v81, v89
	v_min_f32_e32 v89, v81, v89
	v_max_f32_e32 v86, v64, v20
	v_min_f32_e32 v20, v64, v20
	v_max_f32_e32 v95, v91, v27
	v_min_f32_e32 v27, v91, v27
	v_max_f32_e32 v82, v26, v78
	v_min_f32_e32 v78, v26, v78
	v_max_f32_e32 v0, v93, v80
	v_min_f32_e32 v80, v93, v80
	v_max_f32_e32 v90, v86, v89
	v_min_f32_e32 v89, v86, v89
	v_max_f32_e32 v3, v82, v28
	v_min_f32_e32 v28, v82, v28
	v_max_f32_e32 v29, v78, v87
	v_min_f32_e32 v87, v78, v87
	v_max_f32_e32 v7, v30, v0
	v_min_f32_e32 v0, v30, v0
	v_max_f32_e32 v88, v18, v80
	v_min_f32_e32 v80, v18, v80
	v_max_f32_e32 v9, v3, v27
	v_min_f32_e32 v27, v3, v27
	v_max_f32_e32 v144, v28, v29
	v_min_f32_e32 v29, v28, v29
	v_max_f32_e32 v146, v7, v87
	v_min_f32_e32 v87, v7, v87
	v_max_f32_e32 v84, v0, v88
	v_min_f32_e32 v88, v0, v88
	v_max_f32_e32 v6, v90, v80
	v_min_f32_e32 v80, v90, v80
	v_max_f32_e32 v8, v29, v146
	v_min_f32_e32 v146, v29, v146
	v_max_f32_e32 v94, v87, v84
	v_min_f32_e32 v84, v87, v84
	v_max_f32_e32 v249, v48, v61
	v_min_f32_e32 v61, v48, v61
	v_max_f32_e32 v1, v49, v60
	v_min_f32_e32 v60, v49, v60
	v_max_f32_e32 v148, v50, v63
	v_min_f32_e32 v63, v50, v63
	v_max_f32_e32 v92, v51, v62
	v_min_f32_e32 v62, v51, v62
	v_max_f32_e32 v255, v52, v56
	v_min_f32_e32 v56, v52, v56
	v_max_f32_e32 v10, v53, v54
	v_min_f32_e32 v54, v53, v54
	v_max_f32_e32 v97, v55, v59
	v_min_f32_e32 v59, v55, v59
	v_max_f32_e32 v250, v57, v58
	v_min_f32_e32 v58, v57, v58
	v_max_f32_e32 v149, v249, v10
	v_min_f32_e32 v10, v249, v10
	v_max_f32_e32 v145, v1, v97
	v_min_f32_e32 v97, v1, v97
	v_max_f32_e32 v14, v148, v250
	v_min_f32_e32 v250, v148, v250
	v_max_f32_e32 v2, v92, v255
	v_min_f32_e32 v255, v92, v255
	v_max_f32_e32 v103, v54, v61
	v_min_f32_e32 v61, v54, v61
	v_max_f32_e32 v12, v56, v62
	v_min_f32_e32 v62, v56, v62
	v_max_f32_e32 v106, v58, v63
	v_min_f32_e32 v63, v58, v63
	v_max_f32_e32 v100, v59, v60
	v_min_f32_e32 v60, v59, v60
	v_max_f32_e32 v254, v149, v145
	v_min_f32_e32 v145, v149, v145
	v_max_f32_e32 v13, v14, v2
	v_min_f32_e32 v2, v14, v2
	v_max_f32_e32 v251, v255, v10
	v_min_f32_e32 v10, v255, v10
	v_max_f32_e32 v32, v103, v12
	v_min_f32_e32 v12, v103, v12
	v_max_f32_e32 v33, v97, v250
	v_min_f32_e32 v250, v97, v250
	v_max_f32_e32 v34, v106, v100
	v_min_f32_e32 v100, v106, v100
	v_max_f32_e32 v35, v60, v61
	v_min_f32_e32 v61, v60, v61
	v_max_f32_e32 v36, v62, v63
	v_min_f32_e32 v63, v62, v63
	v_max_f32_e32 v37, v254, v13
	v_min_f32_e32 v13, v254, v13
	v_max_f32_e32 v39, v145, v2
	v_min_f32_e32 v2, v145, v2
	v_max_f32_e32 v41, v251, v34
	v_min_f32_e32 v34, v251, v34
	v_max_f32_e32 v116, v10, v100
	v_min_f32_e32 v100, v10, v100
	v_max_f32_e32 v101, v32, v33
	v_min_f32_e32 v33, v32, v33
	v_max_f32_e32 v118, v12, v250
	v_min_f32_e32 v250, v12, v250
	v_max_f32_e32 v96, v35, v36
	v_min_f32_e32 v36, v35, v36
	v_max_f32_e32 v38, v61, v63
	v_min_f32_e32 v63, v61, v63
	v_max_f32_e32 v40, v39, v13
	v_min_f32_e32 v13, v39, v13
	v_max_f32_e32 v42, v2, v96
	v_min_f32_e32 v96, v2, v96
	v_max_f32_e32 v43, v41, v101
	v_min_f32_e32 v101, v41, v101
	v_max_f32_e32 v127, v116, v33
	v_min_f32_e32 v33, v116, v33
	v_max_f32_e32 v123, v118, v34
	v_min_f32_e32 v34, v118, v34
	v_max_f32_e32 v121, v250, v100
	v_min_f32_e32 v100, v250, v100
	v_max_f32_e32 v66, v38, v36
	v_min_f32_e32 v36, v38, v36
	v_max_f32_e32 v124, v40, v43
	v_min_f32_e32 v43, v40, v43
	v_max_f32_e32 v68, v13, v101
	v_min_f32_e32 v101, v13, v101
	v_max_f32_e32 v44, v127, v123
	v_min_f32_e32 v123, v127, v123
	v_max_f32_e32 v46, v33, v34
	v_min_f32_e32 v34, v33, v34
	v_max_f32_e32 v65, v121, v66
	v_min_f32_e32 v66, v121, v66
	v_max_f32_e32 v109, v100, v36
	v_min_f32_e32 v36, v100, v36
	v_max_f32_e32 v117, v68, v43
	v_min_f32_e32 v43, v68, v43
	v_max_f32_e32 v114, v42, v101
	v_min_f32_e32 v101, v42, v101
	v_max_f32_e32 v16, v65, v96
	v_min_f32_e32 v96, v65, v96
	v_max_f32_e32 v122, v109, v66
	v_min_f32_e32 v66, v109, v66
	v_max_f32_e32 v19, v114, v44
	v_min_f32_e32 v44, v114, v44
	v_max_f32_e32 v45, v101, v123
	v_min_f32_e32 v123, v101, v123
	v_max_f32_e32 v23, v46, v16
	v_min_f32_e32 v16, v46, v16
	v_max_f32_e32 v102, v34, v96
	v_min_f32_e32 v96, v34, v96
	v_max_f32_e32 v25, v19, v43
	v_min_f32_e32 v43, v19, v43
	v_max_f32_e32 v77, v44, v45
	v_min_f32_e32 v45, v44, v45
	v_max_f32_e32 v79, v23, v123
	v_min_f32_e32 v123, v23, v123
	v_max_f32_e32 v125, v16, v102
	v_min_f32_e32 v102, v16, v102
	v_max_f32_e32 v22, v122, v96
	v_min_f32_e32 v96, v122, v96
	v_max_f32_e32 v24, v45, v79
	v_min_f32_e32 v79, v45, v79
	v_max_f32_e32 v67, v123, v125
	v_min_f32_e32 v125, v123, v125
	s_waitcnt vmcnt(0)
	v_pk_mul_f32 v[160:161], v[160:161], v[176:177]
	v_pk_mul_f32 v[162:163], v[162:163], v[178:179]
	v_pk_mul_f32 v[164:165], v[164:165], v[180:181]
	v_pk_mul_f32 v[166:167], v[166:167], v[182:183]
	v_pk_mul_f32 v[168:169], v[168:169], v[184:185]
	v_pk_mul_f32 v[170:171], v[170:171], v[186:187]
	v_pk_mul_f32 v[172:173], v[172:173], v[188:189]
	v_pk_mul_f32 v[174:175], v[174:175], v[190:191]
	v_max3_f32 v192, |v160|, |v161|, |v162|
	v_max3_f32 v192, |v163|, |v164|, v192
	v_max3_f32 v192, |v165|, |v166|, v192
	v_max3_f32 v192, |v167|, |v168|, v192
	v_max3_f32 v192, |v169|, |v170|, v192
	v_max3_f32 v192, |v171|, |v172|, v192
	v_max3_f32 v192, |v173|, |v174|, v192
	v_max_f32_e64 v192, |v175|, v192
	s_nop 1
	v_mov_b32_dpp v193, v192 quad_perm:[1,0,3,2] row_mask:0xf bank_mask:0xf bound_ctrl:1
	v_max_f32_e32 v192, v192, v193
	s_nop 1
	v_mov_b32_dpp v193, v192 quad_perm:[2,3,0,1] row_mask:0xf bank_mask:0xf bound_ctrl:1
	v_max_f32_e32 v192, v192, v193
	s_nop 1
	v_mov_b32_dpp v193, v192 row_half_mirror row_mask:0xf bank_mask:0xf bound_ctrl:1
	v_max_f32_e32 v192, v192, v193
	s_nop 1
	v_mov_b32_dpp v193, v192 row_mirror row_mask:0xf bank_mask:0xf bound_ctrl:1
	v_max_f32_e32 v192, v192, v193
	v_mov_b32_e32 v193, v192
	s_nop 1
	v_permlane16_swap_b32_e32 v192, v193
	s_nop 1
	v_max_f32_e32 v192, v192, v193
	v_mov_b32_e32 v193, v192
	s_nop 1
	v_permlane32_swap_b32_e32 v192, v193
	s_nop 1
	v_max_f32_e32 v192, v192, v193
	v_max_f32_e32 v192, 0xda24260, v192
	v_mul_f32_e32 v194, 0x3e2aaaab, v192
	global_store_dword v214, v194, s[12:13]
	v_div_scale_f32 v195, s[26:27], v194, v194, 1.0
	v_rcp_f32_e32 v196, v195
	v_div_scale_f32 v204, vcc, 1.0, v194, 1.0
	v_fma_f32 v205, -v195, v196, 1.0
	v_fmac_f32_e32 v196, v205, v196
	v_mul_f32_e32 v205, v204, v196
	v_fma_f32 v206, -v195, v205, v204
	v_fmac_f32_e32 v205, v206, v196
	v_fma_f32 v195, -v195, v205, v204
	s_nop 0
	v_div_fmas_f32 v195, v195, v196, v205
	v_div_fixup_f32 v207, v195, v194, 1.0
	v_mul_f32_e32 v160, v207, v160
	v_mul_f32_e32 v161, v207, v161
	v_mul_f32_e32 v162, v207, v162
	v_mul_f32_e32 v163, v207, v163
	v_mul_f32_e32 v164, v207, v164
	v_mul_f32_e32 v165, v207, v165
	v_mul_f32_e32 v166, v207, v166
	v_mul_f32_e32 v167, v207, v167
	v_mul_f32_e32 v168, v207, v168
	v_mul_f32_e32 v169, v207, v169
	v_mul_f32_e32 v170, v207, v170
	v_mul_f32_e32 v171, v207, v171
	v_mul_f32_e32 v172, v207, v172
	v_mul_f32_e32 v173, v207, v173
	v_mul_f32_e32 v174, v207, v174
	v_mul_f32_e32 v175, v207, v175
	v_mov_b32_e32 v208, 0
	v_mov_b32_e32 v209, 0
	v_mov_b32_e32 v210, 0
	v_mov_b32_e32 v193, 0
	v_cvt_scalef32_pk_fp4_f32 v208, v160, v161, 1.0
	v_cvt_scalef32_pk_fp4_f32 v209, v164, v165, 1.0
	v_cvt_scalef32_pk_fp4_f32 v210, v168, v169, 1.0
	v_cvt_scalef32_pk_fp4_f32 v193, v172, v173, 1.0
	v_cvt_scalef32_pk_fp4_f32 v208, v162, v163, 1.0 op_sel:[0,0,1,0]
	v_cvt_scalef32_pk_fp4_f32 v209, v166, v167, 1.0 op_sel:[0,0,1,0]
	v_cvt_scalef32_pk_fp4_f32 v210, v170, v171, 1.0 op_sel:[0,0,1,0]
	v_cvt_scalef32_pk_fp4_f32 v193, v174, v175, 1.0 op_sel:[0,0,1,0]
	global_store_short v213, v208, s[10:11] nt
	s_add_u32 s14, s10, 0x200000
	s_addc_u32 s15, s11, 0
	global_store_short v213, v209, s[14:15] nt
	s_add_u32 s14, s10, 0x400000
	s_addc_u32 s15, s11, 0
	global_store_short v213, v210, s[14:15] nt
	s_add_u32 s14, s10, 0x600000
	s_addc_u32 s15, s11, 0
	global_store_short v213, v193, s[14:15] nt
	s_add_u32 s10, s10, 0x20000
	s_addc_u32 s11, s11, 0
	s_add_u32 s12, s12, 0x2000
	s_addc_u32 s13, s13, 0
	global_load_dwordx4 v[160:163], v212, s[8:9] offset:0 nt
	global_load_dwordx4 v[164:167], v212, s[8:9] offset:1024 nt
	global_load_dwordx4 v[168:171], v212, s[8:9] offset:2048 nt
	global_load_dwordx4 v[172:175], v212, s[8:9] offset:3072 nt
	s_add_u32 s8, s8, 0x800000
	s_addc_u32 s9, s9, 0
	v_max_f32_e32 v105, v105, v31
	v_max_f32_e32 v120, v120, v4
	v_max_f32_e32 v126, v126, v253
	v_max_f32_e32 v70, v70, v147
	v_max_f32_e32 v115, v115, v112
	v_max_f32_e32 v71, v71, v252
	v_max_f32_e32 v75, v75, v151
	v_max_f32_e32 v72, v72, v98
	v_max_f32_e32 v76, v76, v110
	v_max_f32_e32 v73, v73, v113
	v_max_f32_e32 v69, v69, v108
	v_max_f32_e32 v74, v74, v11
	v_max_f32_e32 v111, v111, v107
	v_max_f32_e32 v119, v119, v99
	v_max_f32_e32 v104, v104, v150
	v_max_f32_e32 v15, v15, v5
	v_max_f32_e32 v85, v105, v76
	v_min_f32_e32 v76, v105, v76
	v_max_f32_e32 v17, v120, v73
	v_min_f32_e32 v73, v120, v73
	v_max_f32_e32 v81, v126, v69
	v_min_f32_e32 v69, v126, v69
	v_max_f32_e32 v64, v70, v74
	v_min_f32_e32 v74, v70, v74
	v_max_f32_e32 v91, v115, v111
	v_min_f32_e32 v111, v115, v111
	v_max_f32_e32 v26, v71, v119
	v_min_f32_e32 v119, v71, v119
	v_max_f32_e32 v93, v75, v104
	v_min_f32_e32 v104, v75, v104
	v_max_f32_e32 v86, v72, v15
	v_min_f32_e32 v15, v72, v15
	v_max_f32_e32 v82, v85, v91
	v_min_f32_e32 v91, v85, v91
	v_max_f32_e32 v78, v17, v26
	v_min_f32_e32 v26, v17, v26
	v_max_f32_e32 v30, v81, v93
	v_min_f32_e32 v93, v81, v93
	v_max_f32_e32 v18, v64, v86
	v_min_f32_e32 v86, v64, v86
	v_max_f32_e32 v3, v76, v111
	v_min_f32_e32 v111, v76, v111
	v_max_f32_e32 v28, v73, v119
	v_min_f32_e32 v119, v73, v119
	v_max_f32_e32 v7, v69, v104
	v_min_f32_e32 v104, v69, v104
	v_max_f32_e32 v0, v74, v15
	v_min_f32_e32 v15, v74, v15
	v_max_f32_e32 v90, v82, v30
	v_min_f32_e32 v30, v82, v30
	v_max_f32_e32 v29, v78, v18
	v_min_f32_e32 v18, v78, v18
	v_max_f32_e32 v87, v91, v93
	v_min_f32_e32 v93, v91, v93
	v_max_f32_e32 v48, v26, v86
	v_min_f32_e32 v86, v26, v86
	v_max_f32_e32 v49, v3, v7
	v_min_f32_e32 v7, v3, v7
	v_max_f32_e32 v50, v28, v0
	v_min_f32_e32 v0, v28, v0
	v_max_f32_e32 v51, v111, v104
	v_min_f32_e32 v104, v111, v104
	v_max_f32_e32 v52, v119, v15
	v_min_f32_e32 v15, v119, v15
	v_max_f32_e32 v53, v90, v29
	v_min_f32_e32 v29, v90, v29
	v_max_f32_e32 v55, v30, v18
	v_min_f32_e32 v18, v30, v18
	v_max_f32_e32 v57, v87, v48
	v_min_f32_e32 v48, v87, v48
	v_max_f32_e32 v249, v93, v86
	v_min_f32_e32 v86, v93, v86
	v_max_f32_e32 v1, v49, v50
	v_min_f32_e32 v50, v49, v50
	v_max_f32_e32 v148, v7, v0
	v_min_f32_e32 v0, v7, v0
	v_max_f32_e32 v92, v51, v52
	v_min_f32_e32 v52, v51, v52
	v_max_f32_e32 v54, v104, v15
	v_min_f32_e32 v15, v104, v15
	v_max_f32_e32 v21, v21, v63
	v_max_f32_e32 v83, v83, v36
	v_max_f32_e32 v95, v95, v66
	v_max_f32_e32 v9, v9, v96
	v_max_f32_e32 v27, v27, v22
	v_max_f32_e32 v144, v144, v102
	v_max_f32_e32 v8, v8, v125
	v_max_f32_e32 v146, v146, v67
	v_max_f32_e32 v94, v94, v79
	v_max_f32_e32 v84, v84, v24
	v_max_f32_e32 v88, v88, v77
	v_max_f32_e32 v6, v6, v43
	v_max_f32_e32 v80, v80, v25
	v_max_f32_e32 v89, v89, v117
	v_max_f32_e32 v20, v20, v124
	v_max_f32_e32 v47, v47, v37
	v_max_f32_e32 v56, v21, v94
	v_min_f32_e32 v94, v21, v94
	v_max_f32_e32 v58, v83, v84
	v_min_f32_e32 v84, v83, v84
	v_max_f32_e32 v59, v95, v88
	v_min_f32_e32 v88, v95, v88
	v_max_f32_e32 v149, v9, v6
	v_min_f32_e32 v6, v9, v6
	v_max_f32_e32 v14, v27, v80
	v_min_f32_e32 v80, v27, v80
	v_max_f32_e32 v255, v144, v89
	v_min_f32_e32 v89, v144, v89
	v_max_f32_e32 v103, v8, v20
	v_min_f32_e32 v20, v8, v20
	v_max_f32_e32 v97, v146, v47
	v_min_f32_e32 v47, v146, v47
	v_max_f32_e32 v106, v56, v14
	v_min_f32_e32 v14, v56, v14
	v_max_f32_e32 v60, v58, v255
	v_min_f32_e32 v255, v58, v255
	v_max_f32_e32 v62, v59, v103
	v_min_f32_e32 v103, v59, v103
	v_max_f32_e32 v254, v149, v97
	v_min_f32_e32 v97, v149, v97
	v_max_f32_e32 v145, v94, v80
	v_min_f32_e32 v80, v94, v80
	v_max_f32_e32 v251, v84, v89
	v_min_f32_e32 v89, v84, v89
	v_max_f32_e32 v10, v88, v20
	v_min_f32_e32 v20, v88, v20
	v_max_f32_e32 v32, v6, v47
	v_min_f32_e32 v47, v6, v47
	v_max_f32_e32 v12, v106, v62
	v_min_f32_e32 v62, v106, v62
	v_max_f32_e32 v35, v60, v254
	v_min_f32_e32 v254, v60, v254
	v_max_f32_e32 v61, v14, v103
	v_min_f32_e32 v103, v14, v103
	v_max_f32_e32 v39, v255, v97
	v_min_f32_e32 v97, v255, v97
	v_max_f32_e32 v2, v145, v10
	v_min_f32_e32 v10, v145, v10
	v_max_f32_e32 v41, v251, v32
	v_min_f32_e32 v32, v251, v32
	v_max_f32_e32 v116, v80, v20
	v_min_f32_e32 v20, v80, v20
	v_max_f32_e32 v118, v89, v47
	v_min_f32_e32 v47, v89, v47
	v_max_f32_e32 v250, v12, v35
	v_min_f32_e32 v35, v12, v35
	v_max_f32_e32 v38, v62, v254
	v_min_f32_e32 v254, v62, v254
	v_max_f32_e32 v40, v61, v39
	v_min_f32_e32 v39, v61, v39
	v_max_f32_e32 v13, v103, v97
	v_min_f32_e32 v97, v103, v97
	v_max_f32_e32 v127, v2, v41
	v_min_f32_e32 v41, v2, v41
	v_max_f32_e32 v33, v10, v32
	v_min_f32_e32 v32, v10, v32
	v_max_f32_e32 v121, v116, v118
	v_min_f32_e32 v118, v116, v118
	v_max_f32_e32 v100, v20, v47
	v_min_f32_e32 v47, v20, v47
	v_max_f32_e32 v53, v53, v47
	v_max_f32_e32 v29, v29, v100
	v_max_f32_e32 v55, v55, v118
	v_max_f32_e32 v18, v18, v121
	v_max_f32_e32 v57, v57, v32
	v_max_f32_e32 v48, v48, v33
	v_max_f32_e32 v249, v249, v41
	v_max_f32_e32 v86, v86, v127
	v_max_f32_e32 v1, v1, v97
	v_max_f32_e32 v50, v50, v13
	v_max_f32_e32 v148, v148, v39
	v_max_f32_e32 v0, v0, v40
	v_max_f32_e32 v92, v92, v254
	v_max_f32_e32 v52, v52, v38
	v_max_f32_e32 v54, v54, v35
	v_max_f32_e32 v15, v15, v250
	v_max_f32_e32 v68, v53, v1
	v_min_f32_e32 v1, v53, v1
	v_max_f32_e32 v42, v29, v50
	v_min_f32_e32 v50, v29, v50
	v_max_f32_e32 v65, v55, v148
	v_min_f32_e32 v148, v55, v148
	v_max_f32_e32 v109, v18, v0
	v_min_f32_e32 v0, v18, v0
	v_max_f32_e32 v114, v57, v92
	v_min_f32_e32 v92, v57, v92
	v_max_f32_e32 v101, v48, v52
	v_min_f32_e32 v52, v48, v52
	v_max_f32_e32 v46, v249, v54
	v_min_f32_e32 v54, v249, v54
	v_max_f32_e32 v34, v86, v15
	v_min_f32_e32 v15, v86, v15
	v_max_f32_e32 v19, v68, v114
	v_min_f32_e32 v114, v68, v114
	v_max_f32_e32 v44, v42, v101
	v_min_f32_e32 v101, v42, v101
	v_max_f32_e32 v23, v65, v46
	v_min_f32_e32 v46, v65, v46
	v_max_f32_e32 v16, v109, v34
	v_min_f32_e32 v34, v109, v34
	v_max_f32_e32 v122, v1, v92
	v_min_f32_e32 v92, v1, v92
	v_max_f32_e32 v45, v50, v52
	v_min_f32_e32 v52, v50, v52
	v_max_f32_e32 v123, v148, v54
	v_min_f32_e32 v54, v148, v54
	v_max_f32_e32 v5, v0, v15
	v_min_f32_e32 v15, v0, v15
	v_max_f32_e32 v150, v19, v23
	v_min_f32_e32 v23, v19, v23
	v_max_f32_e32 v99, v44, v16
	v_min_f32_e32 v16, v44, v16
	v_max_f32_e32 v107, v114, v46
	v_min_f32_e32 v46, v114, v46
	v_max_f32_e32 v11, v101, v34
	v_min_f32_e32 v34, v101, v34
	v_max_f32_e32 v108, v122, v123
	v_min_f32_e32 v123, v122, v123
	v_max_f32_e32 v113, v45, v5
	v_min_f32_e32 v5, v45, v5
	v_max_f32_e32 v110, v92, v54
	v_min_f32_e32 v54, v92, v54
	v_max_f32_e32 v98, v52, v15
	v_min_f32_e32 v15, v52, v15
	v_max_f32_e32 v151, v150, v99
	v_min_f32_e32 v99, v150, v99
	v_max_f32_e32 v252, v23, v16
	v_min_f32_e32 v16, v23, v16
	v_max_f32_e32 v112, v107, v11
	v_min_f32_e32 v11, v107, v11
	v_max_f32_e32 v147, v46, v34
	v_min_f32_e32 v34, v46, v34
	v_max_f32_e32 v253, v108, v113
	v_min_f32_e32 v113, v108, v113
	v_max_f32_e32 v4, v123, v5
	v_min_f32_e32 v5, v123, v5
	v_max_f32_e32 v31, v110, v98
	v_min_f32_e32 v98, v110, v98
	v_max_f32_e32 v105, v54, v15
	v_min_f32_e32 v15, v54, v15
	v_mov_b32_e32 v120, v151
	v_mov_b32_e32 v126, v99
	v_mov_b32_e32 v70, v252
	v_mov_b32_e32 v115, v16
	v_mov_b32_e32 v71, v112
	v_mov_b32_e32 v75, v11
	v_mov_b32_e32 v72, v147
	v_mov_b32_e32 v85, v34
	v_mov_b32_e32 v17, v253
	v_mov_b32_e32 v81, v113
	v_mov_b32_e32 v64, v4
	v_mov_b32_e32 v76, v5
	v_mov_b32_e32 v73, v31
	v_mov_b32_e32 v69, v98
	v_mov_b32_e32 v74, v105
	v_mov_b32_e32 v82, v15
	s_nop 1
	v_permlane32_swap_b32_e32 v151, v120
	v_permlane32_swap_b32_e32 v99, v126
	v_permlane32_swap_b32_e32 v252, v70
	v_permlane32_swap_b32_e32 v16, v115
	v_permlane32_swap_b32_e32 v112, v71
	v_permlane32_swap_b32_e32 v11, v75
	v_permlane32_swap_b32_e32 v147, v72
	v_permlane32_swap_b32_e32 v34, v85
	v_permlane32_swap_b32_e32 v253, v17
	v_permlane32_swap_b32_e32 v113, v81
	v_permlane32_swap_b32_e32 v4, v64
	v_permlane32_swap_b32_e32 v5, v76
	v_permlane32_swap_b32_e32 v31, v73
	v_permlane32_swap_b32_e32 v98, v69
	v_permlane32_swap_b32_e32 v105, v74
	v_permlane32_swap_b32_e32 v15, v82
	s_nop 1
	v_max_f32_e32 v151, v151, v82
	v_max_f32_e32 v99, v99, v74
	v_max_f32_e32 v252, v252, v69
	v_max_f32_e32 v16, v16, v73
	v_max_f32_e32 v112, v112, v76
	v_max_f32_e32 v11, v11, v64
	v_max_f32_e32 v147, v147, v81
	v_max_f32_e32 v34, v34, v17
	v_max_f32_e32 v253, v253, v85
	v_max_f32_e32 v113, v113, v72
	v_max_f32_e32 v4, v4, v75
	v_max_f32_e32 v5, v5, v71
	v_max_f32_e32 v31, v31, v115
	v_max_f32_e32 v98, v98, v70
	v_max_f32_e32 v105, v105, v126
	v_max_f32_e32 v15, v15, v120
	v_max_f32_e32 v78, v151, v253
	v_min_f32_e32 v253, v151, v253
	v_max_f32_e32 v91, v99, v113
	v_min_f32_e32 v113, v99, v113
	v_max_f32_e32 v26, v252, v4
	v_min_f32_e32 v4, v252, v4
	v_max_f32_e32 v3, v16, v5
	v_min_f32_e32 v5, v16, v5
	v_max_f32_e32 v28, v112, v31
	v_min_f32_e32 v31, v112, v31
	v_max_f32_e32 v111, v11, v98
	v_min_f32_e32 v98, v11, v98
	v_max_f32_e32 v119, v147, v105
	v_min_f32_e32 v105, v147, v105
	v_max_f32_e32 v90, v34, v15
	v_min_f32_e32 v15, v34, v15
	v_max_f32_e32 v30, v78, v28
	v_min_f32_e32 v28, v78, v28
	v_max_f32_e32 v87, v91, v111
	v_min_f32_e32 v111, v91, v111
	v_max_f32_e32 v93, v26, v119
	v_min_f32_e32 v119, v26, v119
	v_max_f32_e32 v49, v3, v90
	v_min_f32_e32 v90, v3, v90
	v_max_f32_e32 v7, v253, v31
	v_min_f32_e32 v31, v253, v31
	v_max_f32_e32 v51, v113, v98
	v_min_f32_e32 v98, v113, v98
	v_max_f32_e32 v104, v4, v105
	v_min_f32_e32 v105, v4, v105
	v_max_f32_e32 v37, v5, v15
	v_min_f32_e32 v15, v5, v15
	v_max_f32_e32 v124, v30, v93
	v_min_f32_e32 v93, v30, v93
	v_max_f32_e32 v117, v87, v49
	v_min_f32_e32 v49, v87, v49
	v_max_f32_e32 v25, v28, v119
	v_min_f32_e32 v119, v28, v119
	v_max_f32_e32 v43, v111, v90
	v_min_f32_e32 v90, v111, v90
	v_max_f32_e32 v77, v7, v104
	v_min_f32_e32 v104, v7, v104
	v_max_f32_e32 v24, v51, v37
	v_min_f32_e32 v37, v51, v37
	v_max_f32_e32 v79, v31, v105
	v_min_f32_e32 v105, v31, v105
	v_max_f32_e32 v67, v98, v15
	v_min_f32_e32 v15, v98, v15
	v_max_f32_e32 v125, v124, v117
	v_min_f32_e32 v117, v124, v117
	v_max_f32_e32 v102, v93, v49
	v_min_f32_e32 v49, v93, v49
	v_max_f32_e32 v22, v25, v43
	v_min_f32_e32 v43, v25, v43
	v_max_f32_e32 v96, v119, v90
	v_min_f32_e32 v90, v119, v90
	v_max_f32_e32 v66, v77, v24
	v_min_f32_e32 v24, v77, v24
	v_max_f32_e32 v36, v104, v37
	v_min_f32_e32 v37, v104, v37
	v_max_f32_e32 v63, v79, v67
	v_min_f32_e32 v67, v79, v67
	v_max_f32_e32 v21, v105, v15
	v_min_f32_e32 v15, v105, v15
	s_waitcnt vmcnt(0)
	v_pk_mul_f32 v[160:161], v[160:161], v[176:177]
	v_pk_mul_f32 v[162:163], v[162:163], v[178:179]
	v_pk_mul_f32 v[164:165], v[164:165], v[180:181]
	v_pk_mul_f32 v[166:167], v[166:167], v[182:183]
	v_pk_mul_f32 v[168:169], v[168:169], v[184:185]
	v_pk_mul_f32 v[170:171], v[170:171], v[186:187]
	v_pk_mul_f32 v[172:173], v[172:173], v[188:189]
	v_pk_mul_f32 v[174:175], v[174:175], v[190:191]
	v_max3_f32 v192, |v160|, |v161|, |v162|
	v_max3_f32 v192, |v163|, |v164|, v192
	v_max3_f32 v192, |v165|, |v166|, v192
	v_max3_f32 v192, |v167|, |v168|, v192
	v_max3_f32 v192, |v169|, |v170|, v192
	v_max3_f32 v192, |v171|, |v172|, v192
	v_max3_f32 v192, |v173|, |v174|, v192
	v_max_f32_e64 v192, |v175|, v192
	s_nop 1
	v_mov_b32_dpp v193, v192 quad_perm:[1,0,3,2] row_mask:0xf bank_mask:0xf bound_ctrl:1
	v_max_f32_e32 v192, v192, v193
	s_nop 1
	v_mov_b32_dpp v193, v192 quad_perm:[2,3,0,1] row_mask:0xf bank_mask:0xf bound_ctrl:1
	v_max_f32_e32 v192, v192, v193
	s_nop 1
	v_mov_b32_dpp v193, v192 row_half_mirror row_mask:0xf bank_mask:0xf bound_ctrl:1
	v_max_f32_e32 v192, v192, v193
	s_nop 1
	v_mov_b32_dpp v193, v192 row_mirror row_mask:0xf bank_mask:0xf bound_ctrl:1
	v_max_f32_e32 v192, v192, v193
	v_mov_b32_e32 v193, v192
	s_nop 1
	v_permlane16_swap_b32_e32 v192, v193
	s_nop 1
	v_max_f32_e32 v192, v192, v193
	v_mov_b32_e32 v193, v192
	s_nop 1
	v_permlane32_swap_b32_e32 v192, v193
	s_nop 1
	v_max_f32_e32 v192, v192, v193
	v_max_f32_e32 v192, 0xda24260, v192
	v_mul_f32_e32 v194, 0x3e2aaaab, v192
	global_store_dword v214, v194, s[12:13]
	v_div_scale_f32 v195, s[26:27], v194, v194, 1.0
	v_rcp_f32_e32 v196, v195
	v_div_scale_f32 v204, vcc, 1.0, v194, 1.0
	v_fma_f32 v205, -v195, v196, 1.0
	v_fmac_f32_e32 v196, v205, v196
	v_mul_f32_e32 v205, v204, v196
	v_fma_f32 v206, -v195, v205, v204
	v_fmac_f32_e32 v205, v206, v196
	v_fma_f32 v195, -v195, v205, v204
	s_nop 0
	v_div_fmas_f32 v195, v195, v196, v205
	v_div_fixup_f32 v207, v195, v194, 1.0
	v_mul_f32_e32 v160, v207, v160
	v_mul_f32_e32 v161, v207, v161
	v_mul_f32_e32 v162, v207, v162
	v_mul_f32_e32 v163, v207, v163
	v_mul_f32_e32 v164, v207, v164
	v_mul_f32_e32 v165, v207, v165
	v_mul_f32_e32 v166, v207, v166
	v_mul_f32_e32 v167, v207, v167
	v_mul_f32_e32 v168, v207, v168
	v_mul_f32_e32 v169, v207, v169
	v_mul_f32_e32 v170, v207, v170
	v_mul_f32_e32 v171, v207, v171
	v_mul_f32_e32 v172, v207, v172
	v_mul_f32_e32 v173, v207, v173
	v_mul_f32_e32 v174, v207, v174
	v_mul_f32_e32 v175, v207, v175
	v_mov_b32_e32 v208, 0
	v_mov_b32_e32 v209, 0
	v_mov_b32_e32 v210, 0
	v_mov_b32_e32 v193, 0
	v_cvt_scalef32_pk_fp4_f32 v208, v160, v161, 1.0
	v_cvt_scalef32_pk_fp4_f32 v209, v164, v165, 1.0
	v_cvt_scalef32_pk_fp4_f32 v210, v168, v169, 1.0
	v_cvt_scalef32_pk_fp4_f32 v193, v172, v173, 1.0
	v_cvt_scalef32_pk_fp4_f32 v208, v162, v163, 1.0 op_sel:[0,0,1,0]
	v_cvt_scalef32_pk_fp4_f32 v209, v166, v167, 1.0 op_sel:[0,0,1,0]
	v_cvt_scalef32_pk_fp4_f32 v210, v170, v171, 1.0 op_sel:[0,0,1,0]
	v_cvt_scalef32_pk_fp4_f32 v193, v174, v175, 1.0 op_sel:[0,0,1,0]
	global_store_short v213, v208, s[10:11] nt
	s_add_u32 s14, s10, 0x200000
	s_addc_u32 s15, s11, 0
	global_store_short v213, v209, s[14:15] nt
	s_add_u32 s14, s10, 0x400000
	s_addc_u32 s15, s11, 0
	global_store_short v213, v210, s[14:15] nt
	s_add_u32 s14, s10, 0x600000
	s_addc_u32 s15, s11, 0
	global_store_short v213, v193, s[14:15] nt
	s_add_u32 s10, s10, 0x20000
	s_addc_u32 s11, s11, 0
	s_add_u32 s12, s12, 0x2000
	s_addc_u32 s13, s13, 0
	global_load_dwordx4 v[160:163], v212, s[8:9] offset:0 nt
	global_load_dwordx4 v[164:167], v212, s[8:9] offset:1024 nt
	global_load_dwordx4 v[168:171], v212, s[8:9] offset:2048 nt
	global_load_dwordx4 v[172:175], v212, s[8:9] offset:3072 nt
	s_add_u32 s8, s8, 0x800000
	s_addc_u32 s9, s9, 0
	ds_write_b8 v240, v125 offset:512
	ds_write_b8 v240, v117 offset:513
	ds_write_b8 v240, v102 offset:514
	ds_write_b8 v240, v49 offset:515
	ds_write_b8 v240, v22 offset:516
	ds_write_b8 v240, v43 offset:517
	ds_write_b8 v240, v96 offset:518
	ds_write_b8 v240, v90 offset:519
	ds_write_b8 v240, v66 offset:520
	ds_write_b8 v240, v24 offset:521
	ds_write_b8 v240, v36 offset:522
	ds_write_b8 v240, v37 offset:523
	ds_write_b8 v240, v63 offset:524
	ds_write_b8 v240, v67 offset:525
	ds_write_b8 v240, v21 offset:526
	ds_write_b8 v240, v15 offset:527
	v_cndmask_b32_e64 v0, v128, v125, s[4:5]
	v_cndmask_b32_e64 v17, v125, v128, s[4:5]
	v_cndmask_b32_e64 v1, v129, v117, s[4:5]
	v_cndmask_b32_e64 v18, v117, v129, s[4:5]
	v_cndmask_b32_e64 v2, v130, v102, s[4:5]
	v_cndmask_b32_e64 v19, v102, v130, s[4:5]
	v_cndmask_b32_e64 v3, v131, v49, s[4:5]
	v_cndmask_b32_e64 v20, v49, v131, s[4:5]
	v_cndmask_b32_e64 v4, v132, v22, s[4:5]
	v_cndmask_b32_e64 v23, v22, v132, s[4:5]
	v_cndmask_b32_e64 v5, v133, v43, s[4:5]
	v_cndmask_b32_e64 v25, v43, v133, s[4:5]
	v_cndmask_b32_e64 v6, v134, v96, s[4:5]
	v_cndmask_b32_e64 v26, v96, v134, s[4:5]
	v_cndmask_b32_e64 v7, v135, v90, s[4:5]
	v_cndmask_b32_e64 v27, v90, v135, s[4:5]
	v_cndmask_b32_e64 v8, v136, v66, s[4:5]
	v_cndmask_b32_e64 v28, v66, v136, s[4:5]
	v_cndmask_b32_e64 v9, v137, v24, s[4:5]
	v_cndmask_b32_e64 v29, v24, v137, s[4:5]
	v_cndmask_b32_e64 v10, v138, v36, s[4:5]
	v_cndmask_b32_e64 v30, v36, v138, s[4:5]
	v_cndmask_b32_e64 v11, v139, v37, s[4:5]
	v_cndmask_b32_e64 v31, v37, v139, s[4:5]
	v_cndmask_b32_e64 v12, v140, v63, s[4:5]
	v_cndmask_b32_e64 v32, v63, v140, s[4:5]
	v_cndmask_b32_e64 v13, v141, v67, s[4:5]
	v_cndmask_b32_e64 v33, v67, v141, s[4:5]
	v_cndmask_b32_e64 v14, v142, v21, s[4:5]
	v_cndmask_b32_e64 v34, v21, v142, s[4:5]
	v_cndmask_b32_e64 v16, v143, v15, s[4:5]
	v_cndmask_b32_e64 v35, v15, v143, s[4:5]
	v_and_b32_e32 v0, s6, v0
	v_and_b32_e32 v17, s6, v17
	v_and_b32_e32 v1, s6, v1
	v_and_b32_e32 v18, s6, v18
	v_and_b32_e32 v2, s6, v2
	v_and_b32_e32 v19, s6, v19
	v_and_b32_e32 v3, s6, v3
	v_and_b32_e32 v20, s6, v20
	v_and_b32_e32 v4, s6, v4
	v_and_b32_e32 v23, s6, v23
	v_and_b32_e32 v5, s6, v5
	v_and_b32_e32 v25, s6, v25
	v_and_b32_e32 v6, s6, v6
	v_and_b32_e32 v26, s6, v26
	v_and_b32_e32 v7, s6, v7
	v_and_b32_e32 v27, s6, v27
	v_and_b32_e32 v8, s6, v8
	v_and_b32_e32 v28, s6, v28
	v_and_b32_e32 v9, s6, v9
	v_and_b32_e32 v29, s6, v29
	v_and_b32_e32 v10, s6, v10
	v_and_b32_e32 v30, s6, v30
	v_and_b32_e32 v11, s6, v11
	v_and_b32_e32 v31, s6, v31
	v_and_b32_e32 v12, s6, v12
	v_and_b32_e32 v32, s6, v32
	v_and_b32_e32 v13, s6, v13
	v_and_b32_e32 v33, s6, v33
	v_and_b32_e32 v14, s6, v14
	v_and_b32_e32 v34, s6, v34
	v_and_b32_e32 v16, s6, v16
	v_and_b32_e32 v35, s6, v35
	v_add_f32_e32 v38, v0, v18
	v_and_or_b32 v38, v38, s7, 0
	v_add_f32_e32 v39, v0, v19
	v_and_or_b32 v39, v39, s7, 2
	v_add_f32_e32 v40, v0, v20
	v_and_or_b32 v40, v40, s7, 4
	v_add_f32_e32 v41, v0, v23
	v_and_or_b32 v41, v41, s7, 6
	v_add_f32_e32 v42, v0, v25
	v_and_or_b32 v42, v42, s7, 8
	v_add_f32_e32 v44, v0, v26
	v_and_or_b32 v44, v44, s7, 10
	v_add_f32_e32 v45, v0, v27
	v_and_or_b32 v45, v45, s7, 12
	v_add_f32_e32 v46, v0, v28
	v_and_or_b32 v46, v46, s7, 14
	v_add_f32_e32 v47, v0, v29
	v_and_or_b32 v47, v47, s7, 16
	v_add_f32_e32 v48, v0, v30
	v_and_or_b32 v48, v48, s7, 18
	v_add_f32_e32 v50, v0, v31
	v_and_or_b32 v50, v50, s7, 20
	v_add_f32_e32 v51, v0, v32
	v_and_or_b32 v51, v51, s7, 22
	v_add_f32_e32 v52, v0, v33
	v_and_or_b32 v52, v52, s7, 24
	v_add_f32_e32 v53, v0, v34
	v_and_or_b32 v53, v53, s7, 26
	v_add_f32_e32 v54, v0, v35
	v_and_or_b32 v54, v54, s7, 28
	v_add_f32_e32 v55, v1, v19
	v_and_or_b32 v55, v55, s7, 30
	v_add_f32_e32 v56, v1, v20
	v_and_or_b32 v56, v56, s7, 32
	v_add_f32_e32 v57, v1, v23
	v_and_or_b32 v57, v57, s7, 34
	v_add_f32_e32 v58, v1, v25
	v_and_or_b32 v58, v58, s7, 36
	v_add_f32_e32 v59, v1, v26
	v_and_or_b32 v59, v59, s7, 38
	v_add_f32_e32 v60, v1, v27
	v_and_or_b32 v60, v60, s7, 40
	v_add_f32_e32 v61, v2, v20
	v_and_or_b32 v61, v61, s7, 42
	v_add_f32_e32 v62, v2, v23
	v_and_or_b32 v62, v62, s7, 44
	v_add_f32_e32 v64, v0, v17
	v_and_or_b32 v64, v64, s7, 46
	v_cndmask_b32_e64 v64, v64, v244, s[4:5]
	v_add_f32_e32 v65, v1, v18
	v_and_or_b32 v65, v65, s7, 48
	v_cndmask_b32_e64 v65, v65, v244, s[4:5]
	v_add_f32_e32 v68, v2, v19
	v_and_or_b32 v68, v68, s7, 50
	v_cndmask_b32_e64 v68, v68, v244, s[4:5]
	v_add_f32_e32 v69, v3, v20
	v_and_or_b32 v69, v69, s7, 52
	v_cndmask_b32_e64 v69, v69, v244, s[4:5]
	v_max_f32_e32 v70, v38, v53
	v_min_f32_e32 v53, v38, v53
	v_max_f32_e32 v71, v39, v52
	v_min_f32_e32 v52, v39, v52
	v_max_f32_e32 v72, v40, v55
	v_min_f32_e32 v55, v40, v55
	v_max_f32_e32 v73, v41, v54
	v_min_f32_e32 v54, v41, v54
	v_max_f32_e32 v74, v42, v47
	v_min_f32_e32 v47, v42, v47
	v_max_f32_e32 v75, v44, v45
	v_min_f32_e32 v45, v44, v45
	v_max_f32_e32 v76, v46, v51
	v_min_f32_e32 v51, v46, v51
	v_max_f32_e32 v77, v48, v50
	v_min_f32_e32 v50, v48, v50
	v_max_f32_e32 v78, v70, v75
	v_min_f32_e32 v75, v70, v75
	v_max_f32_e32 v79, v71, v76
	v_min_f32_e32 v76, v71, v76
	v_max_f32_e32 v80, v72, v77
	v_min_f32_e32 v77, v72, v77
	v_max_f32_e32 v81, v73, v74
	v_min_f32_e32 v74, v73, v74
	v_max_f32_e32 v82, v45, v53
	v_min_f32_e32 v53, v45, v53
	v_max_f32_e32 v83, v47, v54
	v_min_f32_e32 v54, v47, v54
	v_max_f32_e32 v84, v50, v55
	v_min_f32_e32 v55, v50, v55
	v_max_f32_e32 v85, v51, v52
	v_min_f32_e32 v52, v51, v52
	v_max_f32_e32 v86, v78, v79
	v_min_f32_e32 v79, v78, v79
	v_max_f32_e32 v87, v80, v81
	v_min_f32_e32 v81, v80, v81
	v_max_f32_e32 v88, v74, v75
	v_min_f32_e32 v75, v74, v75
	v_max_f32_e32 v89, v82, v83
	v_min_f32_e32 v83, v82, v83
	v_max_f32_e32 v91, v76, v77
	v_min_f32_e32 v77, v76, v77
	v_max_f32_e32 v92, v84, v85
	v_min_f32_e32 v85, v84, v85
	v_max_f32_e32 v93, v52, v53
	v_min_f32_e32 v53, v52, v53
	v_max_f32_e32 v94, v54, v55
	v_min_f32_e32 v55, v54, v55
	v_max_f32_e32 v95, v86, v87
	v_min_f32_e32 v87, v86, v87
	v_max_f32_e32 v97, v79, v81
	v_min_f32_e32 v81, v79, v81
	v_max_f32_e32 v98, v88, v92
	v_min_f32_e32 v92, v88, v92
	v_max_f32_e32 v99, v75, v85
	v_min_f32_e32 v85, v75, v85
	v_max_f32_e32 v100, v89, v91
	v_min_f32_e32 v91, v89, v91
	v_max_f32_e32 v101, v83, v77
	v_min_f32_e32 v77, v83, v77
	v_max_f32_e32 v103, v93, v94
	v_min_f32_e32 v94, v93, v94
	v_max_f32_e32 v104, v53, v55
	v_min_f32_e32 v55, v53, v55
	v_max_f32_e32 v105, v97, v87
	v_min_f32_e32 v87, v97, v87
	v_max_f32_e32 v106, v81, v103
	v_min_f32_e32 v103, v81, v103
	v_max_f32_e32 v107, v98, v100
	v_min_f32_e32 v100, v98, v100
	v_max_f32_e32 v108, v99, v91
	v_min_f32_e32 v91, v99, v91
	v_max_f32_e32 v109, v101, v92
	v_min_f32_e32 v92, v101, v92
	v_max_f32_e32 v110, v77, v85
	v_min_f32_e32 v85, v77, v85
	v_max_f32_e32 v111, v104, v94
	v_min_f32_e32 v94, v104, v94
	v_max_f32_e32 v112, v105, v107
	v_min_f32_e32 v107, v105, v107
	v_max_f32_e32 v113, v87, v100
	v_min_f32_e32 v100, v87, v100
	v_max_f32_e32 v114, v108, v109
	v_min_f32_e32 v109, v108, v109
	v_max_f32_e32 v115, v91, v92
	v_min_f32_e32 v92, v91, v92
	v_max_f32_e32 v116, v110, v111
	v_min_f32_e32 v111, v110, v111
	v_max_f32_e32 v118, v85, v94
	v_min_f32_e32 v94, v85, v94
	v_max_f32_e32 v119, v113, v107
	v_min_f32_e32 v107, v113, v107
	v_max_f32_e32 v120, v106, v100
	v_min_f32_e32 v100, v106, v100
	v_max_f32_e32 v121, v116, v103
	v_min_f32_e32 v103, v116, v103
	v_max_f32_e32 v122, v118, v111
	v_min_f32_e32 v111, v118, v111
	v_max_f32_e32 v123, v120, v114
	v_min_f32_e32 v114, v120, v114
	v_max_f32_e32 v124, v100, v109
	v_min_f32_e32 v109, v100, v109
	v_max_f32_e32 v126, v115, v121
	v_min_f32_e32 v121, v115, v121
	v_max_f32_e32 v127, v92, v103
	v_min_f32_e32 v103, v92, v103
	v_max_f32_e32 v144, v123, v107
	v_min_f32_e32 v107, v123, v107
	v_max_f32_e32 v145, v114, v124
	v_min_f32_e32 v124, v114, v124
	v_max_f32_e32 v146, v126, v109
	v_min_f32_e32 v109, v126, v109
	v_max_f32_e32 v147, v121, v127
	v_min_f32_e32 v127, v121, v127
	v_max_f32_e32 v148, v122, v103
	v_min_f32_e32 v103, v122, v103
	v_max_f32_e32 v149, v124, v146
	v_min_f32_e32 v146, v124, v146
	v_max_f32_e32 v150, v109, v147
	v_min_f32_e32 v147, v109, v147
	v_max_f32_e32 v151, v60, v65
	v_min_f32_e32 v65, v60, v65
	v_max_f32_e32 v249, v61, v62
	v_min_f32_e32 v62, v61, v62
	v_max_f32_e32 v250, v68, v69
	v_min_f32_e32 v69, v68, v69
	v_max_f32_e32 v251, v56, v249
	v_min_f32_e32 v249, v56, v249
	v_max_f32_e32 v252, v57, v64
	v_min_f32_e32 v64, v57, v64
	v_max_f32_e32 v253, v58, v250
	v_min_f32_e32 v250, v58, v250
	v_max_f32_e32 v254, v59, v151
	v_min_f32_e32 v151, v59, v151
	v_max_f32_e32 v255, v251, v252
	v_min_f32_e32 v252, v251, v252
	v_max_f32_e32 v128, v253, v254
	v_min_f32_e32 v254, v253, v254
	v_max_f32_e32 v129, v151, v249
	v_min_f32_e32 v249, v151, v249
	v_max_f32_e32 v130, v62, v65
	v_min_f32_e32 v65, v62, v65
	v_max_f32_e32 v131, v64, v250
	v_min_f32_e32 v250, v64, v250
	v_max_f32_e32 v132, v255, v128
	v_min_f32_e32 v128, v255, v128
	v_max_f32_e32 v133, v252, v254
	v_min_f32_e32 v254, v252, v254
	v_max_f32_e32 v134, v129, v69
	v_min_f32_e32 v69, v129, v69
	v_max_f32_e32 v135, v130, v131
	v_min_f32_e32 v131, v130, v131
	v_max_f32_e32 v136, v65, v250
	v_min_f32_e32 v250, v65, v250
	v_max_f32_e32 v137, v133, v128
	v_min_f32_e32 v128, v133, v128
	v_max_f32_e32 v138, v134, v135
	v_min_f32_e32 v135, v134, v135
	v_max_f32_e32 v139, v249, v131
	v_min_f32_e32 v131, v249, v131
	v_max_f32_e32 v140, v136, v69
	v_min_f32_e32 v69, v136, v69
	v_max_f32_e32 v141, v137, v138
	v_min_f32_e32 v138, v137, v138
	v_max_f32_e32 v142, v128, v135
	v_min_f32_e32 v135, v128, v135
	v_max_f32_e32 v143, v139, v140
	v_min_f32_e32 v140, v139, v140
	v_max_f32_e32 v125, v131, v69
	v_min_f32_e32 v69, v131, v69
	v_max_f32_e32 v117, v142, v138
	v_min_f32_e32 v138, v142, v138
	v_max_f32_e32 v102, v254, v135
	v_min_f32_e32 v135, v254, v135
	v_max_f32_e32 v49, v102, v143
	v_min_f32_e32 v143, v102, v143
	v_max_f32_e32 v22, v135, v140
	v_min_f32_e32 v140, v135, v140
	v_max_f32_e32 v43, v125, v250
	v_min_f32_e32 v250, v125, v250
	v_max_f32_e32 v96, v49, v138
	v_min_f32_e32 v138, v49, v138
	v_max_f32_e32 v90, v143, v22
	v_min_f32_e32 v22, v143, v22
	v_max_f32_e32 v66, v43, v140
	v_min_f32_e32 v140, v43, v140
	v_max_f32_e32 v24, v250, v69
	v_min_f32_e32 v69, v250, v69
	v_max_f32_e32 v36, v22, v66
	v_min_f32_e32 v66, v22, v66
	v_max_f32_e32 v37, v140, v24
	v_min_f32_e32 v24, v140, v24
	s_waitcnt vmcnt(0)
	v_pk_mul_f32 v[160:161], v[160:161], v[176:177]
	v_pk_mul_f32 v[162:163], v[162:163], v[178:179]
	v_pk_mul_f32 v[164:165], v[164:165], v[180:181]
	v_pk_mul_f32 v[166:167], v[166:167], v[182:183]
	v_pk_mul_f32 v[168:169], v[168:169], v[184:185]
	v_pk_mul_f32 v[170:171], v[170:171], v[186:187]
	v_pk_mul_f32 v[172:173], v[172:173], v[188:189]
	v_pk_mul_f32 v[174:175], v[174:175], v[190:191]
	v_max3_f32 v192, |v160|, |v161|, |v162|
	v_max3_f32 v192, |v163|, |v164|, v192
	v_max3_f32 v192, |v165|, |v166|, v192
	v_max3_f32 v192, |v167|, |v168|, v192
	v_max3_f32 v192, |v169|, |v170|, v192
	v_max3_f32 v192, |v171|, |v172|, v192
	v_max3_f32 v192, |v173|, |v174|, v192
	v_max_f32_e64 v192, |v175|, v192
	s_nop 1
	v_mov_b32_dpp v193, v192 quad_perm:[1,0,3,2] row_mask:0xf bank_mask:0xf bound_ctrl:1
	v_max_f32_e32 v192, v192, v193
	s_nop 1
	v_mov_b32_dpp v193, v192 quad_perm:[2,3,0,1] row_mask:0xf bank_mask:0xf bound_ctrl:1
	v_max_f32_e32 v192, v192, v193
	s_nop 1
	v_mov_b32_dpp v193, v192 row_half_mirror row_mask:0xf bank_mask:0xf bound_ctrl:1
	v_max_f32_e32 v192, v192, v193
	s_nop 1
	v_mov_b32_dpp v193, v192 row_mirror row_mask:0xf bank_mask:0xf bound_ctrl:1
	v_max_f32_e32 v192, v192, v193
	v_mov_b32_e32 v193, v192
	s_nop 1
	v_permlane16_swap_b32_e32 v192, v193
	s_nop 1
	v_max_f32_e32 v192, v192, v193
	v_mov_b32_e32 v193, v192
	s_nop 1
	v_permlane32_swap_b32_e32 v192, v193
	s_nop 1
	v_max_f32_e32 v192, v192, v193
	v_max_f32_e32 v192, 0xda24260, v192
	v_mul_f32_e32 v194, 0x3e2aaaab, v192
	global_store_dword v214, v194, s[12:13]
	v_div_scale_f32 v195, s[26:27], v194, v194, 1.0
	v_rcp_f32_e32 v196, v195
	v_div_scale_f32 v204, vcc, 1.0, v194, 1.0
	v_fma_f32 v205, -v195, v196, 1.0
	v_fmac_f32_e32 v196, v205, v196
	v_mul_f32_e32 v205, v204, v196
	v_fma_f32 v206, -v195, v205, v204
	v_fmac_f32_e32 v205, v206, v196
	v_fma_f32 v195, -v195, v205, v204
	s_nop 0
	v_div_fmas_f32 v195, v195, v196, v205
	v_div_fixup_f32 v207, v195, v194, 1.0
	v_mul_f32_e32 v160, v207, v160
	v_mul_f32_e32 v161, v207, v161
	v_mul_f32_e32 v162, v207, v162
	v_mul_f32_e32 v163, v207, v163
	v_mul_f32_e32 v164, v207, v164
	v_mul_f32_e32 v165, v207, v165
	v_mul_f32_e32 v166, v207, v166
	v_mul_f32_e32 v167, v207, v167
	v_mul_f32_e32 v168, v207, v168
	v_mul_f32_e32 v169, v207, v169
	v_mul_f32_e32 v170, v207, v170
	v_mul_f32_e32 v171, v207, v171
	v_mul_f32_e32 v172, v207, v172
	v_mul_f32_e32 v173, v207, v173
	v_mul_f32_e32 v174, v207, v174
	v_mul_f32_e32 v175, v207, v175
	v_mov_b32_e32 v208, 0
	v_mov_b32_e32 v209, 0
	v_mov_b32_e32 v210, 0
	v_mov_b32_e32 v193, 0
	v_cvt_scalef32_pk_fp4_f32 v208, v160, v161, 1.0
	v_cvt_scalef32_pk_fp4_f32 v209, v164, v165, 1.0
	v_cvt_scalef32_pk_fp4_f32 v210, v168, v169, 1.0
	v_cvt_scalef32_pk_fp4_f32 v193, v172, v173, 1.0
	v_cvt_scalef32_pk_fp4_f32 v208, v162, v163, 1.0 op_sel:[0,0,1,0]
	v_cvt_scalef32_pk_fp4_f32 v209, v166, v167, 1.0 op_sel:[0,0,1,0]
	v_cvt_scalef32_pk_fp4_f32 v210, v170, v171, 1.0 op_sel:[0,0,1,0]
	v_cvt_scalef32_pk_fp4_f32 v193, v174, v175, 1.0 op_sel:[0,0,1,0]
	global_store_short v213, v208, s[10:11] nt
	s_add_u32 s14, s10, 0x200000
	s_addc_u32 s15, s11, 0
	global_store_short v213, v209, s[14:15] nt
	s_add_u32 s14, s10, 0x400000
	s_addc_u32 s15, s11, 0
	global_store_short v213, v210, s[14:15] nt
	s_add_u32 s14, s10, 0x600000
	s_addc_u32 s15, s11, 0
	global_store_short v213, v193, s[14:15] nt
	s_add_u32 s10, s10, 0x20000
	s_addc_u32 s11, s11, 0
	s_add_u32 s12, s12, 0x2000
	s_addc_u32 s13, s13, 0
	global_load_dwordx4 v[160:163], v212, s[8:9] offset:0 nt
	global_load_dwordx4 v[164:167], v212, s[8:9] offset:1024 nt
	global_load_dwordx4 v[168:171], v212, s[8:9] offset:2048 nt
	global_load_dwordx4 v[172:175], v212, s[8:9] offset:3072 nt
	s_add_u32 s8, s8, 0x800000
	s_addc_u32 s9, s9, 0
	v_max_f32_e32 v145, v145, v69
	v_max_f32_e32 v149, v149, v24
	v_max_f32_e32 v146, v146, v37
	v_max_f32_e32 v150, v150, v66
	v_max_f32_e32 v147, v147, v36
	v_max_f32_e32 v127, v127, v90
	v_max_f32_e32 v148, v148, v138
	v_max_f32_e32 v103, v103, v96
	v_max_f32_e32 v111, v111, v117
	v_max_f32_e32 v94, v94, v141
	v_max_f32_e32 v55, v55, v132
	v_max_f32_e32 v63, v95, v150
	v_min_f32_e32 v150, v95, v150
	v_max_f32_e32 v67, v112, v147
	v_min_f32_e32 v147, v112, v147
	v_max_f32_e32 v21, v119, v127
	v_min_f32_e32 v127, v119, v127
	v_max_f32_e32 v15, v144, v148
	v_min_f32_e32 v148, v144, v148
	v_max_f32_e32 v0, v107, v103
	v_min_f32_e32 v103, v107, v103
	v_max_f32_e32 v1, v145, v111
	v_min_f32_e32 v111, v145, v111
	v_max_f32_e32 v2, v149, v94
	v_min_f32_e32 v94, v149, v94
	v_max_f32_e32 v3, v146, v55
	v_min_f32_e32 v55, v146, v55
	v_max_f32_e32 v4, v63, v0
	v_min_f32_e32 v0, v63, v0
	v_max_f32_e32 v5, v67, v1
	v_min_f32_e32 v1, v67, v1
	v_max_f32_e32 v6, v21, v2
	v_min_f32_e32 v2, v21, v2
	v_max_f32_e32 v7, v15, v3
	v_min_f32_e32 v3, v15, v3
	v_max_f32_e32 v8, v150, v103
	v_min_f32_e32 v103, v150, v103
	v_max_f32_e32 v9, v147, v111
	v_min_f32_e32 v111, v147, v111
	v_max_f32_e32 v10, v127, v94
	v_min_f32_e32 v94, v127, v94
	v_max_f32_e32 v11, v148, v55
	v_min_f32_e32 v55, v148, v55
	v_max_f32_e32 v12, v4, v6
	v_min_f32_e32 v6, v4, v6
	v_max_f32_e32 v13, v5, v7
	v_min_f32_e32 v7, v5, v7
	v_max_f32_e32 v14, v0, v2
	v_min_f32_e32 v2, v0, v2
	v_max_f32_e32 v16, v1, v3
	v_min_f32_e32 v3, v1, v3
	v_max_f32_e32 v17, v8, v10
	v_min_f32_e32 v10, v8, v10
	v_max_f32_e32 v18, v9, v11
	v_min_f32_e32 v11, v9, v11
	v_max_f32_e32 v19, v103, v94
	v_min_f32_e32 v94, v103, v94
	v_max_f32_e32 v20, v111, v55
	v_min_f32_e32 v55, v111, v55
	v_max_f32_e32 v23, v12, v13
	v_min_f32_e32 v13, v12, v13
	v_max_f32_e32 v25, v6, v7
	v_min_f32_e32 v7, v6, v7
	v_max_f32_e32 v26, v14, v16
	v_min_f32_e32 v16, v14, v16
	v_max_f32_e32 v27, v2, v3
	v_min_f32_e32 v3, v2, v3
	v_max_f32_e32 v28, v17, v18
	v_min_f32_e32 v18, v17, v18
	v_max_f32_e32 v29, v10, v11
	v_min_f32_e32 v11, v10, v11
	v_max_f32_e32 v30, v19, v20
	v_min_f32_e32 v20, v19, v20
	v_max_f32_e32 v31, v94, v55
	v_min_f32_e32 v55, v94, v55
	v_or_b32_e32 v23, v23, v245
	v_or_b32_e32 v13, v13, v245
	v_or_b32_e32 v25, v25, v245
	v_or_b32_e32 v7, v7, v245
	v_or_b32_e32 v26, v26, v245
	v_or_b32_e32 v16, v16, v245
	v_or_b32_e32 v27, v27, v245
	v_or_b32_e32 v3, v3, v245
	v_or_b32_e32 v28, v28, v245
	v_or_b32_e32 v18, v18, v245
	v_or_b32_e32 v29, v29, v245
	v_or_b32_e32 v11, v11, v245
	v_or_b32_e32 v30, v30, v245
	v_or_b32_e32 v20, v20, v245
	v_or_b32_e32 v31, v31, v245
	v_or_b32_e32 v55, v55, v245
	v_mov_b32_e32 v32, v23
	v_mov_b32_e32 v33, v13
	v_mov_b32_e32 v34, v25
	v_mov_b32_e32 v35, v7
	v_mov_b32_e32 v38, v26
	v_mov_b32_e32 v39, v16
	v_mov_b32_e32 v40, v27
	v_mov_b32_e32 v41, v3
	v_mov_b32_e32 v42, v28
	v_mov_b32_e32 v44, v18
	v_mov_b32_e32 v46, v29
	v_mov_b32_e32 v48, v11
	v_mov_b32_e32 v70, v30
	v_mov_b32_e32 v71, v20
	v_mov_b32_e32 v72, v31
	v_mov_b32_e32 v73, v55
	s_nop 1
	v_permlane32_swap_b32_e32 v23, v32
	v_permlane32_swap_b32_e32 v13, v33
	v_permlane32_swap_b32_e32 v25, v34
	v_permlane32_swap_b32_e32 v7, v35
	v_permlane32_swap_b32_e32 v26, v38
	v_permlane32_swap_b32_e32 v16, v39
	v_permlane32_swap_b32_e32 v27, v40
	v_permlane32_swap_b32_e32 v3, v41
	v_permlane32_swap_b32_e32 v28, v42
	v_permlane32_swap_b32_e32 v18, v44
	v_permlane32_swap_b32_e32 v29, v46
	v_permlane32_swap_b32_e32 v11, v48
	v_permlane32_swap_b32_e32 v30, v70
	v_permlane32_swap_b32_e32 v20, v71
	v_permlane32_swap_b32_e32 v31, v72
	v_permlane32_swap_b32_e32 v55, v73
	s_nop 1
	v_max_f32_e32 v23, v23, v73
	v_max_f32_e32 v13, v13, v72
	v_max_f32_e32 v25, v25, v71
	v_max_f32_e32 v7, v7, v70
	v_max_f32_e32 v26, v26, v48
	v_max_f32_e32 v16, v16, v46
	v_max_f32_e32 v27, v27, v44
	v_max_f32_e32 v3, v3, v42
	v_max_f32_e32 v28, v28, v41
	v_max_f32_e32 v18, v18, v40
	v_max_f32_e32 v29, v29, v39
	v_max_f32_e32 v11, v11, v38
	v_max_f32_e32 v30, v30, v35
	v_max_f32_e32 v20, v20, v34
	v_max_f32_e32 v31, v31, v33
	v_max_f32_e32 v55, v55, v32
	v_max_f32_e32 v45, v23, v28
	v_min_f32_e32 v28, v23, v28
	v_max_f32_e32 v47, v13, v18
	v_min_f32_e32 v18, v13, v18
	v_max_f32_e32 v50, v25, v29
	v_min_f32_e32 v29, v25, v29
	v_max_f32_e32 v51, v7, v11
	v_min_f32_e32 v11, v7, v11
	v_max_f32_e32 v78, v26, v30
	v_min_f32_e32 v30, v26, v30
	v_max_f32_e32 v80, v16, v20
	v_min_f32_e32 v20, v16, v20
	v_max_f32_e32 v74, v27, v31
	v_min_f32_e32 v31, v27, v31
	v_max_f32_e32 v82, v3, v55
	v_min_f32_e32 v55, v3, v55
	v_max_f32_e32 v76, v45, v78
	v_min_f32_e32 v78, v45, v78
	v_max_f32_e32 v84, v47, v80
	v_min_f32_e32 v80, v47, v80
	v_max_f32_e32 v52, v50, v74
	v_min_f32_e32 v74, v50, v74
	v_max_f32_e32 v54, v51, v82
	v_min_f32_e32 v82, v51, v82
	v_max_f32_e32 v86, v28, v30
	v_min_f32_e32 v30, v28, v30
	v_max_f32_e32 v79, v18, v20
	v_min_f32_e32 v20, v18, v20
	v_max_f32_e32 v88, v29, v31
	v_min_f32_e32 v31, v29, v31
	v_max_f32_e32 v75, v11, v55
	v_min_f32_e32 v55, v11, v55
	v_max_f32_e32 v89, v76, v52
	v_min_f32_e32 v52, v76, v52
	v_max_f32_e32 v83, v84, v54
	v_min_f32_e32 v54, v84, v54
	v_max_f32_e32 v93, v78, v74
	v_min_f32_e32 v74, v78, v74
	v_max_f32_e32 v53, v80, v82
	v_min_f32_e32 v82, v80, v82
	v_max_f32_e32 v97, v86, v88
	v_min_f32_e32 v88, v86, v88
	v_max_f32_e32 v81, v79, v75
	v_min_f32_e32 v75, v79, v75
	v_max_f32_e32 v98, v30, v31
	v_min_f32_e32 v31, v30, v31
	v_max_f32_e32 v99, v20, v55
	v_min_f32_e32 v55, v20, v55
	v_max_f32_e32 v101, v89, v83
	v_min_f32_e32 v83, v89, v83
	v_max_f32_e32 v77, v52, v54
	v_min_f32_e32 v54, v52, v54
	v_max_f32_e32 v104, v93, v53
	v_min_f32_e32 v53, v93, v53
	v_max_f32_e32 v105, v74, v82
	v_min_f32_e32 v82, v74, v82
	v_max_f32_e32 v87, v97, v81
	v_min_f32_e32 v81, v97, v81
	v_max_f32_e32 v108, v88, v75
	v_min_f32_e32 v75, v88, v75
	v_max_f32_e32 v91, v98, v99
	v_min_f32_e32 v99, v98, v99
	v_max_f32_e32 v110, v31, v55
	v_min_f32_e32 v55, v31, v55
	v_and_b32_e32 v85, s7, v101
	v_cndmask_b32_e64 v113, v101, v87, s[4:5]
	v_cndmask_b32_e64 v106, v83, v81, s[4:5]
	v_cndmask_b32_e64 v116, v77, v108, s[4:5]
	v_cndmask_b32_e64 v118, v54, v75, s[4:5]
	v_cndmask_b32_e64 v120, v104, v91, s[4:5]
	v_cndmask_b32_e64 v100, v53, v99, s[4:5]
	v_cndmask_b32_e64 v115, v105, v110, s[4:5]
	v_cndmask_b32_e64 v92, v82, v55, s[4:5]
	v_and_or_b32 v123, v113, 63, v246
	ds_read_u8 v123, v123
	v_and_or_b32 v114, v106, 63, v246
	ds_read_u8 v114, v114
	v_and_or_b32 v126, v116, 63, v246
	ds_read_u8 v126, v126
	v_and_or_b32 v121, v118, 63, v246
	ds_read_u8 v121, v121
	v_and_or_b32 v122, v120, 63, v246
	ds_read_u8 v122, v122
	v_and_or_b32 v124, v100, 63, v246
	ds_read_u8 v124, v124
	v_and_or_b32 v109, v115, 63, v246
	ds_read_u8 v109, v109
	v_and_or_b32 v60, v92, 63, v246
	ds_read_u8 v60, v60
	v_and_b32_e32 v113, s7, v113
	v_sub_f32_e32 v113, v113, v85
	v_mul_f32_e32 v113, 0x3fb8aa3b, v113
	v_exp_f32_e32 v113, v113
	v_and_b32_e32 v106, s7, v106
	v_sub_f32_e32 v106, v106, v85
	v_mul_f32_e32 v106, 0x3fb8aa3b, v106
	v_exp_f32_e32 v106, v106
	v_and_b32_e32 v116, s7, v116
	v_sub_f32_e32 v116, v116, v85
	v_mul_f32_e32 v116, 0x3fb8aa3b, v116
	v_exp_f32_e32 v116, v116
	v_and_b32_e32 v118, s7, v118
	v_sub_f32_e32 v118, v118, v85
	v_mul_f32_e32 v118, 0x3fb8aa3b, v118
	v_exp_f32_e32 v118, v118
	v_and_b32_e32 v120, s7, v120
	v_sub_f32_e32 v120, v120, v85
	v_mul_f32_e32 v120, 0x3fb8aa3b, v120
	v_exp_f32_e32 v120, v120
	v_and_b32_e32 v100, s7, v100
	v_sub_f32_e32 v100, v100, v85
	v_mul_f32_e32 v100, 0x3fb8aa3b, v100
	v_exp_f32_e32 v100, v100
	v_and_b32_e32 v115, s7, v115
	v_sub_f32_e32 v115, v115, v85
	v_mul_f32_e32 v115, 0x3fb8aa3b, v115
	v_exp_f32_e32 v115, v115
	v_and_b32_e32 v92, s7, v92
	v_sub_f32_e32 v92, v92, v85
	v_mul_f32_e32 v92, 0x3fb8aa3b, v92
	v_exp_f32_e32 v92, v92
	s_nop 0
	v_add_f32_e32 v85, v113, v106
	v_add_f32_e32 v85, v85, v116
	v_add_f32_e32 v85, v85, v118
	v_add_f32_e32 v85, v85, v120
	v_add_f32_e32 v85, v85, v100
	v_add_f32_e32 v85, v85, v115
	v_add_f32_e32 v85, v85, v92
	v_mov_b32_e32 v61, v85
	s_nop 1
	v_permlane32_swap_b32_e32 v85, v61
	s_nop 1
	v_add_f32_e32 v85, v85, v61
	s_waitcnt lgkmcnt(0)
	v_bfe_u32 v68, v123, 4, 4
	v_or_b32_e32 v68, v68, v240
	v_and_or_b32 v123, v123, 15, v240
	ds_read_u8 v68, v68
	ds_read_u8 v123, v123 offset:512
	v_bfe_u32 v56, v114, 4, 4
	v_or_b32_e32 v56, v56, v240
	v_and_or_b32 v114, v114, 15, v240
	ds_read_u8 v56, v56
	ds_read_u8 v114, v114 offset:512
	v_bfe_u32 v57, v126, 4, 4
	v_or_b32_e32 v57, v57, v240
	v_and_or_b32 v126, v126, 15, v240
	ds_read_u8 v57, v57
	ds_read_u8 v126, v126 offset:512
	v_bfe_u32 v58, v121, 4, 4
	v_or_b32_e32 v58, v58, v240
	v_and_or_b32 v121, v121, 15, v240
	ds_read_u8 v58, v58
	ds_read_u8 v121, v121 offset:512
	v_bfe_u32 v59, v122, 4, 4
	v_or_b32_e32 v59, v59, v240
	v_and_or_b32 v122, v122, 15, v240
	ds_read_u8 v59, v59
	ds_read_u8 v122, v122 offset:512
	v_bfe_u32 v251, v124, 4, 4
	v_or_b32_e32 v251, v251, v240
	v_and_or_b32 v124, v124, 15, v240
	ds_read_u8 v251, v251
	ds_read_u8 v124, v124 offset:512
	v_bfe_u32 v253, v109, 4, 4
	v_or_b32_e32 v253, v253, v240
	v_and_or_b32 v109, v109, 15, v240
	ds_read_u8 v253, v253
	ds_read_u8 v109, v109 offset:512
	v_bfe_u32 v151, v60, 4, 4
	v_or_b32_e32 v151, v151, v240
	v_and_or_b32 v60, v60, 15, v240
	ds_read_u8 v151, v151
	ds_read_u8 v60, v60 offset:512
	v_div_scale_f32 v134, s[26:27], v85, v85, v113
	v_rcp_f32_e32 v249, v134
	s_nop 0
	v_fma_f32 v136, -v134, v249, 1.0
	v_fmac_f32_e32 v249, v136, v249
	v_div_scale_f32 v136, vcc, v113, v85, v113
	v_mul_f32_e32 v137, v136, v249
	v_fma_f32 v62, -v134, v137, v136
	v_fmac_f32_e32 v137, v62, v249
	v_fma_f32 v136, -v134, v137, v136
	s_nop 0
	v_div_fmas_f32 v136, v136, v249, v137
	v_div_fixup_f32 v62, v136, v85, v113
	v_div_scale_f32 v134, s[26:27], v85, v85, v106
	v_rcp_f32_e32 v249, v134
	s_nop 0
	v_fma_f32 v136, -v134, v249, 1.0
	v_fmac_f32_e32 v249, v136, v249
	v_div_scale_f32 v136, vcc, v106, v85, v106
	v_mul_f32_e32 v137, v136, v249
	v_fma_f32 v64, -v134, v137, v136
	v_fmac_f32_e32 v137, v64, v249
	v_fma_f32 v136, -v134, v137, v136
	s_nop 0
	v_div_fmas_f32 v136, v136, v249, v137
	v_div_fixup_f32 v64, v136, v85, v106
	v_div_scale_f32 v134, s[26:27], v85, v85, v116
	v_rcp_f32_e32 v249, v134
	s_nop 0
	v_fma_f32 v136, -v134, v249, 1.0
	v_fmac_f32_e32 v249, v136, v249
	v_div_scale_f32 v136, vcc, v116, v85, v116
	v_mul_f32_e32 v137, v136, v249
	v_fma_f32 v255, -v134, v137, v136
	v_fmac_f32_e32 v137, v255, v249
	v_fma_f32 v136, -v134, v137, v136
	s_nop 0
	v_div_fmas_f32 v136, v136, v249, v137
	v_div_fixup_f32 v255, v136, v85, v116
	v_div_scale_f32 v134, s[26:27], v85, v85, v118
	v_rcp_f32_e32 v249, v134
	s_nop 0
	v_fma_f32 v136, -v134, v249, 1.0
	v_fmac_f32_e32 v249, v136, v249
	v_div_scale_f32 v136, vcc, v118, v85, v118
	v_mul_f32_e32 v137, v136, v249
	v_fma_f32 v252, -v134, v137, v136
	v_fmac_f32_e32 v137, v252, v249
	v_fma_f32 v136, -v134, v137, v136
	s_nop 0
	v_div_fmas_f32 v136, v136, v249, v137
	v_div_fixup_f32 v252, v136, v85, v118
	v_div_scale_f32 v134, s[26:27], v85, v85, v120
	v_rcp_f32_e32 v249, v134
	s_nop 0
	v_fma_f32 v136, -v134, v249, 1.0
	v_fmac_f32_e32 v249, v136, v249
	v_div_scale_f32 v136, vcc, v120, v85, v120
	v_mul_f32_e32 v137, v136, v249
	v_fma_f32 v129, -v134, v137, v136
	v_fmac_f32_e32 v137, v129, v249
	v_fma_f32 v136, -v134, v137, v136
	s_nop 0
	v_div_fmas_f32 v136, v136, v249, v137
	v_div_fixup_f32 v129, v136, v85, v120
	v_div_scale_f32 v134, s[26:27], v85, v85, v100
	v_rcp_f32_e32 v249, v134
	s_nop 0
	v_fma_f32 v136, -v134, v249, 1.0
	v_fmac_f32_e32 v249, v136, v249
	v_div_scale_f32 v136, vcc, v100, v85, v100
	v_mul_f32_e32 v137, v136, v249
	v_fma_f32 v130, -v134, v137, v136
	v_fmac_f32_e32 v137, v130, v249
	v_fma_f32 v136, -v134, v137, v136
	s_nop 0
	v_div_fmas_f32 v136, v136, v249, v137
	v_div_fixup_f32 v130, v136, v85, v100
	v_div_scale_f32 v134, s[26:27], v85, v85, v115
	v_rcp_f32_e32 v249, v134
	s_nop 0
	v_fma_f32 v136, -v134, v249, 1.0
	v_fmac_f32_e32 v249, v136, v249
	v_div_scale_f32 v136, vcc, v115, v85, v115
	v_mul_f32_e32 v137, v136, v249
	v_fma_f32 v65, -v134, v137, v136
	v_fmac_f32_e32 v137, v65, v249
	v_fma_f32 v136, -v134, v137, v136
	s_nop 0
	v_div_fmas_f32 v136, v136, v249, v137
	v_div_fixup_f32 v65, v136, v85, v115
	v_div_scale_f32 v134, s[26:27], v85, v85, v92
	v_rcp_f32_e32 v249, v134
	s_nop 0
	v_fma_f32 v136, -v134, v249, 1.0
	v_fmac_f32_e32 v249, v136, v249
	v_div_scale_f32 v136, vcc, v92, v85, v92
	v_mul_f32_e32 v137, v136, v249
	v_fma_f32 v133, -v134, v137, v136
	v_fmac_f32_e32 v137, v133, v249
	v_fma_f32 v136, -v134, v137, v136
	s_nop 0
	v_div_fmas_f32 v136, v136, v249, v137
	v_div_fixup_f32 v133, v136, v85, v92
	s_waitcnt lgkmcnt(0)
	v_and_b32_e32 v68, 0x7f, v68
	v_and_b32_e32 v123, 0x7f, v123
	v_lshl_or_b32 v68, v68, 7, v123
	v_xor_b32_e32 v68, 0x3fff, v68
	v_and_b32_e32 v56, 0x7f, v56
	v_and_b32_e32 v114, 0x7f, v114
	v_lshl_or_b32 v56, v56, 7, v114
	v_xor_b32_e32 v56, 0x3fff, v56
	v_and_b32_e32 v57, 0x7f, v57
	v_and_b32_e32 v126, 0x7f, v126
	v_lshl_or_b32 v57, v57, 7, v126
	v_xor_b32_e32 v57, 0x3fff, v57
	v_and_b32_e32 v58, 0x7f, v58
	v_and_b32_e32 v121, 0x7f, v121
	v_lshl_or_b32 v58, v58, 7, v121
	v_xor_b32_e32 v58, 0x3fff, v58
	v_and_b32_e32 v59, 0x7f, v59
	v_and_b32_e32 v122, 0x7f, v122
	v_lshl_or_b32 v59, v59, 7, v122
	v_xor_b32_e32 v59, 0x3fff, v59
	v_and_b32_e32 v251, 0x7f, v251
	v_and_b32_e32 v124, 0x7f, v124
	v_lshl_or_b32 v251, v251, 7, v124
	v_xor_b32_e32 v251, 0x3fff, v251
	v_and_b32_e32 v253, 0x7f, v253
	v_and_b32_e32 v109, 0x7f, v109
	v_lshl_or_b32 v253, v253, 7, v109
	v_xor_b32_e32 v253, 0x3fff, v253
	v_and_b32_e32 v151, 0x7f, v151
	v_and_b32_e32 v60, 0x7f, v60
	v_lshl_or_b32 v151, v151, 7, v60
	v_xor_b32_e32 v151, 0x3fff, v151
	s_waitcnt vmcnt(0)
	v_pk_mul_f32 v[160:161], v[160:161], v[176:177]
	v_pk_mul_f32 v[162:163], v[162:163], v[178:179]
	v_pk_mul_f32 v[164:165], v[164:165], v[180:181]
	v_pk_mul_f32 v[166:167], v[166:167], v[182:183]
	v_pk_mul_f32 v[168:169], v[168:169], v[184:185]
	v_pk_mul_f32 v[170:171], v[170:171], v[186:187]
	v_pk_mul_f32 v[172:173], v[172:173], v[188:189]
	v_pk_mul_f32 v[174:175], v[174:175], v[190:191]
	v_max3_f32 v192, |v160|, |v161|, |v162|
	v_max3_f32 v192, |v163|, |v164|, v192
	v_max3_f32 v192, |v165|, |v166|, v192
	v_max3_f32 v192, |v167|, |v168|, v192
	v_max3_f32 v192, |v169|, |v170|, v192
	v_max3_f32 v192, |v171|, |v172|, v192
	v_max3_f32 v192, |v173|, |v174|, v192
	v_max_f32_e64 v192, |v175|, v192
	s_nop 1
	v_mov_b32_dpp v193, v192 quad_perm:[1,0,3,2] row_mask:0xf bank_mask:0xf bound_ctrl:1
	v_max_f32_e32 v192, v192, v193
	s_nop 1
	v_mov_b32_dpp v193, v192 quad_perm:[2,3,0,1] row_mask:0xf bank_mask:0xf bound_ctrl:1
	v_max_f32_e32 v192, v192, v193
	s_nop 1
	v_mov_b32_dpp v193, v192 row_half_mirror row_mask:0xf bank_mask:0xf bound_ctrl:1
	v_max_f32_e32 v192, v192, v193
	s_nop 1
	v_mov_b32_dpp v193, v192 row_mirror row_mask:0xf bank_mask:0xf bound_ctrl:1
	v_max_f32_e32 v192, v192, v193
	v_mov_b32_e32 v193, v192
	s_nop 1
	v_permlane16_swap_b32_e32 v192, v193
	s_nop 1
	v_max_f32_e32 v192, v192, v193
	v_mov_b32_e32 v193, v192
	s_nop 1
	v_permlane32_swap_b32_e32 v192, v193
	s_nop 1
	v_max_f32_e32 v192, v192, v193
	v_max_f32_e32 v192, 0xda24260, v192
	v_mul_f32_e32 v194, 0x3e2aaaab, v192
	global_store_dword v214, v194, s[12:13]
	v_div_scale_f32 v195, s[26:27], v194, v194, 1.0
	v_rcp_f32_e32 v196, v195
	v_div_scale_f32 v204, vcc, 1.0, v194, 1.0
	v_fma_f32 v205, -v195, v196, 1.0
	v_fmac_f32_e32 v196, v205, v196
	v_mul_f32_e32 v205, v204, v196
	v_fma_f32 v206, -v195, v205, v204
	v_fmac_f32_e32 v205, v206, v196
	v_fma_f32 v195, -v195, v205, v204
	s_nop 0
	v_div_fmas_f32 v195, v195, v196, v205
	v_div_fixup_f32 v207, v195, v194, 1.0
	v_mul_f32_e32 v160, v207, v160
	v_mul_f32_e32 v161, v207, v161
	v_mul_f32_e32 v162, v207, v162
	v_mul_f32_e32 v163, v207, v163
	v_mul_f32_e32 v164, v207, v164
	v_mul_f32_e32 v165, v207, v165
	v_mul_f32_e32 v166, v207, v166
	v_mul_f32_e32 v167, v207, v167
	v_mul_f32_e32 v168, v207, v168
	v_mul_f32_e32 v169, v207, v169
	v_mul_f32_e32 v170, v207, v170
	v_mul_f32_e32 v171, v207, v171
	v_mul_f32_e32 v172, v207, v172
	v_mul_f32_e32 v173, v207, v173
	v_mul_f32_e32 v174, v207, v174
	v_mul_f32_e32 v175, v207, v175
	v_mov_b32_e32 v208, 0
	v_mov_b32_e32 v209, 0
	v_mov_b32_e32 v210, 0
	v_mov_b32_e32 v193, 0
	v_cvt_scalef32_pk_fp4_f32 v208, v160, v161, 1.0
	v_cvt_scalef32_pk_fp4_f32 v209, v164, v165, 1.0
	v_cvt_scalef32_pk_fp4_f32 v210, v168, v169, 1.0
	v_cvt_scalef32_pk_fp4_f32 v193, v172, v173, 1.0
	v_cvt_scalef32_pk_fp4_f32 v208, v162, v163, 1.0 op_sel:[0,0,1,0]
	v_cvt_scalef32_pk_fp4_f32 v209, v166, v167, 1.0 op_sel:[0,0,1,0]
	v_cvt_scalef32_pk_fp4_f32 v210, v170, v171, 1.0 op_sel:[0,0,1,0]
	v_cvt_scalef32_pk_fp4_f32 v193, v174, v175, 1.0 op_sel:[0,0,1,0]
	global_store_short v213, v208, s[10:11] nt
	s_add_u32 s14, s10, 0x200000
	s_addc_u32 s15, s11, 0
	global_store_short v213, v209, s[14:15] nt
	s_add_u32 s14, s10, 0x400000
	s_addc_u32 s15, s11, 0
	global_store_short v213, v210, s[14:15] nt
	s_add_u32 s14, s10, 0x600000
	s_addc_u32 s15, s11, 0
	global_store_short v213, v193, s[14:15] nt
	s_add_u32 s10, s10, 0x20000
	s_addc_u32 s11, s11, 0
	s_add_u32 s12, s12, 0x2000
	s_addc_u32 s13, s13, 0
	s_cmp_eq_u32 s22, 1
	s_cbranch_scc1 .Ltk0_noload7
	global_load_dwordx4 v[160:163], v212, s[8:9] offset:0 nt
	global_load_dwordx4 v[164:167], v212, s[8:9] offset:1024 nt
	global_load_dwordx4 v[168:171], v212, s[8:9] offset:2048 nt
	global_load_dwordx4 v[172:175], v212, s[8:9] offset:3072 nt
	s_add_u32 s8, s8, 0x800000
	s_addc_u32 s9, s9, 0

.LpgL0_group:
	v_mbcnt_lo_u32_b32 v249, -1, 0
	v_mbcnt_hi_u32_b32 v249, -1, v249
	v_and_b32_e32 v250, 15, v249
	v_lshrrev_b32_e32 v251, 4, v249
	v_and_b32_e32 v252, 3, v250
	v_cmp_eq_u32_e64 s[4:5], 1, v252
	v_cmp_eq_u32_e64 s[6:7], 2, v252
	v_cmp_eq_u32_e64 s[8:9], 3, v252
	v_cmp_eq_u32_e64 s[10:11], 0, v249
	s_add_u32 s12, s54, 0x29800000
	s_addc_u32 s13, s55, 0
	s_and_b32 s13, s13, 0xffff
	s_mov_b32 s14, 0x2000000
	s_mov_b32 s15, 0x20000
	s_add_u32 s16, s54, 0x8000000
	s_addc_u32 s17, s55, 0
	s_and_b32 s17, s17, 0xffff
	s_mov_b32 s18, 0x1000000
	s_mov_b32 s19, 0x20000
	s_add_u32 s20, s54, 0xc000000
	s_addc_u32 s21, s55, 0
	s_and_b32 s21, s21, 0xffff
	s_mov_b32 s22, 0x1000000
	s_mov_b32 s23, 0x20000
	s_add_u32 s30, s54, 0x80000
	s_addc_u32 s31, s55, 0
	s_add_u32 s34, s54, 0xc0000
	s_addc_u32 s35, s55, 0
	s_mov_b32 s94, 0xc3e00000
	s_mov_b32 s96, 0x800000
	s_mov_b32 s81, 0x1010101
	v_lshrrev_b32_e32 v253, 2, v250
	v_lshrrev_b32_e32 v254, 1, v251
	v_lshl_add_u32 v255, v253, 1, v254
	v_lshl_add_u32 v237, v255, 2, s91
	v_and_b32_e32 v255, 1, v251
	v_lshl_add_u32 v236, v255, 2, v252
	v_lshlrev_b32_e32 v236, 4, v236
	v_lshlrev_b32_e32 v254, 7, v254
	v_lshl_add_u32 v254, v252, 5, v254
	v_lshl_add_u32 v254, v255, 4, v254
	v_and_b32_e32 v253, 1, v253
	v_mov_b32_e32 v255, 0x7fff0000
	v_cmp_eq_u32_e32 vcc, 0, v253
	s_nop 1
	v_cndmask_b32_e32 v238, v255, v254, vcc
	v_cndmask_b32_e32 v239, v254, v255, vcc
	v_mov_b32_e32 v240, 0x7f7f7f7f
	v_mov_b32_e32 v255, 0x20202020
	v_cmp_gt_u32_e32 vcc, 8, v250
	s_nop 1
	v_cndmask_b32_e32 v241, v255, v240, vcc
	v_cndmask_b32_e32 v242, v240, v255, vcc
	v_lshrrev_b32_e32 v254, 3, v250
	v_lshl_add_u32 v254, v252, 1, v254
	v_lshl_add_u32 v255, v251, 1, v253
	v_lshl_add_u32 v244, v254, 3, v255
	v_lshlrev_b32_e32 v244, 2, v244
	v_add_u32_e32 v243, s91, v244
	v_and_b32_e32 v253, 3, v255
	v_lshrrev_b32_e32 v255, 2, v255
	v_lshl_add_u32 v253, v253, 1, v255
	v_lshl_add_u32 v253, v254, 3, v253
	v_lshlrev_b32_e32 v253, 2, v253
	v_add_u32_e32 v245, s91, v253
	v_add_u32_e32 v245, 0x1000, v245
	v_mov_b32_e32 v246, 0
	s_lshl_b32 s64, s63, 12
	s_add_u32 s24, s54, 0x28000000
	s_addc_u32 s25, s55, 0
	s_add_u32 s24, s24, s64
	s_addc_u32 s25, s25, 0
	s_lshl_b32 s64, s63, 12
	s_add_u32 s26, s54, 0x28800000
	s_addc_u32 s27, s55, 0
	s_add_u32 s26, s26, s64
	s_addc_u32 s27, s27, 0
	s_lshl_b32 s64, s63, 15
	s_add_u32 s28, s54, 0x18000000
	s_addc_u32 s29, s55, 0
	s_add_u32 s28, s28, s64
	s_addc_u32 s29, s29, 0
	s_lshl_b32 s64, s63, 5
	s_add_u32 s40, s54, 0x40000
	s_addc_u32 s41, s55, 0
	s_add_u32 s40, s40, s64
	s_addc_u32 s41, s41, 0
	s_lshl_b32 s64, s63, 5
	s_add_u32 s44, s54, 0x50000
	s_addc_u32 s45, s55, 0
	s_add_u32 s44, s44, s64
	s_addc_u32 s45, s45, 0
	s_lshl_b32 s61, s63, 14
	s_add_u32 s62, s61, 0x100
	v_mbcnt_lo_u32_b32 v253, -1, 0
	v_mbcnt_hi_u32_b32 v253, -1, v253
	v_lshlrev_b32_e32 v253, 2, v253
	global_load_dword v0, v253, s[24:25] offset:0 nt
	global_load_dword v1, v253, s[24:25] offset:256 nt
	global_load_dword v2, v253, s[24:25] offset:512 nt
	global_load_dword v3, v253, s[24:25] offset:768 nt
	global_load_dword v4, v253, s[24:25] offset:1024 nt
	global_load_dword v5, v253, s[24:25] offset:1280 nt
	global_load_dword v6, v253, s[24:25] offset:1536 nt
	global_load_dword v7, v253, s[24:25] offset:1792 nt
	global_load_dword v8, v253, s[24:25] offset:2048 nt
	global_load_dword v9, v253, s[24:25] offset:2304 nt
	global_load_dword v10, v253, s[24:25] offset:2560 nt
	global_load_dword v11, v253, s[24:25] offset:2816 nt
	global_load_dword v12, v253, s[24:25] offset:3072 nt
	global_load_dword v13, v253, s[24:25] offset:3328 nt
	global_load_dword v14, v253, s[24:25] offset:3584 nt
	global_load_dword v15, v253, s[24:25] offset:3840 nt
	v_add_u32_e32 v254, s91, v253
	s_waitcnt vmcnt(0)
	ds_write_b32 v254, v0 offset:0
	ds_write_b32 v254, v1 offset:256
	ds_write_b32 v254, v2 offset:512
	ds_write_b32 v254, v3 offset:768
	ds_write_b32 v254, v4 offset:1024
	ds_write_b32 v254, v5 offset:1280
	ds_write_b32 v254, v6 offset:1536
	ds_write_b32 v254, v7 offset:1792
	ds_write_b32 v254, v8 offset:2048
	ds_write_b32 v254, v9 offset:2304
	ds_write_b32 v254, v10 offset:2560
	ds_write_b32 v254, v11 offset:2816
	ds_write_b32 v254, v12 offset:3072
	ds_write_b32 v254, v13 offset:3328
	ds_write_b32 v254, v14 offset:3584
	ds_write_b32 v254, v15 offset:3840
	s_waitcnt lgkmcnt(0)
	s_lshl_b32 s61, s63, 14
	s_add_u32 s62, s61, 0x100
	v_mov_b32_e32 v204, 0
	v_mov_b32_e32 v205, 0
	v_mov_b32_e32 v206, 0
	v_mov_b32_e32 v207, 0
	v_mov_b32_e32 v208, 0
	v_mov_b32_e32 v209, 0
	v_mov_b32_e32 v210, 0
	v_mov_b32_e32 v211, 0
	v_mov_b32_e32 v212, 0
	v_mov_b32_e32 v213, 0
	v_mov_b32_e32 v214, 0
	v_mov_b32_e32 v215, 0
	v_mov_b32_e32 v216, 0
	v_mov_b32_e32 v217, 0
	v_mov_b32_e32 v218, 0
	v_mov_b32_e32 v219, 0
	v_mov_b32_e32 v176, 0
	v_mov_b32_e32 v177, 0
	v_mov_b32_e32 v178, 0
	v_mov_b32_e32 v179, 0
	v_mov_b32_e32 v180, 0
	v_mov_b32_e32 v181, 0
	v_mov_b32_e32 v182, 0
	v_mov_b32_e32 v183, 0
	v_mov_b32_e32 v184, 0
	v_mov_b32_e32 v185, 0
	v_mov_b32_e32 v186, 0
	v_mov_b32_e32 v187, 0
	v_mov_b32_e32 v188, 0
	v_mov_b32_e32 v189, 0
	v_mov_b32_e32 v190, 0
	v_mov_b32_e32 v191, 0
	s_mov_b32 s0, 0
	s_mov_b32 s1, 0
	s_mov_b32 s60, 0x200000
	ds_read_b32 v144, v237 offset:0
	ds_read_b32 v145, v237 offset:32
	ds_read_b32 v146, v237 offset:64
	ds_read_b32 v147, v237 offset:96
	ds_read_b32 v148, v237 offset:128
	ds_read_b32 v149, v237 offset:160
	ds_read_b32 v150, v237 offset:192
	ds_read_b32 v151, v237 offset:224
	s_waitcnt lgkmcnt(0)
	v_lshl_or_b32 v144, v144, 7, v236
	v_lshl_or_b32 v145, v145, 7, v236
	v_lshl_or_b32 v146, v146, 7, v236
	v_lshl_or_b32 v147, v147, 7, v236
	v_lshl_or_b32 v148, v148, 7, v236
	v_lshl_or_b32 v149, v149, 7, v236
	v_lshl_or_b32 v150, v150, 7, v236
	v_lshl_or_b32 v151, v151, 7, v236
	buffer_load_dwordx4 v[0:3], v144, s[16:19], s1 offen
	buffer_load_dwordx4 v[4:7], v145, s[16:19], s1 offen
	buffer_load_dwordx4 v[8:11], v146, s[16:19], s1 offen
	buffer_load_dwordx4 v[12:15], v147, s[16:19], s1 offen
	buffer_load_dwordx4 v[16:19], v148, s[16:19], s1 offen
	buffer_load_dwordx4 v[20:23], v149, s[16:19], s1 offen
	buffer_load_dwordx4 v[24:27], v150, s[16:19], s1 offen
	buffer_load_dwordx4 v[28:31], v151, s[16:19], s1 offen
	ds_read_b32 v144, v237 offset:256
	ds_read_b32 v145, v237 offset:288
	ds_read_b32 v146, v237 offset:320
	ds_read_b32 v147, v237 offset:352
	ds_read_b32 v148, v237 offset:384
	ds_read_b32 v149, v237 offset:416
	ds_read_b32 v150, v237 offset:448
	ds_read_b32 v151, v237 offset:480
	s_add_u32 s80, s61, 0x0
	buffer_load_dwordx4 v[128:131], v238, s[12:15], s80 offen nt
	buffer_load_dwordx4 v[132:135], v239, s[12:15], s80 offen nt
	s_waitcnt lgkmcnt(0)
	v_lshl_or_b32 v144, v144, 7, v236
	v_lshl_or_b32 v145, v145, 7, v236
	v_lshl_or_b32 v146, v146, 7, v236
	v_lshl_or_b32 v147, v147, 7, v236
	v_lshl_or_b32 v148, v148, 7, v236
	v_lshl_or_b32 v149, v149, 7, v236
	v_lshl_or_b32 v150, v150, 7, v236
	v_lshl_or_b32 v151, v151, 7, v236
	buffer_load_dwordx4 v[32:35], v144, s[16:19], s1 offen
	buffer_load_dwordx4 v[36:39], v145, s[16:19], s1 offen
	buffer_load_dwordx4 v[40:43], v146, s[16:19], s1 offen
	buffer_load_dwordx4 v[44:47], v147, s[16:19], s1 offen
	buffer_load_dwordx4 v[48:51], v148, s[16:19], s1 offen
	buffer_load_dwordx4 v[52:55], v149, s[16:19], s1 offen
	buffer_load_dwordx4 v[56:59], v150, s[16:19], s1 offen
	buffer_load_dwordx4 v[60:63], v151, s[16:19], s1 offen
	ds_read_b32 v144, v237 offset:512
	ds_read_b32 v145, v237 offset:544
	ds_read_b32 v146, v237 offset:576
	ds_read_b32 v147, v237 offset:608
	ds_read_b32 v148, v237 offset:640
	ds_read_b32 v149, v237 offset:672
	ds_read_b32 v150, v237 offset:704
	ds_read_b32 v151, v237 offset:736
	s_waitcnt lgkmcnt(0)
	v_lshl_or_b32 v144, v144, 7, v236
	v_lshl_or_b32 v145, v145, 7, v236
	v_lshl_or_b32 v146, v146, 7, v236
	v_lshl_or_b32 v147, v147, 7, v236
	v_lshl_or_b32 v148, v148, 7, v236
	v_lshl_or_b32 v149, v149, 7, v236
	v_lshl_or_b32 v150, v150, 7, v236
	v_lshl_or_b32 v151, v151, 7, v236
	buffer_load_dwordx4 v[64:67], v144, s[16:19], s1 offen
	buffer_load_dwordx4 v[68:71], v145, s[16:19], s1 offen
	buffer_load_dwordx4 v[72:75], v146, s[16:19], s1 offen
	buffer_load_dwordx4 v[76:79], v147, s[16:19], s1 offen
	buffer_load_dwordx4 v[80:83], v148, s[16:19], s1 offen
	buffer_load_dwordx4 v[84:87], v149, s[16:19], s1 offen
	buffer_load_dwordx4 v[88:91], v150, s[16:19], s1 offen
	buffer_load_dwordx4 v[92:95], v151, s[16:19], s1 offen
	ds_read_b32 v144, v237 offset:768
	ds_read_b32 v145, v237 offset:800
	ds_read_b32 v146, v237 offset:832
	ds_read_b32 v147, v237 offset:864
	ds_read_b32 v148, v237 offset:896
	ds_read_b32 v149, v237 offset:928
	ds_read_b32 v150, v237 offset:960
	ds_read_b32 v151, v237 offset:992
.LpgL0_uloopu0:
	s_add_u32 s80, s61, 0x800
	buffer_load_dwordx4 v[136:139], v238, s[12:15], s80 offen nt
	buffer_load_dwordx4 v[140:143], v239, s[12:15], s80 offen nt
	s_waitcnt lgkmcnt(0)
	v_lshl_or_b32 v144, v144, 7, v236
	v_lshl_or_b32 v145, v145, 7, v236
	v_lshl_or_b32 v146, v146, 7, v236
	v_lshl_or_b32 v147, v147, 7, v236
	v_lshl_or_b32 v148, v148, 7, v236
	v_lshl_or_b32 v149, v149, 7, v236
	v_lshl_or_b32 v150, v150, 7, v236
	v_lshl_or_b32 v151, v151, 7, v236
	buffer_load_dwordx4 v[96:99], v144, s[16:19], s1 offen
	buffer_load_dwordx4 v[100:103], v145, s[16:19], s1 offen
	buffer_load_dwordx4 v[104:107], v146, s[16:19], s1 offen
	buffer_load_dwordx4 v[108:111], v147, s[16:19], s1 offen
	buffer_load_dwordx4 v[112:115], v148, s[16:19], s1 offen
	buffer_load_dwordx4 v[116:119], v149, s[16:19], s1 offen
	buffer_load_dwordx4 v[120:123], v150, s[16:19], s1 offen
	buffer_load_dwordx4 v[124:127], v151, s[16:19], s1 offen
	ds_read_b32 v144, v237 offset:1024
	ds_read_b32 v145, v237 offset:1056
	ds_read_b32 v146, v237 offset:1088
	ds_read_b32 v147, v237 offset:1120
	ds_read_b32 v148, v237 offset:1152
	ds_read_b32 v149, v237 offset:1184
	ds_read_b32 v150, v237 offset:1216
	ds_read_b32 v151, v237 offset:1248
	s_waitcnt vmcnt(26)
	v_mfma_scale_f32_16x16x128_f8f6f4 v[160:163], v[0:3], v[128:135], 0, v240, v241 op_sel_hi:[0,0,0] cbsz:4
	v_cndmask_b32_e64 v176, v176, v177, s[4:5]
	v_cndmask_b32_e64 v180, v180, v181, s[4:5]
	v_cndmask_b32_e64 v184, v184, v185, s[4:5]
	v_mfma_scale_f32_16x16x128_f8f6f4 v[164:167], v[8:11], v[128:135], 0, v240, v241 op_sel_hi:[0,0,0] cbsz:4
	v_cndmask_b32_e64 v188, v188, v189, s[4:5]
	v_cndmask_b32_e64 v176, v176, v178, s[6:7]
	v_cndmask_b32_e64 v180, v180, v182, s[6:7]
	v_mfma_scale_f32_16x16x128_f8f6f4 v[168:171], v[16:19], v[128:135], 0, v240, v241 op_sel_hi:[0,0,0] cbsz:4
	v_cndmask_b32_e64 v184, v184, v186, s[6:7]
	v_cndmask_b32_e64 v188, v188, v190, s[6:7]
	v_cndmask_b32_e64 v176, v176, v179, s[8:9]
	v_mfma_scale_f32_16x16x128_f8f6f4 v[172:175], v[24:27], v[128:135], 0, v240, v241 op_sel_hi:[0,0,0] cbsz:4
	v_cndmask_b32_e64 v180, v180, v183, s[8:9]
	v_cndmask_b32_e64 v184, v184, v187, s[8:9]
	v_cndmask_b32_e64 v188, v188, v191, s[8:9]
	v_mfma_scale_f32_16x16x128_f8f6f4 v[160:163], v[4:7], v[128:135], v[160:163], v240, v242 op_sel_hi:[0,0,0] cbsz:4
	v_add_f32_dpp v176, v176, v176 quad_perm:[1,0,3,2] row_mask:0xf bank_mask:0xf bound_ctrl:1
	v_add_f32_dpp v180, v180, v180 quad_perm:[1,0,3,2] row_mask:0xf bank_mask:0xf bound_ctrl:1
	v_add_f32_dpp v184, v184, v184 quad_perm:[1,0,3,2] row_mask:0xf bank_mask:0xf bound_ctrl:1
	v_mfma_scale_f32_16x16x128_f8f6f4 v[164:167], v[12:15], v[128:135], v[164:167], v240, v242 op_sel_hi:[0,0,0] cbsz:4
	v_add_f32_dpp v188, v188, v188 quad_perm:[1,0,3,2] row_mask:0xf bank_mask:0xf bound_ctrl:1
	v_add_f32_dpp v176, v176, v176 quad_perm:[2,3,0,1] row_mask:0xf bank_mask:0xf bound_ctrl:1
	v_add_f32_dpp v180, v180, v180 quad_perm:[2,3,0,1] row_mask:0xf bank_mask:0xf bound_ctrl:1
	v_mfma_scale_f32_16x16x128_f8f6f4 v[168:171], v[20:23], v[128:135], v[168:171], v240, v242 op_sel_hi:[0,0,0] cbsz:4
	v_add_f32_dpp v184, v184, v184 quad_perm:[2,3,0,1] row_mask:0xf bank_mask:0xf bound_ctrl:1
	v_add_f32_dpp v188, v188, v188 quad_perm:[2,3,0,1] row_mask:0xf bank_mask:0xf bound_ctrl:1
	v_cndmask_b32_e64 v176, v176, v180, s[4:5]
	v_mfma_scale_f32_16x16x128_f8f6f4 v[172:175], v[28:31], v[128:135], v[172:175], v240, v242 op_sel_hi:[0,0,0] cbsz:4
	v_cndmask_b32_e64 v176, v176, v184, s[6:7]
	v_cndmask_b32_e64 v176, v176, v188, s[8:9]
	v_add_f32_e32 v219, v219, v176
	s_waitcnt lgkmcnt(0)
	v_lshl_or_b32 v144, v144, 7, v236
	v_lshl_or_b32 v145, v145, 7, v236
	v_lshl_or_b32 v146, v146, 7, v236
	v_lshl_or_b32 v147, v147, 7, v236
	v_lshl_or_b32 v148, v148, 7, v236
	v_lshl_or_b32 v149, v149, 7, v236
	v_lshl_or_b32 v150, v150, 7, v236
	v_lshl_or_b32 v151, v151, 7, v236
	buffer_load_dwordx4 v[0:3], v144, s[16:19], s1 offen
	buffer_load_dwordx4 v[4:7], v145, s[16:19], s1 offen
	buffer_load_dwordx4 v[8:11], v146, s[16:19], s1 offen
	buffer_load_dwordx4 v[12:15], v147, s[16:19], s1 offen
	buffer_load_dwordx4 v[16:19], v148, s[16:19], s1 offen
	buffer_load_dwordx4 v[20:23], v149, s[16:19], s1 offen
	buffer_load_dwordx4 v[24:27], v150, s[16:19], s1 offen
	buffer_load_dwordx4 v[28:31], v151, s[16:19], s1 offen
	ds_read_b32 v144, v237 offset:1280
	ds_read_b32 v145, v237 offset:1312
	ds_read_b32 v146, v237 offset:1344
	ds_read_b32 v147, v237 offset:1376
	ds_read_b32 v148, v237 offset:1408
	ds_read_b32 v149, v237 offset:1440
	ds_read_b32 v150, v237 offset:1472
	ds_read_b32 v151, v237 offset:1504
	s_waitcnt vmcnt(26)
	v_mfma_scale_f32_16x16x128_f8f6f4 v[176:179], v[32:35], v[128:135], 0, v240, v241 op_sel_hi:[0,0,0] cbsz:4
	v_cndmask_b32_e64 v160, v160, v161, s[4:5]
	v_cndmask_b32_e64 v164, v164, v165, s[4:5]
	v_cndmask_b32_e64 v168, v168, v169, s[4:5]
	v_mfma_scale_f32_16x16x128_f8f6f4 v[180:183], v[40:43], v[128:135], 0, v240, v241 op_sel_hi:[0,0,0] cbsz:4
	v_cndmask_b32_e64 v172, v172, v173, s[4:5]
	v_cndmask_b32_e64 v160, v160, v162, s[6:7]
	v_cndmask_b32_e64 v164, v164, v166, s[6:7]
	v_mfma_scale_f32_16x16x128_f8f6f4 v[184:187], v[48:51], v[128:135], 0, v240, v241 op_sel_hi:[0,0,0] cbsz:4
	v_cndmask_b32_e64 v168, v168, v170, s[6:7]
	v_cndmask_b32_e64 v172, v172, v174, s[6:7]
	v_cndmask_b32_e64 v160, v160, v163, s[8:9]
	v_mfma_scale_f32_16x16x128_f8f6f4 v[188:191], v[56:59], v[128:135], 0, v240, v241 op_sel_hi:[0,0,0] cbsz:4
	v_cndmask_b32_e64 v164, v164, v167, s[8:9]
	v_cndmask_b32_e64 v168, v168, v171, s[8:9]
	v_cndmask_b32_e64 v172, v172, v175, s[8:9]
	v_mfma_scale_f32_16x16x128_f8f6f4 v[176:179], v[36:39], v[128:135], v[176:179], v240, v242 op_sel_hi:[0,0,0] cbsz:4
	v_add_f32_dpp v160, v160, v160 quad_perm:[1,0,3,2] row_mask:0xf bank_mask:0xf bound_ctrl:1
	v_add_f32_dpp v164, v164, v164 quad_perm:[1,0,3,2] row_mask:0xf bank_mask:0xf bound_ctrl:1
	v_add_f32_dpp v168, v168, v168 quad_perm:[1,0,3,2] row_mask:0xf bank_mask:0xf bound_ctrl:1
	v_mfma_scale_f32_16x16x128_f8f6f4 v[180:183], v[44:47], v[128:135], v[180:183], v240, v242 op_sel_hi:[0,0,0] cbsz:4
	v_add_f32_dpp v172, v172, v172 quad_perm:[1,0,3,2] row_mask:0xf bank_mask:0xf bound_ctrl:1
	v_add_f32_dpp v160, v160, v160 quad_perm:[2,3,0,1] row_mask:0xf bank_mask:0xf bound_ctrl:1
	v_add_f32_dpp v164, v164, v164 quad_perm:[2,3,0,1] row_mask:0xf bank_mask:0xf bound_ctrl:1
	v_mfma_scale_f32_16x16x128_f8f6f4 v[184:187], v[52:55], v[128:135], v[184:187], v240, v242 op_sel_hi:[0,0,0] cbsz:4
	v_add_f32_dpp v168, v168, v168 quad_perm:[2,3,0,1] row_mask:0xf bank_mask:0xf bound_ctrl:1
	v_add_f32_dpp v172, v172, v172 quad_perm:[2,3,0,1] row_mask:0xf bank_mask:0xf bound_ctrl:1
	v_cndmask_b32_e64 v160, v160, v164, s[4:5]
	v_mfma_scale_f32_16x16x128_f8f6f4 v[188:191], v[60:63], v[128:135], v[188:191], v240, v242 op_sel_hi:[0,0,0] cbsz:4
	v_cndmask_b32_e64 v160, v160, v168, s[6:7]
	v_cndmask_b32_e64 v160, v160, v172, s[8:9]
	v_add_f32_e32 v204, v204, v160
	s_add_u32 s80, s61, 0x1000
	buffer_load_dwordx4 v[128:131], v238, s[12:15], s80 offen nt
	buffer_load_dwordx4 v[132:135], v239, s[12:15], s80 offen nt
	s_waitcnt lgkmcnt(0)
	v_lshl_or_b32 v144, v144, 7, v236
	v_lshl_or_b32 v145, v145, 7, v236
	v_lshl_or_b32 v146, v146, 7, v236
	v_lshl_or_b32 v147, v147, 7, v236
	v_lshl_or_b32 v148, v148, 7, v236
	v_lshl_or_b32 v149, v149, 7, v236
	v_lshl_or_b32 v150, v150, 7, v236
	v_lshl_or_b32 v151, v151, 7, v236
	buffer_load_dwordx4 v[32:35], v144, s[16:19], s1 offen
	buffer_load_dwordx4 v[36:39], v145, s[16:19], s1 offen
	buffer_load_dwordx4 v[40:43], v146, s[16:19], s1 offen
	buffer_load_dwordx4 v[44:47], v147, s[16:19], s1 offen
	buffer_load_dwordx4 v[48:51], v148, s[16:19], s1 offen
	buffer_load_dwordx4 v[52:55], v149, s[16:19], s1 offen
	buffer_load_dwordx4 v[56:59], v150, s[16:19], s1 offen
	buffer_load_dwordx4 v[60:63], v151, s[16:19], s1 offen
	ds_read_b32 v144, v237 offset:1536
	ds_read_b32 v145, v237 offset:1568
	ds_read_b32 v146, v237 offset:1600
	ds_read_b32 v147, v237 offset:1632
	ds_read_b32 v148, v237 offset:1664
	ds_read_b32 v149, v237 offset:1696
	ds_read_b32 v150, v237 offset:1728
	ds_read_b32 v151, v237 offset:1760
	s_waitcnt vmcnt(26)
	v_mfma_scale_f32_16x16x128_f8f6f4 v[160:163], v[64:67], v[136:143], 0, v240, v241 op_sel_hi:[0,0,0] cbsz:4
	v_cndmask_b32_e64 v176, v176, v177, s[4:5]
	v_cndmask_b32_e64 v180, v180, v181, s[4:5]
	v_cndmask_b32_e64 v184, v184, v185, s[4:5]
	v_mfma_scale_f32_16x16x128_f8f6f4 v[164:167], v[72:75], v[136:143], 0, v240, v241 op_sel_hi:[0,0,0] cbsz:4
	v_cndmask_b32_e64 v188, v188, v189, s[4:5]
	v_cndmask_b32_e64 v176, v176, v178, s[6:7]
	v_cndmask_b32_e64 v180, v180, v182, s[6:7]
	v_mfma_scale_f32_16x16x128_f8f6f4 v[168:171], v[80:83], v[136:143], 0, v240, v241 op_sel_hi:[0,0,0] cbsz:4
	v_cndmask_b32_e64 v184, v184, v186, s[6:7]
	v_cndmask_b32_e64 v188, v188, v190, s[6:7]
	v_cndmask_b32_e64 v176, v176, v179, s[8:9]
	v_mfma_scale_f32_16x16x128_f8f6f4 v[172:175], v[88:91], v[136:143], 0, v240, v241 op_sel_hi:[0,0,0] cbsz:4
	v_cndmask_b32_e64 v180, v180, v183, s[8:9]
	v_cndmask_b32_e64 v184, v184, v187, s[8:9]
	v_cndmask_b32_e64 v188, v188, v191, s[8:9]
	v_mfma_scale_f32_16x16x128_f8f6f4 v[160:163], v[68:71], v[136:143], v[160:163], v240, v242 op_sel_hi:[0,0,0] cbsz:4
	v_add_f32_dpp v176, v176, v176 quad_perm:[1,0,3,2] row_mask:0xf bank_mask:0xf bound_ctrl:1
	v_add_f32_dpp v180, v180, v180 quad_perm:[1,0,3,2] row_mask:0xf bank_mask:0xf bound_ctrl:1
	v_add_f32_dpp v184, v184, v184 quad_perm:[1,0,3,2] row_mask:0xf bank_mask:0xf bound_ctrl:1
	v_mfma_scale_f32_16x16x128_f8f6f4 v[164:167], v[76:79], v[136:143], v[164:167], v240, v242 op_sel_hi:[0,0,0] cbsz:4
	v_add_f32_dpp v188, v188, v188 quad_perm:[1,0,3,2] row_mask:0xf bank_mask:0xf bound_ctrl:1
	v_add_f32_dpp v176, v176, v176 quad_perm:[2,3,0,1] row_mask:0xf bank_mask:0xf bound_ctrl:1
	v_add_f32_dpp v180, v180, v180 quad_perm:[2,3,0,1] row_mask:0xf bank_mask:0xf bound_ctrl:1
	v_mfma_scale_f32_16x16x128_f8f6f4 v[168:171], v[84:87], v[136:143], v[168:171], v240, v242 op_sel_hi:[0,0,0] cbsz:4
	v_add_f32_dpp v184, v184, v184 quad_perm:[2,3,0,1] row_mask:0xf bank_mask:0xf bound_ctrl:1
	v_add_f32_dpp v188, v188, v188 quad_perm:[2,3,0,1] row_mask:0xf bank_mask:0xf bound_ctrl:1
	v_cndmask_b32_e64 v176, v176, v180, s[4:5]
	v_mfma_scale_f32_16x16x128_f8f6f4 v[172:175], v[92:95], v[136:143], v[172:175], v240, v242 op_sel_hi:[0,0,0] cbsz:4
	v_cndmask_b32_e64 v176, v176, v184, s[6:7]
	v_cndmask_b32_e64 v176, v176, v188, s[8:9]
	v_add_f32_e32 v205, v205, v176
	s_waitcnt lgkmcnt(0)
	v_lshl_or_b32 v144, v144, 7, v236
	v_lshl_or_b32 v145, v145, 7, v236
	v_lshl_or_b32 v146, v146, 7, v236
	v_lshl_or_b32 v147, v147, 7, v236
	v_lshl_or_b32 v148, v148, 7, v236
	v_lshl_or_b32 v149, v149, 7, v236
	v_lshl_or_b32 v150, v150, 7, v236
	v_lshl_or_b32 v151, v151, 7, v236
	buffer_load_dwordx4 v[64:67], v144, s[16:19], s1 offen
	buffer_load_dwordx4 v[68:71], v145, s[16:19], s1 offen
	buffer_load_dwordx4 v[72:75], v146, s[16:19], s1 offen
	buffer_load_dwordx4 v[76:79], v147, s[16:19], s1 offen
	buffer_load_dwordx4 v[80:83], v148, s[16:19], s1 offen
	buffer_load_dwordx4 v[84:87], v149, s[16:19], s1 offen
	buffer_load_dwordx4 v[88:91], v150, s[16:19], s1 offen
	buffer_load_dwordx4 v[92:95], v151, s[16:19], s1 offen
	ds_read_b32 v144, v237 offset:1792
	ds_read_b32 v145, v237 offset:1824
	ds_read_b32 v146, v237 offset:1856
	ds_read_b32 v147, v237 offset:1888
	ds_read_b32 v148, v237 offset:1920
	ds_read_b32 v149, v237 offset:1952
	ds_read_b32 v150, v237 offset:1984
	ds_read_b32 v151, v237 offset:2016
	s_waitcnt vmcnt(26)
	v_mfma_scale_f32_16x16x128_f8f6f4 v[176:179], v[96:99], v[136:143], 0, v240, v241 op_sel_hi:[0,0,0] cbsz:4
	v_cndmask_b32_e64 v160, v160, v161, s[4:5]
	v_cndmask_b32_e64 v164, v164, v165, s[4:5]
	v_cndmask_b32_e64 v168, v168, v169, s[4:5]
	v_mfma_scale_f32_16x16x128_f8f6f4 v[180:183], v[104:107], v[136:143], 0, v240, v241 op_sel_hi:[0,0,0] cbsz:4
	v_cndmask_b32_e64 v172, v172, v173, s[4:5]
	v_cndmask_b32_e64 v160, v160, v162, s[6:7]
	v_cndmask_b32_e64 v164, v164, v166, s[6:7]
	v_mfma_scale_f32_16x16x128_f8f6f4 v[184:187], v[112:115], v[136:143], 0, v240, v241 op_sel_hi:[0,0,0] cbsz:4
	v_cndmask_b32_e64 v168, v168, v170, s[6:7]
	v_cndmask_b32_e64 v172, v172, v174, s[6:7]
	v_cndmask_b32_e64 v160, v160, v163, s[8:9]
	v_mfma_scale_f32_16x16x128_f8f6f4 v[188:191], v[120:123], v[136:143], 0, v240, v241 op_sel_hi:[0,0,0] cbsz:4
	v_cndmask_b32_e64 v164, v164, v167, s[8:9]
	v_cndmask_b32_e64 v168, v168, v171, s[8:9]
	v_cndmask_b32_e64 v172, v172, v175, s[8:9]
	v_mfma_scale_f32_16x16x128_f8f6f4 v[176:179], v[100:103], v[136:143], v[176:179], v240, v242 op_sel_hi:[0,0,0] cbsz:4
	v_add_f32_dpp v160, v160, v160 quad_perm:[1,0,3,2] row_mask:0xf bank_mask:0xf bound_ctrl:1
	v_add_f32_dpp v164, v164, v164 quad_perm:[1,0,3,2] row_mask:0xf bank_mask:0xf bound_ctrl:1
	v_add_f32_dpp v168, v168, v168 quad_perm:[1,0,3,2] row_mask:0xf bank_mask:0xf bound_ctrl:1
	v_mfma_scale_f32_16x16x128_f8f6f4 v[180:183], v[108:111], v[136:143], v[180:183], v240, v242 op_sel_hi:[0,0,0] cbsz:4
	v_add_f32_dpp v172, v172, v172 quad_perm:[1,0,3,2] row_mask:0xf bank_mask:0xf bound_ctrl:1
	v_add_f32_dpp v160, v160, v160 quad_perm:[2,3,0,1] row_mask:0xf bank_mask:0xf bound_ctrl:1
	v_add_f32_dpp v164, v164, v164 quad_perm:[2,3,0,1] row_mask:0xf bank_mask:0xf bound_ctrl:1
	v_mfma_scale_f32_16x16x128_f8f6f4 v[184:187], v[116:119], v[136:143], v[184:187], v240, v242 op_sel_hi:[0,0,0] cbsz:4
	v_add_f32_dpp v168, v168, v168 quad_perm:[2,3,0,1] row_mask:0xf bank_mask:0xf bound_ctrl:1
	v_add_f32_dpp v172, v172, v172 quad_perm:[2,3,0,1] row_mask:0xf bank_mask:0xf bound_ctrl:1
	v_cndmask_b32_e64 v160, v160, v164, s[4:5]
	v_mfma_scale_f32_16x16x128_f8f6f4 v[188:191], v[124:127], v[136:143], v[188:191], v240, v242 op_sel_hi:[0,0,0] cbsz:4
	v_cndmask_b32_e64 v160, v160, v168, s[6:7]
	v_cndmask_b32_e64 v160, v160, v172, s[8:9]
	v_add_f32_e32 v206, v206, v160
	s_add_u32 s80, s61, 0x1800
	buffer_load_dwordx4 v[136:139], v238, s[12:15], s80 offen nt
	buffer_load_dwordx4 v[140:143], v239, s[12:15], s80 offen nt
	s_waitcnt lgkmcnt(0)
	v_lshl_or_b32 v144, v144, 7, v236
	v_lshl_or_b32 v145, v145, 7, v236
	v_lshl_or_b32 v146, v146, 7, v236
	v_lshl_or_b32 v147, v147, 7, v236
	v_lshl_or_b32 v148, v148, 7, v236
	v_lshl_or_b32 v149, v149, 7, v236
	v_lshl_or_b32 v150, v150, 7, v236
	v_lshl_or_b32 v151, v151, 7, v236
	buffer_load_dwordx4 v[96:99], v144, s[16:19], s1 offen
	buffer_load_dwordx4 v[100:103], v145, s[16:19], s1 offen
	buffer_load_dwordx4 v[104:107], v146, s[16:19], s1 offen
	buffer_load_dwordx4 v[108:111], v147, s[16:19], s1 offen
	buffer_load_dwordx4 v[112:115], v148, s[16:19], s1 offen
	buffer_load_dwordx4 v[116:119], v149, s[16:19], s1 offen
	buffer_load_dwordx4 v[120:123], v150, s[16:19], s1 offen
	buffer_load_dwordx4 v[124:127], v151, s[16:19], s1 offen
	ds_read_b32 v144, v237 offset:2048
	ds_read_b32 v145, v237 offset:2080
	ds_read_b32 v146, v237 offset:2112
	ds_read_b32 v147, v237 offset:2144
	ds_read_b32 v148, v237 offset:2176
	ds_read_b32 v149, v237 offset:2208
	ds_read_b32 v150, v237 offset:2240
	ds_read_b32 v151, v237 offset:2272
	s_waitcnt vmcnt(26)
	v_mfma_scale_f32_16x16x128_f8f6f4 v[160:163], v[0:3], v[128:135], 0, v240, v241 op_sel_hi:[0,0,0] cbsz:4
	v_cndmask_b32_e64 v176, v176, v177, s[4:5]
	v_cndmask_b32_e64 v180, v180, v181, s[4:5]
	v_cndmask_b32_e64 v184, v184, v185, s[4:5]
	v_mfma_scale_f32_16x16x128_f8f6f4 v[164:167], v[8:11], v[128:135], 0, v240, v241 op_sel_hi:[0,0,0] cbsz:4
	v_cndmask_b32_e64 v188, v188, v189, s[4:5]
	v_cndmask_b32_e64 v176, v176, v178, s[6:7]
	v_cndmask_b32_e64 v180, v180, v182, s[6:7]
	v_mfma_scale_f32_16x16x128_f8f6f4 v[168:171], v[16:19], v[128:135], 0, v240, v241 op_sel_hi:[0,0,0] cbsz:4
	v_cndmask_b32_e64 v184, v184, v186, s[6:7]
	v_cndmask_b32_e64 v188, v188, v190, s[6:7]
	v_cndmask_b32_e64 v176, v176, v179, s[8:9]
	v_mfma_scale_f32_16x16x128_f8f6f4 v[172:175], v[24:27], v[128:135], 0, v240, v241 op_sel_hi:[0,0,0] cbsz:4
	v_cndmask_b32_e64 v180, v180, v183, s[8:9]
	v_cndmask_b32_e64 v184, v184, v187, s[8:9]
	v_cndmask_b32_e64 v188, v188, v191, s[8:9]
	v_mfma_scale_f32_16x16x128_f8f6f4 v[160:163], v[4:7], v[128:135], v[160:163], v240, v242 op_sel_hi:[0,0,0] cbsz:4
	v_add_f32_dpp v176, v176, v176 quad_perm:[1,0,3,2] row_mask:0xf bank_mask:0xf bound_ctrl:1
	v_add_f32_dpp v180, v180, v180 quad_perm:[1,0,3,2] row_mask:0xf bank_mask:0xf bound_ctrl:1
	v_add_f32_dpp v184, v184, v184 quad_perm:[1,0,3,2] row_mask:0xf bank_mask:0xf bound_ctrl:1
	v_mfma_scale_f32_16x16x128_f8f6f4 v[164:167], v[12:15], v[128:135], v[164:167], v240, v242 op_sel_hi:[0,0,0] cbsz:4
	v_add_f32_dpp v188, v188, v188 quad_perm:[1,0,3,2] row_mask:0xf bank_mask:0xf bound_ctrl:1
	v_add_f32_dpp v176, v176, v176 quad_perm:[2,3,0,1] row_mask:0xf bank_mask:0xf bound_ctrl:1
	v_add_f32_dpp v180, v180, v180 quad_perm:[2,3,0,1] row_mask:0xf bank_mask:0xf bound_ctrl:1
	v_mfma_scale_f32_16x16x128_f8f6f4 v[168:171], v[20:23], v[128:135], v[168:171], v240, v242 op_sel_hi:[0,0,0] cbsz:4
	v_add_f32_dpp v184, v184, v184 quad_perm:[2,3,0,1] row_mask:0xf bank_mask:0xf bound_ctrl:1
	v_add_f32_dpp v188, v188, v188 quad_perm:[2,3,0,1] row_mask:0xf bank_mask:0xf bound_ctrl:1
	v_cndmask_b32_e64 v176, v176, v180, s[4:5]
	v_mfma_scale_f32_16x16x128_f8f6f4 v[172:175], v[28:31], v[128:135], v[172:175], v240, v242 op_sel_hi:[0,0,0] cbsz:4
	v_cndmask_b32_e64 v176, v176, v184, s[6:7]
	v_cndmask_b32_e64 v176, v176, v188, s[8:9]
	v_add_f32_e32 v207, v207, v176
	s_waitcnt lgkmcnt(0)
	v_lshl_or_b32 v144, v144, 7, v236
	v_lshl_or_b32 v145, v145, 7, v236
	v_lshl_or_b32 v146, v146, 7, v236
	v_lshl_or_b32 v147, v147, 7, v236
	v_lshl_or_b32 v148, v148, 7, v236
	v_lshl_or_b32 v149, v149, 7, v236
	v_lshl_or_b32 v150, v150, 7, v236
	v_lshl_or_b32 v151, v151, 7, v236
	buffer_load_dwordx4 v[0:3], v144, s[16:19], s1 offen
	buffer_load_dwordx4 v[4:7], v145, s[16:19], s1 offen
	buffer_load_dwordx4 v[8:11], v146, s[16:19], s1 offen
	buffer_load_dwordx4 v[12:15], v147, s[16:19], s1 offen
	buffer_load_dwordx4 v[16:19], v148, s[16:19], s1 offen
	buffer_load_dwordx4 v[20:23], v149, s[16:19], s1 offen
	buffer_load_dwordx4 v[24:27], v150, s[16:19], s1 offen
	buffer_load_dwordx4 v[28:31], v151, s[16:19], s1 offen
	ds_read_b32 v144, v237 offset:2304
	ds_read_b32 v145, v237 offset:2336
	ds_read_b32 v146, v237 offset:2368
	ds_read_b32 v147, v237 offset:2400
	ds_read_b32 v148, v237 offset:2432
	ds_read_b32 v149, v237 offset:2464
	ds_read_b32 v150, v237 offset:2496
	ds_read_b32 v151, v237 offset:2528
	s_waitcnt vmcnt(26)
	v_mfma_scale_f32_16x16x128_f8f6f4 v[176:179], v[32:35], v[128:135], 0, v240, v241 op_sel_hi:[0,0,0] cbsz:4
	v_cndmask_b32_e64 v160, v160, v161, s[4:5]
	v_cndmask_b32_e64 v164, v164, v165, s[4:5]
	v_cndmask_b32_e64 v168, v168, v169, s[4:5]
	v_mfma_scale_f32_16x16x128_f8f6f4 v[180:183], v[40:43], v[128:135], 0, v240, v241 op_sel_hi:[0,0,0] cbsz:4
	v_cndmask_b32_e64 v172, v172, v173, s[4:5]
	v_cndmask_b32_e64 v160, v160, v162, s[6:7]
	v_cndmask_b32_e64 v164, v164, v166, s[6:7]
	v_mfma_scale_f32_16x16x128_f8f6f4 v[184:187], v[48:51], v[128:135], 0, v240, v241 op_sel_hi:[0,0,0] cbsz:4
	v_cndmask_b32_e64 v168, v168, v170, s[6:7]
	v_cndmask_b32_e64 v172, v172, v174, s[6:7]
	v_cndmask_b32_e64 v160, v160, v163, s[8:9]
	v_mfma_scale_f32_16x16x128_f8f6f4 v[188:191], v[56:59], v[128:135], 0, v240, v241 op_sel_hi:[0,0,0] cbsz:4
	v_cndmask_b32_e64 v164, v164, v167, s[8:9]
	v_cndmask_b32_e64 v168, v168, v171, s[8:9]
	v_cndmask_b32_e64 v172, v172, v175, s[8:9]
	v_mfma_scale_f32_16x16x128_f8f6f4 v[176:179], v[36:39], v[128:135], v[176:179], v240, v242 op_sel_hi:[0,0,0] cbsz:4
	v_add_f32_dpp v160, v160, v160 quad_perm:[1,0,3,2] row_mask:0xf bank_mask:0xf bound_ctrl:1
	v_add_f32_dpp v164, v164, v164 quad_perm:[1,0,3,2] row_mask:0xf bank_mask:0xf bound_ctrl:1
	v_add_f32_dpp v168, v168, v168 quad_perm:[1,0,3,2] row_mask:0xf bank_mask:0xf bound_ctrl:1
	v_mfma_scale_f32_16x16x128_f8f6f4 v[180:183], v[44:47], v[128:135], v[180:183], v240, v242 op_sel_hi:[0,0,0] cbsz:4
	v_add_f32_dpp v172, v172, v172 quad_perm:[1,0,3,2] row_mask:0xf bank_mask:0xf bound_ctrl:1
	v_add_f32_dpp v160, v160, v160 quad_perm:[2,3,0,1] row_mask:0xf bank_mask:0xf bound_ctrl:1
	v_add_f32_dpp v164, v164, v164 quad_perm:[2,3,0,1] row_mask:0xf bank_mask:0xf bound_ctrl:1
	v_mfma_scale_f32_16x16x128_f8f6f4 v[184:187], v[52:55], v[128:135], v[184:187], v240, v242 op_sel_hi:[0,0,0] cbsz:4
	v_add_f32_dpp v168, v168, v168 quad_perm:[2,3,0,1] row_mask:0xf bank_mask:0xf bound_ctrl:1
	v_add_f32_dpp v172, v172, v172 quad_perm:[2,3,0,1] row_mask:0xf bank_mask:0xf bound_ctrl:1
	v_cndmask_b32_e64 v160, v160, v164, s[4:5]
	v_mfma_scale_f32_16x16x128_f8f6f4 v[188:191], v[60:63], v[128:135], v[188:191], v240, v242 op_sel_hi:[0,0,0] cbsz:4
	v_cndmask_b32_e64 v160, v160, v168, s[6:7]
	v_cndmask_b32_e64 v160, v160, v172, s[8:9]
	v_add_f32_e32 v208, v208, v160
	s_add_u32 s80, s61, 0x2000
	buffer_load_dwordx4 v[128:131], v238, s[12:15], s80 offen nt
	buffer_load_dwordx4 v[132:135], v239, s[12:15], s80 offen nt
	s_waitcnt lgkmcnt(0)
	v_lshl_or_b32 v144, v144, 7, v236
	v_lshl_or_b32 v145, v145, 7, v236
	v_lshl_or_b32 v146, v146, 7, v236
	v_lshl_or_b32 v147, v147, 7, v236
	v_lshl_or_b32 v148, v148, 7, v236
	v_lshl_or_b32 v149, v149, 7, v236
	v_lshl_or_b32 v150, v150, 7, v236
	v_lshl_or_b32 v151, v151, 7, v236
	buffer_load_dwordx4 v[32:35], v144, s[16:19], s1 offen
	buffer_load_dwordx4 v[36:39], v145, s[16:19], s1 offen
	buffer_load_dwordx4 v[40:43], v146, s[16:19], s1 offen
	buffer_load_dwordx4 v[44:47], v147, s[16:19], s1 offen
	buffer_load_dwordx4 v[48:51], v148, s[16:19], s1 offen
	buffer_load_dwordx4 v[52:55], v149, s[16:19], s1 offen
	buffer_load_dwordx4 v[56:59], v150, s[16:19], s1 offen
	buffer_load_dwordx4 v[60:63], v151, s[16:19], s1 offen
	ds_read_b32 v144, v237 offset:2560
	ds_read_b32 v145, v237 offset:2592
	ds_read_b32 v146, v237 offset:2624
	ds_read_b32 v147, v237 offset:2656
	ds_read_b32 v148, v237 offset:2688
	ds_read_b32 v149, v237 offset:2720
	ds_read_b32 v150, v237 offset:2752
	ds_read_b32 v151, v237 offset:2784
	s_waitcnt vmcnt(26)
	v_mfma_scale_f32_16x16x128_f8f6f4 v[160:163], v[64:67], v[136:143], 0, v240, v241 op_sel_hi:[0,0,0] cbsz:4
	v_cndmask_b32_e64 v176, v176, v177, s[4:5]
	v_cndmask_b32_e64 v180, v180, v181, s[4:5]
	v_cndmask_b32_e64 v184, v184, v185, s[4:5]
	v_mfma_scale_f32_16x16x128_f8f6f4 v[164:167], v[72:75], v[136:143], 0, v240, v241 op_sel_hi:[0,0,0] cbsz:4
	v_cndmask_b32_e64 v188, v188, v189, s[4:5]
	v_cndmask_b32_e64 v176, v176, v178, s[6:7]
	v_cndmask_b32_e64 v180, v180, v182, s[6:7]
	v_mfma_scale_f32_16x16x128_f8f6f4 v[168:171], v[80:83], v[136:143], 0, v240, v241 op_sel_hi:[0,0,0] cbsz:4
	v_cndmask_b32_e64 v184, v184, v186, s[6:7]
	v_cndmask_b32_e64 v188, v188, v190, s[6:7]
	v_cndmask_b32_e64 v176, v176, v179, s[8:9]
	v_mfma_scale_f32_16x16x128_f8f6f4 v[172:175], v[88:91], v[136:143], 0, v240, v241 op_sel_hi:[0,0,0] cbsz:4
	v_cndmask_b32_e64 v180, v180, v183, s[8:9]
	v_cndmask_b32_e64 v184, v184, v187, s[8:9]
	v_cndmask_b32_e64 v188, v188, v191, s[8:9]
	v_mfma_scale_f32_16x16x128_f8f6f4 v[160:163], v[68:71], v[136:143], v[160:163], v240, v242 op_sel_hi:[0,0,0] cbsz:4
	v_add_f32_dpp v176, v176, v176 quad_perm:[1,0,3,2] row_mask:0xf bank_mask:0xf bound_ctrl:1
	v_add_f32_dpp v180, v180, v180 quad_perm:[1,0,3,2] row_mask:0xf bank_mask:0xf bound_ctrl:1
	v_add_f32_dpp v184, v184, v184 quad_perm:[1,0,3,2] row_mask:0xf bank_mask:0xf bound_ctrl:1
	v_mfma_scale_f32_16x16x128_f8f6f4 v[164:167], v[76:79], v[136:143], v[164:167], v240, v242 op_sel_hi:[0,0,0] cbsz:4
	v_add_f32_dpp v188, v188, v188 quad_perm:[1,0,3,2] row_mask:0xf bank_mask:0xf bound_ctrl:1
	v_add_f32_dpp v176, v176, v176 quad_perm:[2,3,0,1] row_mask:0xf bank_mask:0xf bound_ctrl:1
	v_add_f32_dpp v180, v180, v180 quad_perm:[2,3,0,1] row_mask:0xf bank_mask:0xf bound_ctrl:1
	v_mfma_scale_f32_16x16x128_f8f6f4 v[168:171], v[84:87], v[136:143], v[168:171], v240, v242 op_sel_hi:[0,0,0] cbsz:4
	v_add_f32_dpp v184, v184, v184 quad_perm:[2,3,0,1] row_mask:0xf bank_mask:0xf bound_ctrl:1
	v_add_f32_dpp v188, v188, v188 quad_perm:[2,3,0,1] row_mask:0xf bank_mask:0xf bound_ctrl:1
	v_cndmask_b32_e64 v176, v176, v180, s[4:5]
	v_mfma_scale_f32_16x16x128_f8f6f4 v[172:175], v[92:95], v[136:143], v[172:175], v240, v242 op_sel_hi:[0,0,0] cbsz:4
	v_cndmask_b32_e64 v176, v176, v184, s[6:7]
	v_cndmask_b32_e64 v176, v176, v188, s[8:9]
	v_add_f32_e32 v209, v209, v176
	s_waitcnt lgkmcnt(0)
	v_lshl_or_b32 v144, v144, 7, v236
	v_lshl_or_b32 v145, v145, 7, v236
	v_lshl_or_b32 v146, v146, 7, v236
	v_lshl_or_b32 v147, v147, 7, v236
	v_lshl_or_b32 v148, v148, 7, v236
	v_lshl_or_b32 v149, v149, 7, v236
	v_lshl_or_b32 v150, v150, 7, v236
	v_lshl_or_b32 v151, v151, 7, v236
	buffer_load_dwordx4 v[64:67], v144, s[16:19], s1 offen
	buffer_load_dwordx4 v[68:71], v145, s[16:19], s1 offen
	buffer_load_dwordx4 v[72:75], v146, s[16:19], s1 offen
	buffer_load_dwordx4 v[76:79], v147, s[16:19], s1 offen
	buffer_load_dwordx4 v[80:83], v148, s[16:19], s1 offen
	buffer_load_dwordx4 v[84:87], v149, s[16:19], s1 offen
	buffer_load_dwordx4 v[88:91], v150, s[16:19], s1 offen
	buffer_load_dwordx4 v[92:95], v151, s[16:19], s1 offen
	ds_read_b32 v144, v237 offset:2816
	ds_read_b32 v145, v237 offset:2848
	ds_read_b32 v146, v237 offset:2880
	ds_read_b32 v147, v237 offset:2912
	ds_read_b32 v148, v237 offset:2944
	ds_read_b32 v149, v237 offset:2976
	ds_read_b32 v150, v237 offset:3008
	ds_read_b32 v151, v237 offset:3040
	s_waitcnt vmcnt(26)
	v_mfma_scale_f32_16x16x128_f8f6f4 v[176:179], v[96:99], v[136:143], 0, v240, v241 op_sel_hi:[0,0,0] cbsz:4
	v_cndmask_b32_e64 v160, v160, v161, s[4:5]
	v_cndmask_b32_e64 v164, v164, v165, s[4:5]
	v_cndmask_b32_e64 v168, v168, v169, s[4:5]
	v_mfma_scale_f32_16x16x128_f8f6f4 v[180:183], v[104:107], v[136:143], 0, v240, v241 op_sel_hi:[0,0,0] cbsz:4
	v_cndmask_b32_e64 v172, v172, v173, s[4:5]
	v_cndmask_b32_e64 v160, v160, v162, s[6:7]
	v_cndmask_b32_e64 v164, v164, v166, s[6:7]
	v_mfma_scale_f32_16x16x128_f8f6f4 v[184:187], v[112:115], v[136:143], 0, v240, v241 op_sel_hi:[0,0,0] cbsz:4
	v_cndmask_b32_e64 v168, v168, v170, s[6:7]
	v_cndmask_b32_e64 v172, v172, v174, s[6:7]
	v_cndmask_b32_e64 v160, v160, v163, s[8:9]
	v_mfma_scale_f32_16x16x128_f8f6f4 v[188:191], v[120:123], v[136:143], 0, v240, v241 op_sel_hi:[0,0,0] cbsz:4
	v_cndmask_b32_e64 v164, v164, v167, s[8:9]
	v_cndmask_b32_e64 v168, v168, v171, s[8:9]
	v_cndmask_b32_e64 v172, v172, v175, s[8:9]
	v_mfma_scale_f32_16x16x128_f8f6f4 v[176:179], v[100:103], v[136:143], v[176:179], v240, v242 op_sel_hi:[0,0,0] cbsz:4
	v_add_f32_dpp v160, v160, v160 quad_perm:[1,0,3,2] row_mask:0xf bank_mask:0xf bound_ctrl:1
	v_add_f32_dpp v164, v164, v164 quad_perm:[1,0,3,2] row_mask:0xf bank_mask:0xf bound_ctrl:1
	v_add_f32_dpp v168, v168, v168 quad_perm:[1,0,3,2] row_mask:0xf bank_mask:0xf bound_ctrl:1
	v_mfma_scale_f32_16x16x128_f8f6f4 v[180:183], v[108:111], v[136:143], v[180:183], v240, v242 op_sel_hi:[0,0,0] cbsz:4
	v_add_f32_dpp v172, v172, v172 quad_perm:[1,0,3,2] row_mask:0xf bank_mask:0xf bound_ctrl:1
	v_add_f32_dpp v160, v160, v160 quad_perm:[2,3,0,1] row_mask:0xf bank_mask:0xf bound_ctrl:1
	v_add_f32_dpp v164, v164, v164 quad_perm:[2,3,0,1] row_mask:0xf bank_mask:0xf bound_ctrl:1
	v_mfma_scale_f32_16x16x128_f8f6f4 v[184:187], v[116:119], v[136:143], v[184:187], v240, v242 op_sel_hi:[0,0,0] cbsz:4
	v_add_f32_dpp v168, v168, v168 quad_perm:[2,3,0,1] row_mask:0xf bank_mask:0xf bound_ctrl:1
	v_add_f32_dpp v172, v172, v172 quad_perm:[2,3,0,1] row_mask:0xf bank_mask:0xf bound_ctrl:1
	v_cndmask_b32_e64 v160, v160, v164, s[4:5]
	v_mfma_scale_f32_16x16x128_f8f6f4 v[188:191], v[124:127], v[136:143], v[188:191], v240, v242 op_sel_hi:[0,0,0] cbsz:4
	v_cndmask_b32_e64 v160, v160, v168, s[6:7]
	v_cndmask_b32_e64 v160, v160, v172, s[8:9]
	v_add_f32_e32 v210, v210, v160
	s_add_u32 s80, s61, 0x2800
	buffer_load_dwordx4 v[136:139], v238, s[12:15], s80 offen nt
	buffer_load_dwordx4 v[140:143], v239, s[12:15], s80 offen nt
	s_waitcnt lgkmcnt(0)
	v_lshl_or_b32 v144, v144, 7, v236
	v_lshl_or_b32 v145, v145, 7, v236
	v_lshl_or_b32 v146, v146, 7, v236
	v_lshl_or_b32 v147, v147, 7, v236
	v_lshl_or_b32 v148, v148, 7, v236
	v_lshl_or_b32 v149, v149, 7, v236
	v_lshl_or_b32 v150, v150, 7, v236
	v_lshl_or_b32 v151, v151, 7, v236
	buffer_load_dwordx4 v[96:99], v144, s[16:19], s1 offen
	buffer_load_dwordx4 v[100:103], v145, s[16:19], s1 offen
	buffer_load_dwordx4 v[104:107], v146, s[16:19], s1 offen
	buffer_load_dwordx4 v[108:111], v147, s[16:19], s1 offen
	buffer_load_dwordx4 v[112:115], v148, s[16:19], s1 offen
	buffer_load_dwordx4 v[116:119], v149, s[16:19], s1 offen
	buffer_load_dwordx4 v[120:123], v150, s[16:19], s1 offen
	buffer_load_dwordx4 v[124:127], v151, s[16:19], s1 offen
	ds_read_b32 v144, v237 offset:3072
	ds_read_b32 v145, v237 offset:3104
	ds_read_b32 v146, v237 offset:3136
	ds_read_b32 v147, v237 offset:3168
	ds_read_b32 v148, v237 offset:3200
	ds_read_b32 v149, v237 offset:3232
	ds_read_b32 v150, v237 offset:3264
	ds_read_b32 v151, v237 offset:3296
	s_waitcnt vmcnt(26)
	v_mfma_scale_f32_16x16x128_f8f6f4 v[160:163], v[0:3], v[128:135], 0, v240, v241 op_sel_hi:[0,0,0] cbsz:4
	v_cndmask_b32_e64 v176, v176, v177, s[4:5]
	v_cndmask_b32_e64 v180, v180, v181, s[4:5]
	v_cndmask_b32_e64 v184, v184, v185, s[4:5]
	v_mfma_scale_f32_16x16x128_f8f6f4 v[164:167], v[8:11], v[128:135], 0, v240, v241 op_sel_hi:[0,0,0] cbsz:4
	v_cndmask_b32_e64 v188, v188, v189, s[4:5]
	v_cndmask_b32_e64 v176, v176, v178, s[6:7]
	v_cndmask_b32_e64 v180, v180, v182, s[6:7]
	v_mfma_scale_f32_16x16x128_f8f6f4 v[168:171], v[16:19], v[128:135], 0, v240, v241 op_sel_hi:[0,0,0] cbsz:4
	v_cndmask_b32_e64 v184, v184, v186, s[6:7]
	v_cndmask_b32_e64 v188, v188, v190, s[6:7]
	v_cndmask_b32_e64 v176, v176, v179, s[8:9]
	v_mfma_scale_f32_16x16x128_f8f6f4 v[172:175], v[24:27], v[128:135], 0, v240, v241 op_sel_hi:[0,0,0] cbsz:4
	v_cndmask_b32_e64 v180, v180, v183, s[8:9]
	v_cndmask_b32_e64 v184, v184, v187, s[8:9]
	v_cndmask_b32_e64 v188, v188, v191, s[8:9]
	v_mfma_scale_f32_16x16x128_f8f6f4 v[160:163], v[4:7], v[128:135], v[160:163], v240, v242 op_sel_hi:[0,0,0] cbsz:4
	v_add_f32_dpp v176, v176, v176 quad_perm:[1,0,3,2] row_mask:0xf bank_mask:0xf bound_ctrl:1
	v_add_f32_dpp v180, v180, v180 quad_perm:[1,0,3,2] row_mask:0xf bank_mask:0xf bound_ctrl:1
	v_add_f32_dpp v184, v184, v184 quad_perm:[1,0,3,2] row_mask:0xf bank_mask:0xf bound_ctrl:1
	v_mfma_scale_f32_16x16x128_f8f6f4 v[164:167], v[12:15], v[128:135], v[164:167], v240, v242 op_sel_hi:[0,0,0] cbsz:4
	v_add_f32_dpp v188, v188, v188 quad_perm:[1,0,3,2] row_mask:0xf bank_mask:0xf bound_ctrl:1
	v_add_f32_dpp v176, v176, v176 quad_perm:[2,3,0,1] row_mask:0xf bank_mask:0xf bound_ctrl:1
	v_add_f32_dpp v180, v180, v180 quad_perm:[2,3,0,1] row_mask:0xf bank_mask:0xf bound_ctrl:1
	v_mfma_scale_f32_16x16x128_f8f6f4 v[168:171], v[20:23], v[128:135], v[168:171], v240, v242 op_sel_hi:[0,0,0] cbsz:4
	v_add_f32_dpp v184, v184, v184 quad_perm:[2,3,0,1] row_mask:0xf bank_mask:0xf bound_ctrl:1
	v_add_f32_dpp v188, v188, v188 quad_perm:[2,3,0,1] row_mask:0xf bank_mask:0xf bound_ctrl:1
	v_cndmask_b32_e64 v176, v176, v180, s[4:5]
	v_mfma_scale_f32_16x16x128_f8f6f4 v[172:175], v[28:31], v[128:135], v[172:175], v240, v242 op_sel_hi:[0,0,0] cbsz:4
	v_cndmask_b32_e64 v176, v176, v184, s[6:7]
	v_cndmask_b32_e64 v176, v176, v188, s[8:9]
	v_add_f32_e32 v211, v211, v176
	s_waitcnt lgkmcnt(0)
	v_lshl_or_b32 v144, v144, 7, v236
	v_lshl_or_b32 v145, v145, 7, v236
	v_lshl_or_b32 v146, v146, 7, v236
	v_lshl_or_b32 v147, v147, 7, v236
	v_lshl_or_b32 v148, v148, 7, v236
	v_lshl_or_b32 v149, v149, 7, v236
	v_lshl_or_b32 v150, v150, 7, v236
	v_lshl_or_b32 v151, v151, 7, v236
	buffer_load_dwordx4 v[0:3], v144, s[16:19], s1 offen
	buffer_load_dwordx4 v[4:7], v145, s[16:19], s1 offen
	buffer_load_dwordx4 v[8:11], v146, s[16:19], s1 offen
	buffer_load_dwordx4 v[12:15], v147, s[16:19], s1 offen
	buffer_load_dwordx4 v[16:19], v148, s[16:19], s1 offen
	buffer_load_dwordx4 v[20:23], v149, s[16:19], s1 offen
	buffer_load_dwordx4 v[24:27], v150, s[16:19], s1 offen
	buffer_load_dwordx4 v[28:31], v151, s[16:19], s1 offen
	ds_read_b32 v144, v237 offset:3328
	ds_read_b32 v145, v237 offset:3360
	ds_read_b32 v146, v237 offset:3392
	ds_read_b32 v147, v237 offset:3424
	ds_read_b32 v148, v237 offset:3456
	ds_read_b32 v149, v237 offset:3488
	ds_read_b32 v150, v237 offset:3520
	ds_read_b32 v151, v237 offset:3552
	s_waitcnt vmcnt(26)
	v_mfma_scale_f32_16x16x128_f8f6f4 v[176:179], v[32:35], v[128:135], 0, v240, v241 op_sel_hi:[0,0,0] cbsz:4
	v_cndmask_b32_e64 v160, v160, v161, s[4:5]
	v_cndmask_b32_e64 v164, v164, v165, s[4:5]
	v_cndmask_b32_e64 v168, v168, v169, s[4:5]
	v_mfma_scale_f32_16x16x128_f8f6f4 v[180:183], v[40:43], v[128:135], 0, v240, v241 op_sel_hi:[0,0,0] cbsz:4
	v_cndmask_b32_e64 v172, v172, v173, s[4:5]
	v_cndmask_b32_e64 v160, v160, v162, s[6:7]
	v_cndmask_b32_e64 v164, v164, v166, s[6:7]
	v_mfma_scale_f32_16x16x128_f8f6f4 v[184:187], v[48:51], v[128:135], 0, v240, v241 op_sel_hi:[0,0,0] cbsz:4
	v_cndmask_b32_e64 v168, v168, v170, s[6:7]
	v_cndmask_b32_e64 v172, v172, v174, s[6:7]
	v_cndmask_b32_e64 v160, v160, v163, s[8:9]
	v_mfma_scale_f32_16x16x128_f8f6f4 v[188:191], v[56:59], v[128:135], 0, v240, v241 op_sel_hi:[0,0,0] cbsz:4
	v_cndmask_b32_e64 v164, v164, v167, s[8:9]
	v_cndmask_b32_e64 v168, v168, v171, s[8:9]
	v_cndmask_b32_e64 v172, v172, v175, s[8:9]
	v_mfma_scale_f32_16x16x128_f8f6f4 v[176:179], v[36:39], v[128:135], v[176:179], v240, v242 op_sel_hi:[0,0,0] cbsz:4
	v_add_f32_dpp v160, v160, v160 quad_perm:[1,0,3,2] row_mask:0xf bank_mask:0xf bound_ctrl:1
	v_add_f32_dpp v164, v164, v164 quad_perm:[1,0,3,2] row_mask:0xf bank_mask:0xf bound_ctrl:1
	v_add_f32_dpp v168, v168, v168 quad_perm:[1,0,3,2] row_mask:0xf bank_mask:0xf bound_ctrl:1
	v_mfma_scale_f32_16x16x128_f8f6f4 v[180:183], v[44:47], v[128:135], v[180:183], v240, v242 op_sel_hi:[0,0,0] cbsz:4
	v_add_f32_dpp v172, v172, v172 quad_perm:[1,0,3,2] row_mask:0xf bank_mask:0xf bound_ctrl:1
	v_add_f32_dpp v160, v160, v160 quad_perm:[2,3,0,1] row_mask:0xf bank_mask:0xf bound_ctrl:1
	v_add_f32_dpp v164, v164, v164 quad_perm:[2,3,0,1] row_mask:0xf bank_mask:0xf bound_ctrl:1
	v_mfma_scale_f32_16x16x128_f8f6f4 v[184:187], v[52:55], v[128:135], v[184:187], v240, v242 op_sel_hi:[0,0,0] cbsz:4
	v_add_f32_dpp v168, v168, v168 quad_perm:[2,3,0,1] row_mask:0xf bank_mask:0xf bound_ctrl:1
	v_add_f32_dpp v172, v172, v172 quad_perm:[2,3,0,1] row_mask:0xf bank_mask:0xf bound_ctrl:1
	v_cndmask_b32_e64 v160, v160, v164, s[4:5]
	v_mfma_scale_f32_16x16x128_f8f6f4 v[188:191], v[60:63], v[128:135], v[188:191], v240, v242 op_sel_hi:[0,0,0] cbsz:4
	v_cndmask_b32_e64 v160, v160, v168, s[6:7]
	v_cndmask_b32_e64 v160, v160, v172, s[8:9]
	v_add_f32_e32 v212, v212, v160
	s_add_u32 s80, s61, 0x3000
	buffer_load_dwordx4 v[128:131], v238, s[12:15], s80 offen nt
	buffer_load_dwordx4 v[132:135], v239, s[12:15], s80 offen nt
	s_waitcnt lgkmcnt(0)
	v_lshl_or_b32 v144, v144, 7, v236
	v_lshl_or_b32 v145, v145, 7, v236
	v_lshl_or_b32 v146, v146, 7, v236
	v_lshl_or_b32 v147, v147, 7, v236
	v_lshl_or_b32 v148, v148, 7, v236
	v_lshl_or_b32 v149, v149, 7, v236
	v_lshl_or_b32 v150, v150, 7, v236
	v_lshl_or_b32 v151, v151, 7, v236
	buffer_load_dwordx4 v[32:35], v144, s[16:19], s1 offen
	buffer_load_dwordx4 v[36:39], v145, s[16:19], s1 offen
	buffer_load_dwordx4 v[40:43], v146, s[16:19], s1 offen
	buffer_load_dwordx4 v[44:47], v147, s[16:19], s1 offen
	buffer_load_dwordx4 v[48:51], v148, s[16:19], s1 offen
	buffer_load_dwordx4 v[52:55], v149, s[16:19], s1 offen
	buffer_load_dwordx4 v[56:59], v150, s[16:19], s1 offen
	buffer_load_dwordx4 v[60:63], v151, s[16:19], s1 offen
	ds_read_b32 v144, v237 offset:3584
	ds_read_b32 v145, v237 offset:3616
	ds_read_b32 v146, v237 offset:3648
	ds_read_b32 v147, v237 offset:3680
	ds_read_b32 v148, v237 offset:3712
	ds_read_b32 v149, v237 offset:3744
	ds_read_b32 v150, v237 offset:3776
	ds_read_b32 v151, v237 offset:3808
	s_waitcnt vmcnt(26)
	v_mfma_scale_f32_16x16x128_f8f6f4 v[160:163], v[64:67], v[136:143], 0, v240, v241 op_sel_hi:[0,0,0] cbsz:4
	v_cndmask_b32_e64 v176, v176, v177, s[4:5]
	v_cndmask_b32_e64 v180, v180, v181, s[4:5]
	v_cndmask_b32_e64 v184, v184, v185, s[4:5]
	v_mfma_scale_f32_16x16x128_f8f6f4 v[164:167], v[72:75], v[136:143], 0, v240, v241 op_sel_hi:[0,0,0] cbsz:4
	v_cndmask_b32_e64 v188, v188, v189, s[4:5]
	v_cndmask_b32_e64 v176, v176, v178, s[6:7]
	v_cndmask_b32_e64 v180, v180, v182, s[6:7]
	v_mfma_scale_f32_16x16x128_f8f6f4 v[168:171], v[80:83], v[136:143], 0, v240, v241 op_sel_hi:[0,0,0] cbsz:4
	v_cndmask_b32_e64 v184, v184, v186, s[6:7]
	v_cndmask_b32_e64 v188, v188, v190, s[6:7]
	v_cndmask_b32_e64 v176, v176, v179, s[8:9]
	v_mfma_scale_f32_16x16x128_f8f6f4 v[172:175], v[88:91], v[136:143], 0, v240, v241 op_sel_hi:[0,0,0] cbsz:4
	v_cndmask_b32_e64 v180, v180, v183, s[8:9]
	v_cndmask_b32_e64 v184, v184, v187, s[8:9]
	v_cndmask_b32_e64 v188, v188, v191, s[8:9]
	v_mfma_scale_f32_16x16x128_f8f6f4 v[160:163], v[68:71], v[136:143], v[160:163], v240, v242 op_sel_hi:[0,0,0] cbsz:4
	v_add_f32_dpp v176, v176, v176 quad_perm:[1,0,3,2] row_mask:0xf bank_mask:0xf bound_ctrl:1
	v_add_f32_dpp v180, v180, v180 quad_perm:[1,0,3,2] row_mask:0xf bank_mask:0xf bound_ctrl:1
	v_add_f32_dpp v184, v184, v184 quad_perm:[1,0,3,2] row_mask:0xf bank_mask:0xf bound_ctrl:1
	v_mfma_scale_f32_16x16x128_f8f6f4 v[164:167], v[76:79], v[136:143], v[164:167], v240, v242 op_sel_hi:[0,0,0] cbsz:4
	v_add_f32_dpp v188, v188, v188 quad_perm:[1,0,3,2] row_mask:0xf bank_mask:0xf bound_ctrl:1
	v_add_f32_dpp v176, v176, v176 quad_perm:[2,3,0,1] row_mask:0xf bank_mask:0xf bound_ctrl:1
	v_add_f32_dpp v180, v180, v180 quad_perm:[2,3,0,1] row_mask:0xf bank_mask:0xf bound_ctrl:1
	v_mfma_scale_f32_16x16x128_f8f6f4 v[168:171], v[84:87], v[136:143], v[168:171], v240, v242 op_sel_hi:[0,0,0] cbsz:4
	v_add_f32_dpp v184, v184, v184 quad_perm:[2,3,0,1] row_mask:0xf bank_mask:0xf bound_ctrl:1
	v_add_f32_dpp v188, v188, v188 quad_perm:[2,3,0,1] row_mask:0xf bank_mask:0xf bound_ctrl:1
	v_cndmask_b32_e64 v176, v176, v180, s[4:5]
	v_mfma_scale_f32_16x16x128_f8f6f4 v[172:175], v[92:95], v[136:143], v[172:175], v240, v242 op_sel_hi:[0,0,0] cbsz:4
	v_cndmask_b32_e64 v176, v176, v184, s[6:7]
	v_cndmask_b32_e64 v176, v176, v188, s[8:9]
	v_add_f32_e32 v213, v213, v176
	s_waitcnt lgkmcnt(0)
	v_lshl_or_b32 v144, v144, 7, v236
	v_lshl_or_b32 v145, v145, 7, v236
	v_lshl_or_b32 v146, v146, 7, v236
	v_lshl_or_b32 v147, v147, 7, v236
	v_lshl_or_b32 v148, v148, 7, v236
	v_lshl_or_b32 v149, v149, 7, v236
	v_lshl_or_b32 v150, v150, 7, v236
	v_lshl_or_b32 v151, v151, 7, v236
	buffer_load_dwordx4 v[64:67], v144, s[16:19], s1 offen
	buffer_load_dwordx4 v[68:71], v145, s[16:19], s1 offen
	buffer_load_dwordx4 v[72:75], v146, s[16:19], s1 offen
	buffer_load_dwordx4 v[76:79], v147, s[16:19], s1 offen
	buffer_load_dwordx4 v[80:83], v148, s[16:19], s1 offen
	buffer_load_dwordx4 v[84:87], v149, s[16:19], s1 offen
	buffer_load_dwordx4 v[88:91], v150, s[16:19], s1 offen
	buffer_load_dwordx4 v[92:95], v151, s[16:19], s1 offen
	ds_read_b32 v144, v237 offset:3840
	ds_read_b32 v145, v237 offset:3872
	ds_read_b32 v146, v237 offset:3904
	ds_read_b32 v147, v237 offset:3936
	ds_read_b32 v148, v237 offset:3968
	ds_read_b32 v149, v237 offset:4000
	ds_read_b32 v150, v237 offset:4032
	ds_read_b32 v151, v237 offset:4064
	s_waitcnt vmcnt(26)
	v_mfma_scale_f32_16x16x128_f8f6f4 v[176:179], v[96:99], v[136:143], 0, v240, v241 op_sel_hi:[0,0,0] cbsz:4
	v_cndmask_b32_e64 v160, v160, v161, s[4:5]
	v_cndmask_b32_e64 v164, v164, v165, s[4:5]
	v_cndmask_b32_e64 v168, v168, v169, s[4:5]
	v_mfma_scale_f32_16x16x128_f8f6f4 v[180:183], v[104:107], v[136:143], 0, v240, v241 op_sel_hi:[0,0,0] cbsz:4
	v_cndmask_b32_e64 v172, v172, v173, s[4:5]
	v_cndmask_b32_e64 v160, v160, v162, s[6:7]
	v_cndmask_b32_e64 v164, v164, v166, s[6:7]
	v_mfma_scale_f32_16x16x128_f8f6f4 v[184:187], v[112:115], v[136:143], 0, v240, v241 op_sel_hi:[0,0,0] cbsz:4
	v_cndmask_b32_e64 v168, v168, v170, s[6:7]
	v_cndmask_b32_e64 v172, v172, v174, s[6:7]
	v_cndmask_b32_e64 v160, v160, v163, s[8:9]
	v_mfma_scale_f32_16x16x128_f8f6f4 v[188:191], v[120:123], v[136:143], 0, v240, v241 op_sel_hi:[0,0,0] cbsz:4
	v_cndmask_b32_e64 v164, v164, v167, s[8:9]
	v_cndmask_b32_e64 v168, v168, v171, s[8:9]
	v_cndmask_b32_e64 v172, v172, v175, s[8:9]
	v_mfma_scale_f32_16x16x128_f8f6f4 v[176:179], v[100:103], v[136:143], v[176:179], v240, v242 op_sel_hi:[0,0,0] cbsz:4
	v_add_f32_dpp v160, v160, v160 quad_perm:[1,0,3,2] row_mask:0xf bank_mask:0xf bound_ctrl:1
	v_add_f32_dpp v164, v164, v164 quad_perm:[1,0,3,2] row_mask:0xf bank_mask:0xf bound_ctrl:1
	v_add_f32_dpp v168, v168, v168 quad_perm:[1,0,3,2] row_mask:0xf bank_mask:0xf bound_ctrl:1
	v_mfma_scale_f32_16x16x128_f8f6f4 v[180:183], v[108:111], v[136:143], v[180:183], v240, v242 op_sel_hi:[0,0,0] cbsz:4
	v_add_f32_dpp v172, v172, v172 quad_perm:[1,0,3,2] row_mask:0xf bank_mask:0xf bound_ctrl:1
	v_add_f32_dpp v160, v160, v160 quad_perm:[2,3,0,1] row_mask:0xf bank_mask:0xf bound_ctrl:1
	v_add_f32_dpp v164, v164, v164 quad_perm:[2,3,0,1] row_mask:0xf bank_mask:0xf bound_ctrl:1
	v_mfma_scale_f32_16x16x128_f8f6f4 v[184:187], v[116:119], v[136:143], v[184:187], v240, v242 op_sel_hi:[0,0,0] cbsz:4
	v_add_f32_dpp v168, v168, v168 quad_perm:[2,3,0,1] row_mask:0xf bank_mask:0xf bound_ctrl:1
	v_add_f32_dpp v172, v172, v172 quad_perm:[2,3,0,1] row_mask:0xf bank_mask:0xf bound_ctrl:1
	v_cndmask_b32_e64 v160, v160, v164, s[4:5]
	v_mfma_scale_f32_16x16x128_f8f6f4 v[188:191], v[124:127], v[136:143], v[188:191], v240, v242 op_sel_hi:[0,0,0] cbsz:4
	v_cndmask_b32_e64 v160, v160, v168, s[6:7]
	v_cndmask_b32_e64 v160, v160, v172, s[8:9]
	v_add_f32_e32 v214, v214, v160
	s_add_u32 s80, s61, 0x3800
	buffer_load_dwordx4 v[136:139], v238, s[12:15], s80 offen nt
	buffer_load_dwordx4 v[140:143], v239, s[12:15], s80 offen nt
	s_waitcnt lgkmcnt(0)
	v_lshl_or_b32 v144, v144, 7, v236
	v_lshl_or_b32 v145, v145, 7, v236
	v_lshl_or_b32 v146, v146, 7, v236
	v_lshl_or_b32 v147, v147, 7, v236
	v_lshl_or_b32 v148, v148, 7, v236
	v_lshl_or_b32 v149, v149, 7, v236
	v_lshl_or_b32 v150, v150, 7, v236
	v_lshl_or_b32 v151, v151, 7, v236
	buffer_load_dwordx4 v[96:99], v144, s[16:19], s1 offen
	buffer_load_dwordx4 v[100:103], v145, s[16:19], s1 offen
	buffer_load_dwordx4 v[104:107], v146, s[16:19], s1 offen
	buffer_load_dwordx4 v[108:111], v147, s[16:19], s1 offen
	buffer_load_dwordx4 v[112:115], v148, s[16:19], s1 offen
	buffer_load_dwordx4 v[116:119], v149, s[16:19], s1 offen
	buffer_load_dwordx4 v[120:123], v150, s[16:19], s1 offen
	buffer_load_dwordx4 v[124:127], v151, s[16:19], s1 offen
	ds_read_b32 v144, v237 offset:0
	ds_read_b32 v145, v237 offset:32
	ds_read_b32 v146, v237 offset:64
	ds_read_b32 v147, v237 offset:96
	ds_read_b32 v148, v237 offset:128
	ds_read_b32 v149, v237 offset:160
	ds_read_b32 v150, v237 offset:192
	ds_read_b32 v151, v237 offset:224
	s_waitcnt vmcnt(26)
	v_mfma_scale_f32_16x16x128_f8f6f4 v[160:163], v[0:3], v[128:135], 0, v240, v241 op_sel_hi:[0,0,0] cbsz:4
	v_cndmask_b32_e64 v176, v176, v177, s[4:5]
	v_cndmask_b32_e64 v180, v180, v181, s[4:5]
	v_cndmask_b32_e64 v184, v184, v185, s[4:5]
	v_mfma_scale_f32_16x16x128_f8f6f4 v[164:167], v[8:11], v[128:135], 0, v240, v241 op_sel_hi:[0,0,0] cbsz:4
	v_cndmask_b32_e64 v188, v188, v189, s[4:5]
	v_cndmask_b32_e64 v176, v176, v178, s[6:7]
	v_cndmask_b32_e64 v180, v180, v182, s[6:7]
	v_mfma_scale_f32_16x16x128_f8f6f4 v[168:171], v[16:19], v[128:135], 0, v240, v241 op_sel_hi:[0,0,0] cbsz:4
	v_cndmask_b32_e64 v184, v184, v186, s[6:7]
	v_cndmask_b32_e64 v188, v188, v190, s[6:7]
	v_cndmask_b32_e64 v176, v176, v179, s[8:9]
	v_mfma_scale_f32_16x16x128_f8f6f4 v[172:175], v[24:27], v[128:135], 0, v240, v241 op_sel_hi:[0,0,0] cbsz:4
	v_cndmask_b32_e64 v180, v180, v183, s[8:9]
	v_cndmask_b32_e64 v184, v184, v187, s[8:9]
	v_cndmask_b32_e64 v188, v188, v191, s[8:9]
	v_mfma_scale_f32_16x16x128_f8f6f4 v[160:163], v[4:7], v[128:135], v[160:163], v240, v242 op_sel_hi:[0,0,0] cbsz:4
	v_add_f32_dpp v176, v176, v176 quad_perm:[1,0,3,2] row_mask:0xf bank_mask:0xf bound_ctrl:1
	v_add_f32_dpp v180, v180, v180 quad_perm:[1,0,3,2] row_mask:0xf bank_mask:0xf bound_ctrl:1
	v_add_f32_dpp v184, v184, v184 quad_perm:[1,0,3,2] row_mask:0xf bank_mask:0xf bound_ctrl:1
	v_mfma_scale_f32_16x16x128_f8f6f4 v[164:167], v[12:15], v[128:135], v[164:167], v240, v242 op_sel_hi:[0,0,0] cbsz:4
	v_add_f32_dpp v188, v188, v188 quad_perm:[1,0,3,2] row_mask:0xf bank_mask:0xf bound_ctrl:1
	v_add_f32_dpp v176, v176, v176 quad_perm:[2,3,0,1] row_mask:0xf bank_mask:0xf bound_ctrl:1
	v_add_f32_dpp v180, v180, v180 quad_perm:[2,3,0,1] row_mask:0xf bank_mask:0xf bound_ctrl:1
	v_mfma_scale_f32_16x16x128_f8f6f4 v[168:171], v[20:23], v[128:135], v[168:171], v240, v242 op_sel_hi:[0,0,0] cbsz:4
	v_add_f32_dpp v184, v184, v184 quad_perm:[2,3,0,1] row_mask:0xf bank_mask:0xf bound_ctrl:1
	v_add_f32_dpp v188, v188, v188 quad_perm:[2,3,0,1] row_mask:0xf bank_mask:0xf bound_ctrl:1
	v_cndmask_b32_e64 v176, v176, v180, s[4:5]
	v_mfma_scale_f32_16x16x128_f8f6f4 v[172:175], v[28:31], v[128:135], v[172:175], v240, v242 op_sel_hi:[0,0,0] cbsz:4
	v_cndmask_b32_e64 v176, v176, v184, s[6:7]
	v_cndmask_b32_e64 v176, v176, v188, s[8:9]
	v_add_f32_e32 v215, v215, v176
	s_waitcnt lgkmcnt(0)
	v_lshl_or_b32 v144, v144, 7, v236
	v_lshl_or_b32 v145, v145, 7, v236
	v_lshl_or_b32 v146, v146, 7, v236
	v_lshl_or_b32 v147, v147, 7, v236
	v_lshl_or_b32 v148, v148, 7, v236
	v_lshl_or_b32 v149, v149, 7, v236
	v_lshl_or_b32 v150, v150, 7, v236
	v_lshl_or_b32 v151, v151, 7, v236
	buffer_load_dwordx4 v[0:3], v144, s[16:19], s60 offen
	buffer_load_dwordx4 v[4:7], v145, s[16:19], s60 offen
	buffer_load_dwordx4 v[8:11], v146, s[16:19], s60 offen
	buffer_load_dwordx4 v[12:15], v147, s[16:19], s60 offen
	buffer_load_dwordx4 v[16:19], v148, s[16:19], s60 offen
	buffer_load_dwordx4 v[20:23], v149, s[16:19], s60 offen
	buffer_load_dwordx4 v[24:27], v150, s[16:19], s60 offen
	buffer_load_dwordx4 v[28:31], v151, s[16:19], s60 offen
	ds_read_b32 v144, v237 offset:256
	ds_read_b32 v145, v237 offset:288
	ds_read_b32 v146, v237 offset:320
	ds_read_b32 v147, v237 offset:352
	ds_read_b32 v148, v237 offset:384
	ds_read_b32 v149, v237 offset:416
	ds_read_b32 v150, v237 offset:448
	ds_read_b32 v151, v237 offset:480
	s_waitcnt vmcnt(26)
	v_mfma_scale_f32_16x16x128_f8f6f4 v[176:179], v[32:35], v[128:135], 0, v240, v241 op_sel_hi:[0,0,0] cbsz:4
	v_cndmask_b32_e64 v160, v160, v161, s[4:5]
	v_cndmask_b32_e64 v164, v164, v165, s[4:5]
	v_cndmask_b32_e64 v168, v168, v169, s[4:5]
	v_mfma_scale_f32_16x16x128_f8f6f4 v[180:183], v[40:43], v[128:135], 0, v240, v241 op_sel_hi:[0,0,0] cbsz:4
	v_cndmask_b32_e64 v172, v172, v173, s[4:5]
	v_cndmask_b32_e64 v160, v160, v162, s[6:7]
	v_cndmask_b32_e64 v164, v164, v166, s[6:7]
	v_mfma_scale_f32_16x16x128_f8f6f4 v[184:187], v[48:51], v[128:135], 0, v240, v241 op_sel_hi:[0,0,0] cbsz:4
	v_cndmask_b32_e64 v168, v168, v170, s[6:7]
	v_cndmask_b32_e64 v172, v172, v174, s[6:7]
	v_cndmask_b32_e64 v160, v160, v163, s[8:9]
	v_mfma_scale_f32_16x16x128_f8f6f4 v[188:191], v[56:59], v[128:135], 0, v240, v241 op_sel_hi:[0,0,0] cbsz:4
	v_cndmask_b32_e64 v164, v164, v167, s[8:9]
	v_cndmask_b32_e64 v168, v168, v171, s[8:9]
	v_cndmask_b32_e64 v172, v172, v175, s[8:9]
	v_mfma_scale_f32_16x16x128_f8f6f4 v[176:179], v[36:39], v[128:135], v[176:179], v240, v242 op_sel_hi:[0,0,0] cbsz:4
	v_add_f32_dpp v160, v160, v160 quad_perm:[1,0,3,2] row_mask:0xf bank_mask:0xf bound_ctrl:1
	v_add_f32_dpp v164, v164, v164 quad_perm:[1,0,3,2] row_mask:0xf bank_mask:0xf bound_ctrl:1
	v_add_f32_dpp v168, v168, v168 quad_perm:[1,0,3,2] row_mask:0xf bank_mask:0xf bound_ctrl:1
	v_mfma_scale_f32_16x16x128_f8f6f4 v[180:183], v[44:47], v[128:135], v[180:183], v240, v242 op_sel_hi:[0,0,0] cbsz:4
	v_add_f32_dpp v172, v172, v172 quad_perm:[1,0,3,2] row_mask:0xf bank_mask:0xf bound_ctrl:1
	v_add_f32_dpp v160, v160, v160 quad_perm:[2,3,0,1] row_mask:0xf bank_mask:0xf bound_ctrl:1
	v_add_f32_dpp v164, v164, v164 quad_perm:[2,3,0,1] row_mask:0xf bank_mask:0xf bound_ctrl:1
	v_mfma_scale_f32_16x16x128_f8f6f4 v[184:187], v[52:55], v[128:135], v[184:187], v240, v242 op_sel_hi:[0,0,0] cbsz:4
	v_add_f32_dpp v168, v168, v168 quad_perm:[2,3,0,1] row_mask:0xf bank_mask:0xf bound_ctrl:1
	v_add_f32_dpp v172, v172, v172 quad_perm:[2,3,0,1] row_mask:0xf bank_mask:0xf bound_ctrl:1
	v_cndmask_b32_e64 v160, v160, v164, s[4:5]
	v_mfma_scale_f32_16x16x128_f8f6f4 v[188:191], v[60:63], v[128:135], v[188:191], v240, v242 op_sel_hi:[0,0,0] cbsz:4
	v_cndmask_b32_e64 v160, v160, v168, s[6:7]
	v_cndmask_b32_e64 v160, v160, v172, s[8:9]
	v_add_f32_e32 v216, v216, v160
	s_add_u32 s80, s62, 0x0
	buffer_load_dwordx4 v[128:131], v238, s[12:15], s80 offen nt
	buffer_load_dwordx4 v[132:135], v239, s[12:15], s80 offen nt
	s_waitcnt lgkmcnt(0)
	v_lshl_or_b32 v144, v144, 7, v236
	v_lshl_or_b32 v145, v145, 7, v236
	v_lshl_or_b32 v146, v146, 7, v236
	v_lshl_or_b32 v147, v147, 7, v236
	v_lshl_or_b32 v148, v148, 7, v236
	v_lshl_or_b32 v149, v149, 7, v236
	v_lshl_or_b32 v150, v150, 7, v236
	v_lshl_or_b32 v151, v151, 7, v236
	buffer_load_dwordx4 v[32:35], v144, s[16:19], s60 offen
	buffer_load_dwordx4 v[36:39], v145, s[16:19], s60 offen
	buffer_load_dwordx4 v[40:43], v146, s[16:19], s60 offen
	buffer_load_dwordx4 v[44:47], v147, s[16:19], s60 offen
	buffer_load_dwordx4 v[48:51], v148, s[16:19], s60 offen
	buffer_load_dwordx4 v[52:55], v149, s[16:19], s60 offen
	buffer_load_dwordx4 v[56:59], v150, s[16:19], s60 offen
	buffer_load_dwordx4 v[60:63], v151, s[16:19], s60 offen
	ds_read_b32 v144, v237 offset:512
	ds_read_b32 v145, v237 offset:544
	ds_read_b32 v146, v237 offset:576
	ds_read_b32 v147, v237 offset:608
	ds_read_b32 v148, v237 offset:640
	ds_read_b32 v149, v237 offset:672
	ds_read_b32 v150, v237 offset:704
	ds_read_b32 v151, v237 offset:736
	s_waitcnt vmcnt(26)
	v_mfma_scale_f32_16x16x128_f8f6f4 v[160:163], v[64:67], v[136:143], 0, v240, v241 op_sel_hi:[0,0,0] cbsz:4
	v_cndmask_b32_e64 v176, v176, v177, s[4:5]
	v_cndmask_b32_e64 v180, v180, v181, s[4:5]
	v_cndmask_b32_e64 v184, v184, v185, s[4:5]
	v_mfma_scale_f32_16x16x128_f8f6f4 v[164:167], v[72:75], v[136:143], 0, v240, v241 op_sel_hi:[0,0,0] cbsz:4
	v_cndmask_b32_e64 v188, v188, v189, s[4:5]
	v_cndmask_b32_e64 v176, v176, v178, s[6:7]
	v_cndmask_b32_e64 v180, v180, v182, s[6:7]
	v_mfma_scale_f32_16x16x128_f8f6f4 v[168:171], v[80:83], v[136:143], 0, v240, v241 op_sel_hi:[0,0,0] cbsz:4
	v_cndmask_b32_e64 v184, v184, v186, s[6:7]
	v_cndmask_b32_e64 v188, v188, v190, s[6:7]
	v_cndmask_b32_e64 v176, v176, v179, s[8:9]
	v_mfma_scale_f32_16x16x128_f8f6f4 v[172:175], v[88:91], v[136:143], 0, v240, v241 op_sel_hi:[0,0,0] cbsz:4
	v_cndmask_b32_e64 v180, v180, v183, s[8:9]
	v_cndmask_b32_e64 v184, v184, v187, s[8:9]
	v_cndmask_b32_e64 v188, v188, v191, s[8:9]
	v_mfma_scale_f32_16x16x128_f8f6f4 v[160:163], v[68:71], v[136:143], v[160:163], v240, v242 op_sel_hi:[0,0,0] cbsz:4
	v_add_f32_dpp v176, v176, v176 quad_perm:[1,0,3,2] row_mask:0xf bank_mask:0xf bound_ctrl:1
	v_add_f32_dpp v180, v180, v180 quad_perm:[1,0,3,2] row_mask:0xf bank_mask:0xf bound_ctrl:1
	v_add_f32_dpp v184, v184, v184 quad_perm:[1,0,3,2] row_mask:0xf bank_mask:0xf bound_ctrl:1
	v_mfma_scale_f32_16x16x128_f8f6f4 v[164:167], v[76:79], v[136:143], v[164:167], v240, v242 op_sel_hi:[0,0,0] cbsz:4
	v_add_f32_dpp v188, v188, v188 quad_perm:[1,0,3,2] row_mask:0xf bank_mask:0xf bound_ctrl:1
	v_add_f32_dpp v176, v176, v176 quad_perm:[2,3,0,1] row_mask:0xf bank_mask:0xf bound_ctrl:1
	v_add_f32_dpp v180, v180, v180 quad_perm:[2,3,0,1] row_mask:0xf bank_mask:0xf bound_ctrl:1
	v_mfma_scale_f32_16x16x128_f8f6f4 v[168:171], v[84:87], v[136:143], v[168:171], v240, v242 op_sel_hi:[0,0,0] cbsz:4
	v_add_f32_dpp v184, v184, v184 quad_perm:[2,3,0,1] row_mask:0xf bank_mask:0xf bound_ctrl:1
	v_add_f32_dpp v188, v188, v188 quad_perm:[2,3,0,1] row_mask:0xf bank_mask:0xf bound_ctrl:1
	v_cndmask_b32_e64 v176, v176, v180, s[4:5]
	v_mfma_scale_f32_16x16x128_f8f6f4 v[172:175], v[92:95], v[136:143], v[172:175], v240, v242 op_sel_hi:[0,0,0] cbsz:4
	v_cndmask_b32_e64 v176, v176, v184, s[6:7]
	v_cndmask_b32_e64 v176, v176, v188, s[8:9]
	v_add_f32_e32 v217, v217, v176
	s_waitcnt lgkmcnt(0)
	v_lshl_or_b32 v144, v144, 7, v236
	v_lshl_or_b32 v145, v145, 7, v236
	v_lshl_or_b32 v146, v146, 7, v236
	v_lshl_or_b32 v147, v147, 7, v236
	v_lshl_or_b32 v148, v148, 7, v236
	v_lshl_or_b32 v149, v149, 7, v236
	v_lshl_or_b32 v150, v150, 7, v236
	v_lshl_or_b32 v151, v151, 7, v236
	buffer_load_dwordx4 v[64:67], v144, s[16:19], s60 offen
	buffer_load_dwordx4 v[68:71], v145, s[16:19], s60 offen
	buffer_load_dwordx4 v[72:75], v146, s[16:19], s60 offen
	buffer_load_dwordx4 v[76:79], v147, s[16:19], s60 offen
	buffer_load_dwordx4 v[80:83], v148, s[16:19], s60 offen
	buffer_load_dwordx4 v[84:87], v149, s[16:19], s60 offen
	buffer_load_dwordx4 v[88:91], v150, s[16:19], s60 offen
	buffer_load_dwordx4 v[92:95], v151, s[16:19], s60 offen
	ds_read_b32 v144, v237 offset:768
	ds_read_b32 v145, v237 offset:800
	ds_read_b32 v146, v237 offset:832
	ds_read_b32 v147, v237 offset:864
	ds_read_b32 v148, v237 offset:896
	ds_read_b32 v149, v237 offset:928
	ds_read_b32 v150, v237 offset:960
	ds_read_b32 v151, v237 offset:992
	s_waitcnt vmcnt(26)
	v_mfma_scale_f32_16x16x128_f8f6f4 v[176:179], v[96:99], v[136:143], 0, v240, v241 op_sel_hi:[0,0,0] cbsz:4
	v_cndmask_b32_e64 v160, v160, v161, s[4:5]
	v_cndmask_b32_e64 v164, v164, v165, s[4:5]
	v_cndmask_b32_e64 v168, v168, v169, s[4:5]
	v_mfma_scale_f32_16x16x128_f8f6f4 v[180:183], v[104:107], v[136:143], 0, v240, v241 op_sel_hi:[0,0,0] cbsz:4
	v_cndmask_b32_e64 v172, v172, v173, s[4:5]
	v_cndmask_b32_e64 v160, v160, v162, s[6:7]
	v_cndmask_b32_e64 v164, v164, v166, s[6:7]
	v_mfma_scale_f32_16x16x128_f8f6f4 v[184:187], v[112:115], v[136:143], 0, v240, v241 op_sel_hi:[0,0,0] cbsz:4
	v_cndmask_b32_e64 v168, v168, v170, s[6:7]
	v_cndmask_b32_e64 v172, v172, v174, s[6:7]
	v_cndmask_b32_e64 v160, v160, v163, s[8:9]
	v_mfma_scale_f32_16x16x128_f8f6f4 v[188:191], v[120:123], v[136:143], 0, v240, v241 op_sel_hi:[0,0,0] cbsz:4
	v_cndmask_b32_e64 v164, v164, v167, s[8:9]
	v_cndmask_b32_e64 v168, v168, v171, s[8:9]
	v_cndmask_b32_e64 v172, v172, v175, s[8:9]
	v_mfma_scale_f32_16x16x128_f8f6f4 v[176:179], v[100:103], v[136:143], v[176:179], v240, v242 op_sel_hi:[0,0,0] cbsz:4
	v_add_f32_dpp v160, v160, v160 quad_perm:[1,0,3,2] row_mask:0xf bank_mask:0xf bound_ctrl:1
	v_add_f32_dpp v164, v164, v164 quad_perm:[1,0,3,2] row_mask:0xf bank_mask:0xf bound_ctrl:1
	v_add_f32_dpp v168, v168, v168 quad_perm:[1,0,3,2] row_mask:0xf bank_mask:0xf bound_ctrl:1
	v_mfma_scale_f32_16x16x128_f8f6f4 v[180:183], v[108:111], v[136:143], v[180:183], v240, v242 op_sel_hi:[0,0,0] cbsz:4
	v_add_f32_dpp v172, v172, v172 quad_perm:[1,0,3,2] row_mask:0xf bank_mask:0xf bound_ctrl:1
	v_add_f32_dpp v160, v160, v160 quad_perm:[2,3,0,1] row_mask:0xf bank_mask:0xf bound_ctrl:1
	v_add_f32_dpp v164, v164, v164 quad_perm:[2,3,0,1] row_mask:0xf bank_mask:0xf bound_ctrl:1
	v_mfma_scale_f32_16x16x128_f8f6f4 v[184:187], v[116:119], v[136:143], v[184:187], v240, v242 op_sel_hi:[0,0,0] cbsz:4
	v_add_f32_dpp v168, v168, v168 quad_perm:[2,3,0,1] row_mask:0xf bank_mask:0xf bound_ctrl:1
	v_add_f32_dpp v172, v172, v172 quad_perm:[2,3,0,1] row_mask:0xf bank_mask:0xf bound_ctrl:1
	v_cndmask_b32_e64 v160, v160, v164, s[4:5]
	v_mfma_scale_f32_16x16x128_f8f6f4 v[188:191], v[124:127], v[136:143], v[188:191], v240, v242 op_sel_hi:[0,0,0] cbsz:4
	v_cndmask_b32_e64 v160, v160, v168, s[6:7]
	v_cndmask_b32_e64 v160, v160, v172, s[8:9]
	v_add_f32_e32 v218, v218, v160
	s_add_u32 s0, s0, 1
	s_lshl_b32 s1, s0, 21
	s_add_u32 s60, s1, 0x200000
	s_add_u32 s61, s61, 0x100
	s_add_u32 s62, s61, 0x100
	s_cmp_eq_u32 s0, 4
	s_cbranch_scc0 .LpgL0_unoflushu0
	s_nop 15
	v_cndmask_b32_e64 v176, v176, v177, s[4:5]
	v_cndmask_b32_e64 v180, v180, v181, s[4:5]
	v_cndmask_b32_e64 v184, v184, v185, s[4:5]
	v_cndmask_b32_e64 v188, v188, v189, s[4:5]
	v_cndmask_b32_e64 v176, v176, v178, s[6:7]
	v_cndmask_b32_e64 v180, v180, v182, s[6:7]
	v_cndmask_b32_e64 v184, v184, v186, s[6:7]
	v_cndmask_b32_e64 v188, v188, v190, s[6:7]
	v_cndmask_b32_e64 v176, v176, v179, s[8:9]
	v_cndmask_b32_e64 v180, v180, v183, s[8:9]
	v_cndmask_b32_e64 v184, v184, v187, s[8:9]
	v_cndmask_b32_e64 v188, v188, v191, s[8:9]
	v_add_f32_dpp v176, v176, v176 quad_perm:[1,0,3,2] row_mask:0xf bank_mask:0xf bound_ctrl:1
	v_add_f32_dpp v180, v180, v180 quad_perm:[1,0,3,2] row_mask:0xf bank_mask:0xf bound_ctrl:1
	v_add_f32_dpp v184, v184, v184 quad_perm:[1,0,3,2] row_mask:0xf bank_mask:0xf bound_ctrl:1
	v_add_f32_dpp v188, v188, v188 quad_perm:[1,0,3,2] row_mask:0xf bank_mask:0xf bound_ctrl:1
	v_add_f32_dpp v176, v176, v176 quad_perm:[2,3,0,1] row_mask:0xf bank_mask:0xf bound_ctrl:1
	v_add_f32_dpp v180, v180, v180 quad_perm:[2,3,0,1] row_mask:0xf bank_mask:0xf bound_ctrl:1
	v_add_f32_dpp v184, v184, v184 quad_perm:[2,3,0,1] row_mask:0xf bank_mask:0xf bound_ctrl:1
	v_add_f32_dpp v188, v188, v188 quad_perm:[2,3,0,1] row_mask:0xf bank_mask:0xf bound_ctrl:1
	v_cndmask_b32_e64 v176, v176, v180, s[4:5]
	v_cndmask_b32_e64 v176, v176, v184, s[6:7]
	v_cndmask_b32_e64 v176, v176, v188, s[8:9]
	v_add_f32_e32 v219, v219, v176
	v_mov_b32_e32 v220, v204
	v_mov_b32_e32 v221, v205
	v_mov_b32_e32 v222, v206
	v_mov_b32_e32 v223, v207
	v_mov_b32_e32 v224, v208
	v_mov_b32_e32 v225, v209
	v_mov_b32_e32 v226, v210
	v_mov_b32_e32 v227, v211
	v_mov_b32_e32 v228, v212
	v_mov_b32_e32 v229, v213
	v_mov_b32_e32 v230, v214
	v_mov_b32_e32 v231, v215
	v_mov_b32_e32 v232, v216
	v_mov_b32_e32 v233, v217
	v_mov_b32_e32 v234, v218
	v_mov_b32_e32 v235, v219
	v_mov_b32_e32 v204, 0
	v_mov_b32_e32 v205, 0
	v_mov_b32_e32 v206, 0
	v_mov_b32_e32 v207, 0
	v_mov_b32_e32 v208, 0
	v_mov_b32_e32 v209, 0
	v_mov_b32_e32 v210, 0
	v_mov_b32_e32 v211, 0
	v_mov_b32_e32 v212, 0
	v_mov_b32_e32 v213, 0
	v_mov_b32_e32 v214, 0
	v_mov_b32_e32 v215, 0
	v_mov_b32_e32 v216, 0
	v_mov_b32_e32 v217, 0
	v_mov_b32_e32 v218, 0
	v_mov_b32_e32 v219, 0
	v_mov_b32_e32 v176, 0
	v_mov_b32_e32 v177, 0
	v_mov_b32_e32 v178, 0
	v_mov_b32_e32 v179, 0
	v_mov_b32_e32 v180, 0
	v_mov_b32_e32 v181, 0
	v_mov_b32_e32 v182, 0
	v_mov_b32_e32 v183, 0
	v_mov_b32_e32 v184, 0
	v_mov_b32_e32 v185, 0
	v_mov_b32_e32 v186, 0
	v_mov_b32_e32 v187, 0
	v_mov_b32_e32 v188, 0
	v_mov_b32_e32 v189, 0
	v_mov_b32_e32 v190, 0
	v_mov_b32_e32 v191, 0
.LpgL0_unoflushu0:
	s_cmp_lt_u32 s0, 8
	s_cbranch_scc1 .LpgL0_uloopu0
	s_waitcnt vmcnt(0)
	s_nop 15
	v_cndmask_b32_e64 v176, v176, v177, s[4:5]
	v_cndmask_b32_e64 v180, v180, v181, s[4:5]
	v_cndmask_b32_e64 v184, v184, v185, s[4:5]
	v_cndmask_b32_e64 v188, v188, v189, s[4:5]
	v_cndmask_b32_e64 v176, v176, v178, s[6:7]
	v_cndmask_b32_e64 v180, v180, v182, s[6:7]
	v_cndmask_b32_e64 v184, v184, v186, s[6:7]
	v_cndmask_b32_e64 v188, v188, v190, s[6:7]
	v_cndmask_b32_e64 v176, v176, v179, s[8:9]
	v_cndmask_b32_e64 v180, v180, v183, s[8:9]
	v_cndmask_b32_e64 v184, v184, v187, s[8:9]
	v_cndmask_b32_e64 v188, v188, v191, s[8:9]
	v_add_f32_dpp v176, v176, v176 quad_perm:[1,0,3,2] row_mask:0xf bank_mask:0xf bound_ctrl:1
	v_add_f32_dpp v180, v180, v180 quad_perm:[1,0,3,2] row_mask:0xf bank_mask:0xf bound_ctrl:1
	v_add_f32_dpp v184, v184, v184 quad_perm:[1,0,3,2] row_mask:0xf bank_mask:0xf bound_ctrl:1
	v_add_f32_dpp v188, v188, v188 quad_perm:[1,0,3,2] row_mask:0xf bank_mask:0xf bound_ctrl:1
	v_add_f32_dpp v176, v176, v176 quad_perm:[2,3,0,1] row_mask:0xf bank_mask:0xf bound_ctrl:1
	v_add_f32_dpp v180, v180, v180 quad_perm:[2,3,0,1] row_mask:0xf bank_mask:0xf bound_ctrl:1
	v_add_f32_dpp v184, v184, v184 quad_perm:[2,3,0,1] row_mask:0xf bank_mask:0xf bound_ctrl:1
	v_add_f32_dpp v188, v188, v188 quad_perm:[2,3,0,1] row_mask:0xf bank_mask:0xf bound_ctrl:1
	v_cndmask_b32_e64 v176, v176, v180, s[4:5]
	v_cndmask_b32_e64 v176, v176, v184, s[6:7]
	v_cndmask_b32_e64 v176, v176, v188, s[8:9]
	v_add_f32_e32 v219, v219, v176
	ds_read_b32 v0, v243 offset:0
	ds_read_b32 v1, v243 offset:256
	ds_read_b32 v2, v243 offset:512
	ds_read_b32 v3, v243 offset:768
	ds_read_b32 v4, v243 offset:1024
	ds_read_b32 v5, v243 offset:1280
	ds_read_b32 v6, v243 offset:1536
	ds_read_b32 v7, v243 offset:1792
	ds_read_b32 v8, v243 offset:2048
	ds_read_b32 v9, v243 offset:2304
	ds_read_b32 v10, v243 offset:2560
	ds_read_b32 v11, v243 offset:2816
	ds_read_b32 v12, v243 offset:3072
	ds_read_b32 v13, v243 offset:3328
	ds_read_b32 v14, v243 offset:3584
	ds_read_b32 v15, v243 offset:3840
	global_load_dword v96, v246, s[40:41] offset:0
	global_load_dword v97, v246, s[40:41] offset:4
	global_load_dword v98, v246, s[40:41] offset:8
	global_load_dword v99, v246, s[40:41] offset:12
	global_load_dword v100, v246, s[40:41] offset:16
	global_load_dword v101, v246, s[40:41] offset:20
	global_load_dword v102, v246, s[40:41] offset:24
	global_load_dword v103, v246, s[40:41] offset:28
	global_load_dword v16, v244, s[26:27] offset:0 nt
	global_load_dword v17, v244, s[26:27] offset:256 nt
	global_load_dword v18, v244, s[26:27] offset:512 nt
	global_load_dword v19, v244, s[26:27] offset:768 nt
	global_load_dword v20, v244, s[26:27] offset:1024 nt
	global_load_dword v21, v244, s[26:27] offset:1280 nt
	global_load_dword v22, v244, s[26:27] offset:1536 nt
	global_load_dword v23, v244, s[26:27] offset:1792 nt
	global_load_dword v24, v244, s[26:27] offset:2048 nt
	global_load_dword v25, v244, s[26:27] offset:2304 nt
	global_load_dword v26, v244, s[26:27] offset:2560 nt
	global_load_dword v27, v244, s[26:27] offset:2816 nt
	global_load_dword v28, v244, s[26:27] offset:3072 nt
	global_load_dword v29, v244, s[26:27] offset:3328 nt
	global_load_dword v30, v244, s[26:27] offset:3584 nt
	global_load_dword v31, v244, s[26:27] offset:3840 nt
	s_waitcnt lgkmcnt(0)
	v_lshlrev_b32_e32 v0, 3, v0
	global_load_dwordx2 v[32:33], v0, s[30:31]
	global_load_dwordx2 v[64:65], v0, s[34:35]
	v_lshlrev_b32_e32 v1, 3, v1
	global_load_dwordx2 v[34:35], v1, s[30:31]
	global_load_dwordx2 v[66:67], v1, s[34:35]
	v_lshlrev_b32_e32 v2, 3, v2
	global_load_dwordx2 v[36:37], v2, s[30:31]
	global_load_dwordx2 v[68:69], v2, s[34:35]
	v_lshlrev_b32_e32 v3, 3, v3
	global_load_dwordx2 v[38:39], v3, s[30:31]
	global_load_dwordx2 v[70:71], v3, s[34:35]
	v_lshlrev_b32_e32 v4, 3, v4
	global_load_dwordx2 v[40:41], v4, s[30:31]
	global_load_dwordx2 v[72:73], v4, s[34:35]
	v_lshlrev_b32_e32 v5, 3, v5
	global_load_dwordx2 v[42:43], v5, s[30:31]
	global_load_dwordx2 v[74:75], v5, s[34:35]
	v_lshlrev_b32_e32 v6, 3, v6
	global_load_dwordx2 v[44:45], v6, s[30:31]
	global_load_dwordx2 v[76:77], v6, s[34:35]
	v_lshlrev_b32_e32 v7, 3, v7
	global_load_dwordx2 v[46:47], v7, s[30:31]
	global_load_dwordx2 v[78:79], v7, s[34:35]
	v_lshlrev_b32_e32 v8, 3, v8
	global_load_dwordx2 v[48:49], v8, s[30:31]
	global_load_dwordx2 v[80:81], v8, s[34:35]
	v_lshlrev_b32_e32 v9, 3, v9
	global_load_dwordx2 v[50:51], v9, s[30:31]
	global_load_dwordx2 v[82:83], v9, s[34:35]
	v_lshlrev_b32_e32 v10, 3, v10
	global_load_dwordx2 v[52:53], v10, s[30:31]
	global_load_dwordx2 v[84:85], v10, s[34:35]
	v_lshlrev_b32_e32 v11, 3, v11
	global_load_dwordx2 v[54:55], v11, s[30:31]
	global_load_dwordx2 v[86:87], v11, s[34:35]
	v_lshlrev_b32_e32 v12, 3, v12
	global_load_dwordx2 v[56:57], v12, s[30:31]
	global_load_dwordx2 v[88:89], v12, s[34:35]
	v_lshlrev_b32_e32 v13, 3, v13
	global_load_dwordx2 v[58:59], v13, s[30:31]
	global_load_dwordx2 v[90:91], v13, s[34:35]
	v_lshlrev_b32_e32 v14, 3, v14
	global_load_dwordx2 v[60:61], v14, s[30:31]
	global_load_dwordx2 v[92:93], v14, s[34:35]
	v_lshlrev_b32_e32 v15, 3, v15
	global_load_dwordx2 v[62:63], v15, s[30:31]
	global_load_dwordx2 v[94:95], v15, s[34:35]
	s_waitcnt vmcnt(0)
	v_mov_b32_e32 v120, 0x358637bd
	v_fmamk_f32 v96, v96, 0x3a000000, v120
	v_cmp_gt_f32_e32 vcc, s96, v96
	v_mul_f32_e32 v121, 0x4b800000, v96
	s_nop 0
	v_cndmask_b32_e32 v96, v96, v121, vcc
	v_rsq_f32_e32 v96, v96
	s_nop 0
	v_mul_f32_e32 v121, 0x45800000, v96
	v_cndmask_b32_e32 v96, v96, v121, vcc
	v_fmamk_f32 v97, v97, 0x3a000000, v120
	v_cmp_gt_f32_e32 vcc, s96, v97
	v_mul_f32_e32 v121, 0x4b800000, v97
	s_nop 0
	v_cndmask_b32_e32 v97, v97, v121, vcc
	v_rsq_f32_e32 v97, v97
	s_nop 0
	v_mul_f32_e32 v121, 0x45800000, v97
	v_cndmask_b32_e32 v97, v97, v121, vcc
	v_fmamk_f32 v98, v98, 0x3a000000, v120
	v_cmp_gt_f32_e32 vcc, s96, v98
	v_mul_f32_e32 v121, 0x4b800000, v98
	s_nop 0
	v_cndmask_b32_e32 v98, v98, v121, vcc
	v_rsq_f32_e32 v98, v98
	s_nop 0
	v_mul_f32_e32 v121, 0x45800000, v98
	v_cndmask_b32_e32 v98, v98, v121, vcc
	v_fmamk_f32 v99, v99, 0x3a000000, v120
	v_cmp_gt_f32_e32 vcc, s96, v99
	v_mul_f32_e32 v121, 0x4b800000, v99
	s_nop 0
	v_cndmask_b32_e32 v99, v99, v121, vcc
	v_rsq_f32_e32 v99, v99
	s_nop 0
	v_mul_f32_e32 v121, 0x45800000, v99
	v_cndmask_b32_e32 v99, v99, v121, vcc
	v_fmamk_f32 v100, v100, 0x3a000000, v120
	v_cmp_gt_f32_e32 vcc, s96, v100
	v_mul_f32_e32 v121, 0x4b800000, v100
	s_nop 0
	v_cndmask_b32_e32 v100, v100, v121, vcc
	v_rsq_f32_e32 v100, v100
	s_nop 0
	v_mul_f32_e32 v121, 0x45800000, v100
	v_cndmask_b32_e32 v100, v100, v121, vcc
	v_fmamk_f32 v101, v101, 0x3a000000, v120
	v_cmp_gt_f32_e32 vcc, s96, v101
	v_mul_f32_e32 v121, 0x4b800000, v101
	s_nop 0
	v_cndmask_b32_e32 v101, v101, v121, vcc
	v_rsq_f32_e32 v101, v101
	s_nop 0
	v_mul_f32_e32 v121, 0x45800000, v101
	v_cndmask_b32_e32 v101, v101, v121, vcc
	v_fmamk_f32 v102, v102, 0x3a000000, v120
	v_cmp_gt_f32_e32 vcc, s96, v102
	v_mul_f32_e32 v121, 0x4b800000, v102
	s_nop 0
	v_cndmask_b32_e32 v102, v102, v121, vcc
	v_rsq_f32_e32 v102, v102
	s_nop 0
	v_mul_f32_e32 v121, 0x45800000, v102
	v_cndmask_b32_e32 v102, v102, v121, vcc
	v_fmamk_f32 v103, v103, 0x3a000000, v120
	v_cmp_gt_f32_e32 vcc, s96, v103
	v_mul_f32_e32 v121, 0x4b800000, v103
	s_nop 0
	v_cndmask_b32_e32 v103, v103, v121, vcc
	v_rsq_f32_e32 v103, v103
	s_nop 0
	v_mul_f32_e32 v121, 0x45800000, v103
	v_cndmask_b32_e32 v103, v103, v121, vcc
	v_mul_f32_e32 v104, v220, v32
	v_fmac_f32_e32 v104, v204, v33
	v_mul_f32_e32 v104, v104, v96
	v_mul_f32_e32 v105, 0x3d372713, v104
	v_mul_f32_e32 v105, v104, v105
	v_fma_f32 v105, v104, v105, v104
	v_mul_f32_e32 v105, 0x3f4c422a, v105
	v_add_f32_e32 v105, v105, v105
	v_mul_f32_e32 v105, 0x3fb8aa3b, v105
	v_exp_f32_e32 v105, v105
	v_mul_f32_e32 v104, 0.5, v104
	v_add_f32_e32 v105, 1.0, v105
	v_div_scale_f32 v106, s[70:71], v105, v105, 2.0
	v_rcp_f32_e32 v107, v106
	s_nop 0
	v_fma_f32 v108, -v106, v107, 1.0
	v_fmac_f32_e32 v107, v108, v107
	v_div_scale_f32 v108, vcc, 2.0, v105, 2.0
	v_mul_f32_e32 v109, v108, v107
	v_fma_f32 v110, -v106, v109, v108
	v_fmac_f32_e32 v109, v110, v107
	v_fma_f32 v106, -v106, v109, v108
	v_div_fmas_f32 v106, v106, v107, v109
	v_div_fixup_f32 v105, v106, v105, 2.0
	v_sub_f32_e32 v105, 1.0, v105
	v_add_f32_e32 v105, 1.0, v105
	v_mul_f32_e32 v104, v104, v105
	v_mul_f32_e32 v104, v16, v104
	v_mul_f32_e32 v105, v64, v104
	v_mul_f32_e32 v105, 0x43800000, v105
	v_mov_b32_e32 v106, 0x43e00000
	v_med3_f32 v105, v105, s94, v106
	v_mov_b32_e32 v106, 0
	v_cvt_pk_fp8_f32 v106, v105, 0
	s_nop 0
	v_and_b32_e32 v106, 0xff, v106
	v_mul_lo_u32 v106, v106, s81
	ds_write_b32 v245, v106 offset:0
	v_mul_f32_e32 v105, v65, v104
	v_mul_f32_e32 v105, 0x43800000, v105
	v_mov_b32_e32 v106, 0x43e00000
	v_med3_f32 v105, v105, s94, v106
	v_mov_b32_e32 v106, 0
	v_cvt_pk_fp8_f32 v106, v105, 0
	s_nop 0
	v_and_b32_e32 v106, 0xff, v106
	v_mul_lo_u32 v106, v106, s81
	ds_write_b32 v245, v106 offset:4096
	v_mul_f32_e32 v104, v221, v34
	v_fmac_f32_e32 v104, v205, v35
	v_mul_f32_e32 v104, v104, v96
	v_mul_f32_e32 v105, 0x3d372713, v104
	v_mul_f32_e32 v105, v104, v105
	v_fma_f32 v105, v104, v105, v104
	v_mul_f32_e32 v105, 0x3f4c422a, v105
	v_add_f32_e32 v105, v105, v105
	v_mul_f32_e32 v105, 0x3fb8aa3b, v105
	v_exp_f32_e32 v105, v105
	v_mul_f32_e32 v104, 0.5, v104
	v_add_f32_e32 v105, 1.0, v105
	v_div_scale_f32 v106, s[70:71], v105, v105, 2.0
	v_rcp_f32_e32 v107, v106
	s_nop 0
	v_fma_f32 v108, -v106, v107, 1.0
	v_fmac_f32_e32 v107, v108, v107
	v_div_scale_f32 v108, vcc, 2.0, v105, 2.0
	v_mul_f32_e32 v109, v108, v107
	v_fma_f32 v110, -v106, v109, v108
	v_fmac_f32_e32 v109, v110, v107
	v_fma_f32 v106, -v106, v109, v108
	v_div_fmas_f32 v106, v106, v107, v109
	v_div_fixup_f32 v105, v106, v105, 2.0
	v_sub_f32_e32 v105, 1.0, v105
	v_add_f32_e32 v105, 1.0, v105
	v_mul_f32_e32 v104, v104, v105
	v_mul_f32_e32 v104, v17, v104
	v_mul_f32_e32 v105, v66, v104
	v_mul_f32_e32 v105, 0x43800000, v105
	v_mov_b32_e32 v106, 0x43e00000
	v_med3_f32 v105, v105, s94, v106
	v_mov_b32_e32 v106, 0
	v_cvt_pk_fp8_f32 v106, v105, 0
	s_nop 0
	v_and_b32_e32 v106, 0xff, v106
	v_mul_lo_u32 v106, v106, s81
	ds_write_b32 v245, v106 offset:256
	v_mul_f32_e32 v105, v67, v104
	v_mul_f32_e32 v105, 0x43800000, v105
	v_mov_b32_e32 v106, 0x43e00000
	v_med3_f32 v105, v105, s94, v106
	v_mov_b32_e32 v106, 0
	v_cvt_pk_fp8_f32 v106, v105, 0
	s_nop 0
	v_and_b32_e32 v106, 0xff, v106
	v_mul_lo_u32 v106, v106, s81
	ds_write_b32 v245, v106 offset:4352
	v_mul_f32_e32 v104, v222, v36
	v_fmac_f32_e32 v104, v206, v37
	v_mul_f32_e32 v104, v104, v97
	v_mul_f32_e32 v105, 0x3d372713, v104
	v_mul_f32_e32 v105, v104, v105
	v_fma_f32 v105, v104, v105, v104
	v_mul_f32_e32 v105, 0x3f4c422a, v105
	v_add_f32_e32 v105, v105, v105
	v_mul_f32_e32 v105, 0x3fb8aa3b, v105
	v_exp_f32_e32 v105, v105
	v_mul_f32_e32 v104, 0.5, v104
	v_add_f32_e32 v105, 1.0, v105
	v_div_scale_f32 v106, s[70:71], v105, v105, 2.0
	v_rcp_f32_e32 v107, v106
	s_nop 0
	v_fma_f32 v108, -v106, v107, 1.0
	v_fmac_f32_e32 v107, v108, v107
	v_div_scale_f32 v108, vcc, 2.0, v105, 2.0
	v_mul_f32_e32 v109, v108, v107
	v_fma_f32 v110, -v106, v109, v108
	v_fmac_f32_e32 v109, v110, v107
	v_fma_f32 v106, -v106, v109, v108
	v_div_fmas_f32 v106, v106, v107, v109
	v_div_fixup_f32 v105, v106, v105, 2.0
	v_sub_f32_e32 v105, 1.0, v105
	v_add_f32_e32 v105, 1.0, v105
	v_mul_f32_e32 v104, v104, v105
	v_mul_f32_e32 v104, v18, v104
	v_mul_f32_e32 v105, v68, v104
	v_mul_f32_e32 v105, 0x43800000, v105
	v_mov_b32_e32 v106, 0x43e00000
	v_med3_f32 v105, v105, s94, v106
	v_mov_b32_e32 v106, 0
	v_cvt_pk_fp8_f32 v106, v105, 0
	s_nop 0
	v_and_b32_e32 v106, 0xff, v106
	v_mul_lo_u32 v106, v106, s81
	ds_write_b32 v245, v106 offset:512
	v_mul_f32_e32 v105, v69, v104
	v_mul_f32_e32 v105, 0x43800000, v105
	v_mov_b32_e32 v106, 0x43e00000
	v_med3_f32 v105, v105, s94, v106
	v_mov_b32_e32 v106, 0
	v_cvt_pk_fp8_f32 v106, v105, 0
	s_nop 0
	v_and_b32_e32 v106, 0xff, v106
	v_mul_lo_u32 v106, v106, s81
	ds_write_b32 v245, v106 offset:4608
	v_mul_f32_e32 v104, v223, v38
	v_fmac_f32_e32 v104, v207, v39
	v_mul_f32_e32 v104, v104, v97
	v_mul_f32_e32 v105, 0x3d372713, v104
	v_mul_f32_e32 v105, v104, v105
	v_fma_f32 v105, v104, v105, v104
	v_mul_f32_e32 v105, 0x3f4c422a, v105
	v_add_f32_e32 v105, v105, v105
	v_mul_f32_e32 v105, 0x3fb8aa3b, v105
	v_exp_f32_e32 v105, v105
	v_mul_f32_e32 v104, 0.5, v104
	v_add_f32_e32 v105, 1.0, v105
	v_div_scale_f32 v106, s[70:71], v105, v105, 2.0
	v_rcp_f32_e32 v107, v106
	s_nop 0
	v_fma_f32 v108, -v106, v107, 1.0
	v_fmac_f32_e32 v107, v108, v107
	v_div_scale_f32 v108, vcc, 2.0, v105, 2.0
	v_mul_f32_e32 v109, v108, v107
	v_fma_f32 v110, -v106, v109, v108
	v_fmac_f32_e32 v109, v110, v107
	v_fma_f32 v106, -v106, v109, v108
	v_div_fmas_f32 v106, v106, v107, v109
	v_div_fixup_f32 v105, v106, v105, 2.0
	v_sub_f32_e32 v105, 1.0, v105
	v_add_f32_e32 v105, 1.0, v105
	v_mul_f32_e32 v104, v104, v105
	v_mul_f32_e32 v104, v19, v104
	v_mul_f32_e32 v105, v70, v104
	v_mul_f32_e32 v105, 0x43800000, v105
	v_mov_b32_e32 v106, 0x43e00000
	v_med3_f32 v105, v105, s94, v106
	v_mov_b32_e32 v106, 0
	v_cvt_pk_fp8_f32 v106, v105, 0
	s_nop 0
	v_and_b32_e32 v106, 0xff, v106
	v_mul_lo_u32 v106, v106, s81
	ds_write_b32 v245, v106 offset:768
	v_mul_f32_e32 v105, v71, v104
	v_mul_f32_e32 v105, 0x43800000, v105
	v_mov_b32_e32 v106, 0x43e00000
	v_med3_f32 v105, v105, s94, v106
	v_mov_b32_e32 v106, 0
	v_cvt_pk_fp8_f32 v106, v105, 0
	s_nop 0
	v_and_b32_e32 v106, 0xff, v106
	v_mul_lo_u32 v106, v106, s81
	ds_write_b32 v245, v106 offset:4864
	v_mul_f32_e32 v104, v224, v40
	v_fmac_f32_e32 v104, v208, v41
	v_mul_f32_e32 v104, v104, v98
	v_mul_f32_e32 v105, 0x3d372713, v104
	v_mul_f32_e32 v105, v104, v105
	v_fma_f32 v105, v104, v105, v104
	v_mul_f32_e32 v105, 0x3f4c422a, v105
	v_add_f32_e32 v105, v105, v105
	v_mul_f32_e32 v105, 0x3fb8aa3b, v105
	v_exp_f32_e32 v105, v105
	v_mul_f32_e32 v104, 0.5, v104
	v_add_f32_e32 v105, 1.0, v105
	v_div_scale_f32 v106, s[70:71], v105, v105, 2.0
	v_rcp_f32_e32 v107, v106
	s_nop 0
	v_fma_f32 v108, -v106, v107, 1.0
	v_fmac_f32_e32 v107, v108, v107
	v_div_scale_f32 v108, vcc, 2.0, v105, 2.0
	v_mul_f32_e32 v109, v108, v107
	v_fma_f32 v110, -v106, v109, v108
	v_fmac_f32_e32 v109, v110, v107
	v_fma_f32 v106, -v106, v109, v108
	v_div_fmas_f32 v106, v106, v107, v109
	v_div_fixup_f32 v105, v106, v105, 2.0
	v_sub_f32_e32 v105, 1.0, v105
	v_add_f32_e32 v105, 1.0, v105
	v_mul_f32_e32 v104, v104, v105
	v_mul_f32_e32 v104, v20, v104
	v_mul_f32_e32 v105, v72, v104
	v_mul_f32_e32 v105, 0x43800000, v105
	v_mov_b32_e32 v106, 0x43e00000
	v_med3_f32 v105, v105, s94, v106
	v_mov_b32_e32 v106, 0
	v_cvt_pk_fp8_f32 v106, v105, 0
	s_nop 0
	v_and_b32_e32 v106, 0xff, v106
	v_mul_lo_u32 v106, v106, s81
	ds_write_b32 v245, v106 offset:1024
	v_mul_f32_e32 v105, v73, v104
	v_mul_f32_e32 v105, 0x43800000, v105
	v_mov_b32_e32 v106, 0x43e00000
	v_med3_f32 v105, v105, s94, v106
	v_mov_b32_e32 v106, 0
	v_cvt_pk_fp8_f32 v106, v105, 0
	s_nop 0
	v_and_b32_e32 v106, 0xff, v106
	v_mul_lo_u32 v106, v106, s81
	ds_write_b32 v245, v106 offset:5120
	v_mul_f32_e32 v104, v225, v42
	v_fmac_f32_e32 v104, v209, v43
	v_mul_f32_e32 v104, v104, v98
	v_mul_f32_e32 v105, 0x3d372713, v104
	v_mul_f32_e32 v105, v104, v105
	v_fma_f32 v105, v104, v105, v104
	v_mul_f32_e32 v105, 0x3f4c422a, v105
	v_add_f32_e32 v105, v105, v105
	v_mul_f32_e32 v105, 0x3fb8aa3b, v105
	v_exp_f32_e32 v105, v105
	v_mul_f32_e32 v104, 0.5, v104
	v_add_f32_e32 v105, 1.0, v105
	v_div_scale_f32 v106, s[70:71], v105, v105, 2.0
	v_rcp_f32_e32 v107, v106
	s_nop 0
	v_fma_f32 v108, -v106, v107, 1.0
	v_fmac_f32_e32 v107, v108, v107
	v_div_scale_f32 v108, vcc, 2.0, v105, 2.0
	v_mul_f32_e32 v109, v108, v107
	v_fma_f32 v110, -v106, v109, v108
	v_fmac_f32_e32 v109, v110, v107
	v_fma_f32 v106, -v106, v109, v108
	v_div_fmas_f32 v106, v106, v107, v109
	v_div_fixup_f32 v105, v106, v105, 2.0
	v_sub_f32_e32 v105, 1.0, v105
	v_add_f32_e32 v105, 1.0, v105
	v_mul_f32_e32 v104, v104, v105
	v_mul_f32_e32 v104, v21, v104
	v_mul_f32_e32 v105, v74, v104
	v_mul_f32_e32 v105, 0x43800000, v105
	v_mov_b32_e32 v106, 0x43e00000
	v_med3_f32 v105, v105, s94, v106
	v_mov_b32_e32 v106, 0
	v_cvt_pk_fp8_f32 v106, v105, 0
	s_nop 0
	v_and_b32_e32 v106, 0xff, v106
	v_mul_lo_u32 v106, v106, s81
	ds_write_b32 v245, v106 offset:1280
	v_mul_f32_e32 v105, v75, v104
	v_mul_f32_e32 v105, 0x43800000, v105
	v_mov_b32_e32 v106, 0x43e00000
	v_med3_f32 v105, v105, s94, v106
	v_mov_b32_e32 v106, 0
	v_cvt_pk_fp8_f32 v106, v105, 0
	s_nop 0
	v_and_b32_e32 v106, 0xff, v106
	v_mul_lo_u32 v106, v106, s81
	ds_write_b32 v245, v106 offset:5376
	v_mul_f32_e32 v104, v226, v44
	v_fmac_f32_e32 v104, v210, v45
	v_mul_f32_e32 v104, v104, v99
	v_mul_f32_e32 v105, 0x3d372713, v104
	v_mul_f32_e32 v105, v104, v105
	v_fma_f32 v105, v104, v105, v104
	v_mul_f32_e32 v105, 0x3f4c422a, v105
	v_add_f32_e32 v105, v105, v105
	v_mul_f32_e32 v105, 0x3fb8aa3b, v105
	v_exp_f32_e32 v105, v105
	v_mul_f32_e32 v104, 0.5, v104
	v_add_f32_e32 v105, 1.0, v105
	v_div_scale_f32 v106, s[70:71], v105, v105, 2.0
	v_rcp_f32_e32 v107, v106
	s_nop 0
	v_fma_f32 v108, -v106, v107, 1.0
	v_fmac_f32_e32 v107, v108, v107
	v_div_scale_f32 v108, vcc, 2.0, v105, 2.0
	v_mul_f32_e32 v109, v108, v107
	v_fma_f32 v110, -v106, v109, v108
	v_fmac_f32_e32 v109, v110, v107
	v_fma_f32 v106, -v106, v109, v108
	v_div_fmas_f32 v106, v106, v107, v109
	v_div_fixup_f32 v105, v106, v105, 2.0
	v_sub_f32_e32 v105, 1.0, v105
	v_add_f32_e32 v105, 1.0, v105
	v_mul_f32_e32 v104, v104, v105
	v_mul_f32_e32 v104, v22, v104
	v_mul_f32_e32 v105, v76, v104
	v_mul_f32_e32 v105, 0x43800000, v105
	v_mov_b32_e32 v106, 0x43e00000
	v_med3_f32 v105, v105, s94, v106
	v_mov_b32_e32 v106, 0
	v_cvt_pk_fp8_f32 v106, v105, 0
	s_nop 0
	v_and_b32_e32 v106, 0xff, v106
	v_mul_lo_u32 v106, v106, s81
	ds_write_b32 v245, v106 offset:1536
	v_mul_f32_e32 v105, v77, v104
	v_mul_f32_e32 v105, 0x43800000, v105
	v_mov_b32_e32 v106, 0x43e00000
	v_med3_f32 v105, v105, s94, v106
	v_mov_b32_e32 v106, 0
	v_cvt_pk_fp8_f32 v106, v105, 0
	s_nop 0
	v_and_b32_e32 v106, 0xff, v106
	v_mul_lo_u32 v106, v106, s81
	ds_write_b32 v245, v106 offset:5632
	v_mul_f32_e32 v104, v227, v46
	v_fmac_f32_e32 v104, v211, v47
	v_mul_f32_e32 v104, v104, v99
	v_mul_f32_e32 v105, 0x3d372713, v104
	v_mul_f32_e32 v105, v104, v105
	v_fma_f32 v105, v104, v105, v104
	v_mul_f32_e32 v105, 0x3f4c422a, v105
	v_add_f32_e32 v105, v105, v105
	v_mul_f32_e32 v105, 0x3fb8aa3b, v105
	v_exp_f32_e32 v105, v105
	v_mul_f32_e32 v104, 0.5, v104
	v_add_f32_e32 v105, 1.0, v105
	v_div_scale_f32 v106, s[70:71], v105, v105, 2.0
	v_rcp_f32_e32 v107, v106
	s_nop 0
	v_fma_f32 v108, -v106, v107, 1.0
	v_fmac_f32_e32 v107, v108, v107
	v_div_scale_f32 v108, vcc, 2.0, v105, 2.0
	v_mul_f32_e32 v109, v108, v107
	v_fma_f32 v110, -v106, v109, v108
	v_fmac_f32_e32 v109, v110, v107
	v_fma_f32 v106, -v106, v109, v108
	v_div_fmas_f32 v106, v106, v107, v109
	v_div_fixup_f32 v105, v106, v105, 2.0
	v_sub_f32_e32 v105, 1.0, v105
	v_add_f32_e32 v105, 1.0, v105
	v_mul_f32_e32 v104, v104, v105
	v_mul_f32_e32 v104, v23, v104
	v_mul_f32_e32 v105, v78, v104
	v_mul_f32_e32 v105, 0x43800000, v105
	v_mov_b32_e32 v106, 0x43e00000
	v_med3_f32 v105, v105, s94, v106
	v_mov_b32_e32 v106, 0
	v_cvt_pk_fp8_f32 v106, v105, 0
	s_nop 0
	v_and_b32_e32 v106, 0xff, v106
	v_mul_lo_u32 v106, v106, s81
	ds_write_b32 v245, v106 offset:1792
	v_mul_f32_e32 v105, v79, v104
	v_mul_f32_e32 v105, 0x43800000, v105
	v_mov_b32_e32 v106, 0x43e00000
	v_med3_f32 v105, v105, s94, v106
	v_mov_b32_e32 v106, 0
	v_cvt_pk_fp8_f32 v106, v105, 0
	s_nop 0
	v_and_b32_e32 v106, 0xff, v106
	v_mul_lo_u32 v106, v106, s81
	ds_write_b32 v245, v106 offset:5888
	v_mul_f32_e32 v104, v228, v48
	v_fmac_f32_e32 v104, v212, v49
	v_mul_f32_e32 v104, v104, v100
	v_mul_f32_e32 v105, 0x3d372713, v104
	v_mul_f32_e32 v105, v104, v105
	v_fma_f32 v105, v104, v105, v104
	v_mul_f32_e32 v105, 0x3f4c422a, v105
	v_add_f32_e32 v105, v105, v105
	v_mul_f32_e32 v105, 0x3fb8aa3b, v105
	v_exp_f32_e32 v105, v105
	v_mul_f32_e32 v104, 0.5, v104
	v_add_f32_e32 v105, 1.0, v105
	v_div_scale_f32 v106, s[70:71], v105, v105, 2.0
	v_rcp_f32_e32 v107, v106
	s_nop 0
	v_fma_f32 v108, -v106, v107, 1.0
	v_fmac_f32_e32 v107, v108, v107
	v_div_scale_f32 v108, vcc, 2.0, v105, 2.0
	v_mul_f32_e32 v109, v108, v107
	v_fma_f32 v110, -v106, v109, v108
	v_fmac_f32_e32 v109, v110, v107
	v_fma_f32 v106, -v106, v109, v108
	v_div_fmas_f32 v106, v106, v107, v109
	v_div_fixup_f32 v105, v106, v105, 2.0
	v_sub_f32_e32 v105, 1.0, v105
	v_add_f32_e32 v105, 1.0, v105
	v_mul_f32_e32 v104, v104, v105
	v_mul_f32_e32 v104, v24, v104
	v_mul_f32_e32 v105, v80, v104
	v_mul_f32_e32 v105, 0x43800000, v105
	v_mov_b32_e32 v106, 0x43e00000
	v_med3_f32 v105, v105, s94, v106
	v_mov_b32_e32 v106, 0
	v_cvt_pk_fp8_f32 v106, v105, 0
	s_nop 0
	v_and_b32_e32 v106, 0xff, v106
	v_mul_lo_u32 v106, v106, s81
	ds_write_b32 v245, v106 offset:2048
	v_mul_f32_e32 v105, v81, v104
	v_mul_f32_e32 v105, 0x43800000, v105
	v_mov_b32_e32 v106, 0x43e00000
	v_med3_f32 v105, v105, s94, v106
	v_mov_b32_e32 v106, 0
	v_cvt_pk_fp8_f32 v106, v105, 0
	s_nop 0
	v_and_b32_e32 v106, 0xff, v106
	v_mul_lo_u32 v106, v106, s81
	ds_write_b32 v245, v106 offset:6144
	v_mul_f32_e32 v104, v229, v50
	v_fmac_f32_e32 v104, v213, v51
	v_mul_f32_e32 v104, v104, v100
	v_mul_f32_e32 v105, 0x3d372713, v104
	v_mul_f32_e32 v105, v104, v105
	v_fma_f32 v105, v104, v105, v104
	v_mul_f32_e32 v105, 0x3f4c422a, v105
	v_add_f32_e32 v105, v105, v105
	v_mul_f32_e32 v105, 0x3fb8aa3b, v105
	v_exp_f32_e32 v105, v105
	v_mul_f32_e32 v104, 0.5, v104
	v_add_f32_e32 v105, 1.0, v105
	v_div_scale_f32 v106, s[70:71], v105, v105, 2.0
	v_rcp_f32_e32 v107, v106
	s_nop 0
	v_fma_f32 v108, -v106, v107, 1.0
	v_fmac_f32_e32 v107, v108, v107
	v_div_scale_f32 v108, vcc, 2.0, v105, 2.0
	v_mul_f32_e32 v109, v108, v107
	v_fma_f32 v110, -v106, v109, v108
	v_fmac_f32_e32 v109, v110, v107
	v_fma_f32 v106, -v106, v109, v108
	v_div_fmas_f32 v106, v106, v107, v109
	v_div_fixup_f32 v105, v106, v105, 2.0
	v_sub_f32_e32 v105, 1.0, v105
	v_add_f32_e32 v105, 1.0, v105
	v_mul_f32_e32 v104, v104, v105
	v_mul_f32_e32 v104, v25, v104
	v_mul_f32_e32 v105, v82, v104
	v_mul_f32_e32 v105, 0x43800000, v105
	v_mov_b32_e32 v106, 0x43e00000
	v_med3_f32 v105, v105, s94, v106
	v_mov_b32_e32 v106, 0
	v_cvt_pk_fp8_f32 v106, v105, 0
	s_nop 0
	v_and_b32_e32 v106, 0xff, v106
	v_mul_lo_u32 v106, v106, s81
	ds_write_b32 v245, v106 offset:2304
	v_mul_f32_e32 v105, v83, v104
	v_mul_f32_e32 v105, 0x43800000, v105
	v_mov_b32_e32 v106, 0x43e00000
	v_med3_f32 v105, v105, s94, v106
	v_mov_b32_e32 v106, 0
	v_cvt_pk_fp8_f32 v106, v105, 0
	s_nop 0
	v_and_b32_e32 v106, 0xff, v106
	v_mul_lo_u32 v106, v106, s81
	ds_write_b32 v245, v106 offset:6400
	v_mul_f32_e32 v104, v230, v52
	v_fmac_f32_e32 v104, v214, v53
	v_mul_f32_e32 v104, v104, v101
	v_mul_f32_e32 v105, 0x3d372713, v104
	v_mul_f32_e32 v105, v104, v105
	v_fma_f32 v105, v104, v105, v104
	v_mul_f32_e32 v105, 0x3f4c422a, v105
	v_add_f32_e32 v105, v105, v105
	v_mul_f32_e32 v105, 0x3fb8aa3b, v105
	v_exp_f32_e32 v105, v105
	v_mul_f32_e32 v104, 0.5, v104
	v_add_f32_e32 v105, 1.0, v105
	v_div_scale_f32 v106, s[70:71], v105, v105, 2.0
	v_rcp_f32_e32 v107, v106
	s_nop 0
	v_fma_f32 v108, -v106, v107, 1.0
	v_fmac_f32_e32 v107, v108, v107
	v_div_scale_f32 v108, vcc, 2.0, v105, 2.0
	v_mul_f32_e32 v109, v108, v107
	v_fma_f32 v110, -v106, v109, v108
	v_fmac_f32_e32 v109, v110, v107
	v_fma_f32 v106, -v106, v109, v108
	v_div_fmas_f32 v106, v106, v107, v109
	v_div_fixup_f32 v105, v106, v105, 2.0
	v_sub_f32_e32 v105, 1.0, v105
	v_add_f32_e32 v105, 1.0, v105
	v_mul_f32_e32 v104, v104, v105
	v_mul_f32_e32 v104, v26, v104
	v_mul_f32_e32 v105, v84, v104
	v_mul_f32_e32 v105, 0x43800000, v105
	v_mov_b32_e32 v106, 0x43e00000
	v_med3_f32 v105, v105, s94, v106
	v_mov_b32_e32 v106, 0
	v_cvt_pk_fp8_f32 v106, v105, 0
	s_nop 0
	v_and_b32_e32 v106, 0xff, v106
	v_mul_lo_u32 v106, v106, s81
	ds_write_b32 v245, v106 offset:2560
	v_mul_f32_e32 v105, v85, v104
	v_mul_f32_e32 v105, 0x43800000, v105
	v_mov_b32_e32 v106, 0x43e00000
	v_med3_f32 v105, v105, s94, v106
	v_mov_b32_e32 v106, 0
	v_cvt_pk_fp8_f32 v106, v105, 0
	s_nop 0
	v_and_b32_e32 v106, 0xff, v106
	v_mul_lo_u32 v106, v106, s81
	ds_write_b32 v245, v106 offset:6656
	v_mul_f32_e32 v104, v231, v54
	v_fmac_f32_e32 v104, v215, v55
	v_mul_f32_e32 v104, v104, v101
	v_mul_f32_e32 v105, 0x3d372713, v104
	v_mul_f32_e32 v105, v104, v105
	v_fma_f32 v105, v104, v105, v104
	v_mul_f32_e32 v105, 0x3f4c422a, v105
	v_add_f32_e32 v105, v105, v105
	v_mul_f32_e32 v105, 0x3fb8aa3b, v105
	v_exp_f32_e32 v105, v105
	v_mul_f32_e32 v104, 0.5, v104
	v_add_f32_e32 v105, 1.0, v105
	v_div_scale_f32 v106, s[70:71], v105, v105, 2.0
	v_rcp_f32_e32 v107, v106
	s_nop 0
	v_fma_f32 v108, -v106, v107, 1.0
	v_fmac_f32_e32 v107, v108, v107
	v_div_scale_f32 v108, vcc, 2.0, v105, 2.0
	v_mul_f32_e32 v109, v108, v107
	v_fma_f32 v110, -v106, v109, v108
	v_fmac_f32_e32 v109, v110, v107
	v_fma_f32 v106, -v106, v109, v108
	v_div_fmas_f32 v106, v106, v107, v109
	v_div_fixup_f32 v105, v106, v105, 2.0
	v_sub_f32_e32 v105, 1.0, v105
	v_add_f32_e32 v105, 1.0, v105
	v_mul_f32_e32 v104, v104, v105
	v_mul_f32_e32 v104, v27, v104
	v_mul_f32_e32 v105, v86, v104
	v_mul_f32_e32 v105, 0x43800000, v105
	v_mov_b32_e32 v106, 0x43e00000
	v_med3_f32 v105, v105, s94, v106
	v_mov_b32_e32 v106, 0
	v_cvt_pk_fp8_f32 v106, v105, 0
	s_nop 0
	v_and_b32_e32 v106, 0xff, v106
	v_mul_lo_u32 v106, v106, s81
	ds_write_b32 v245, v106 offset:2816
	v_mul_f32_e32 v105, v87, v104
	v_mul_f32_e32 v105, 0x43800000, v105
	v_mov_b32_e32 v106, 0x43e00000
	v_med3_f32 v105, v105, s94, v106
	v_mov_b32_e32 v106, 0
	v_cvt_pk_fp8_f32 v106, v105, 0
	s_nop 0
	v_and_b32_e32 v106, 0xff, v106
	v_mul_lo_u32 v106, v106, s81
	ds_write_b32 v245, v106 offset:6912
	v_mul_f32_e32 v104, v232, v56
	v_fmac_f32_e32 v104, v216, v57
	v_mul_f32_e32 v104, v104, v102
	v_mul_f32_e32 v105, 0x3d372713, v104
	v_mul_f32_e32 v105, v104, v105
	v_fma_f32 v105, v104, v105, v104
	v_mul_f32_e32 v105, 0x3f4c422a, v105
	v_add_f32_e32 v105, v105, v105
	v_mul_f32_e32 v105, 0x3fb8aa3b, v105
	v_exp_f32_e32 v105, v105
	v_mul_f32_e32 v104, 0.5, v104
	v_add_f32_e32 v105, 1.0, v105
	v_div_scale_f32 v106, s[70:71], v105, v105, 2.0
	v_rcp_f32_e32 v107, v106
	s_nop 0
	v_fma_f32 v108, -v106, v107, 1.0
	v_fmac_f32_e32 v107, v108, v107
	v_div_scale_f32 v108, vcc, 2.0, v105, 2.0
	v_mul_f32_e32 v109, v108, v107
	v_fma_f32 v110, -v106, v109, v108
	v_fmac_f32_e32 v109, v110, v107
	v_fma_f32 v106, -v106, v109, v108
	v_div_fmas_f32 v106, v106, v107, v109
	v_div_fixup_f32 v105, v106, v105, 2.0
	v_sub_f32_e32 v105, 1.0, v105
	v_add_f32_e32 v105, 1.0, v105
	v_mul_f32_e32 v104, v104, v105
	v_mul_f32_e32 v104, v28, v104
	v_mul_f32_e32 v105, v88, v104
	v_mul_f32_e32 v105, 0x43800000, v105
	v_mov_b32_e32 v106, 0x43e00000
	v_med3_f32 v105, v105, s94, v106
	v_mov_b32_e32 v106, 0
	v_cvt_pk_fp8_f32 v106, v105, 0
	s_nop 0
	v_and_b32_e32 v106, 0xff, v106
	v_mul_lo_u32 v106, v106, s81
	ds_write_b32 v245, v106 offset:3072
	v_mul_f32_e32 v105, v89, v104
	v_mul_f32_e32 v105, 0x43800000, v105
	v_mov_b32_e32 v106, 0x43e00000
	v_med3_f32 v105, v105, s94, v106
	v_mov_b32_e32 v106, 0
	v_cvt_pk_fp8_f32 v106, v105, 0
	s_nop 0
	v_and_b32_e32 v106, 0xff, v106
	v_mul_lo_u32 v106, v106, s81
	ds_write_b32 v245, v106 offset:7168
	v_mul_f32_e32 v104, v233, v58
	v_fmac_f32_e32 v104, v217, v59
	v_mul_f32_e32 v104, v104, v102
	v_mul_f32_e32 v105, 0x3d372713, v104
	v_mul_f32_e32 v105, v104, v105
	v_fma_f32 v105, v104, v105, v104
	v_mul_f32_e32 v105, 0x3f4c422a, v105
	v_add_f32_e32 v105, v105, v105
	v_mul_f32_e32 v105, 0x3fb8aa3b, v105
	v_exp_f32_e32 v105, v105
	v_mul_f32_e32 v104, 0.5, v104
	v_add_f32_e32 v105, 1.0, v105
	v_div_scale_f32 v106, s[70:71], v105, v105, 2.0
	v_rcp_f32_e32 v107, v106
	s_nop 0
	v_fma_f32 v108, -v106, v107, 1.0
	v_fmac_f32_e32 v107, v108, v107
	v_div_scale_f32 v108, vcc, 2.0, v105, 2.0
	v_mul_f32_e32 v109, v108, v107
	v_fma_f32 v110, -v106, v109, v108
	v_fmac_f32_e32 v109, v110, v107
	v_fma_f32 v106, -v106, v109, v108
	v_div_fmas_f32 v106, v106, v107, v109
	v_div_fixup_f32 v105, v106, v105, 2.0
	v_sub_f32_e32 v105, 1.0, v105
	v_add_f32_e32 v105, 1.0, v105
	v_mul_f32_e32 v104, v104, v105
	v_mul_f32_e32 v104, v29, v104
	v_mul_f32_e32 v105, v90, v104
	v_mul_f32_e32 v105, 0x43800000, v105
	v_mov_b32_e32 v106, 0x43e00000
	v_med3_f32 v105, v105, s94, v106
	v_mov_b32_e32 v106, 0
	v_cvt_pk_fp8_f32 v106, v105, 0
	s_nop 0
	v_and_b32_e32 v106, 0xff, v106
	v_mul_lo_u32 v106, v106, s81
	ds_write_b32 v245, v106 offset:3328
	v_mul_f32_e32 v105, v91, v104
	v_mul_f32_e32 v105, 0x43800000, v105
	v_mov_b32_e32 v106, 0x43e00000
	v_med3_f32 v105, v105, s94, v106
	v_mov_b32_e32 v106, 0
	v_cvt_pk_fp8_f32 v106, v105, 0
	s_nop 0
	v_and_b32_e32 v106, 0xff, v106
	v_mul_lo_u32 v106, v106, s81
	ds_write_b32 v245, v106 offset:7424
	v_mul_f32_e32 v104, v234, v60
	v_fmac_f32_e32 v104, v218, v61
	v_mul_f32_e32 v104, v104, v103
	v_mul_f32_e32 v105, 0x3d372713, v104
	v_mul_f32_e32 v105, v104, v105
	v_fma_f32 v105, v104, v105, v104
	v_mul_f32_e32 v105, 0x3f4c422a, v105
	v_add_f32_e32 v105, v105, v105
	v_mul_f32_e32 v105, 0x3fb8aa3b, v105
	v_exp_f32_e32 v105, v105
	v_mul_f32_e32 v104, 0.5, v104
	v_add_f32_e32 v105, 1.0, v105
	v_div_scale_f32 v106, s[70:71], v105, v105, 2.0
	v_rcp_f32_e32 v107, v106
	s_nop 0
	v_fma_f32 v108, -v106, v107, 1.0
	v_fmac_f32_e32 v107, v108, v107
	v_div_scale_f32 v108, vcc, 2.0, v105, 2.0
	v_mul_f32_e32 v109, v108, v107
	v_fma_f32 v110, -v106, v109, v108
	v_fmac_f32_e32 v109, v110, v107
	v_fma_f32 v106, -v106, v109, v108
	v_div_fmas_f32 v106, v106, v107, v109
	v_div_fixup_f32 v105, v106, v105, 2.0
	v_sub_f32_e32 v105, 1.0, v105
	v_add_f32_e32 v105, 1.0, v105
	v_mul_f32_e32 v104, v104, v105
	v_mul_f32_e32 v104, v30, v104
	v_mul_f32_e32 v105, v92, v104
	v_mul_f32_e32 v105, 0x43800000, v105
	v_mov_b32_e32 v106, 0x43e00000
	v_med3_f32 v105, v105, s94, v106
	v_mov_b32_e32 v106, 0
	v_cvt_pk_fp8_f32 v106, v105, 0
	s_nop 0
	v_and_b32_e32 v106, 0xff, v106
	v_mul_lo_u32 v106, v106, s81
	ds_write_b32 v245, v106 offset:3584
	v_mul_f32_e32 v105, v93, v104
	v_mul_f32_e32 v105, 0x43800000, v105
	v_mov_b32_e32 v106, 0x43e00000
	v_med3_f32 v105, v105, s94, v106
	v_mov_b32_e32 v106, 0
	v_cvt_pk_fp8_f32 v106, v105, 0
	s_nop 0
	v_and_b32_e32 v106, 0xff, v106
	v_mul_lo_u32 v106, v106, s81
	ds_write_b32 v245, v106 offset:7680
	v_mul_f32_e32 v104, v235, v62
	v_fmac_f32_e32 v104, v219, v63
	v_mul_f32_e32 v104, v104, v103
	v_mul_f32_e32 v105, 0x3d372713, v104
	v_mul_f32_e32 v105, v104, v105
	v_fma_f32 v105, v104, v105, v104
	v_mul_f32_e32 v105, 0x3f4c422a, v105
	v_add_f32_e32 v105, v105, v105
	v_mul_f32_e32 v105, 0x3fb8aa3b, v105
	v_exp_f32_e32 v105, v105
	v_mul_f32_e32 v104, 0.5, v104
	v_add_f32_e32 v105, 1.0, v105
	v_div_scale_f32 v106, s[70:71], v105, v105, 2.0
	v_rcp_f32_e32 v107, v106
	s_nop 0
	v_fma_f32 v108, -v106, v107, 1.0
	v_fmac_f32_e32 v107, v108, v107
	v_div_scale_f32 v108, vcc, 2.0, v105, 2.0
	v_mul_f32_e32 v109, v108, v107
	v_fma_f32 v110, -v106, v109, v108
	v_fmac_f32_e32 v109, v110, v107
	v_fma_f32 v106, -v106, v109, v108
	v_div_fmas_f32 v106, v106, v107, v109
	v_div_fixup_f32 v105, v106, v105, 2.0
	v_sub_f32_e32 v105, 1.0, v105
	v_add_f32_e32 v105, 1.0, v105
	v_mul_f32_e32 v104, v104, v105
	v_mul_f32_e32 v104, v31, v104
	v_mul_f32_e32 v105, v94, v104
	v_mul_f32_e32 v105, 0x43800000, v105
	v_mov_b32_e32 v106, 0x43e00000
	v_med3_f32 v105, v105, s94, v106
	v_mov_b32_e32 v106, 0
	v_cvt_pk_fp8_f32 v106, v105, 0
	s_nop 0
	v_and_b32_e32 v106, 0xff, v106
	v_mul_lo_u32 v106, v106, s81
	ds_write_b32 v245, v106 offset:3840
	v_mul_f32_e32 v105, v95, v104
	v_mul_f32_e32 v105, 0x43800000, v105
	v_mov_b32_e32 v106, 0x43e00000
	v_med3_f32 v105, v105, s94, v106
	v_mov_b32_e32 v106, 0
	v_cvt_pk_fp8_f32 v106, v105, 0
	s_nop 0
	v_and_b32_e32 v106, 0xff, v106
	v_mul_lo_u32 v106, v106, s81
	ds_write_b32 v245, v106 offset:7936
	s_waitcnt lgkmcnt(0)
	v_mbcnt_lo_u32_b32 v249, -1, 0
	v_mbcnt_hi_u32_b32 v249, -1, v249
	v_and_b32_e32 v250, 15, v249
	v_lshrrev_b32_e32 v251, 4, v249
	v_and_b32_e32 v252, 3, v250
	v_lshl_add_u32 v233, v251, 3, s91
	v_lshrrev_b32_e32 v253, 3, v250
	v_lshl_add_u32 v253, v253, 2, v252
	v_lshlrev_b32_e32 v232, 4, v253
	v_bfe_u32 v253, v250, 2, 1
	v_lshl_add_u32 v254, v251, 1, v253
	v_lshl_add_u32 v243, v254, 2, s91
	v_cmp_eq_u32_e64 s[4:5], 1, v253
	v_cmp_eq_u32_e64 s[6:7], 0, v253
	v_lshlrev_b32_e32 v239, 3, v249
	v_mov_b32_e32 v241, 0x77777777
	v_lshlrev_b32_e32 v253, 3, v252
	v_mov_b32_e32 v254, 0xff
	v_lshlrev_b32_e32 v254, v253, v254
	v_lshrrev_b32_e32 v253, 2, v250
	v_cmp_eq_u32_e32 vcc, 0, v253
	s_nop 1
	v_cndmask_b32_e32 v235, 0, v254, vcc
	v_cmp_eq_u32_e32 vcc, 1, v253
	s_nop 1
	v_cndmask_b32_e32 v236, 0, v254, vcc
	v_cmp_eq_u32_e32 vcc, 2, v253
	s_nop 1
	v_cndmask_b32_e32 v237, 0, v254, vcc
	v_cmp_eq_u32_e32 vcc, 3, v253
	s_nop 1
	v_cndmask_b32_e32 v238, 0, v254, vcc
	v_add_u32_e32 v234, 0x1000, v233
	v_add_u32_e32 v247, 0x1000, v233
	v_mov_b32_e32 v220, 0
	v_mov_b32_e32 v221, 0
	v_mov_b32_e32 v222, 0
	v_mov_b32_e32 v223, 0
	v_mov_b32_e32 v224, 0
	v_mov_b32_e32 v225, 0
	v_mov_b32_e32 v226, 0
	v_mov_b32_e32 v227, 0
	s_mov_b32 s0, 0
	s_mov_b32 s1, 0
	s_mov_b32 s60, 0x200000
	ds_read_b32 v128, v243 offset:0
	ds_read_b32 v129, v243 offset:32
	ds_read_b32 v130, v243 offset:64
	ds_read_b32 v131, v243 offset:96
	ds_read_b32 v132, v243 offset:128
	ds_read_b32 v133, v243 offset:160
	ds_read_b32 v134, v243 offset:192
	ds_read_b32 v135, v243 offset:224
	s_waitcnt lgkmcnt(0)
	v_lshl_or_b32 v128, v128, 7, v232
	v_lshl_or_b32 v129, v129, 7, v232
	v_lshl_or_b32 v130, v130, 7, v232
	v_lshl_or_b32 v131, v131, 7, v232
	v_lshl_or_b32 v132, v132, 7, v232
	v_lshl_or_b32 v133, v133, 7, v232
	v_lshl_or_b32 v134, v134, 7, v232
	v_lshl_or_b32 v135, v135, 7, v232
	buffer_load_dwordx4 v[0:3], v128, s[20:23], s1 offen
	buffer_load_dwordx4 v[4:7], v129, s[20:23], s1 offen
	buffer_load_dwordx4 v[8:11], v130, s[20:23], s1 offen
	buffer_load_dwordx4 v[12:15], v131, s[20:23], s1 offen
	buffer_load_dwordx4 v[16:19], v132, s[20:23], s1 offen
	buffer_load_dwordx4 v[20:23], v133, s[20:23], s1 offen
	buffer_load_dwordx4 v[24:27], v134, s[20:23], s1 offen
	buffer_load_dwordx4 v[28:31], v135, s[20:23], s1 offen
	ds_read_b32 v128, v243 offset:256
	ds_read_b32 v129, v243 offset:288
	ds_read_b32 v130, v243 offset:320
	ds_read_b32 v131, v243 offset:352
	ds_read_b32 v132, v243 offset:384
	ds_read_b32 v133, v243 offset:416
	ds_read_b32 v134, v243 offset:448
	ds_read_b32 v135, v243 offset:480
	global_load_dword v242, v246, s[40:41]
	global_load_dword v242, v246, s[40:41]
	s_waitcnt lgkmcnt(0)
	v_lshl_or_b32 v128, v128, 7, v232
	v_lshl_or_b32 v129, v129, 7, v232
	v_lshl_or_b32 v130, v130, 7, v232
	v_lshl_or_b32 v131, v131, 7, v232
	v_lshl_or_b32 v132, v132, 7, v232
	v_lshl_or_b32 v133, v133, 7, v232
	v_lshl_or_b32 v134, v134, 7, v232
	v_lshl_or_b32 v135, v135, 7, v232
	buffer_load_dwordx4 v[32:35], v128, s[20:23], s1 offen
	buffer_load_dwordx4 v[36:39], v129, s[20:23], s1 offen
	buffer_load_dwordx4 v[40:43], v130, s[20:23], s1 offen
	buffer_load_dwordx4 v[44:47], v131, s[20:23], s1 offen
	buffer_load_dwordx4 v[48:51], v132, s[20:23], s1 offen
	buffer_load_dwordx4 v[52:55], v133, s[20:23], s1 offen
	buffer_load_dwordx4 v[56:59], v134, s[20:23], s1 offen
	buffer_load_dwordx4 v[60:63], v135, s[20:23], s1 offen
	ds_read_b32 v128, v243 offset:512
	ds_read_b32 v129, v243 offset:544
	ds_read_b32 v130, v243 offset:576
	ds_read_b32 v131, v243 offset:608
	ds_read_b32 v132, v243 offset:640
	ds_read_b32 v133, v243 offset:672
	ds_read_b32 v134, v243 offset:704
	ds_read_b32 v135, v243 offset:736
	s_waitcnt lgkmcnt(0)
	v_lshl_or_b32 v128, v128, 7, v232
	v_lshl_or_b32 v129, v129, 7, v232
	v_lshl_or_b32 v130, v130, 7, v232
	v_lshl_or_b32 v131, v131, 7, v232
	v_lshl_or_b32 v132, v132, 7, v232
	v_lshl_or_b32 v133, v133, 7, v232
	v_lshl_or_b32 v134, v134, 7, v232
	v_lshl_or_b32 v135, v135, 7, v232
	buffer_load_dwordx4 v[64:67], v128, s[20:23], s1 offen
	buffer_load_dwordx4 v[68:71], v129, s[20:23], s1 offen
	buffer_load_dwordx4 v[72:75], v130, s[20:23], s1 offen
	buffer_load_dwordx4 v[76:79], v131, s[20:23], s1 offen
	buffer_load_dwordx4 v[80:83], v132, s[20:23], s1 offen
	buffer_load_dwordx4 v[84:87], v133, s[20:23], s1 offen
	buffer_load_dwordx4 v[88:91], v134, s[20:23], s1 offen
	buffer_load_dwordx4 v[92:95], v135, s[20:23], s1 offen
	ds_read_b32 v128, v243 offset:768
	ds_read_b32 v129, v243 offset:800
	ds_read_b32 v130, v243 offset:832
	ds_read_b32 v131, v243 offset:864
	ds_read_b32 v132, v243 offset:896
	ds_read_b32 v133, v243 offset:928
	ds_read_b32 v134, v243 offset:960
	ds_read_b32 v135, v243 offset:992
	ds_read_b64 v[160:161], v234 offset:0
	ds_read_b64 v[162:163], v234 offset:32
	ds_read_b64 v[164:165], v234 offset:64
	ds_read_b64 v[166:167], v234 offset:96
	ds_read_b64 v[168:169], v234 offset:128
	ds_read_b64 v[170:171], v234 offset:160
	ds_read_b64 v[172:173], v234 offset:192
	ds_read_b64 v[174:175], v234 offset:224
	global_load_dword v242, v246, s[40:41]

.LBB0_782:
	s_and_b32 s5, s19, 0xe00
	s_add_i32 s16, s18, s5
	s_pack_ll_b32_b16 s5, s4, s4
	s_or_b32 s5, s5, 0x1c00180
	s_and_b32 s10, s5, 0xfff
	s_mulk_i32 s10, 0xaab
	s_lshr_b32 s10, s10, 20
	s_mulk_i32 s10, 0x180
	s_sub_i32 s10, s5, s10
	s_and_b32 s10, s10, 0xffff
	v_add_u32_e32 v1, s10, v120
	v_lshlrev_b32_e32 v28, 7, v1
	v_lshrrev_b32_e32 v1, 1, v1
	s_lshr_b32 s5, s5, 16
	v_xor_b32_e32 v1, v1, v115
	s_mul_i32 s17, s5, 0xaab
	v_lshlrev_b32_e32 v1, 4, v1
	s_lshr_b32 s17, s17, 20
	v_and_b32_e32 v1, 0x70, v1
	s_mulk_i32 s17, 0x180
	v_add3_u32 v1, 0, v28, v1
	s_sub_i32 s5, s5, s17
	s_waitcnt vmcnt(1)
	ds_write_b128 v1, v[22:25]
	v_or_b32_e32 v1, s10, v110
	s_and_b32 s5, s5, 0xffff
	v_lshlrev_b32_e32 v1, 1, v1
	v_add_u32_e32 v26, s5, v111
	v_add3_u32 v1, v121, v1, s21
	ds_write2_b64 v1, v[14:15], v[16:17] offset1:1
	v_lshrrev_b32_e32 v1, 1, v26
	v_xor_b32_e32 v1, v1, v115
	v_lshlrev_b32_e32 v1, 4, v1
	v_lshlrev_b32_e32 v27, 7, v26
	v_and_b32_e32 v1, 0x70, v1
	v_add3_u32 v1, 0, v27, v1
	s_addk_i32 s4, 0x200
	ds_write_b128 v1, v[18:21]
	v_or_b32_e32 v1, s5, v110
	s_and_b32 s5, s4, 0x1fff
	s_mulk_i32 s5, 0xaab
	s_lshr_b32 s5, s5, 20
	s_mulk_i32 s5, 0x180
	v_lshlrev_b32_e32 v1, 1, v1
	s_sub_i32 s4, s4, s5
	v_add3_u32 v1, v121, v1, s21
	s_and_b32 s4, s4, 0xffff
	ds_write2_b64 v1, v[10:11], v[12:13] offset1:1
	v_add_u32_e32 v1, s4, v108
	v_lshlrev_b32_e32 v10, 7, v1
	v_lshrrev_b32_e32 v1, 1, v1
	v_xor_b32_e32 v1, v1, v115
	v_lshlrev_b32_e32 v1, 4, v1
	v_and_b32_e32 v1, 0x70, v1
	v_add3_u32 v1, 0, v10, v1
	ds_write_b128 v1, v[6:9]
	v_or_b32_e32 v1, s4, v110
	s_lshl_b32 s4, s24, 2
	s_or_b32 s4, s4, s0
	s_lshl_b32 s10, s4, 7
	s_lshl_b32 s4, s4, 2
	v_lshlrev_b32_e32 v1, 1, v1
	v_or_b32_e32 v130, s14, v114
	s_add_u32 s14, s48, s4
	v_add3_u32 v1, v121, v1, s21
	v_mov_b32_e32 v131, s15
	v_lshl_add_u64 v[134:135], v[116:117], 0, s[10:11]
	s_addc_u32 s15, s49, 0
	v_lshl_add_u64 v[136:137], v[118:119], 0, s[10:11]
	s_waitcnt vmcnt(0)
	ds_write2_b64 v1, v[2:3], v[4:5] offset1:1
	s_waitcnt lgkmcnt(0)
	s_barrier
	s_add_i32 s10, s12, s1
	v_lshl_add_u64 v[186:187], v[130:131], 0, s[10:11]
	v_lshlrev_b64 v[186:187], 11, v[186:187]
	v_lshl_add_u64 v[186:187], v[186:187], 1, v[134:135]
	v_mov_b32_e32 v189, 0
	global_load_dwordx4 v[170:173], v[186:187], off nt
	global_load_dwordx4 v[174:177], v[186:187], off offset:32 nt
	global_load_dwordx4 v[178:181], v[186:187], off offset:64 nt
	global_load_dwordx4 v[182:185], v[186:187], off offset:96 nt
	global_load_dword v188, v189, s[14:15]
	s_waitcnt vmcnt(0)
	v_mul_f32_e32 v188, 0x3fb8aa3b, v188
	v_mbcnt_lo_u32_b32 v249, -1, 0
	v_mbcnt_hi_u32_b32 v249, -1, v249
	v_and_b32_e32 v251, 3, v249
	v_lshrrev_b32_e32 v250, 4, v249
	v_lshlrev_b32_e32 v250, 5, v250
	v_lshl_or_b32 v250, v251, 3, v250
	v_bfe_u32 v252, v249, 3, 1
	v_lshl_or_b32 v250, v252, 2, v250
	v_lshlrev_b32_e32 v251, 2, v251
	v_lshlrev_b32_e32 v249, 4, v249
	v_mov_b32_e32 v252, 0
	v_lshrrev_b32_e32 v254, 9, v249
	v_mul_u32_u24_e32 v254, 24, v254
	v_mov_b32_e32 v255, 0
	v_readlane_b32 s86, v248, 0
	s_lshr_b32 s86, s86, 6
	s_lshl_b32 s94, s2, 3
	s_add_i32 s94, s94, s86
	s_and_b32 s86, s94, 1
	s_lshr_b32 s94, s94, 1
	v_readlane_b32 s74, v248, 16
	v_readlane_b32 s75, v248, 17
	s_lshl_b32 s95, s94, 13
	s_lshl_b32 s80, s86, 12
	s_add_i32 s95, s95, s80
	s_add_i32 s95, s95, 0x8000000
	s_add_u32 s74, s74, s95
	s_addc_u32 s75, s75, 0
	s_lshl_b32 s95, s86, 23
	s_lshl_b32 s80, s94, 7
	s_add_i32 s95, s95, s80
	s_add_i32 s95, s95, 0x14000000
	s_add_u32 s76, s54, s95
	s_addc_u32 s77, s55, 0
	s_lshl_b32 s95, s94, 3
	s_lshl_b32 s80, s86, 2
	s_add_i32 s95, s95, s80
	s_add_i32 s95, s95, 0xe0000
	s_add_u32 s78, s54, s95
	s_addc_u32 s79, s55, 0
	s_branch .LBB0_784

.LBB0_786:
	s_add_i32 s10, s17, s1
	s_sub_i32 s24, 0x80, s10
	s_ashr_i32 s24, s24, 5
	s_cmpk_lt_u32 s10, 0x80
	v_lshl_add_u64 v[2:3], v[130:131], 0, s[10:11]
	s_cselect_b32 s24, s24, 0
	s_sub_i32 s10, 0x1060, s10
	s_ashr_i32 s10, s10, 5
	s_min_i32 s10, s10, 8
	v_lshlrev_b64 v[138:139], 11, v[2:3]
	s_waitcnt vmcnt(26)
	v_mov_b32_e32 v88, v170
	v_mov_b32_e32 v89, v171
	v_mov_b32_e32 v90, v172
	v_mov_b32_e32 v91, v173
	v_mov_b32_e32 v92, v174
	v_mov_b32_e32 v93, v175
	v_mov_b32_e32 v94, v176
	v_mov_b32_e32 v95, v177
	v_mov_b32_e32 v96, v178
	v_mov_b32_e32 v97, v179
	v_mov_b32_e32 v98, v180
	v_mov_b32_e32 v99, v181
	v_mov_b32_e32 v100, v182
	v_mov_b32_e32 v101, v183
	v_mov_b32_e32 v102, v184
	v_mov_b32_e32 v103, v185
	v_lshl_add_u64 v[186:187], v[138:139], 1, v[134:135]
	v_add_co_u32_e32 v186, vcc, 0x40000, v186
	s_nop 1
	v_addc_co_u32_e32 v187, vcc, 0, v187, vcc
	global_load_dwordx4 v[170:173], v[186:187], off nt
	global_load_dwordx4 v[174:177], v[186:187], off offset:32 nt
	global_load_dwordx4 v[178:181], v[186:187], off offset:64 nt
	global_load_dwordx4 v[182:185], v[186:187], off offset:96 nt
	global_load_dwordx4 v[204:207], v249, s[74:75] offset:0 nt
	global_load_dwordx4 v[208:211], v249, s[74:75] offset:1024 nt
	global_load_dwordx4 v[212:215], v249, s[74:75] offset:2048 nt
	global_load_dwordx4 v[216:219], v249, s[74:75] offset:3072 nt
	s_add_u32 s74, s74, 0x800000
	s_addc_u32 s75, s75, 0
	global_load_dwordx4 v[220:223], v249, s[74:75] offset:0 nt
	global_load_dwordx4 v[224:227], v249, s[74:75] offset:1024 nt
	global_load_dwordx4 v[228:231], v249, s[74:75] offset:2048 nt
	global_load_dwordx4 v[232:235], v249, s[74:75] offset:3072 nt
	s_add_u32 s74, s74, 0x800000
	s_addc_u32 s75, s75, 0
	v_mov_b32_e32 v31, 0
	s_cmp_gt_i32 s24, s10
	v_mov_b32_e32 v30, 0
	v_mov_b32_e32 v29, 0
	v_mov_b32_e32 v28, 0
	v_mov_b32_e32 v27, 0
	v_mov_b32_e32 v26, 0
	v_mov_b32_e32 v25, 0
	v_mov_b32_e32 v24, 0
	v_mov_b32_e32 v23, 0
	v_mov_b32_e32 v22, 0
	v_mov_b32_e32 v21, 0
	v_mov_b32_e32 v20, 0
	v_mov_b32_e32 v19, 0
	v_mov_b32_e32 v18, 0
	v_mov_b32_e32 v17, 0
	v_mov_b32_e32 v16, 0
	v_mov_b32_e32 v47, 0
	v_mov_b32_e32 v46, 0
	v_mov_b32_e32 v45, 0
	v_mov_b32_e32 v44, 0
	v_mov_b32_e32 v43, 0
	v_mov_b32_e32 v42, 0
	v_mov_b32_e32 v41, 0
	v_mov_b32_e32 v40, 0
	v_mov_b32_e32 v39, 0
	v_mov_b32_e32 v38, 0
	v_mov_b32_e32 v37, 0
	v_mov_b32_e32 v36, 0
	v_mov_b32_e32 v35, 0
	v_mov_b32_e32 v34, 0
	v_mov_b32_e32 v33, 0
	v_mov_b32_e32 v32, 0
	v_mov_b32_e32 v148, v141
	s_cbranch_scc1 .LBB0_794
	v_mov_b32_e32 v14, v0
	v_mov_b32_e32 v15, v0
	v_mov_b32_e32 v1, v0
	v_mov_b32_e32 v2, v0
	v_mov_b32_e32 v3, v0
	v_mov_b32_e32 v4, v0
	v_mov_b32_e32 v5, v0
	v_mov_b32_e32 v6, v0
	v_mov_b32_e32 v7, v0
	v_mov_b32_e32 v8, v0
	v_mov_b32_e32 v9, v0
	v_mov_b32_e32 v10, v0
	v_mov_b32_e32 v11, v0
	v_mov_b32_e32 v12, v0
	v_mov_b32_e32 v13, v0
	v_mov_b64_e32 v[30:31], v[14:15]
	s_lshl_b32 s25, s24, 5
	s_mov_b32 s26, s16
	v_mov_b32_e32 v149, v146
	v_mov_b32_e32 v148, v141
	v_mov_b64_e32 v[28:29], v[12:13]
	v_mov_b64_e32 v[26:27], v[10:11]
	v_mov_b64_e32 v[24:25], v[8:9]
	v_mov_b64_e32 v[22:23], v[6:7]
	v_mov_b64_e32 v[20:21], v[4:5]
	v_mov_b64_e32 v[18:19], v[2:3]
	v_mov_b64_e32 v[16:17], v[0:1]
	v_mov_b32_e32 v150, v188
	v_mov_b64_e32 v[46:47], v[14:15]
	v_mov_b64_e32 v[44:45], v[12:13]
	v_mov_b64_e32 v[42:43], v[10:11]
	v_mov_b64_e32 v[40:41], v[8:9]
	v_mov_b64_e32 v[38:39], v[6:7]
	v_mov_b64_e32 v[36:37], v[4:5]
	v_mov_b64_e32 v[34:35], v[2:3]
	v_mov_b64_e32 v[32:33], v[0:1]

.Ltk1_unit:
	s_lshl_b32 s26, s24, 9
	s_lshl_b32 s20, s23, 12
	s_add_i32 s26, s26, s20
	s_add_i32 s26, s26, 0x1c000000
	s_add_u32 s16, s54, s26
	s_addc_u32 s17, s55, 0
	s_lshl_b32 s26, s24, 16
	s_add_i32 s26, s26, 0x380000
	s_add_u32 s18, s54, s26
	s_addc_u32 s19, s55, 0
	s_lshl_b32 s20, s23, 9
	s_lshl_b32 s26, s24, 6
	s_add_i32 s20, s20, s26
	s_add_i32 s26, s20, 0x28000000
	s_add_u32 s28, s54, s26
	s_addc_u32 s29, s55, 0
	s_add_i32 s26, s20, 0x28800000
	s_add_u32 s30, s54, s26
	s_addc_u32 s31, s55, 0
	s_barrier
	global_load_dwordx4 v[0:3], v242, s[18:19]
	v_add_u32_e32 v247, 0x2000, v242
	global_load_dwordx4 v[4:7], v247, s[18:19]
	v_add_u32_e32 v247, 0x4000, v242
	global_load_dwordx4 v[8:11], v247, s[18:19]
	v_add_u32_e32 v247, 0x6000, v242
	global_load_dwordx4 v[12:15], v247, s[18:19]
	v_add_u32_e32 v247, 0x8000, v242
	global_load_dwordx4 v[16:19], v247, s[18:19]
	v_add_u32_e32 v247, 0xa000, v242
	global_load_dwordx4 v[20:23], v247, s[18:19]
	v_add_u32_e32 v247, 0xc000, v242
	global_load_dwordx4 v[24:27], v247, s[18:19]
	v_add_u32_e32 v247, 0xe000, v242
	global_load_dwordx4 v[28:31], v247, s[18:19]
	global_load_dwordx4 v[64:67], v239, s[16:17] offset:0 nt
	global_load_dwordx4 v[68:71], v239, s[16:17] offset:32 nt
	global_load_dwordx4 v[72:75], v239, s[16:17] offset:64 nt
	global_load_dwordx4 v[76:79], v239, s[16:17] offset:96 nt
	global_load_dwordx4 v[80:83], v239, s[16:17] offset:128 nt
	global_load_dwordx4 v[84:87], v239, s[16:17] offset:160 nt
	global_load_dwordx4 v[88:91], v239, s[16:17] offset:192 nt
	global_load_dwordx4 v[92:95], v239, s[16:17] offset:224 nt
	s_waitcnt vmcnt(15)
	ds_write_b128 v243, v[0:3] offset:0
	s_waitcnt vmcnt(14)
	ds_write_b128 v243, v[4:7] offset:8192
	s_waitcnt vmcnt(13)
	ds_write_b128 v243, v[8:11] offset:16384
	s_waitcnt vmcnt(12)
	ds_write_b128 v243, v[12:15] offset:24576
	s_waitcnt vmcnt(11)
	ds_write_b128 v243, v[16:19] offset:32768
	s_waitcnt vmcnt(10)
	ds_write_b128 v243, v[20:23] offset:40960
	s_waitcnt vmcnt(9)
	ds_write_b128 v243, v[24:27] offset:49152
	s_waitcnt vmcnt(8)
	ds_write_b128 v243, v[28:31] offset:57344
	s_waitcnt lgkmcnt(0)
	s_barrier
	ds_read_b128 v[96:99], v215 offset:0
	ds_read_b128 v[100:103], v232 offset:0
	ds_read_b128 v[104:107], v233 offset:0
	ds_read_b128 v[108:111], v234 offset:0
	ds_read_b128 v[112:115], v235 offset:0
	ds_read_b128 v[116:119], v236 offset:0
	ds_read_b128 v[120:123], v237 offset:0
	ds_read_b128 v[124:127], v238 offset:0
	s_waitcnt vmcnt(0)
	s_waitcnt lgkmcnt(4)
	v_mfma_f32_32x32x16_bf16 v[0:15], v[96:99], v[64:67], 0
	v_mfma_f32_32x32x16_bf16 v[0:15], v[100:103], v[68:71], v[0:15]
	v_mfma_f32_32x32x16_bf16 v[0:15], v[104:107], v[72:75], v[0:15]
	v_mfma_f32_32x32x16_bf16 v[0:15], v[108:111], v[76:79], v[0:15]
	ds_read_b128 v[96:99], v215 offset:8192
	ds_read_b128 v[100:103], v232 offset:8192
	ds_read_b128 v[104:107], v233 offset:8192
	ds_read_b128 v[108:111], v234 offset:8192
	s_waitcnt lgkmcnt(4)
	v_mfma_f32_32x32x16_bf16 v[0:15], v[112:115], v[80:83], v[0:15]
	v_mfma_f32_32x32x16_bf16 v[0:15], v[116:119], v[84:87], v[0:15]
	v_mfma_f32_32x32x16_bf16 v[0:15], v[120:123], v[88:91], v[0:15]
	v_mfma_f32_32x32x16_bf16 v[0:15], v[124:127], v[92:95], v[0:15]
	ds_read_b128 v[112:115], v235 offset:8192
	ds_read_b128 v[116:119], v236 offset:8192
	ds_read_b128 v[120:123], v237 offset:8192
	ds_read_b128 v[124:127], v238 offset:8192
	s_waitcnt lgkmcnt(4)
	v_mfma_f32_32x32x16_bf16 v[16:31], v[96:99], v[64:67], 0
	v_mfma_f32_32x32x16_bf16 v[16:31], v[100:103], v[68:71], v[16:31]
	v_mfma_f32_32x32x16_bf16 v[16:31], v[104:107], v[72:75], v[16:31]
	v_mfma_f32_32x32x16_bf16 v[16:31], v[108:111], v[76:79], v[16:31]
	ds_read_b128 v[96:99], v215 offset:16384
	ds_read_b128 v[100:103], v232 offset:16384
	ds_read_b128 v[104:107], v233 offset:16384
	ds_read_b128 v[108:111], v234 offset:16384
	s_waitcnt lgkmcnt(4)
	v_mfma_f32_32x32x16_bf16 v[16:31], v[112:115], v[80:83], v[16:31]
	v_mfma_f32_32x32x16_bf16 v[16:31], v[116:119], v[84:87], v[16:31]
	v_mfma_f32_32x32x16_bf16 v[16:31], v[120:123], v[88:91], v[16:31]
	v_mfma_f32_32x32x16_bf16 v[16:31], v[124:127], v[92:95], v[16:31]
	ds_read_b128 v[112:115], v235 offset:16384
	ds_read_b128 v[116:119], v236 offset:16384
	ds_read_b128 v[120:123], v237 offset:16384
	ds_read_b128 v[124:127], v238 offset:16384
	s_waitcnt lgkmcnt(4)
	v_mfma_f32_32x32x16_bf16 v[32:47], v[96:99], v[64:67], 0
	v_mfma_f32_32x32x16_bf16 v[32:47], v[100:103], v[68:71], v[32:47]
	v_mfma_f32_32x32x16_bf16 v[32:47], v[104:107], v[72:75], v[32:47]
	v_mfma_f32_32x32x16_bf16 v[32:47], v[108:111], v[76:79], v[32:47]
	ds_read_b128 v[96:99], v215 offset:24576
	ds_read_b128 v[100:103], v232 offset:24576
	ds_read_b128 v[104:107], v233 offset:24576
	ds_read_b128 v[108:111], v234 offset:24576
	s_waitcnt lgkmcnt(4)
	v_mfma_f32_32x32x16_bf16 v[32:47], v[112:115], v[80:83], v[32:47]
	v_mfma_f32_32x32x16_bf16 v[32:47], v[116:119], v[84:87], v[32:47]
	v_mfma_f32_32x32x16_bf16 v[32:47], v[120:123], v[88:91], v[32:47]
	v_mfma_f32_32x32x16_bf16 v[32:47], v[124:127], v[92:95], v[32:47]
	ds_read_b128 v[112:115], v235 offset:24576
	ds_read_b128 v[116:119], v236 offset:24576
	ds_read_b128 v[120:123], v237 offset:24576
	ds_read_b128 v[124:127], v238 offset:24576
	s_waitcnt lgkmcnt(4)
	v_mfma_f32_32x32x16_bf16 v[48:63], v[96:99], v[64:67], 0
	v_mfma_f32_32x32x16_bf16 v[48:63], v[100:103], v[68:71], v[48:63]
	v_mfma_f32_32x32x16_bf16 v[48:63], v[104:107], v[72:75], v[48:63]
	v_mfma_f32_32x32x16_bf16 v[48:63], v[108:111], v[76:79], v[48:63]
	s_waitcnt lgkmcnt(0)
	v_mfma_f32_32x32x16_bf16 v[48:63], v[112:115], v[80:83], v[48:63]
	v_mfma_f32_32x32x16_bf16 v[48:63], v[116:119], v[84:87], v[48:63]
	v_mfma_f32_32x32x16_bf16 v[48:63], v[120:123], v[88:91], v[48:63]
	v_mfma_f32_32x32x16_bf16 v[48:63], v[124:127], v[92:95], v[48:63]
	global_load_dwordx4 v[64:67], v239, s[16:17] offset:256 nt
	global_load_dwordx4 v[68:71], v239, s[16:17] offset:288 nt
	global_load_dwordx4 v[72:75], v239, s[16:17] offset:320 nt
	global_load_dwordx4 v[76:79], v239, s[16:17] offset:352 nt
	global_load_dwordx4 v[80:83], v239, s[16:17] offset:384 nt
	global_load_dwordx4 v[84:87], v239, s[16:17] offset:416 nt
	global_load_dwordx4 v[88:91], v239, s[16:17] offset:448 nt
	global_load_dwordx4 v[92:95], v239, s[16:17] offset:480 nt
	s_nop 11
	v_and_or_b32 v0, v0, s6, v211
	v_or_b32_e32 v0, 0x7b, v0
	v_and_or_b32 v1, v1, s6, v211
	v_or_b32_e32 v1, 0x7a, v1
	v_and_or_b32 v2, v2, s6, v211
	v_or_b32_e32 v2, 0x79, v2
	v_and_or_b32 v3, v3, s6, v211
	v_or_b32_e32 v3, 0x78, v3
	v_and_or_b32 v4, v4, s6, v211
	v_or_b32_e32 v4, 0x73, v4
	v_and_or_b32 v5, v5, s6, v211
	v_or_b32_e32 v5, 0x72, v5
	v_and_or_b32 v6, v6, s6, v211
	v_or_b32_e32 v6, 0x71, v6
	v_and_or_b32 v7, v7, s6, v211
	v_or_b32_e32 v7, 0x70, v7
	v_and_or_b32 v8, v8, s6, v211
	v_or_b32_e32 v8, 0x6b, v8
	v_and_or_b32 v9, v9, s6, v211
	v_or_b32_e32 v9, 0x6a, v9
	v_and_or_b32 v10, v10, s6, v211
	v_or_b32_e32 v10, 0x69, v10
	v_and_or_b32 v11, v11, s6, v211
	v_or_b32_e32 v11, 0x68, v11
	v_and_or_b32 v12, v12, s6, v211
	v_or_b32_e32 v12, 0x63, v12
	v_and_or_b32 v13, v13, s6, v211
	v_or_b32_e32 v13, 0x62, v13
	v_and_or_b32 v14, v14, s6, v211
	v_or_b32_e32 v14, 0x61, v14
	v_and_or_b32 v15, v15, s6, v211
	v_or_b32_e32 v15, 0x60, v15
	v_and_or_b32 v16, v16, s6, v211
	v_or_b32_e32 v16, 0x5b, v16
	v_and_or_b32 v17, v17, s6, v211
	v_or_b32_e32 v17, 0x5a, v17
	v_and_or_b32 v18, v18, s6, v211
	v_or_b32_e32 v18, 0x59, v18
	v_and_or_b32 v19, v19, s6, v211
	v_or_b32_e32 v19, 0x58, v19
	v_and_or_b32 v20, v20, s6, v211
	v_or_b32_e32 v20, 0x53, v20
	v_and_or_b32 v21, v21, s6, v211
	v_or_b32_e32 v21, 0x52, v21
	v_and_or_b32 v22, v22, s6, v211
	v_or_b32_e32 v22, 0x51, v22
	v_and_or_b32 v23, v23, s6, v211
	v_or_b32_e32 v23, 0x50, v23
	v_and_or_b32 v24, v24, s6, v211
	v_or_b32_e32 v24, 0x4b, v24
	v_and_or_b32 v25, v25, s6, v211
	v_or_b32_e32 v25, 0x4a, v25
	v_and_or_b32 v26, v26, s6, v211
	v_or_b32_e32 v26, 0x49, v26
	v_and_or_b32 v27, v27, s6, v211
	v_or_b32_e32 v27, 0x48, v27
	v_and_or_b32 v28, v28, s6, v211
	v_or_b32_e32 v28, 0x43, v28
	v_and_or_b32 v29, v29, s6, v211
	v_or_b32_e32 v29, 0x42, v29
	v_and_or_b32 v30, v30, s6, v211
	v_or_b32_e32 v30, 0x41, v30
	v_and_or_b32 v31, v31, s6, v211
	v_or_b32_e32 v31, 64, v31
	v_and_or_b32 v32, v32, s6, v211
	v_or_b32_e32 v32, 59, v32
	v_and_or_b32 v33, v33, s6, v211
	v_or_b32_e32 v33, 58, v33
	v_and_or_b32 v34, v34, s6, v211
	v_or_b32_e32 v34, 57, v34
	v_and_or_b32 v35, v35, s6, v211
	v_or_b32_e32 v35, 56, v35
	v_and_or_b32 v36, v36, s6, v211
	v_or_b32_e32 v36, 51, v36
	v_and_or_b32 v37, v37, s6, v211
	v_or_b32_e32 v37, 50, v37
	v_and_or_b32 v38, v38, s6, v211
	v_or_b32_e32 v38, 49, v38
	v_and_or_b32 v39, v39, s6, v211
	v_or_b32_e32 v39, 48, v39
	v_and_or_b32 v40, v40, s6, v211
	v_or_b32_e32 v40, 43, v40
	v_and_or_b32 v41, v41, s6, v211
	v_or_b32_e32 v41, 42, v41
	v_and_or_b32 v42, v42, s6, v211
	v_or_b32_e32 v42, 41, v42
	v_and_or_b32 v43, v43, s6, v211
	v_or_b32_e32 v43, 40, v43
	v_and_or_b32 v44, v44, s6, v211
	v_or_b32_e32 v44, 35, v44
	v_and_or_b32 v45, v45, s6, v211
	v_or_b32_e32 v45, 34, v45
	v_and_or_b32 v46, v46, s6, v211
	v_or_b32_e32 v46, 33, v46
	v_and_or_b32 v47, v47, s6, v211
	v_or_b32_e32 v47, 32, v47
	v_and_or_b32 v48, v48, s6, v211
	v_or_b32_e32 v48, 27, v48
	v_and_or_b32 v49, v49, s6, v211
	v_or_b32_e32 v49, 26, v49
	v_and_or_b32 v50, v50, s6, v211
	v_or_b32_e32 v50, 25, v50
	v_and_or_b32 v51, v51, s6, v211
	v_or_b32_e32 v51, 24, v51
	v_and_or_b32 v52, v52, s6, v211
	v_or_b32_e32 v52, 19, v52
	v_and_or_b32 v53, v53, s6, v211
	v_or_b32_e32 v53, 18, v53
	v_and_or_b32 v54, v54, s6, v211
	v_or_b32_e32 v54, 17, v54
	v_and_or_b32 v55, v55, s6, v211
	v_or_b32_e32 v55, 16, v55
	v_and_or_b32 v56, v56, s6, v211
	v_or_b32_e32 v56, 11, v56
	v_and_or_b32 v57, v57, s6, v211
	v_or_b32_e32 v57, 10, v57
	v_and_or_b32 v58, v58, s6, v211
	v_or_b32_e32 v58, 9, v58
	v_and_or_b32 v59, v59, s6, v211
	v_or_b32_e32 v59, 8, v59
	v_and_or_b32 v60, v60, s6, v211
	v_or_b32_e32 v60, 3, v60
	v_and_or_b32 v61, v61, s6, v211
	v_or_b32_e32 v61, 2, v61
	v_and_or_b32 v62, v62, s6, v211
	v_or_b32_e32 v62, 1, v62
	v_and_or_b32 v63, v63, s6, v211
	v_or_b32_e32 v63, 0, v63
	v_max_f32_e32 v144, v0, v13
	v_min_f32_e32 v13, v0, v13
	v_max_f32_e32 v145, v1, v12
	v_min_f32_e32 v12, v1, v12
	v_max_f32_e32 v146, v2, v15
	v_min_f32_e32 v15, v2, v15
	v_max_f32_e32 v147, v3, v14
	v_min_f32_e32 v14, v3, v14
	v_max_f32_e32 v148, v4, v8
	v_min_f32_e32 v8, v4, v8
	v_max_f32_e32 v149, v5, v6
	v_min_f32_e32 v6, v5, v6
	v_max_f32_e32 v150, v7, v11
	v_min_f32_e32 v11, v7, v11
	v_max_f32_e32 v151, v9, v10
	v_min_f32_e32 v10, v9, v10
	v_max_f32_e32 v249, v144, v149
	v_min_f32_e32 v149, v144, v149
	v_max_f32_e32 v250, v145, v150
	v_min_f32_e32 v150, v145, v150
	v_max_f32_e32 v251, v146, v151
	v_min_f32_e32 v151, v146, v151
	v_max_f32_e32 v252, v147, v148
	v_min_f32_e32 v148, v147, v148
	v_max_f32_e32 v253, v6, v13
	v_min_f32_e32 v13, v6, v13
	v_max_f32_e32 v254, v8, v14
	v_min_f32_e32 v14, v8, v14
	v_max_f32_e32 v255, v10, v15
	v_min_f32_e32 v15, v10, v15
	v_max_f32_e32 v96, v11, v12
	v_min_f32_e32 v12, v11, v12
	v_max_f32_e32 v97, v249, v250
	v_min_f32_e32 v250, v249, v250
	v_max_f32_e32 v98, v251, v252
	v_min_f32_e32 v252, v251, v252
	v_max_f32_e32 v99, v148, v149
	v_min_f32_e32 v149, v148, v149
	v_max_f32_e32 v100, v253, v254
	v_min_f32_e32 v254, v253, v254
	v_max_f32_e32 v101, v150, v151
	v_min_f32_e32 v151, v150, v151
	v_max_f32_e32 v102, v255, v96
	v_min_f32_e32 v96, v255, v96
	v_max_f32_e32 v103, v12, v13
	v_min_f32_e32 v13, v12, v13
	v_max_f32_e32 v104, v14, v15
	v_min_f32_e32 v15, v14, v15
	v_max_f32_e32 v105, v97, v98
	v_min_f32_e32 v98, v97, v98
	v_max_f32_e32 v106, v250, v252
	v_min_f32_e32 v252, v250, v252
	v_max_f32_e32 v107, v99, v102
	v_min_f32_e32 v102, v99, v102
	v_max_f32_e32 v108, v149, v96
	v_min_f32_e32 v96, v149, v96
	v_max_f32_e32 v109, v100, v101
	v_min_f32_e32 v101, v100, v101
	v_max_f32_e32 v110, v254, v151
	v_min_f32_e32 v151, v254, v151
	v_max_f32_e32 v111, v103, v104
	v_min_f32_e32 v104, v103, v104
	v_max_f32_e32 v112, v13, v15
	v_min_f32_e32 v15, v13, v15
	v_max_f32_e32 v113, v106, v98
	v_min_f32_e32 v98, v106, v98
	v_max_f32_e32 v114, v252, v111
	v_min_f32_e32 v111, v252, v111
	v_max_f32_e32 v115, v107, v109
	v_min_f32_e32 v109, v107, v109
	v_max_f32_e32 v116, v108, v101
	v_min_f32_e32 v101, v108, v101
	v_max_f32_e32 v117, v110, v102
	v_min_f32_e32 v102, v110, v102
	v_max_f32_e32 v118, v151, v96
	v_min_f32_e32 v96, v151, v96
	v_max_f32_e32 v119, v112, v104
	v_min_f32_e32 v104, v112, v104
	v_max_f32_e32 v120, v113, v115
	v_min_f32_e32 v115, v113, v115
	v_max_f32_e32 v121, v98, v109
	v_min_f32_e32 v109, v98, v109
	v_max_f32_e32 v122, v116, v117
	v_min_f32_e32 v117, v116, v117
	v_max_f32_e32 v123, v101, v102
	v_min_f32_e32 v102, v101, v102
	v_max_f32_e32 v124, v118, v119
	v_min_f32_e32 v119, v118, v119
	v_max_f32_e32 v125, v96, v104
	v_min_f32_e32 v104, v96, v104
	v_max_f32_e32 v126, v121, v115
	v_min_f32_e32 v115, v121, v115
	v_max_f32_e32 v127, v114, v109
	v_min_f32_e32 v109, v114, v109
	v_max_f32_e32 v0, v124, v111
	v_min_f32_e32 v111, v124, v111
	v_max_f32_e32 v1, v125, v119
	v_min_f32_e32 v119, v125, v119
	v_max_f32_e32 v2, v127, v122
	v_min_f32_e32 v122, v127, v122
	v_max_f32_e32 v3, v109, v117
	v_min_f32_e32 v117, v109, v117
	v_max_f32_e32 v4, v123, v0
	v_min_f32_e32 v0, v123, v0
	v_max_f32_e32 v5, v102, v111
	v_min_f32_e32 v111, v102, v111
	v_max_f32_e32 v7, v2, v115
	v_min_f32_e32 v115, v2, v115
	v_max_f32_e32 v9, v122, v3
	v_min_f32_e32 v3, v122, v3
	v_max_f32_e32 v144, v4, v117
	v_min_f32_e32 v117, v4, v117
	v_max_f32_e32 v145, v0, v5
	v_min_f32_e32 v5, v0, v5
	v_max_f32_e32 v146, v1, v111
	v_min_f32_e32 v111, v1, v111
	v_max_f32_e32 v147, v3, v144
	v_min_f32_e32 v144, v3, v144
	v_max_f32_e32 v6, v117, v145
	v_min_f32_e32 v145, v117, v145
	v_max_f32_e32 v8, v16, v29
	v_min_f32_e32 v29, v16, v29
	v_max_f32_e32 v10, v17, v28
	v_min_f32_e32 v28, v17, v28
	v_max_f32_e32 v11, v18, v31
	v_min_f32_e32 v31, v18, v31
	v_max_f32_e32 v249, v19, v30
	v_min_f32_e32 v30, v19, v30
	v_max_f32_e32 v251, v20, v24
	v_min_f32_e32 v24, v20, v24
	v_max_f32_e32 v148, v21, v22
	v_min_f32_e32 v22, v21, v22
	v_max_f32_e32 v253, v23, v27
	v_min_f32_e32 v27, v23, v27
	v_max_f32_e32 v150, v25, v26
	v_min_f32_e32 v26, v25, v26
	v_max_f32_e32 v255, v8, v148
	v_min_f32_e32 v148, v8, v148
	v_max_f32_e32 v12, v10, v253
	v_min_f32_e32 v253, v10, v253
	v_max_f32_e32 v14, v11, v150
	v_min_f32_e32 v150, v11, v150
	v_max_f32_e32 v97, v249, v251
	v_min_f32_e32 v251, v249, v251
	v_max_f32_e32 v250, v22, v29
	v_min_f32_e32 v29, v22, v29
	v_max_f32_e32 v99, v24, v30
	v_min_f32_e32 v30, v24, v30
	v_max_f32_e32 v149, v26, v31
	v_min_f32_e32 v31, v26, v31
	v_max_f32_e32 v100, v27, v28
	v_min_f32_e32 v28, v27, v28
	v_max_f32_e32 v254, v255, v12
	v_min_f32_e32 v12, v255, v12
	v_max_f32_e32 v103, v14, v97
	v_min_f32_e32 v97, v14, v97
	v_max_f32_e32 v13, v251, v148
	v_min_f32_e32 v148, v251, v148
	v_max_f32_e32 v106, v250, v99
	v_min_f32_e32 v99, v250, v99
	v_max_f32_e32 v252, v253, v150
	v_min_f32_e32 v150, v253, v150
	v_max_f32_e32 v107, v149, v100
	v_min_f32_e32 v100, v149, v100
	v_max_f32_e32 v108, v28, v29
	v_min_f32_e32 v29, v28, v29
	v_max_f32_e32 v110, v30, v31
	v_min_f32_e32 v31, v30, v31
	v_max_f32_e32 v151, v254, v103
	v_min_f32_e32 v103, v254, v103
	v_max_f32_e32 v112, v12, v97
	v_min_f32_e32 v97, v12, v97
	v_max_f32_e32 v113, v13, v107
	v_min_f32_e32 v107, v13, v107
	v_max_f32_e32 v98, v148, v100
	v_min_f32_e32 v100, v148, v100
	v_max_f32_e32 v116, v106, v252
	v_min_f32_e32 v252, v106, v252
	v_max_f32_e32 v101, v99, v150
	v_min_f32_e32 v150, v99, v150
	v_max_f32_e32 v118, v108, v110
	v_min_f32_e32 v110, v108, v110
	v_max_f32_e32 v96, v29, v31
	v_min_f32_e32 v31, v29, v31
	v_max_f32_e32 v121, v112, v103
	v_min_f32_e32 v103, v112, v103
	v_max_f32_e32 v114, v97, v118
	v_min_f32_e32 v118, v97, v118
	v_max_f32_e32 v124, v113, v116
	v_min_f32_e32 v116, v113, v116
	v_max_f32_e32 v125, v98, v252
	v_min_f32_e32 v252, v98, v252
	v_max_f32_e32 v127, v101, v107
	v_min_f32_e32 v107, v101, v107
	v_max_f32_e32 v109, v150, v100
	v_min_f32_e32 v100, v150, v100
	v_max_f32_e32 v123, v96, v110
	v_min_f32_e32 v110, v96, v110
	v_max_f32_e32 v102, v121, v124
	v_min_f32_e32 v124, v121, v124
	v_max_f32_e32 v2, v103, v116
	v_min_f32_e32 v116, v103, v116
	v_max_f32_e32 v122, v125, v127
	v_min_f32_e32 v127, v125, v127
	v_max_f32_e32 v4, v252, v107
	v_min_f32_e32 v107, v252, v107
	v_max_f32_e32 v0, v109, v123
	v_min_f32_e32 v123, v109, v123
	v_max_f32_e32 v1, v100, v110
	v_min_f32_e32 v110, v100, v110
	v_max_f32_e32 v3, v2, v124
	v_min_f32_e32 v124, v2, v124
	v_max_f32_e32 v117, v114, v116
	v_min_f32_e32 v116, v114, v116
	v_max_f32_e32 v16, v0, v118
	v_min_f32_e32 v118, v0, v118
	v_max_f32_e32 v17, v1, v123
	v_min_f32_e32 v123, v1, v123
	v_max_f32_e32 v18, v117, v122
	v_min_f32_e32 v122, v117, v122
	v_max_f32_e32 v19, v116, v127
	v_min_f32_e32 v127, v116, v127
	v_max_f32_e32 v20, v4, v16
	v_min_f32_e32 v16, v4, v16
	v_max_f32_e32 v21, v107, v118
	v_min_f32_e32 v118, v107, v118
	v_max_f32_e32 v23, v18, v124
	v_min_f32_e32 v124, v18, v124
	v_max_f32_e32 v25, v122, v19
	v_min_f32_e32 v19, v122, v19
	v_max_f32_e32 v8, v20, v127
	v_min_f32_e32 v127, v20, v127
	v_max_f32_e32 v10, v16, v21
	v_min_f32_e32 v21, v16, v21
	v_max_f32_e32 v11, v17, v118
	v_min_f32_e32 v118, v17, v118
	v_max_f32_e32 v249, v19, v8
	v_min_f32_e32 v8, v19, v8
	v_max_f32_e32 v22, v127, v10
	v_min_f32_e32 v10, v127, v10
	s_waitcnt vmcnt(24)
	v_pk_mul_f32 v[160:161], v[160:161], v[176:177]
	v_pk_mul_f32 v[162:163], v[162:163], v[178:179]
	v_pk_mul_f32 v[164:165], v[164:165], v[180:181]
	v_pk_mul_f32 v[166:167], v[166:167], v[182:183]
	v_pk_mul_f32 v[168:169], v[168:169], v[184:185]
	v_pk_mul_f32 v[170:171], v[170:171], v[186:187]
	v_pk_mul_f32 v[172:173], v[172:173], v[188:189]
	v_pk_mul_f32 v[174:175], v[174:175], v[190:191]
	v_max3_f32 v192, |v160|, |v161|, |v162|
	v_max3_f32 v192, |v163|, |v164|, v192
	v_max3_f32 v192, |v165|, |v166|, v192
	v_max3_f32 v192, |v167|, |v168|, v192
	v_max3_f32 v192, |v169|, |v170|, v192
	v_max3_f32 v192, |v171|, |v172|, v192
	v_max3_f32 v192, |v173|, |v174|, v192
	v_max_f32_e64 v192, |v175|, v192
	s_nop 1
	v_mov_b32_dpp v193, v192 quad_perm:[1,0,3,2] row_mask:0xf bank_mask:0xf bound_ctrl:1
	v_max_f32_e32 v192, v192, v193
	s_nop 1
	v_mov_b32_dpp v193, v192 quad_perm:[2,3,0,1] row_mask:0xf bank_mask:0xf bound_ctrl:1
	v_max_f32_e32 v192, v192, v193
	s_nop 1
	v_mov_b32_dpp v193, v192 row_half_mirror row_mask:0xf bank_mask:0xf bound_ctrl:1
	v_max_f32_e32 v192, v192, v193
	s_nop 1
	v_mov_b32_dpp v193, v192 row_mirror row_mask:0xf bank_mask:0xf bound_ctrl:1
	v_max_f32_e32 v192, v192, v193
	v_mov_b32_e32 v193, v192
	s_nop 1
	v_permlane16_swap_b32_e32 v192, v193
	s_nop 1
	v_max_f32_e32 v192, v192, v193
	v_mov_b32_e32 v193, v192
	s_nop 1
	v_permlane32_swap_b32_e32 v192, v193
	s_nop 1
	v_max_f32_e32 v192, v192, v193
	v_max_f32_e32 v192, 0xda24260, v192
	v_mul_f32_e32 v194, 0x3e2aaaab, v192
	global_store_dword v214, v194, s[12:13]
	v_div_scale_f32 v195, s[26:27], v194, v194, 1.0
	v_rcp_f32_e32 v196, v195
	v_div_scale_f32 v204, vcc, 1.0, v194, 1.0
	v_fma_f32 v205, -v195, v196, 1.0
	v_fmac_f32_e32 v196, v205, v196
	v_mul_f32_e32 v205, v204, v196
	v_fma_f32 v206, -v195, v205, v204
	v_fmac_f32_e32 v205, v206, v196
	v_fma_f32 v195, -v195, v205, v204
	s_nop 0
	v_div_fmas_f32 v195, v195, v196, v205
	v_div_fixup_f32 v207, v195, v194, 1.0
	v_mul_f32_e32 v160, v207, v160
	v_mul_f32_e32 v161, v207, v161
	v_mul_f32_e32 v162, v207, v162
	v_mul_f32_e32 v163, v207, v163
	v_mul_f32_e32 v164, v207, v164
	v_mul_f32_e32 v165, v207, v165
	v_mul_f32_e32 v166, v207, v166
	v_mul_f32_e32 v167, v207, v167
	v_mul_f32_e32 v168, v207, v168
	v_mul_f32_e32 v169, v207, v169
	v_mul_f32_e32 v170, v207, v170
	v_mul_f32_e32 v171, v207, v171
	v_mul_f32_e32 v172, v207, v172
	v_mul_f32_e32 v173, v207, v173
	v_mul_f32_e32 v174, v207, v174
	v_mul_f32_e32 v175, v207, v175
	v_mov_b32_e32 v208, 0
	v_mov_b32_e32 v209, 0
	v_mov_b32_e32 v210, 0
	v_mov_b32_e32 v193, 0
	v_cvt_scalef32_pk_fp4_f32 v208, v160, v161, 1.0
	v_cvt_scalef32_pk_fp4_f32 v209, v164, v165, 1.0
	v_cvt_scalef32_pk_fp4_f32 v210, v168, v169, 1.0
	v_cvt_scalef32_pk_fp4_f32 v193, v172, v173, 1.0
	v_cvt_scalef32_pk_fp4_f32 v208, v162, v163, 1.0 op_sel:[0,0,1,0]
	v_cvt_scalef32_pk_fp4_f32 v209, v166, v167, 1.0 op_sel:[0,0,1,0]
	v_cvt_scalef32_pk_fp4_f32 v210, v170, v171, 1.0 op_sel:[0,0,1,0]
	v_cvt_scalef32_pk_fp4_f32 v193, v174, v175, 1.0 op_sel:[0,0,1,0]
	global_store_short v213, v208, s[10:11] nt
	s_add_u32 s14, s10, 0x200000
	s_addc_u32 s15, s11, 0
	global_store_short v213, v209, s[14:15] nt
	s_add_u32 s14, s10, 0x400000
	s_addc_u32 s15, s11, 0
	global_store_short v213, v210, s[14:15] nt
	s_add_u32 s14, s10, 0x600000
	s_addc_u32 s15, s11, 0
	global_store_short v213, v193, s[14:15] nt
	s_add_u32 s10, s10, 0x20000
	s_addc_u32 s11, s11, 0
	s_add_u32 s12, s12, 0x2000
	s_addc_u32 s13, s13, 0
	global_load_dwordx4 v[160:163], v212, s[8:9] offset:0 nt
	global_load_dwordx4 v[164:167], v212, s[8:9] offset:1024 nt
	global_load_dwordx4 v[168:171], v212, s[8:9] offset:2048 nt
	global_load_dwordx4 v[172:175], v212, s[8:9] offset:3072 nt
	s_add_u32 s8, s8, 0x800000
	s_addc_u32 s9, s9, 0
	v_max_f32_e32 v24, v32, v45
	v_min_f32_e32 v45, v32, v45
	v_max_f32_e32 v26, v33, v44
	v_min_f32_e32 v44, v33, v44
	v_max_f32_e32 v27, v34, v47
	v_min_f32_e32 v47, v34, v47
	v_max_f32_e32 v255, v35, v46
	v_min_f32_e32 v46, v35, v46
	v_max_f32_e32 v14, v36, v40
	v_min_f32_e32 v40, v36, v40
	v_max_f32_e32 v251, v37, v38
	v_min_f32_e32 v38, v37, v38
	v_max_f32_e32 v250, v39, v43
	v_min_f32_e32 v43, v39, v43
	v_max_f32_e32 v253, v41, v42
	v_min_f32_e32 v42, v41, v42
	v_max_f32_e32 v149, v24, v251
	v_min_f32_e32 v251, v24, v251
	v_max_f32_e32 v28, v26, v250
	v_min_f32_e32 v250, v26, v250
	v_max_f32_e32 v30, v27, v253
	v_min_f32_e32 v253, v27, v253
	v_max_f32_e32 v254, v255, v14
	v_min_f32_e32 v14, v255, v14
	v_max_f32_e32 v12, v38, v45
	v_min_f32_e32 v45, v38, v45
	v_max_f32_e32 v13, v40, v46
	v_min_f32_e32 v46, v40, v46
	v_max_f32_e32 v148, v42, v47
	v_min_f32_e32 v47, v42, v47
	v_max_f32_e32 v106, v43, v44
	v_min_f32_e32 v44, v43, v44
	v_max_f32_e32 v99, v149, v28
	v_min_f32_e32 v28, v149, v28
	v_max_f32_e32 v108, v30, v254
	v_min_f32_e32 v254, v30, v254
	v_max_f32_e32 v29, v14, v251
	v_min_f32_e32 v251, v14, v251
	v_max_f32_e32 v112, v12, v13
	v_min_f32_e32 v13, v12, v13
	v_max_f32_e32 v97, v250, v253
	v_min_f32_e32 v253, v250, v253
	v_max_f32_e32 v113, v148, v106
	v_min_f32_e32 v106, v148, v106
	v_max_f32_e32 v98, v44, v45
	v_min_f32_e32 v45, v44, v45
	v_max_f32_e32 v101, v46, v47
	v_min_f32_e32 v47, v46, v47
	v_max_f32_e32 v150, v99, v108
	v_min_f32_e32 v108, v99, v108
	v_max_f32_e32 v96, v28, v254
	v_min_f32_e32 v254, v28, v254
	v_max_f32_e32 v121, v29, v113
	v_min_f32_e32 v113, v29, v113
	v_max_f32_e32 v103, v251, v106
	v_min_f32_e32 v106, v251, v106
	v_max_f32_e32 v125, v112, v97
	v_min_f32_e32 v97, v112, v97
	v_max_f32_e32 v252, v13, v253
	v_min_f32_e32 v253, v13, v253
	v_max_f32_e32 v109, v98, v101
	v_min_f32_e32 v101, v98, v101
	v_max_f32_e32 v100, v45, v47
	v_min_f32_e32 v47, v45, v47
	v_max_f32_e32 v2, v96, v108
	v_min_f32_e32 v108, v96, v108
	v_max_f32_e32 v114, v254, v109
	v_min_f32_e32 v109, v254, v109
	v_max_f32_e32 v0, v121, v125
	v_min_f32_e32 v125, v121, v125
	v_max_f32_e32 v1, v103, v97
	v_min_f32_e32 v97, v103, v97
	v_max_f32_e32 v117, v252, v113
	v_min_f32_e32 v113, v252, v113
	v_max_f32_e32 v116, v253, v106
	v_min_f32_e32 v106, v253, v106
	v_max_f32_e32 v4, v100, v101
	v_min_f32_e32 v101, v100, v101
	v_max_f32_e32 v107, v2, v0
	v_min_f32_e32 v0, v2, v0
	v_max_f32_e32 v18, v108, v125
	v_min_f32_e32 v125, v108, v125
	v_max_f32_e32 v122, v1, v117
	v_min_f32_e32 v117, v1, v117
	v_max_f32_e32 v20, v97, v113
	v_min_f32_e32 v113, v97, v113
	v_max_f32_e32 v16, v116, v4
	v_min_f32_e32 v4, v116, v4
	v_max_f32_e32 v17, v106, v101
	v_min_f32_e32 v101, v106, v101
	v_max_f32_e32 v19, v18, v0
	v_min_f32_e32 v0, v18, v0
	v_max_f32_e32 v127, v114, v125
	v_min_f32_e32 v125, v114, v125
	v_max_f32_e32 v32, v16, v109
	v_min_f32_e32 v109, v16, v109
	v_max_f32_e32 v33, v17, v4
	v_min_f32_e32 v4, v17, v4
	v_max_f32_e32 v34, v127, v122
	v_min_f32_e32 v122, v127, v122
	v_max_f32_e32 v35, v125, v117
	v_min_f32_e32 v117, v125, v117
	v_max_f32_e32 v36, v20, v32
	v_min_f32_e32 v32, v20, v32
	v_max_f32_e32 v37, v113, v109
	v_min_f32_e32 v109, v113, v109
	v_max_f32_e32 v39, v34, v0
	v_min_f32_e32 v0, v34, v0
	v_max_f32_e32 v41, v122, v35
	v_min_f32_e32 v35, v122, v35
	v_max_f32_e32 v24, v36, v117
	v_min_f32_e32 v117, v36, v117
	v_max_f32_e32 v26, v32, v37
	v_min_f32_e32 v37, v32, v37
	v_max_f32_e32 v27, v33, v109
	v_min_f32_e32 v109, v33, v109
	v_max_f32_e32 v255, v35, v24
	v_min_f32_e32 v24, v35, v24
	v_max_f32_e32 v38, v117, v26
	v_min_f32_e32 v26, v117, v26
	v_max_f32_e32 v40, v48, v61
	v_min_f32_e32 v61, v48, v61
	v_max_f32_e32 v42, v49, v60
	v_min_f32_e32 v60, v49, v60
	v_max_f32_e32 v43, v50, v63
	v_min_f32_e32 v63, v50, v63
	v_max_f32_e32 v149, v51, v62
	v_min_f32_e32 v62, v51, v62
	v_max_f32_e32 v30, v52, v56
	v_min_f32_e32 v56, v52, v56
	v_max_f32_e32 v14, v53, v54
	v_min_f32_e32 v54, v53, v54
	v_max_f32_e32 v12, v55, v59
	v_min_f32_e32 v59, v55, v59
	v_max_f32_e32 v250, v57, v58
	v_min_f32_e32 v58, v57, v58
	v_max_f32_e32 v148, v40, v14
	v_min_f32_e32 v14, v40, v14
	v_max_f32_e32 v44, v42, v12
	v_min_f32_e32 v12, v42, v12
	v_max_f32_e32 v46, v43, v250
	v_min_f32_e32 v250, v43, v250
	v_max_f32_e32 v99, v149, v30
	v_min_f32_e32 v30, v149, v30
	v_max_f32_e32 v28, v54, v61
	v_min_f32_e32 v61, v54, v61
	v_max_f32_e32 v29, v56, v62
	v_min_f32_e32 v62, v56, v62
	v_max_f32_e32 v251, v58, v63
	v_min_f32_e32 v63, v58, v63
	v_max_f32_e32 v112, v59, v60
	v_min_f32_e32 v60, v59, v60
	v_max_f32_e32 v13, v148, v44
	v_min_f32_e32 v44, v148, v44
	v_max_f32_e32 v98, v46, v99
	v_min_f32_e32 v99, v46, v99
	v_max_f32_e32 v45, v30, v14
	v_min_f32_e32 v14, v30, v14
	v_max_f32_e32 v96, v28, v29
	v_min_f32_e32 v29, v28, v29
	v_max_f32_e32 v254, v12, v250
	v_min_f32_e32 v250, v12, v250
	v_max_f32_e32 v121, v251, v112
	v_min_f32_e32 v112, v251, v112
	v_max_f32_e32 v103, v60, v61
	v_min_f32_e32 v61, v60, v61
	v_max_f32_e32 v252, v62, v63
	v_min_f32_e32 v63, v62, v63
	v_max_f32_e32 v253, v13, v98
	v_min_f32_e32 v98, v13, v98
	v_max_f32_e32 v100, v44, v99
	v_min_f32_e32 v99, v44, v99
	v_max_f32_e32 v2, v45, v121
	v_min_f32_e32 v121, v45, v121
	v_max_f32_e32 v108, v14, v112
	v_min_f32_e32 v112, v14, v112
	v_max_f32_e32 v1, v96, v254
	v_min_f32_e32 v254, v96, v254
	v_max_f32_e32 v97, v29, v250
	v_min_f32_e32 v250, v29, v250
	v_max_f32_e32 v116, v103, v252
	v_min_f32_e32 v252, v103, v252
	v_max_f32_e32 v106, v61, v63
	v_min_f32_e32 v63, v61, v63
	v_max_f32_e32 v18, v100, v98
	v_min_f32_e32 v98, v100, v98
	v_max_f32_e32 v114, v99, v116
	v_min_f32_e32 v116, v99, v116
	v_max_f32_e32 v16, v2, v1
	v_min_f32_e32 v1, v2, v1
	v_max_f32_e32 v17, v108, v254
	v_min_f32_e32 v254, v108, v254
	v_max_f32_e32 v127, v97, v121
	v_min_f32_e32 v121, v97, v121
	v_max_f32_e32 v125, v250, v112
	v_min_f32_e32 v112, v250, v112
	v_max_f32_e32 v20, v106, v252
	v_min_f32_e32 v252, v106, v252
	v_max_f32_e32 v113, v18, v16
	v_min_f32_e32 v16, v18, v16
	v_max_f32_e32 v34, v98, v1
	v_min_f32_e32 v1, v98, v1
	v_max_f32_e32 v122, v17, v127
	v_min_f32_e32 v127, v17, v127
	v_max_f32_e32 v36, v254, v121
	v_min_f32_e32 v121, v254, v121
	v_max_f32_e32 v32, v125, v20
	v_min_f32_e32 v20, v125, v20
	v_max_f32_e32 v33, v112, v252
	v_min_f32_e32 v252, v112, v252
	v_max_f32_e32 v35, v34, v16
	v_min_f32_e32 v16, v34, v16
	v_max_f32_e32 v117, v114, v1
	v_min_f32_e32 v1, v114, v1
	v_max_f32_e32 v48, v32, v116
	v_min_f32_e32 v116, v32, v116
	v_max_f32_e32 v49, v33, v20
	v_min_f32_e32 v20, v33, v20
	v_max_f32_e32 v50, v117, v122
	v_min_f32_e32 v122, v117, v122
	v_max_f32_e32 v51, v1, v127
	v_min_f32_e32 v127, v1, v127
	v_max_f32_e32 v52, v36, v48
	v_min_f32_e32 v48, v36, v48
	v_max_f32_e32 v53, v121, v116
	v_min_f32_e32 v116, v121, v116
	v_max_f32_e32 v55, v50, v16
	v_min_f32_e32 v16, v50, v16
	v_max_f32_e32 v57, v122, v51
	v_min_f32_e32 v51, v122, v51
	v_max_f32_e32 v40, v52, v127
	v_min_f32_e32 v127, v52, v127
	v_max_f32_e32 v42, v48, v53
	v_min_f32_e32 v53, v48, v53
	v_max_f32_e32 v43, v49, v116
	v_min_f32_e32 v116, v49, v116
	v_max_f32_e32 v149, v51, v40
	v_min_f32_e32 v40, v51, v40
	v_max_f32_e32 v54, v127, v42
	v_min_f32_e32 v42, v127, v42
	s_waitcnt vmcnt(0)
	v_pk_mul_f32 v[160:161], v[160:161], v[176:177]
	v_pk_mul_f32 v[162:163], v[162:163], v[178:179]
	v_pk_mul_f32 v[164:165], v[164:165], v[180:181]
	v_pk_mul_f32 v[166:167], v[166:167], v[182:183]
	v_pk_mul_f32 v[168:169], v[168:169], v[184:185]
	v_pk_mul_f32 v[170:171], v[170:171], v[186:187]
	v_pk_mul_f32 v[172:173], v[172:173], v[188:189]
	v_pk_mul_f32 v[174:175], v[174:175], v[190:191]
	v_max3_f32 v192, |v160|, |v161|, |v162|
	v_max3_f32 v192, |v163|, |v164|, v192
	v_max3_f32 v192, |v165|, |v166|, v192
	v_max3_f32 v192, |v167|, |v168|, v192
	v_max3_f32 v192, |v169|, |v170|, v192
	v_max3_f32 v192, |v171|, |v172|, v192
	v_max3_f32 v192, |v173|, |v174|, v192
	v_max_f32_e64 v192, |v175|, v192
	s_nop 1
	v_mov_b32_dpp v193, v192 quad_perm:[1,0,3,2] row_mask:0xf bank_mask:0xf bound_ctrl:1
	v_max_f32_e32 v192, v192, v193
	s_nop 1
	v_mov_b32_dpp v193, v192 quad_perm:[2,3,0,1] row_mask:0xf bank_mask:0xf bound_ctrl:1
	v_max_f32_e32 v192, v192, v193
	s_nop 1
	v_mov_b32_dpp v193, v192 row_half_mirror row_mask:0xf bank_mask:0xf bound_ctrl:1
	v_max_f32_e32 v192, v192, v193
	s_nop 1
	v_mov_b32_dpp v193, v192 row_mirror row_mask:0xf bank_mask:0xf bound_ctrl:1
	v_max_f32_e32 v192, v192, v193
	v_mov_b32_e32 v193, v192
	s_nop 1
	v_permlane16_swap_b32_e32 v192, v193
	s_nop 1
	v_max_f32_e32 v192, v192, v193
	v_mov_b32_e32 v193, v192
	s_nop 1
	v_permlane32_swap_b32_e32 v192, v193
	s_nop 1
	v_max_f32_e32 v192, v192, v193
	v_max_f32_e32 v192, 0xda24260, v192
	v_mul_f32_e32 v194, 0x3e2aaaab, v192
	global_store_dword v214, v194, s[12:13]
	v_div_scale_f32 v195, s[26:27], v194, v194, 1.0
	v_rcp_f32_e32 v196, v195
	v_div_scale_f32 v204, vcc, 1.0, v194, 1.0
	v_fma_f32 v205, -v195, v196, 1.0
	v_fmac_f32_e32 v196, v205, v196
	v_mul_f32_e32 v205, v204, v196
	v_fma_f32 v206, -v195, v205, v204
	v_fmac_f32_e32 v205, v206, v196
	v_fma_f32 v195, -v195, v205, v204
	s_nop 0
	v_div_fmas_f32 v195, v195, v196, v205
	v_div_fixup_f32 v207, v195, v194, 1.0
	v_mul_f32_e32 v160, v207, v160
	v_mul_f32_e32 v161, v207, v161
	v_mul_f32_e32 v162, v207, v162
	v_mul_f32_e32 v163, v207, v163
	v_mul_f32_e32 v164, v207, v164
	v_mul_f32_e32 v165, v207, v165
	v_mul_f32_e32 v166, v207, v166
	v_mul_f32_e32 v167, v207, v167
	v_mul_f32_e32 v168, v207, v168
	v_mul_f32_e32 v169, v207, v169
	v_mul_f32_e32 v170, v207, v170
	v_mul_f32_e32 v171, v207, v171
	v_mul_f32_e32 v172, v207, v172
	v_mul_f32_e32 v173, v207, v173
	v_mul_f32_e32 v174, v207, v174
	v_mul_f32_e32 v175, v207, v175
	v_mov_b32_e32 v208, 0
	v_mov_b32_e32 v209, 0
	v_mov_b32_e32 v210, 0
	v_mov_b32_e32 v193, 0
	v_cvt_scalef32_pk_fp4_f32 v208, v160, v161, 1.0
	v_cvt_scalef32_pk_fp4_f32 v209, v164, v165, 1.0
	v_cvt_scalef32_pk_fp4_f32 v210, v168, v169, 1.0
	v_cvt_scalef32_pk_fp4_f32 v193, v172, v173, 1.0
	v_cvt_scalef32_pk_fp4_f32 v208, v162, v163, 1.0 op_sel:[0,0,1,0]
	v_cvt_scalef32_pk_fp4_f32 v209, v166, v167, 1.0 op_sel:[0,0,1,0]
	v_cvt_scalef32_pk_fp4_f32 v210, v170, v171, 1.0 op_sel:[0,0,1,0]
	v_cvt_scalef32_pk_fp4_f32 v193, v174, v175, 1.0 op_sel:[0,0,1,0]
	global_store_short v213, v208, s[10:11] nt
	s_add_u32 s14, s10, 0x200000
	s_addc_u32 s15, s11, 0
	global_store_short v213, v209, s[14:15] nt
	s_add_u32 s14, s10, 0x400000
	s_addc_u32 s15, s11, 0
	global_store_short v213, v210, s[14:15] nt
	s_add_u32 s14, s10, 0x600000
	s_addc_u32 s15, s11, 0
	global_store_short v213, v193, s[14:15] nt
	s_add_u32 s10, s10, 0x20000
	s_addc_u32 s11, s11, 0
	s_add_u32 s12, s12, 0x2000
	s_addc_u32 s13, s13, 0
	global_load_dwordx4 v[160:163], v212, s[8:9] offset:0 nt
	global_load_dwordx4 v[164:167], v212, s[8:9] offset:1024 nt
	global_load_dwordx4 v[168:171], v212, s[8:9] offset:2048 nt
	global_load_dwordx4 v[172:175], v212, s[8:9] offset:3072 nt
	s_add_u32 s8, s8, 0x800000
	s_addc_u32 s9, s9, 0
	v_max_f32_e32 v105, v105, v31
	v_max_f32_e32 v120, v120, v110
	v_max_f32_e32 v126, v126, v123
	v_max_f32_e32 v7, v7, v118
	v_max_f32_e32 v115, v115, v11
	v_max_f32_e32 v9, v9, v21
	v_max_f32_e32 v147, v147, v10
	v_max_f32_e32 v144, v144, v22
	v_max_f32_e32 v6, v6, v8
	v_max_f32_e32 v145, v145, v249
	v_max_f32_e32 v5, v5, v25
	v_max_f32_e32 v146, v146, v124
	v_max_f32_e32 v111, v111, v23
	v_max_f32_e32 v119, v119, v3
	v_max_f32_e32 v104, v104, v102
	v_max_f32_e32 v15, v15, v151
	v_max_f32_e32 v56, v105, v6
	v_min_f32_e32 v6, v105, v6
	v_max_f32_e32 v58, v120, v145
	v_min_f32_e32 v145, v120, v145
	v_max_f32_e32 v59, v126, v5
	v_min_f32_e32 v5, v126, v5
	v_max_f32_e32 v148, v7, v146
	v_min_f32_e32 v146, v7, v146
	v_max_f32_e32 v46, v115, v111
	v_min_f32_e32 v111, v115, v111
	v_max_f32_e32 v30, v9, v119
	v_min_f32_e32 v119, v9, v119
	v_max_f32_e32 v28, v147, v104
	v_min_f32_e32 v104, v147, v104
	v_max_f32_e32 v12, v144, v15
	v_min_f32_e32 v15, v144, v15
	v_max_f32_e32 v251, v56, v46
	v_min_f32_e32 v46, v56, v46
	v_max_f32_e32 v60, v58, v30
	v_min_f32_e32 v30, v58, v30
	v_max_f32_e32 v62, v59, v28
	v_min_f32_e32 v28, v59, v28
	v_max_f32_e32 v13, v148, v12
	v_min_f32_e32 v12, v148, v12
	v_max_f32_e32 v44, v6, v111
	v_min_f32_e32 v111, v6, v111
	v_max_f32_e32 v45, v145, v119
	v_min_f32_e32 v119, v145, v119
	v_max_f32_e32 v14, v5, v104
	v_min_f32_e32 v104, v5, v104
	v_max_f32_e32 v96, v146, v15
	v_min_f32_e32 v15, v146, v15
	v_max_f32_e32 v29, v251, v62
	v_min_f32_e32 v62, v251, v62
	v_max_f32_e32 v103, v60, v13
	v_min_f32_e32 v13, v60, v13
	v_max_f32_e32 v61, v46, v28
	v_min_f32_e32 v28, v46, v28
	v_max_f32_e32 v100, v30, v12
	v_min_f32_e32 v12, v30, v12
	v_max_f32_e32 v99, v44, v14
	v_min_f32_e32 v14, v44, v14
	v_max_f32_e32 v2, v45, v96
	v_min_f32_e32 v96, v45, v96
	v_max_f32_e32 v108, v111, v104
	v_min_f32_e32 v104, v111, v104
	v_max_f32_e32 v97, v119, v15
	v_min_f32_e32 v15, v119, v15
	v_max_f32_e32 v250, v29, v103
	v_min_f32_e32 v103, v29, v103
	v_max_f32_e32 v106, v62, v13
	v_min_f32_e32 v13, v62, v13
	v_max_f32_e32 v18, v61, v100
	v_min_f32_e32 v100, v61, v100
	v_max_f32_e32 v98, v28, v12
	v_min_f32_e32 v12, v28, v12
	v_max_f32_e32 v17, v99, v2
	v_min_f32_e32 v2, v99, v2
	v_max_f32_e32 v254, v14, v96
	v_min_f32_e32 v96, v14, v96
	v_max_f32_e32 v125, v108, v97
	v_min_f32_e32 v97, v108, v97
	v_max_f32_e32 v112, v104, v15
	v_min_f32_e32 v15, v104, v15
	v_max_f32_e32 v150, v150, v63
	v_max_f32_e32 v107, v107, v252
	v_max_f32_e32 v19, v19, v20
	v_max_f32_e32 v39, v39, v116
	v_max_f32_e32 v0, v0, v43
	v_max_f32_e32 v41, v41, v53
	v_max_f32_e32 v255, v255, v42
	v_max_f32_e32 v24, v24, v54
	v_max_f32_e32 v38, v38, v40
	v_max_f32_e32 v26, v26, v149
	v_max_f32_e32 v37, v37, v57
	v_max_f32_e32 v27, v27, v16
	v_max_f32_e32 v109, v109, v55
	v_max_f32_e32 v4, v4, v35
	v_max_f32_e32 v101, v101, v113
	v_max_f32_e32 v47, v47, v253
	v_max_f32_e32 v34, v150, v38
	v_min_f32_e32 v38, v150, v38
	v_max_f32_e32 v114, v107, v26
	v_min_f32_e32 v26, v107, v26
	v_max_f32_e32 v32, v19, v37
	v_min_f32_e32 v37, v19, v37
	v_max_f32_e32 v33, v39, v27
	v_min_f32_e32 v27, v39, v27
	v_max_f32_e32 v117, v0, v109
	v_min_f32_e32 v109, v0, v109
	v_max_f32_e32 v1, v41, v4
	v_min_f32_e32 v4, v41, v4
	v_max_f32_e32 v36, v255, v101
	v_min_f32_e32 v101, v255, v101
	v_max_f32_e32 v121, v24, v47
	v_min_f32_e32 v47, v24, v47
	v_max_f32_e32 v50, v34, v117
	v_min_f32_e32 v117, v34, v117
	v_max_f32_e32 v122, v114, v1
	v_min_f32_e32 v1, v114, v1
	v_max_f32_e32 v52, v32, v36
	v_min_f32_e32 v36, v32, v36
	v_max_f32_e32 v48, v33, v121
	v_min_f32_e32 v121, v33, v121
	v_max_f32_e32 v49, v38, v109
	v_min_f32_e32 v109, v38, v109
	v_max_f32_e32 v51, v26, v4
	v_min_f32_e32 v4, v26, v4
	v_max_f32_e32 v127, v37, v101
	v_min_f32_e32 v101, v37, v101
	v_max_f32_e32 v151, v27, v47
	v_min_f32_e32 v47, v27, v47
	v_max_f32_e32 v102, v50, v52
	v_min_f32_e32 v52, v50, v52
	v_max_f32_e32 v3, v122, v48
	v_min_f32_e32 v48, v122, v48
	v_max_f32_e32 v23, v117, v36
	v_min_f32_e32 v36, v117, v36
	v_max_f32_e32 v124, v1, v121
	v_min_f32_e32 v121, v1, v121
	v_max_f32_e32 v25, v49, v127
	v_min_f32_e32 v127, v49, v127
	v_max_f32_e32 v249, v51, v151
	v_min_f32_e32 v151, v51, v151
	v_max_f32_e32 v8, v109, v101
	v_min_f32_e32 v101, v109, v101
	v_max_f32_e32 v22, v4, v47
	v_min_f32_e32 v47, v4, v47
	v_max_f32_e32 v10, v102, v3
	v_min_f32_e32 v3, v102, v3
	v_max_f32_e32 v21, v52, v48
	v_min_f32_e32 v48, v52, v48
	v_max_f32_e32 v11, v23, v124
	v_min_f32_e32 v124, v23, v124
	v_max_f32_e32 v118, v36, v121
	v_min_f32_e32 v121, v36, v121
	v_max_f32_e32 v123, v25, v249
	v_min_f32_e32 v249, v25, v249
	v_max_f32_e32 v110, v127, v151
	v_min_f32_e32 v151, v127, v151
	v_max_f32_e32 v31, v8, v22
	v_min_f32_e32 v22, v8, v22
	v_max_f32_e32 v105, v101, v47
	v_min_f32_e32 v47, v101, v47
	v_max_f32_e32 v250, v250, v47
	v_max_f32_e32 v103, v103, v105
	v_max_f32_e32 v106, v106, v22
	v_max_f32_e32 v13, v13, v31
	v_max_f32_e32 v18, v18, v151
	v_max_f32_e32 v100, v100, v110
	v_max_f32_e32 v98, v98, v249
	v_max_f32_e32 v12, v12, v123
	v_max_f32_e32 v17, v17, v121
	v_max_f32_e32 v2, v2, v118
	v_max_f32_e32 v254, v254, v124
	v_max_f32_e32 v96, v96, v11
	v_max_f32_e32 v125, v125, v48
	v_max_f32_e32 v97, v97, v21
	v_max_f32_e32 v112, v112, v3
	v_max_f32_e32 v15, v15, v10
	v_max_f32_e32 v120, v250, v17
	v_min_f32_e32 v17, v250, v17
	v_max_f32_e32 v126, v103, v2
	v_min_f32_e32 v2, v103, v2
	v_max_f32_e32 v7, v106, v254
	v_min_f32_e32 v254, v106, v254
	v_max_f32_e32 v115, v13, v96
	v_min_f32_e32 v96, v13, v96
	v_max_f32_e32 v9, v18, v125
	v_min_f32_e32 v125, v18, v125
	v_max_f32_e32 v147, v100, v97
	v_min_f32_e32 v97, v100, v97
	v_max_f32_e32 v144, v98, v112
	v_min_f32_e32 v112, v98, v112
	v_max_f32_e32 v56, v12, v15
	v_min_f32_e32 v15, v12, v15
	v_max_f32_e32 v58, v120, v9
	v_min_f32_e32 v9, v120, v9
	v_max_f32_e32 v59, v126, v147
	v_min_f32_e32 v147, v126, v147
	v_max_f32_e32 v148, v7, v144
	v_min_f32_e32 v144, v7, v144
	v_max_f32_e32 v6, v115, v56
	v_min_f32_e32 v56, v115, v56
	v_max_f32_e32 v145, v17, v125
	v_min_f32_e32 v125, v17, v125
	v_max_f32_e32 v5, v2, v97
	v_min_f32_e32 v97, v2, v97
	v_max_f32_e32 v146, v254, v112
	v_min_f32_e32 v112, v254, v112
	v_max_f32_e32 v251, v96, v15
	v_min_f32_e32 v15, v96, v15
	v_max_f32_e32 v60, v58, v148
	v_min_f32_e32 v148, v58, v148
	v_max_f32_e32 v46, v59, v6
	v_min_f32_e32 v6, v59, v6
	v_max_f32_e32 v30, v9, v144
	v_min_f32_e32 v144, v9, v144
	v_max_f32_e32 v44, v147, v56
	v_min_f32_e32 v56, v147, v56
	v_max_f32_e32 v45, v145, v146
	v_min_f32_e32 v146, v145, v146
	v_max_f32_e32 v111, v5, v251
	v_min_f32_e32 v251, v5, v251
	v_max_f32_e32 v119, v125, v112
	v_min_f32_e32 v112, v125, v112
	v_max_f32_e32 v29, v97, v15
	v_min_f32_e32 v15, v97, v15
	v_max_f32_e32 v62, v60, v46
	v_min_f32_e32 v46, v60, v46
	v_max_f32_e32 v61, v148, v6
	v_min_f32_e32 v6, v148, v6
	v_max_f32_e32 v28, v30, v44
	v_min_f32_e32 v44, v30, v44
	v_max_f32_e32 v99, v144, v56
	v_min_f32_e32 v56, v144, v56
	v_max_f32_e32 v14, v45, v111
	v_min_f32_e32 v111, v45, v111
	v_max_f32_e32 v108, v146, v251
	v_min_f32_e32 v251, v146, v251
	v_max_f32_e32 v104, v119, v29
	v_min_f32_e32 v29, v119, v29
	v_max_f32_e32 v253, v112, v15
	v_min_f32_e32 v15, v112, v15
	v_mov_b32_e32 v113, v62
	v_mov_b32_e32 v35, v46
	v_mov_b32_e32 v55, v61
	v_mov_b32_e32 v16, v6
	v_mov_b32_e32 v57, v28
	v_mov_b32_e32 v149, v44
	v_mov_b32_e32 v40, v99
	v_mov_b32_e32 v54, v56
	v_mov_b32_e32 v42, v14
	v_mov_b32_e32 v53, v111
	v_mov_b32_e32 v43, v108
	v_mov_b32_e32 v116, v251
	v_mov_b32_e32 v20, v104
	v_mov_b32_e32 v252, v29
	v_mov_b32_e32 v63, v253
	v_mov_b32_e32 v150, v15
	s_nop 1
	v_permlane32_swap_b32_e32 v62, v113
	v_permlane32_swap_b32_e32 v46, v35
	v_permlane32_swap_b32_e32 v61, v55
	v_permlane32_swap_b32_e32 v6, v16
	v_permlane32_swap_b32_e32 v28, v57
	v_permlane32_swap_b32_e32 v44, v149
	v_permlane32_swap_b32_e32 v99, v40
	v_permlane32_swap_b32_e32 v56, v54
	v_permlane32_swap_b32_e32 v14, v42
	v_permlane32_swap_b32_e32 v111, v53
	v_permlane32_swap_b32_e32 v108, v43
	v_permlane32_swap_b32_e32 v251, v116
	v_permlane32_swap_b32_e32 v104, v20
	v_permlane32_swap_b32_e32 v29, v252
	v_permlane32_swap_b32_e32 v253, v63
	v_permlane32_swap_b32_e32 v15, v150
	s_nop 1
	v_max_f32_e32 v62, v62, v150
	v_max_f32_e32 v46, v46, v63
	v_max_f32_e32 v61, v61, v252
	v_max_f32_e32 v6, v6, v20
	v_max_f32_e32 v28, v28, v116
	v_max_f32_e32 v44, v44, v43
	v_max_f32_e32 v99, v99, v53
	v_max_f32_e32 v56, v56, v42
	v_max_f32_e32 v14, v14, v54
	v_max_f32_e32 v111, v111, v40
	v_max_f32_e32 v108, v108, v149
	v_max_f32_e32 v251, v251, v57
	v_max_f32_e32 v104, v104, v16
	v_max_f32_e32 v29, v29, v55
	v_max_f32_e32 v253, v253, v35
	v_max_f32_e32 v15, v15, v113
	v_max_f32_e32 v107, v62, v14
	v_min_f32_e32 v14, v62, v14
	v_max_f32_e32 v19, v46, v111
	v_min_f32_e32 v111, v46, v111
	v_max_f32_e32 v39, v61, v108
	v_min_f32_e32 v108, v61, v108
	v_max_f32_e32 v0, v6, v251
	v_min_f32_e32 v251, v6, v251
	v_max_f32_e32 v41, v28, v104
	v_min_f32_e32 v104, v28, v104
	v_max_f32_e32 v255, v44, v29
	v_min_f32_e32 v29, v44, v29
	v_max_f32_e32 v24, v99, v253
	v_min_f32_e32 v253, v99, v253
	v_max_f32_e32 v34, v56, v15
	v_min_f32_e32 v15, v56, v15
	v_max_f32_e32 v114, v107, v41
	v_min_f32_e32 v41, v107, v41
	v_max_f32_e32 v32, v19, v255
	v_min_f32_e32 v255, v19, v255
	v_max_f32_e32 v33, v39, v24
	v_min_f32_e32 v24, v39, v24
	v_max_f32_e32 v38, v0, v34
	v_min_f32_e32 v34, v0, v34
	v_max_f32_e32 v26, v14, v104
	v_min_f32_e32 v104, v14, v104
	v_max_f32_e32 v37, v111, v29
	v_min_f32_e32 v29, v111, v29
	v_max_f32_e32 v27, v108, v253
	v_min_f32_e32 v253, v108, v253
	v_max_f32_e32 v50, v251, v15
	v_min_f32_e32 v15, v251, v15
	v_max_f32_e32 v122, v114, v33
	v_min_f32_e32 v33, v114, v33
	v_max_f32_e32 v117, v32, v38
	v_min_f32_e32 v38, v32, v38
	v_max_f32_e32 v1, v41, v24
	v_min_f32_e32 v24, v41, v24
	v_max_f32_e32 v49, v255, v34
	v_min_f32_e32 v34, v255, v34
	v_max_f32_e32 v51, v26, v27
	v_min_f32_e32 v27, v26, v27
	v_max_f32_e32 v109, v37, v50
	v_min_f32_e32 v50, v37, v50
	v_max_f32_e32 v4, v104, v253
	v_min_f32_e32 v253, v104, v253
	v_max_f32_e32 v102, v29, v15
	v_min_f32_e32 v15, v29, v15
	v_max_f32_e32 v128, v122, v117
	v_min_f32_e32 v129, v122, v117
	v_max_f32_e32 v130, v33, v38
	v_min_f32_e32 v131, v33, v38
	v_max_f32_e32 v132, v1, v49
	v_min_f32_e32 v133, v1, v49
	v_max_f32_e32 v134, v24, v34
	v_min_f32_e32 v135, v24, v34
	v_max_f32_e32 v136, v51, v109
	v_min_f32_e32 v137, v51, v109
	v_max_f32_e32 v138, v27, v50
	v_min_f32_e32 v139, v27, v50
	v_max_f32_e32 v140, v4, v102
	v_min_f32_e32 v141, v4, v102
	v_max_f32_e32 v142, v253, v15
	v_min_f32_e32 v143, v253, v15
	s_waitcnt vmcnt(0)
	v_pk_mul_f32 v[160:161], v[160:161], v[176:177]
	v_pk_mul_f32 v[162:163], v[162:163], v[178:179]
	v_pk_mul_f32 v[164:165], v[164:165], v[180:181]
	v_pk_mul_f32 v[166:167], v[166:167], v[182:183]
	v_pk_mul_f32 v[168:169], v[168:169], v[184:185]
	v_pk_mul_f32 v[170:171], v[170:171], v[186:187]
	v_pk_mul_f32 v[172:173], v[172:173], v[188:189]
	v_pk_mul_f32 v[174:175], v[174:175], v[190:191]
	v_max3_f32 v192, |v160|, |v161|, |v162|
	v_max3_f32 v192, |v163|, |v164|, v192
	v_max3_f32 v192, |v165|, |v166|, v192
	v_max3_f32 v192, |v167|, |v168|, v192
	v_max3_f32 v192, |v169|, |v170|, v192
	v_max3_f32 v192, |v171|, |v172|, v192
	v_max3_f32 v192, |v173|, |v174|, v192
	v_max_f32_e64 v192, |v175|, v192
	s_nop 1
	v_mov_b32_dpp v193, v192 quad_perm:[1,0,3,2] row_mask:0xf bank_mask:0xf bound_ctrl:1
	v_max_f32_e32 v192, v192, v193
	s_nop 1
	v_mov_b32_dpp v193, v192 quad_perm:[2,3,0,1] row_mask:0xf bank_mask:0xf bound_ctrl:1
	v_max_f32_e32 v192, v192, v193
	s_nop 1
	v_mov_b32_dpp v193, v192 row_half_mirror row_mask:0xf bank_mask:0xf bound_ctrl:1
	v_max_f32_e32 v192, v192, v193
	s_nop 1
	v_mov_b32_dpp v193, v192 row_mirror row_mask:0xf bank_mask:0xf bound_ctrl:1
	v_max_f32_e32 v192, v192, v193
	v_mov_b32_e32 v193, v192
	s_nop 1
	v_permlane16_swap_b32_e32 v192, v193
	s_nop 1
	v_max_f32_e32 v192, v192, v193
	v_mov_b32_e32 v193, v192
	s_nop 1
	v_permlane32_swap_b32_e32 v192, v193
	s_nop 1
	v_max_f32_e32 v192, v192, v193
	v_max_f32_e32 v192, 0xda24260, v192
	v_mul_f32_e32 v194, 0x3e2aaaab, v192
	global_store_dword v214, v194, s[12:13]
	v_div_scale_f32 v195, s[26:27], v194, v194, 1.0
	v_rcp_f32_e32 v196, v195
	v_div_scale_f32 v204, vcc, 1.0, v194, 1.0
	v_fma_f32 v205, -v195, v196, 1.0
	v_fmac_f32_e32 v196, v205, v196
	v_mul_f32_e32 v205, v204, v196
	v_fma_f32 v206, -v195, v205, v204
	v_fmac_f32_e32 v205, v206, v196
	v_fma_f32 v195, -v195, v205, v204
	s_nop 0
	v_div_fmas_f32 v195, v195, v196, v205
	v_div_fixup_f32 v207, v195, v194, 1.0
	v_mul_f32_e32 v160, v207, v160
	v_mul_f32_e32 v161, v207, v161
	v_mul_f32_e32 v162, v207, v162
	v_mul_f32_e32 v163, v207, v163
	v_mul_f32_e32 v164, v207, v164
	v_mul_f32_e32 v165, v207, v165
	v_mul_f32_e32 v166, v207, v166
	v_mul_f32_e32 v167, v207, v167
	v_mul_f32_e32 v168, v207, v168
	v_mul_f32_e32 v169, v207, v169
	v_mul_f32_e32 v170, v207, v170
	v_mul_f32_e32 v171, v207, v171
	v_mul_f32_e32 v172, v207, v172
	v_mul_f32_e32 v173, v207, v173
	v_mul_f32_e32 v174, v207, v174
	v_mul_f32_e32 v175, v207, v175
	v_mov_b32_e32 v208, 0
	v_mov_b32_e32 v209, 0
	v_mov_b32_e32 v210, 0
	v_mov_b32_e32 v193, 0
	v_cvt_scalef32_pk_fp4_f32 v208, v160, v161, 1.0
	v_cvt_scalef32_pk_fp4_f32 v209, v164, v165, 1.0
	v_cvt_scalef32_pk_fp4_f32 v210, v168, v169, 1.0
	v_cvt_scalef32_pk_fp4_f32 v193, v172, v173, 1.0
	v_cvt_scalef32_pk_fp4_f32 v208, v162, v163, 1.0 op_sel:[0,0,1,0]
	v_cvt_scalef32_pk_fp4_f32 v209, v166, v167, 1.0 op_sel:[0,0,1,0]
	v_cvt_scalef32_pk_fp4_f32 v210, v170, v171, 1.0 op_sel:[0,0,1,0]
	v_cvt_scalef32_pk_fp4_f32 v193, v174, v175, 1.0 op_sel:[0,0,1,0]
	global_store_short v213, v208, s[10:11] nt
	s_add_u32 s14, s10, 0x200000
	s_addc_u32 s15, s11, 0
	global_store_short v213, v209, s[14:15] nt
	s_add_u32 s14, s10, 0x400000
	s_addc_u32 s15, s11, 0
	global_store_short v213, v210, s[14:15] nt
	s_add_u32 s14, s10, 0x600000
	s_addc_u32 s15, s11, 0
	global_store_short v213, v193, s[14:15] nt
	s_add_u32 s10, s10, 0x20000
	s_addc_u32 s11, s11, 0
	s_add_u32 s12, s12, 0x2000
	s_addc_u32 s13, s13, 0
	global_load_dwordx4 v[160:163], v212, s[8:9] offset:0 nt
	global_load_dwordx4 v[164:167], v212, s[8:9] offset:1024 nt
	global_load_dwordx4 v[168:171], v212, s[8:9] offset:2048 nt
	global_load_dwordx4 v[172:175], v212, s[8:9] offset:3072 nt
	s_add_u32 s8, s8, 0x800000
	s_addc_u32 s9, s9, 0
	ds_write_b8 v240, v128 offset:0
	ds_write_b8 v240, v129 offset:1
	ds_write_b8 v240, v130 offset:2
	ds_write_b8 v240, v131 offset:3
	ds_write_b8 v240, v132 offset:4
	ds_write_b8 v240, v133 offset:5
	ds_write_b8 v240, v134 offset:6
	ds_write_b8 v240, v135 offset:7
	ds_write_b8 v240, v136 offset:8
	ds_write_b8 v240, v137 offset:9
	ds_write_b8 v240, v138 offset:10
	ds_write_b8 v240, v139 offset:11
	ds_write_b8 v240, v140 offset:12
	ds_write_b8 v240, v141 offset:13
	ds_write_b8 v240, v142 offset:14
	ds_write_b8 v240, v143 offset:15
	ds_read_b128 v[96:99], v215 offset:32768
	ds_read_b128 v[100:103], v232 offset:32768
	ds_read_b128 v[104:107], v233 offset:32768
	ds_read_b128 v[108:111], v234 offset:32768
	ds_read_b128 v[112:115], v235 offset:32768
	ds_read_b128 v[116:119], v236 offset:32768
	ds_read_b128 v[120:123], v237 offset:32768
	ds_read_b128 v[124:127], v238 offset:32768
	s_waitcnt vmcnt(27)
	s_waitcnt lgkmcnt(4)
	v_mfma_f32_32x32x16_bf16 v[0:15], v[96:99], v[64:67], 0
	v_mfma_f32_32x32x16_bf16 v[0:15], v[100:103], v[68:71], v[0:15]
	v_mfma_f32_32x32x16_bf16 v[0:15], v[104:107], v[72:75], v[0:15]
	v_mfma_f32_32x32x16_bf16 v[0:15], v[108:111], v[76:79], v[0:15]
	ds_read_b128 v[96:99], v215 offset:40960
	ds_read_b128 v[100:103], v232 offset:40960
	ds_read_b128 v[104:107], v233 offset:40960
	ds_read_b128 v[108:111], v234 offset:40960
	s_waitcnt lgkmcnt(4)
	v_mfma_f32_32x32x16_bf16 v[0:15], v[112:115], v[80:83], v[0:15]
	v_mfma_f32_32x32x16_bf16 v[0:15], v[116:119], v[84:87], v[0:15]
	v_mfma_f32_32x32x16_bf16 v[0:15], v[120:123], v[88:91], v[0:15]
	v_mfma_f32_32x32x16_bf16 v[0:15], v[124:127], v[92:95], v[0:15]
	ds_read_b128 v[112:115], v235 offset:40960
	ds_read_b128 v[116:119], v236 offset:40960
	ds_read_b128 v[120:123], v237 offset:40960
	ds_read_b128 v[124:127], v238 offset:40960
	s_waitcnt lgkmcnt(4)
	v_mfma_f32_32x32x16_bf16 v[16:31], v[96:99], v[64:67], 0
	v_mfma_f32_32x32x16_bf16 v[16:31], v[100:103], v[68:71], v[16:31]
	v_mfma_f32_32x32x16_bf16 v[16:31], v[104:107], v[72:75], v[16:31]
	v_mfma_f32_32x32x16_bf16 v[16:31], v[108:111], v[76:79], v[16:31]
	ds_read_b128 v[96:99], v215 offset:49152
	ds_read_b128 v[100:103], v232 offset:49152
	ds_read_b128 v[104:107], v233 offset:49152
	ds_read_b128 v[108:111], v234 offset:49152
	s_waitcnt lgkmcnt(4)
	v_mfma_f32_32x32x16_bf16 v[16:31], v[112:115], v[80:83], v[16:31]
	v_mfma_f32_32x32x16_bf16 v[16:31], v[116:119], v[84:87], v[16:31]
	v_mfma_f32_32x32x16_bf16 v[16:31], v[120:123], v[88:91], v[16:31]
	v_mfma_f32_32x32x16_bf16 v[16:31], v[124:127], v[92:95], v[16:31]
	ds_read_b128 v[112:115], v235 offset:49152
	ds_read_b128 v[116:119], v236 offset:49152
	ds_read_b128 v[120:123], v237 offset:49152
	ds_read_b128 v[124:127], v238 offset:49152
	s_waitcnt lgkmcnt(4)
	v_mfma_f32_32x32x16_bf16 v[32:47], v[96:99], v[64:67], 0
	v_mfma_f32_32x32x16_bf16 v[32:47], v[100:103], v[68:71], v[32:47]
	v_mfma_f32_32x32x16_bf16 v[32:47], v[104:107], v[72:75], v[32:47]
	v_mfma_f32_32x32x16_bf16 v[32:47], v[108:111], v[76:79], v[32:47]
	ds_read_b128 v[96:99], v215 offset:57344
	ds_read_b128 v[100:103], v232 offset:57344
	ds_read_b128 v[104:107], v233 offset:57344
	ds_read_b128 v[108:111], v234 offset:57344
	s_waitcnt lgkmcnt(4)
	v_mfma_f32_32x32x16_bf16 v[32:47], v[112:115], v[80:83], v[32:47]
	v_mfma_f32_32x32x16_bf16 v[32:47], v[116:119], v[84:87], v[32:47]
	v_mfma_f32_32x32x16_bf16 v[32:47], v[120:123], v[88:91], v[32:47]
	v_mfma_f32_32x32x16_bf16 v[32:47], v[124:127], v[92:95], v[32:47]
	ds_read_b128 v[112:115], v235 offset:57344
	ds_read_b128 v[116:119], v236 offset:57344
	ds_read_b128 v[120:123], v237 offset:57344
	ds_read_b128 v[124:127], v238 offset:57344
	s_waitcnt lgkmcnt(4)
	v_mfma_f32_32x32x16_bf16 v[48:63], v[96:99], v[64:67], 0
	v_mfma_f32_32x32x16_bf16 v[48:63], v[100:103], v[68:71], v[48:63]
	v_mfma_f32_32x32x16_bf16 v[48:63], v[104:107], v[72:75], v[48:63]
	v_mfma_f32_32x32x16_bf16 v[48:63], v[108:111], v[76:79], v[48:63]
	s_waitcnt lgkmcnt(0)
	v_mfma_f32_32x32x16_bf16 v[48:63], v[112:115], v[80:83], v[48:63]
	v_mfma_f32_32x32x16_bf16 v[48:63], v[116:119], v[84:87], v[48:63]
	v_mfma_f32_32x32x16_bf16 v[48:63], v[120:123], v[88:91], v[48:63]
	v_mfma_f32_32x32x16_bf16 v[48:63], v[124:127], v[92:95], v[48:63]
	s_nop 11
	v_and_or_b32 v0, v0, s6, v211
	v_or_b32_e32 v0, 0x7b, v0
	v_and_or_b32 v1, v1, s6, v211
	v_or_b32_e32 v1, 0x7a, v1
	v_and_or_b32 v2, v2, s6, v211
	v_or_b32_e32 v2, 0x79, v2
	v_and_or_b32 v3, v3, s6, v211
	v_or_b32_e32 v3, 0x78, v3
	v_and_or_b32 v4, v4, s6, v211
	v_or_b32_e32 v4, 0x73, v4
	v_and_or_b32 v5, v5, s6, v211
	v_or_b32_e32 v5, 0x72, v5
	v_and_or_b32 v6, v6, s6, v211
	v_or_b32_e32 v6, 0x71, v6
	v_and_or_b32 v7, v7, s6, v211
	v_or_b32_e32 v7, 0x70, v7
	v_and_or_b32 v8, v8, s6, v211
	v_or_b32_e32 v8, 0x6b, v8
	v_and_or_b32 v9, v9, s6, v211
	v_or_b32_e32 v9, 0x6a, v9
	v_and_or_b32 v10, v10, s6, v211
	v_or_b32_e32 v10, 0x69, v10
	v_and_or_b32 v11, v11, s6, v211
	v_or_b32_e32 v11, 0x68, v11
	v_and_or_b32 v12, v12, s6, v211
	v_or_b32_e32 v12, 0x63, v12
	v_and_or_b32 v13, v13, s6, v211
	v_or_b32_e32 v13, 0x62, v13
	v_and_or_b32 v14, v14, s6, v211
	v_or_b32_e32 v14, 0x61, v14
	v_and_or_b32 v15, v15, s6, v211
	v_or_b32_e32 v15, 0x60, v15
	v_and_or_b32 v16, v16, s6, v211
	v_or_b32_e32 v16, 0x5b, v16
	v_and_or_b32 v17, v17, s6, v211
	v_or_b32_e32 v17, 0x5a, v17
	v_and_or_b32 v18, v18, s6, v211
	v_or_b32_e32 v18, 0x59, v18
	v_and_or_b32 v19, v19, s6, v211
	v_or_b32_e32 v19, 0x58, v19
	v_and_or_b32 v20, v20, s6, v211
	v_or_b32_e32 v20, 0x53, v20
	v_and_or_b32 v21, v21, s6, v211
	v_or_b32_e32 v21, 0x52, v21
	v_and_or_b32 v22, v22, s6, v211
	v_or_b32_e32 v22, 0x51, v22
	v_and_or_b32 v23, v23, s6, v211
	v_or_b32_e32 v23, 0x50, v23
	v_and_or_b32 v24, v24, s6, v211
	v_or_b32_e32 v24, 0x4b, v24
	v_and_or_b32 v25, v25, s6, v211
	v_or_b32_e32 v25, 0x4a, v25
	v_and_or_b32 v26, v26, s6, v211
	v_or_b32_e32 v26, 0x49, v26
	v_and_or_b32 v27, v27, s6, v211
	v_or_b32_e32 v27, 0x48, v27
	v_and_or_b32 v28, v28, s6, v211
	v_or_b32_e32 v28, 0x43, v28
	v_and_or_b32 v29, v29, s6, v211
	v_or_b32_e32 v29, 0x42, v29
	v_and_or_b32 v30, v30, s6, v211
	v_or_b32_e32 v30, 0x41, v30
	v_and_or_b32 v31, v31, s6, v211
	v_or_b32_e32 v31, 64, v31
	v_and_or_b32 v32, v32, s6, v211
	v_or_b32_e32 v32, 59, v32
	v_and_or_b32 v33, v33, s6, v211
	v_or_b32_e32 v33, 58, v33
	v_and_or_b32 v34, v34, s6, v211
	v_or_b32_e32 v34, 57, v34
	v_and_or_b32 v35, v35, s6, v211
	v_or_b32_e32 v35, 56, v35
	v_and_or_b32 v36, v36, s6, v211
	v_or_b32_e32 v36, 51, v36
	v_and_or_b32 v37, v37, s6, v211
	v_or_b32_e32 v37, 50, v37
	v_and_or_b32 v38, v38, s6, v211
	v_or_b32_e32 v38, 49, v38
	v_and_or_b32 v39, v39, s6, v211
	v_or_b32_e32 v39, 48, v39
	v_and_or_b32 v40, v40, s6, v211
	v_or_b32_e32 v40, 43, v40
	v_and_or_b32 v41, v41, s6, v211
	v_or_b32_e32 v41, 42, v41
	v_and_or_b32 v42, v42, s6, v211
	v_or_b32_e32 v42, 41, v42
	v_and_or_b32 v43, v43, s6, v211
	v_or_b32_e32 v43, 40, v43
	v_and_or_b32 v44, v44, s6, v211
	v_or_b32_e32 v44, 35, v44
	v_and_or_b32 v45, v45, s6, v211
	v_or_b32_e32 v45, 34, v45
	v_and_or_b32 v46, v46, s6, v211
	v_or_b32_e32 v46, 33, v46
	v_and_or_b32 v47, v47, s6, v211
	v_or_b32_e32 v47, 32, v47
	v_and_or_b32 v48, v48, s6, v211
	v_or_b32_e32 v48, 27, v48
	v_and_or_b32 v49, v49, s6, v211
	v_or_b32_e32 v49, 26, v49
	v_and_or_b32 v50, v50, s6, v211
	v_or_b32_e32 v50, 25, v50
	v_and_or_b32 v51, v51, s6, v211
	v_or_b32_e32 v51, 24, v51
	v_and_or_b32 v52, v52, s6, v211
	v_or_b32_e32 v52, 19, v52
	v_and_or_b32 v53, v53, s6, v211
	v_or_b32_e32 v53, 18, v53
	v_and_or_b32 v54, v54, s6, v211
	v_or_b32_e32 v54, 17, v54
	v_and_or_b32 v55, v55, s6, v211
	v_or_b32_e32 v55, 16, v55
	v_and_or_b32 v56, v56, s6, v211
	v_or_b32_e32 v56, 11, v56
	v_and_or_b32 v57, v57, s6, v211
	v_or_b32_e32 v57, 10, v57
	v_and_or_b32 v58, v58, s6, v211
	v_or_b32_e32 v58, 9, v58
	v_and_or_b32 v59, v59, s6, v211
	v_or_b32_e32 v59, 8, v59
	v_and_or_b32 v60, v60, s6, v211
	v_or_b32_e32 v60, 3, v60
	v_and_or_b32 v61, v61, s6, v211
	v_or_b32_e32 v61, 2, v61
	v_and_or_b32 v62, v62, s6, v211
	v_or_b32_e32 v62, 1, v62
	v_and_or_b32 v63, v63, s6, v211
	v_or_b32_e32 v63, 0, v63
	v_max_f32_e32 v144, v0, v13
	v_min_f32_e32 v13, v0, v13
	v_max_f32_e32 v145, v1, v12
	v_min_f32_e32 v12, v1, v12
	v_max_f32_e32 v146, v2, v15
	v_min_f32_e32 v15, v2, v15
	v_max_f32_e32 v147, v3, v14
	v_min_f32_e32 v14, v3, v14
	v_max_f32_e32 v148, v4, v8
	v_min_f32_e32 v8, v4, v8
	v_max_f32_e32 v149, v5, v6
	v_min_f32_e32 v6, v5, v6
	v_max_f32_e32 v150, v7, v11
	v_min_f32_e32 v11, v7, v11
	v_max_f32_e32 v151, v9, v10
	v_min_f32_e32 v10, v9, v10
	v_max_f32_e32 v249, v144, v149
	v_min_f32_e32 v149, v144, v149
	v_max_f32_e32 v250, v145, v150
	v_min_f32_e32 v150, v145, v150
	v_max_f32_e32 v251, v146, v151
	v_min_f32_e32 v151, v146, v151
	v_max_f32_e32 v252, v147, v148
	v_min_f32_e32 v148, v147, v148
	v_max_f32_e32 v253, v6, v13
	v_min_f32_e32 v13, v6, v13
	v_max_f32_e32 v254, v8, v14
	v_min_f32_e32 v14, v8, v14
	v_max_f32_e32 v255, v10, v15
	v_min_f32_e32 v15, v10, v15
	v_max_f32_e32 v96, v11, v12
	v_min_f32_e32 v12, v11, v12
	v_max_f32_e32 v97, v249, v250
	v_min_f32_e32 v250, v249, v250
	v_max_f32_e32 v98, v251, v252
	v_min_f32_e32 v252, v251, v252
	v_max_f32_e32 v99, v148, v149
	v_min_f32_e32 v149, v148, v149
	v_max_f32_e32 v100, v253, v254
	v_min_f32_e32 v254, v253, v254
	v_max_f32_e32 v101, v150, v151
	v_min_f32_e32 v151, v150, v151
	v_max_f32_e32 v102, v255, v96
	v_min_f32_e32 v96, v255, v96
	v_max_f32_e32 v103, v12, v13
	v_min_f32_e32 v13, v12, v13
	v_max_f32_e32 v104, v14, v15
	v_min_f32_e32 v15, v14, v15
	v_max_f32_e32 v105, v97, v98
	v_min_f32_e32 v98, v97, v98
	v_max_f32_e32 v106, v250, v252
	v_min_f32_e32 v252, v250, v252
	v_max_f32_e32 v107, v99, v102
	v_min_f32_e32 v102, v99, v102
	v_max_f32_e32 v108, v149, v96
	v_min_f32_e32 v96, v149, v96
	v_max_f32_e32 v109, v100, v101
	v_min_f32_e32 v101, v100, v101
	v_max_f32_e32 v110, v254, v151
	v_min_f32_e32 v151, v254, v151
	v_max_f32_e32 v111, v103, v104
	v_min_f32_e32 v104, v103, v104
	v_max_f32_e32 v112, v13, v15
	v_min_f32_e32 v15, v13, v15
	v_max_f32_e32 v113, v106, v98
	v_min_f32_e32 v98, v106, v98
	v_max_f32_e32 v114, v252, v111
	v_min_f32_e32 v111, v252, v111
	v_max_f32_e32 v115, v107, v109
	v_min_f32_e32 v109, v107, v109
	v_max_f32_e32 v116, v108, v101
	v_min_f32_e32 v101, v108, v101
	v_max_f32_e32 v117, v110, v102
	v_min_f32_e32 v102, v110, v102
	v_max_f32_e32 v118, v151, v96
	v_min_f32_e32 v96, v151, v96
	v_max_f32_e32 v119, v112, v104
	v_min_f32_e32 v104, v112, v104
	v_max_f32_e32 v120, v113, v115
	v_min_f32_e32 v115, v113, v115
	v_max_f32_e32 v121, v98, v109
	v_min_f32_e32 v109, v98, v109
	v_max_f32_e32 v122, v116, v117
	v_min_f32_e32 v117, v116, v117
	v_max_f32_e32 v123, v101, v102
	v_min_f32_e32 v102, v101, v102
	v_max_f32_e32 v124, v118, v119
	v_min_f32_e32 v119, v118, v119
	v_max_f32_e32 v125, v96, v104
	v_min_f32_e32 v104, v96, v104
	v_max_f32_e32 v126, v121, v115
	v_min_f32_e32 v115, v121, v115
	v_max_f32_e32 v127, v114, v109
	v_min_f32_e32 v109, v114, v109
	v_max_f32_e32 v64, v124, v111
	v_min_f32_e32 v111, v124, v111
	v_max_f32_e32 v65, v125, v119
	v_min_f32_e32 v119, v125, v119
	v_max_f32_e32 v66, v127, v122
	v_min_f32_e32 v122, v127, v122
	v_max_f32_e32 v67, v109, v117
	v_min_f32_e32 v117, v109, v117
	v_max_f32_e32 v68, v123, v64
	v_min_f32_e32 v64, v123, v64
	v_max_f32_e32 v69, v102, v111
	v_min_f32_e32 v111, v102, v111
	v_max_f32_e32 v70, v66, v115
	v_min_f32_e32 v115, v66, v115
	v_max_f32_e32 v71, v122, v67
	v_min_f32_e32 v67, v122, v67
	v_max_f32_e32 v72, v68, v117
	v_min_f32_e32 v117, v68, v117
	v_max_f32_e32 v73, v64, v69
	v_min_f32_e32 v69, v64, v69
	v_max_f32_e32 v74, v65, v111
	v_min_f32_e32 v111, v65, v111
	v_max_f32_e32 v75, v67, v72
	v_min_f32_e32 v72, v67, v72
	v_max_f32_e32 v76, v117, v73
	v_min_f32_e32 v73, v117, v73
	v_max_f32_e32 v77, v16, v29
	v_min_f32_e32 v29, v16, v29
	v_max_f32_e32 v78, v17, v28
	v_min_f32_e32 v28, v17, v28
	v_max_f32_e32 v79, v18, v31
	v_min_f32_e32 v31, v18, v31
	v_max_f32_e32 v80, v19, v30
	v_min_f32_e32 v30, v19, v30
	v_max_f32_e32 v81, v20, v24
	v_min_f32_e32 v24, v20, v24
	v_max_f32_e32 v82, v21, v22
	v_min_f32_e32 v22, v21, v22
	v_max_f32_e32 v83, v23, v27
	v_min_f32_e32 v27, v23, v27
	v_max_f32_e32 v84, v25, v26
	v_min_f32_e32 v26, v25, v26
	v_max_f32_e32 v85, v77, v82
	v_min_f32_e32 v82, v77, v82
	v_max_f32_e32 v86, v78, v83
	v_min_f32_e32 v83, v78, v83
	v_max_f32_e32 v87, v79, v84
	v_min_f32_e32 v84, v79, v84
	v_max_f32_e32 v88, v80, v81
	v_min_f32_e32 v81, v80, v81
	v_max_f32_e32 v89, v22, v29
	v_min_f32_e32 v29, v22, v29
	v_max_f32_e32 v90, v24, v30
	v_min_f32_e32 v30, v24, v30
	v_max_f32_e32 v91, v26, v31
	v_min_f32_e32 v31, v26, v31
	v_max_f32_e32 v92, v27, v28
	v_min_f32_e32 v28, v27, v28
	v_max_f32_e32 v93, v85, v86
	v_min_f32_e32 v86, v85, v86
	v_max_f32_e32 v94, v87, v88
	v_min_f32_e32 v88, v87, v88
	v_max_f32_e32 v95, v81, v82
	v_min_f32_e32 v82, v81, v82
	v_max_f32_e32 v0, v89, v90
	v_min_f32_e32 v90, v89, v90
	v_max_f32_e32 v1, v83, v84
	v_min_f32_e32 v84, v83, v84
	v_max_f32_e32 v2, v91, v92
	v_min_f32_e32 v92, v91, v92
	v_max_f32_e32 v3, v28, v29
	v_min_f32_e32 v29, v28, v29
	v_max_f32_e32 v4, v30, v31
	v_min_f32_e32 v31, v30, v31
	v_max_f32_e32 v5, v93, v94
	v_min_f32_e32 v94, v93, v94
	v_max_f32_e32 v7, v86, v88
	v_min_f32_e32 v88, v86, v88
	v_max_f32_e32 v9, v95, v2
	v_min_f32_e32 v2, v95, v2
	v_max_f32_e32 v144, v82, v92
	v_min_f32_e32 v92, v82, v92
	v_max_f32_e32 v145, v0, v1
	v_min_f32_e32 v1, v0, v1
	v_max_f32_e32 v146, v90, v84
	v_min_f32_e32 v84, v90, v84
	v_max_f32_e32 v147, v3, v4
	v_min_f32_e32 v4, v3, v4
	v_max_f32_e32 v6, v29, v31
	v_min_f32_e32 v31, v29, v31
	v_max_f32_e32 v8, v7, v94
	v_min_f32_e32 v94, v7, v94
	v_max_f32_e32 v10, v88, v147
	v_min_f32_e32 v147, v88, v147
	v_max_f32_e32 v11, v9, v145
	v_min_f32_e32 v145, v9, v145
	v_max_f32_e32 v249, v144, v1
	v_min_f32_e32 v1, v144, v1
	v_max_f32_e32 v251, v146, v2
	v_min_f32_e32 v2, v146, v2
	v_max_f32_e32 v148, v84, v92
	v_min_f32_e32 v92, v84, v92
	v_max_f32_e32 v253, v6, v4
	v_min_f32_e32 v4, v6, v4
	v_max_f32_e32 v150, v8, v11
	v_min_f32_e32 v11, v8, v11
	v_max_f32_e32 v255, v94, v145
	v_min_f32_e32 v145, v94, v145
	v_max_f32_e32 v12, v249, v251
	v_min_f32_e32 v251, v249, v251
	v_max_f32_e32 v14, v1, v2
	v_min_f32_e32 v2, v1, v2
	v_max_f32_e32 v97, v148, v253
	v_min_f32_e32 v253, v148, v253
	v_max_f32_e32 v250, v92, v4
	v_min_f32_e32 v4, v92, v4
	v_max_f32_e32 v99, v255, v11
	v_min_f32_e32 v11, v255, v11
	v_max_f32_e32 v149, v10, v145
	v_min_f32_e32 v145, v10, v145
	v_max_f32_e32 v100, v97, v147
	v_min_f32_e32 v147, v97, v147
	v_max_f32_e32 v254, v250, v253
	v_min_f32_e32 v253, v250, v253
	v_max_f32_e32 v103, v149, v12
	v_min_f32_e32 v12, v149, v12
	v_max_f32_e32 v13, v145, v251
	v_min_f32_e32 v251, v145, v251
	v_max_f32_e32 v106, v14, v100
	v_min_f32_e32 v100, v14, v100
	v_max_f32_e32 v252, v2, v147
	v_min_f32_e32 v147, v2, v147
	v_max_f32_e32 v107, v103, v11
	v_min_f32_e32 v11, v103, v11
	v_max_f32_e32 v108, v12, v13
	v_min_f32_e32 v13, v12, v13
	v_max_f32_e32 v110, v106, v251
	v_min_f32_e32 v251, v106, v251
	v_max_f32_e32 v151, v100, v252
	v_min_f32_e32 v252, v100, v252
	v_max_f32_e32 v112, v254, v147
	v_min_f32_e32 v147, v254, v147
	v_max_f32_e32 v113, v13, v110
	v_min_f32_e32 v110, v13, v110
	v_max_f32_e32 v98, v251, v151
	v_min_f32_e32 v151, v251, v151
	s_waitcnt vmcnt(0)
	v_pk_mul_f32 v[160:161], v[160:161], v[176:177]
	v_pk_mul_f32 v[162:163], v[162:163], v[178:179]
	v_pk_mul_f32 v[164:165], v[164:165], v[180:181]
	v_pk_mul_f32 v[166:167], v[166:167], v[182:183]
	v_pk_mul_f32 v[168:169], v[168:169], v[184:185]
	v_pk_mul_f32 v[170:171], v[170:171], v[186:187]
	v_pk_mul_f32 v[172:173], v[172:173], v[188:189]
	v_pk_mul_f32 v[174:175], v[174:175], v[190:191]
	v_max3_f32 v192, |v160|, |v161|, |v162|
	v_max3_f32 v192, |v163|, |v164|, v192
	v_max3_f32 v192, |v165|, |v166|, v192
	v_max3_f32 v192, |v167|, |v168|, v192
	v_max3_f32 v192, |v169|, |v170|, v192
	v_max3_f32 v192, |v171|, |v172|, v192
	v_max3_f32 v192, |v173|, |v174|, v192
	v_max_f32_e64 v192, |v175|, v192
	s_nop 1
	v_mov_b32_dpp v193, v192 quad_perm:[1,0,3,2] row_mask:0xf bank_mask:0xf bound_ctrl:1
	v_max_f32_e32 v192, v192, v193
	s_nop 1
	v_mov_b32_dpp v193, v192 quad_perm:[2,3,0,1] row_mask:0xf bank_mask:0xf bound_ctrl:1
	v_max_f32_e32 v192, v192, v193
	s_nop 1
	v_mov_b32_dpp v193, v192 row_half_mirror row_mask:0xf bank_mask:0xf bound_ctrl:1
	v_max_f32_e32 v192, v192, v193
	s_nop 1
	v_mov_b32_dpp v193, v192 row_mirror row_mask:0xf bank_mask:0xf bound_ctrl:1
	v_max_f32_e32 v192, v192, v193
	v_mov_b32_e32 v193, v192
	s_nop 1
	v_permlane16_swap_b32_e32 v192, v193
	s_nop 1
	v_max_f32_e32 v192, v192, v193
	v_mov_b32_e32 v193, v192
	s_nop 1
	v_permlane32_swap_b32_e32 v192, v193
	s_nop 1
	v_max_f32_e32 v192, v192, v193
	v_max_f32_e32 v192, 0xda24260, v192
	v_mul_f32_e32 v194, 0x3e2aaaab, v192
	global_store_dword v214, v194, s[12:13]
	v_div_scale_f32 v195, s[26:27], v194, v194, 1.0
	v_rcp_f32_e32 v196, v195
	v_div_scale_f32 v204, vcc, 1.0, v194, 1.0
	v_fma_f32 v205, -v195, v196, 1.0
	v_fmac_f32_e32 v196, v205, v196
	v_mul_f32_e32 v205, v204, v196
	v_fma_f32 v206, -v195, v205, v204
	v_fmac_f32_e32 v205, v206, v196
	v_fma_f32 v195, -v195, v205, v204
	s_nop 0
	v_div_fmas_f32 v195, v195, v196, v205
	v_div_fixup_f32 v207, v195, v194, 1.0
	v_mul_f32_e32 v160, v207, v160
	v_mul_f32_e32 v161, v207, v161
	v_mul_f32_e32 v162, v207, v162
	v_mul_f32_e32 v163, v207, v163
	v_mul_f32_e32 v164, v207, v164
	v_mul_f32_e32 v165, v207, v165
	v_mul_f32_e32 v166, v207, v166
	v_mul_f32_e32 v167, v207, v167
	v_mul_f32_e32 v168, v207, v168
	v_mul_f32_e32 v169, v207, v169
	v_mul_f32_e32 v170, v207, v170
	v_mul_f32_e32 v171, v207, v171
	v_mul_f32_e32 v172, v207, v172
	v_mul_f32_e32 v173, v207, v173
	v_mul_f32_e32 v174, v207, v174
	v_mul_f32_e32 v175, v207, v175
	v_mov_b32_e32 v208, 0
	v_mov_b32_e32 v209, 0
	v_mov_b32_e32 v210, 0
	v_mov_b32_e32 v193, 0
	v_cvt_scalef32_pk_fp4_f32 v208, v160, v161, 1.0
	v_cvt_scalef32_pk_fp4_f32 v209, v164, v165, 1.0
	v_cvt_scalef32_pk_fp4_f32 v210, v168, v169, 1.0
	v_cvt_scalef32_pk_fp4_f32 v193, v172, v173, 1.0
	v_cvt_scalef32_pk_fp4_f32 v208, v162, v163, 1.0 op_sel:[0,0,1,0]
	v_cvt_scalef32_pk_fp4_f32 v209, v166, v167, 1.0 op_sel:[0,0,1,0]
	v_cvt_scalef32_pk_fp4_f32 v210, v170, v171, 1.0 op_sel:[0,0,1,0]
	v_cvt_scalef32_pk_fp4_f32 v193, v174, v175, 1.0 op_sel:[0,0,1,0]
	global_store_short v213, v208, s[10:11] nt
	s_add_u32 s14, s10, 0x200000
	s_addc_u32 s15, s11, 0
	global_store_short v213, v209, s[14:15] nt
	s_add_u32 s14, s10, 0x400000
	s_addc_u32 s15, s11, 0
	global_store_short v213, v210, s[14:15] nt
	s_add_u32 s14, s10, 0x600000
	s_addc_u32 s15, s11, 0
	global_store_short v213, v193, s[14:15] nt
	s_add_u32 s10, s10, 0x20000
	s_addc_u32 s11, s11, 0
	s_add_u32 s12, s12, 0x2000
	s_addc_u32 s13, s13, 0
	global_load_dwordx4 v[160:163], v212, s[8:9] offset:0 nt
	global_load_dwordx4 v[164:167], v212, s[8:9] offset:1024 nt
	global_load_dwordx4 v[168:171], v212, s[8:9] offset:2048 nt
	global_load_dwordx4 v[172:175], v212, s[8:9] offset:3072 nt
	s_add_u32 s8, s8, 0x800000
	s_addc_u32 s9, s9, 0
	v_max_f32_e32 v116, v32, v45
	v_min_f32_e32 v45, v32, v45
	v_max_f32_e32 v101, v33, v44
	v_min_f32_e32 v44, v33, v44
	v_max_f32_e32 v118, v34, v47
	v_min_f32_e32 v47, v34, v47
	v_max_f32_e32 v96, v35, v46
	v_min_f32_e32 v46, v35, v46
	v_max_f32_e32 v121, v36, v40
	v_min_f32_e32 v40, v36, v40
	v_max_f32_e32 v114, v37, v38
	v_min_f32_e32 v38, v37, v38
	v_max_f32_e32 v124, v39, v43
	v_min_f32_e32 v43, v39, v43
	v_max_f32_e32 v125, v41, v42
	v_min_f32_e32 v42, v41, v42
	v_max_f32_e32 v127, v116, v114
	v_min_f32_e32 v114, v116, v114
	v_max_f32_e32 v109, v101, v124
	v_min_f32_e32 v124, v101, v124
	v_max_f32_e32 v123, v118, v125
	v_min_f32_e32 v125, v118, v125
	v_max_f32_e32 v102, v96, v121
	v_min_f32_e32 v121, v96, v121
	v_max_f32_e32 v66, v38, v45
	v_min_f32_e32 v45, v38, v45
	v_max_f32_e32 v122, v40, v46
	v_min_f32_e32 v46, v40, v46
	v_max_f32_e32 v68, v42, v47
	v_min_f32_e32 v47, v42, v47
	v_max_f32_e32 v64, v43, v44
	v_min_f32_e32 v44, v43, v44
	v_max_f32_e32 v65, v127, v109
	v_min_f32_e32 v109, v127, v109
	v_max_f32_e32 v67, v123, v102
	v_min_f32_e32 v102, v123, v102
	v_max_f32_e32 v117, v121, v114
	v_min_f32_e32 v114, v121, v114
	v_max_f32_e32 v16, v66, v122
	v_min_f32_e32 v122, v66, v122
	v_max_f32_e32 v17, v124, v125
	v_min_f32_e32 v125, v124, v125
	v_max_f32_e32 v18, v68, v64
	v_min_f32_e32 v64, v68, v64
	v_max_f32_e32 v19, v44, v45
	v_min_f32_e32 v45, v44, v45
	v_max_f32_e32 v20, v46, v47
	v_min_f32_e32 v47, v46, v47
	v_max_f32_e32 v21, v65, v67
	v_min_f32_e32 v67, v65, v67
	v_max_f32_e32 v23, v109, v102
	v_min_f32_e32 v102, v109, v102
	v_max_f32_e32 v25, v117, v18
	v_min_f32_e32 v18, v117, v18
	v_max_f32_e32 v77, v114, v64
	v_min_f32_e32 v64, v114, v64
	v_max_f32_e32 v78, v16, v17
	v_min_f32_e32 v17, v16, v17
	v_max_f32_e32 v79, v122, v125
	v_min_f32_e32 v125, v122, v125
	v_max_f32_e32 v80, v19, v20
	v_min_f32_e32 v20, v19, v20
	v_max_f32_e32 v22, v45, v47
	v_min_f32_e32 v47, v45, v47
	v_max_f32_e32 v24, v23, v67
	v_min_f32_e32 v67, v23, v67
	v_max_f32_e32 v26, v102, v80
	v_min_f32_e32 v80, v102, v80
	v_max_f32_e32 v27, v25, v78
	v_min_f32_e32 v78, v25, v78
	v_max_f32_e32 v85, v77, v17
	v_min_f32_e32 v17, v77, v17
	v_max_f32_e32 v87, v79, v18
	v_min_f32_e32 v18, v79, v18
	v_max_f32_e32 v81, v125, v64
	v_min_f32_e32 v64, v125, v64
	v_max_f32_e32 v89, v22, v20
	v_min_f32_e32 v20, v22, v20
	v_max_f32_e32 v83, v24, v27
	v_min_f32_e32 v27, v24, v27
	v_max_f32_e32 v91, v67, v78
	v_min_f32_e32 v78, v67, v78
	v_max_f32_e32 v28, v85, v87
	v_min_f32_e32 v87, v85, v87
	v_max_f32_e32 v30, v17, v18
	v_min_f32_e32 v18, v17, v18
	v_max_f32_e32 v93, v81, v89
	v_min_f32_e32 v89, v81, v89
	v_max_f32_e32 v86, v64, v20
	v_min_f32_e32 v20, v64, v20
	v_max_f32_e32 v95, v91, v27
	v_min_f32_e32 v27, v91, v27
	v_max_f32_e32 v82, v26, v78
	v_min_f32_e32 v78, v26, v78
	v_max_f32_e32 v0, v93, v80
	v_min_f32_e32 v80, v93, v80
	v_max_f32_e32 v90, v86, v89
	v_min_f32_e32 v89, v86, v89
	v_max_f32_e32 v3, v82, v28
	v_min_f32_e32 v28, v82, v28
	v_max_f32_e32 v29, v78, v87
	v_min_f32_e32 v87, v78, v87
	v_max_f32_e32 v7, v30, v0
	v_min_f32_e32 v0, v30, v0
	v_max_f32_e32 v88, v18, v80
	v_min_f32_e32 v80, v18, v80
	v_max_f32_e32 v9, v3, v27
	v_min_f32_e32 v27, v3, v27
	v_max_f32_e32 v144, v28, v29
	v_min_f32_e32 v29, v28, v29
	v_max_f32_e32 v146, v7, v87
	v_min_f32_e32 v87, v7, v87
	v_max_f32_e32 v84, v0, v88
	v_min_f32_e32 v88, v0, v88
	v_max_f32_e32 v6, v90, v80
	v_min_f32_e32 v80, v90, v80
	v_max_f32_e32 v8, v29, v146
	v_min_f32_e32 v146, v29, v146
	v_max_f32_e32 v94, v87, v84
	v_min_f32_e32 v84, v87, v84
	v_max_f32_e32 v249, v48, v61
	v_min_f32_e32 v61, v48, v61
	v_max_f32_e32 v1, v49, v60
	v_min_f32_e32 v60, v49, v60
	v_max_f32_e32 v148, v50, v63
	v_min_f32_e32 v63, v50, v63
	v_max_f32_e32 v92, v51, v62
	v_min_f32_e32 v62, v51, v62
	v_max_f32_e32 v255, v52, v56
	v_min_f32_e32 v56, v52, v56
	v_max_f32_e32 v10, v53, v54
	v_min_f32_e32 v54, v53, v54
	v_max_f32_e32 v97, v55, v59
	v_min_f32_e32 v59, v55, v59
	v_max_f32_e32 v250, v57, v58
	v_min_f32_e32 v58, v57, v58
	v_max_f32_e32 v149, v249, v10
	v_min_f32_e32 v10, v249, v10
	v_max_f32_e32 v145, v1, v97
	v_min_f32_e32 v97, v1, v97
	v_max_f32_e32 v14, v148, v250
	v_min_f32_e32 v250, v148, v250
	v_max_f32_e32 v2, v92, v255
	v_min_f32_e32 v255, v92, v255
	v_max_f32_e32 v103, v54, v61
	v_min_f32_e32 v61, v54, v61
	v_max_f32_e32 v12, v56, v62
	v_min_f32_e32 v62, v56, v62
	v_max_f32_e32 v106, v58, v63
	v_min_f32_e32 v63, v58, v63
	v_max_f32_e32 v100, v59, v60
	v_min_f32_e32 v60, v59, v60
	v_max_f32_e32 v254, v149, v145
	v_min_f32_e32 v145, v149, v145
	v_max_f32_e32 v13, v14, v2
	v_min_f32_e32 v2, v14, v2
	v_max_f32_e32 v251, v255, v10
	v_min_f32_e32 v10, v255, v10
	v_max_f32_e32 v32, v103, v12
	v_min_f32_e32 v12, v103, v12
	v_max_f32_e32 v33, v97, v250
	v_min_f32_e32 v250, v97, v250
	v_max_f32_e32 v34, v106, v100
	v_min_f32_e32 v100, v106, v100
	v_max_f32_e32 v35, v60, v61
	v_min_f32_e32 v61, v60, v61
	v_max_f32_e32 v36, v62, v63
	v_min_f32_e32 v63, v62, v63
	v_max_f32_e32 v37, v254, v13
	v_min_f32_e32 v13, v254, v13
	v_max_f32_e32 v39, v145, v2
	v_min_f32_e32 v2, v145, v2
	v_max_f32_e32 v41, v251, v34
	v_min_f32_e32 v34, v251, v34
	v_max_f32_e32 v116, v10, v100
	v_min_f32_e32 v100, v10, v100
	v_max_f32_e32 v101, v32, v33
	v_min_f32_e32 v33, v32, v33
	v_max_f32_e32 v118, v12, v250
	v_min_f32_e32 v250, v12, v250
	v_max_f32_e32 v96, v35, v36
	v_min_f32_e32 v36, v35, v36
	v_max_f32_e32 v38, v61, v63
	v_min_f32_e32 v63, v61, v63
	v_max_f32_e32 v40, v39, v13
	v_min_f32_e32 v13, v39, v13
	v_max_f32_e32 v42, v2, v96
	v_min_f32_e32 v96, v2, v96
	v_max_f32_e32 v43, v41, v101
	v_min_f32_e32 v101, v41, v101
	v_max_f32_e32 v127, v116, v33
	v_min_f32_e32 v33, v116, v33
	v_max_f32_e32 v123, v118, v34
	v_min_f32_e32 v34, v118, v34
	v_max_f32_e32 v121, v250, v100
	v_min_f32_e32 v100, v250, v100
	v_max_f32_e32 v66, v38, v36
	v_min_f32_e32 v36, v38, v36
	v_max_f32_e32 v124, v40, v43
	v_min_f32_e32 v43, v40, v43
	v_max_f32_e32 v68, v13, v101
	v_min_f32_e32 v101, v13, v101
	v_max_f32_e32 v44, v127, v123
	v_min_f32_e32 v123, v127, v123
	v_max_f32_e32 v46, v33, v34
	v_min_f32_e32 v34, v33, v34
	v_max_f32_e32 v65, v121, v66
	v_min_f32_e32 v66, v121, v66
	v_max_f32_e32 v109, v100, v36
	v_min_f32_e32 v36, v100, v36
	v_max_f32_e32 v117, v68, v43
	v_min_f32_e32 v43, v68, v43
	v_max_f32_e32 v114, v42, v101
	v_min_f32_e32 v101, v42, v101
	v_max_f32_e32 v16, v65, v96
	v_min_f32_e32 v96, v65, v96
	v_max_f32_e32 v122, v109, v66
	v_min_f32_e32 v66, v109, v66
	v_max_f32_e32 v19, v114, v44
	v_min_f32_e32 v44, v114, v44
	v_max_f32_e32 v45, v101, v123
	v_min_f32_e32 v123, v101, v123
	v_max_f32_e32 v23, v46, v16
	v_min_f32_e32 v16, v46, v16
	v_max_f32_e32 v102, v34, v96
	v_min_f32_e32 v96, v34, v96
	v_max_f32_e32 v25, v19, v43
	v_min_f32_e32 v43, v19, v43
	v_max_f32_e32 v77, v44, v45
	v_min_f32_e32 v45, v44, v45
	v_max_f32_e32 v79, v23, v123
	v_min_f32_e32 v123, v23, v123
	v_max_f32_e32 v125, v16, v102
	v_min_f32_e32 v102, v16, v102
	v_max_f32_e32 v22, v122, v96
	v_min_f32_e32 v96, v122, v96
	v_max_f32_e32 v24, v45, v79
	v_min_f32_e32 v79, v45, v79
	v_max_f32_e32 v67, v123, v125
	v_min_f32_e32 v125, v123, v125
	s_waitcnt vmcnt(0)
	v_pk_mul_f32 v[160:161], v[160:161], v[176:177]
	v_pk_mul_f32 v[162:163], v[162:163], v[178:179]
	v_pk_mul_f32 v[164:165], v[164:165], v[180:181]
	v_pk_mul_f32 v[166:167], v[166:167], v[182:183]
	v_pk_mul_f32 v[168:169], v[168:169], v[184:185]
	v_pk_mul_f32 v[170:171], v[170:171], v[186:187]
	v_pk_mul_f32 v[172:173], v[172:173], v[188:189]
	v_pk_mul_f32 v[174:175], v[174:175], v[190:191]
	v_max3_f32 v192, |v160|, |v161|, |v162|
	v_max3_f32 v192, |v163|, |v164|, v192
	v_max3_f32 v192, |v165|, |v166|, v192
	v_max3_f32 v192, |v167|, |v168|, v192
	v_max3_f32 v192, |v169|, |v170|, v192
	v_max3_f32 v192, |v171|, |v172|, v192
	v_max3_f32 v192, |v173|, |v174|, v192
	v_max_f32_e64 v192, |v175|, v192
	s_nop 1
	v_mov_b32_dpp v193, v192 quad_perm:[1,0,3,2] row_mask:0xf bank_mask:0xf bound_ctrl:1
	v_max_f32_e32 v192, v192, v193
	s_nop 1
	v_mov_b32_dpp v193, v192 quad_perm:[2,3,0,1] row_mask:0xf bank_mask:0xf bound_ctrl:1
	v_max_f32_e32 v192, v192, v193
	s_nop 1
	v_mov_b32_dpp v193, v192 row_half_mirror row_mask:0xf bank_mask:0xf bound_ctrl:1
	v_max_f32_e32 v192, v192, v193
	s_nop 1
	v_mov_b32_dpp v193, v192 row_mirror row_mask:0xf bank_mask:0xf bound_ctrl:1
	v_max_f32_e32 v192, v192, v193
	v_mov_b32_e32 v193, v192
	s_nop 1
	v_permlane16_swap_b32_e32 v192, v193
	s_nop 1
	v_max_f32_e32 v192, v192, v193
	v_mov_b32_e32 v193, v192
	s_nop 1
	v_permlane32_swap_b32_e32 v192, v193
	s_nop 1
	v_max_f32_e32 v192, v192, v193
	v_max_f32_e32 v192, 0xda24260, v192
	v_mul_f32_e32 v194, 0x3e2aaaab, v192
	global_store_dword v214, v194, s[12:13]
	v_div_scale_f32 v195, s[26:27], v194, v194, 1.0
	v_rcp_f32_e32 v196, v195
	v_div_scale_f32 v204, vcc, 1.0, v194, 1.0
	v_fma_f32 v205, -v195, v196, 1.0
	v_fmac_f32_e32 v196, v205, v196
	v_mul_f32_e32 v205, v204, v196
	v_fma_f32 v206, -v195, v205, v204
	v_fmac_f32_e32 v205, v206, v196
	v_fma_f32 v195, -v195, v205, v204
	s_nop 0
	v_div_fmas_f32 v195, v195, v196, v205
	v_div_fixup_f32 v207, v195, v194, 1.0
	v_mul_f32_e32 v160, v207, v160
	v_mul_f32_e32 v161, v207, v161
	v_mul_f32_e32 v162, v207, v162
	v_mul_f32_e32 v163, v207, v163
	v_mul_f32_e32 v164, v207, v164
	v_mul_f32_e32 v165, v207, v165
	v_mul_f32_e32 v166, v207, v166
	v_mul_f32_e32 v167, v207, v167
	v_mul_f32_e32 v168, v207, v168
	v_mul_f32_e32 v169, v207, v169
	v_mul_f32_e32 v170, v207, v170
	v_mul_f32_e32 v171, v207, v171
	v_mul_f32_e32 v172, v207, v172
	v_mul_f32_e32 v173, v207, v173
	v_mul_f32_e32 v174, v207, v174
	v_mul_f32_e32 v175, v207, v175
	v_mov_b32_e32 v208, 0
	v_mov_b32_e32 v209, 0
	v_mov_b32_e32 v210, 0
	v_mov_b32_e32 v193, 0
	v_cvt_scalef32_pk_fp4_f32 v208, v160, v161, 1.0
	v_cvt_scalef32_pk_fp4_f32 v209, v164, v165, 1.0
	v_cvt_scalef32_pk_fp4_f32 v210, v168, v169, 1.0
	v_cvt_scalef32_pk_fp4_f32 v193, v172, v173, 1.0
	v_cvt_scalef32_pk_fp4_f32 v208, v162, v163, 1.0 op_sel:[0,0,1,0]
	v_cvt_scalef32_pk_fp4_f32 v209, v166, v167, 1.0 op_sel:[0,0,1,0]
	v_cvt_scalef32_pk_fp4_f32 v210, v170, v171, 1.0 op_sel:[0,0,1,0]
	v_cvt_scalef32_pk_fp4_f32 v193, v174, v175, 1.0 op_sel:[0,0,1,0]
	global_store_short v213, v208, s[10:11] nt
	s_add_u32 s14, s10, 0x200000
	s_addc_u32 s15, s11, 0
	global_store_short v213, v209, s[14:15] nt
	s_add_u32 s14, s10, 0x400000
	s_addc_u32 s15, s11, 0
	global_store_short v213, v210, s[14:15] nt
	s_add_u32 s14, s10, 0x600000
	s_addc_u32 s15, s11, 0
	global_store_short v213, v193, s[14:15] nt
	s_add_u32 s10, s10, 0x20000
	s_addc_u32 s11, s11, 0
	s_add_u32 s12, s12, 0x2000
	s_addc_u32 s13, s13, 0
	global_load_dwordx4 v[160:163], v212, s[8:9] offset:0 nt
	global_load_dwordx4 v[164:167], v212, s[8:9] offset:1024 nt
	global_load_dwordx4 v[168:171], v212, s[8:9] offset:2048 nt
	global_load_dwordx4 v[172:175], v212, s[8:9] offset:3072 nt
	s_add_u32 s8, s8, 0x800000
	s_addc_u32 s9, s9, 0
	v_max_f32_e32 v105, v105, v31
	v_max_f32_e32 v120, v120, v4
	v_max_f32_e32 v126, v126, v253
	v_max_f32_e32 v70, v70, v147
	v_max_f32_e32 v115, v115, v112
	v_max_f32_e32 v71, v71, v252
	v_max_f32_e32 v75, v75, v151
	v_max_f32_e32 v72, v72, v98
	v_max_f32_e32 v76, v76, v110
	v_max_f32_e32 v73, v73, v113
	v_max_f32_e32 v69, v69, v108
	v_max_f32_e32 v74, v74, v11
	v_max_f32_e32 v111, v111, v107
	v_max_f32_e32 v119, v119, v99
	v_max_f32_e32 v104, v104, v150
	v_max_f32_e32 v15, v15, v5
	v_max_f32_e32 v85, v105, v76
	v_min_f32_e32 v76, v105, v76
	v_max_f32_e32 v17, v120, v73
	v_min_f32_e32 v73, v120, v73
	v_max_f32_e32 v81, v126, v69
	v_min_f32_e32 v69, v126, v69
	v_max_f32_e32 v64, v70, v74
	v_min_f32_e32 v74, v70, v74
	v_max_f32_e32 v91, v115, v111
	v_min_f32_e32 v111, v115, v111
	v_max_f32_e32 v26, v71, v119
	v_min_f32_e32 v119, v71, v119
	v_max_f32_e32 v93, v75, v104
	v_min_f32_e32 v104, v75, v104
	v_max_f32_e32 v86, v72, v15
	v_min_f32_e32 v15, v72, v15
	v_max_f32_e32 v82, v85, v91
	v_min_f32_e32 v91, v85, v91
	v_max_f32_e32 v78, v17, v26
	v_min_f32_e32 v26, v17, v26
	v_max_f32_e32 v30, v81, v93
	v_min_f32_e32 v93, v81, v93
	v_max_f32_e32 v18, v64, v86
	v_min_f32_e32 v86, v64, v86
	v_max_f32_e32 v3, v76, v111
	v_min_f32_e32 v111, v76, v111
	v_max_f32_e32 v28, v73, v119
	v_min_f32_e32 v119, v73, v119
	v_max_f32_e32 v7, v69, v104
	v_min_f32_e32 v104, v69, v104
	v_max_f32_e32 v0, v74, v15
	v_min_f32_e32 v15, v74, v15
	v_max_f32_e32 v90, v82, v30
	v_min_f32_e32 v30, v82, v30
	v_max_f32_e32 v29, v78, v18
	v_min_f32_e32 v18, v78, v18
	v_max_f32_e32 v87, v91, v93
	v_min_f32_e32 v93, v91, v93
	v_max_f32_e32 v48, v26, v86
	v_min_f32_e32 v86, v26, v86
	v_max_f32_e32 v49, v3, v7
	v_min_f32_e32 v7, v3, v7
	v_max_f32_e32 v50, v28, v0
	v_min_f32_e32 v0, v28, v0
	v_max_f32_e32 v51, v111, v104
	v_min_f32_e32 v104, v111, v104
	v_max_f32_e32 v52, v119, v15
	v_min_f32_e32 v15, v119, v15
	v_max_f32_e32 v53, v90, v29
	v_min_f32_e32 v29, v90, v29
	v_max_f32_e32 v55, v30, v18
	v_min_f32_e32 v18, v30, v18
	v_max_f32_e32 v57, v87, v48
	v_min_f32_e32 v48, v87, v48
	v_max_f32_e32 v249, v93, v86
	v_min_f32_e32 v86, v93, v86
	v_max_f32_e32 v1, v49, v50
	v_min_f32_e32 v50, v49, v50
	v_max_f32_e32 v148, v7, v0
	v_min_f32_e32 v0, v7, v0
	v_max_f32_e32 v92, v51, v52
	v_min_f32_e32 v52, v51, v52
	v_max_f32_e32 v54, v104, v15
	v_min_f32_e32 v15, v104, v15
	v_max_f32_e32 v21, v21, v63
	v_max_f32_e32 v83, v83, v36
	v_max_f32_e32 v95, v95, v66
	v_max_f32_e32 v9, v9, v96
	v_max_f32_e32 v27, v27, v22
	v_max_f32_e32 v144, v144, v102
	v_max_f32_e32 v8, v8, v125
	v_max_f32_e32 v146, v146, v67
	v_max_f32_e32 v94, v94, v79
	v_max_f32_e32 v84, v84, v24
	v_max_f32_e32 v88, v88, v77
	v_max_f32_e32 v6, v6, v43
	v_max_f32_e32 v80, v80, v25
	v_max_f32_e32 v89, v89, v117
	v_max_f32_e32 v20, v20, v124
	v_max_f32_e32 v47, v47, v37
	v_max_f32_e32 v56, v21, v94
	v_min_f32_e32 v94, v21, v94
	v_max_f32_e32 v58, v83, v84
	v_min_f32_e32 v84, v83, v84
	v_max_f32_e32 v59, v95, v88
	v_min_f32_e32 v88, v95, v88
	v_max_f32_e32 v149, v9, v6
	v_min_f32_e32 v6, v9, v6
	v_max_f32_e32 v14, v27, v80
	v_min_f32_e32 v80, v27, v80
	v_max_f32_e32 v255, v144, v89
	v_min_f32_e32 v89, v144, v89
	v_max_f32_e32 v103, v8, v20
	v_min_f32_e32 v20, v8, v20
	v_max_f32_e32 v97, v146, v47
	v_min_f32_e32 v47, v146, v47
	v_max_f32_e32 v106, v56, v14
	v_min_f32_e32 v14, v56, v14
	v_max_f32_e32 v60, v58, v255
	v_min_f32_e32 v255, v58, v255
	v_max_f32_e32 v62, v59, v103
	v_min_f32_e32 v103, v59, v103
	v_max_f32_e32 v254, v149, v97
	v_min_f32_e32 v97, v149, v97
	v_max_f32_e32 v145, v94, v80
	v_min_f32_e32 v80, v94, v80
	v_max_f32_e32 v251, v84, v89
	v_min_f32_e32 v89, v84, v89
	v_max_f32_e32 v10, v88, v20
	v_min_f32_e32 v20, v88, v20
	v_max_f32_e32 v32, v6, v47
	v_min_f32_e32 v47, v6, v47
	v_max_f32_e32 v12, v106, v62
	v_min_f32_e32 v62, v106, v62
	v_max_f32_e32 v35, v60, v254
	v_min_f32_e32 v254, v60, v254
	v_max_f32_e32 v61, v14, v103
	v_min_f32_e32 v103, v14, v103
	v_max_f32_e32 v39, v255, v97
	v_min_f32_e32 v97, v255, v97
	v_max_f32_e32 v2, v145, v10
	v_min_f32_e32 v10, v145, v10
	v_max_f32_e32 v41, v251, v32
	v_min_f32_e32 v32, v251, v32
	v_max_f32_e32 v116, v80, v20
	v_min_f32_e32 v20, v80, v20
	v_max_f32_e32 v118, v89, v47
	v_min_f32_e32 v47, v89, v47
	v_max_f32_e32 v250, v12, v35
	v_min_f32_e32 v35, v12, v35
	v_max_f32_e32 v38, v62, v254
	v_min_f32_e32 v254, v62, v254
	v_max_f32_e32 v40, v61, v39
	v_min_f32_e32 v39, v61, v39
	v_max_f32_e32 v13, v103, v97
	v_min_f32_e32 v97, v103, v97
	v_max_f32_e32 v127, v2, v41
	v_min_f32_e32 v41, v2, v41
	v_max_f32_e32 v33, v10, v32
	v_min_f32_e32 v32, v10, v32
	v_max_f32_e32 v121, v116, v118
	v_min_f32_e32 v118, v116, v118
	v_max_f32_e32 v100, v20, v47
	v_min_f32_e32 v47, v20, v47
	v_max_f32_e32 v53, v53, v47
	v_max_f32_e32 v29, v29, v100
	v_max_f32_e32 v55, v55, v118
	v_max_f32_e32 v18, v18, v121
	v_max_f32_e32 v57, v57, v32
	v_max_f32_e32 v48, v48, v33
	v_max_f32_e32 v249, v249, v41
	v_max_f32_e32 v86, v86, v127
	v_max_f32_e32 v1, v1, v97
	v_max_f32_e32 v50, v50, v13
	v_max_f32_e32 v148, v148, v39
	v_max_f32_e32 v0, v0, v40
	v_max_f32_e32 v92, v92, v254
	v_max_f32_e32 v52, v52, v38
	v_max_f32_e32 v54, v54, v35
	v_max_f32_e32 v15, v15, v250
	v_max_f32_e32 v68, v53, v1
	v_min_f32_e32 v1, v53, v1
	v_max_f32_e32 v42, v29, v50
	v_min_f32_e32 v50, v29, v50
	v_max_f32_e32 v65, v55, v148
	v_min_f32_e32 v148, v55, v148
	v_max_f32_e32 v109, v18, v0
	v_min_f32_e32 v0, v18, v0
	v_max_f32_e32 v114, v57, v92
	v_min_f32_e32 v92, v57, v92
	v_max_f32_e32 v101, v48, v52
	v_min_f32_e32 v52, v48, v52
	v_max_f32_e32 v46, v249, v54
	v_min_f32_e32 v54, v249, v54
	v_max_f32_e32 v34, v86, v15
	v_min_f32_e32 v15, v86, v15
	v_max_f32_e32 v19, v68, v114
	v_min_f32_e32 v114, v68, v114
	v_max_f32_e32 v44, v42, v101
	v_min_f32_e32 v101, v42, v101
	v_max_f32_e32 v23, v65, v46
	v_min_f32_e32 v46, v65, v46
	v_max_f32_e32 v16, v109, v34
	v_min_f32_e32 v34, v109, v34
	v_max_f32_e32 v122, v1, v92
	v_min_f32_e32 v92, v1, v92
	v_max_f32_e32 v45, v50, v52
	v_min_f32_e32 v52, v50, v52
	v_max_f32_e32 v123, v148, v54
	v_min_f32_e32 v54, v148, v54
	v_max_f32_e32 v5, v0, v15
	v_min_f32_e32 v15, v0, v15
	v_max_f32_e32 v150, v19, v23
	v_min_f32_e32 v23, v19, v23
	v_max_f32_e32 v99, v44, v16
	v_min_f32_e32 v16, v44, v16
	v_max_f32_e32 v107, v114, v46
	v_min_f32_e32 v46, v114, v46
	v_max_f32_e32 v11, v101, v34
	v_min_f32_e32 v34, v101, v34
	v_max_f32_e32 v108, v122, v123
	v_min_f32_e32 v123, v122, v123
	v_max_f32_e32 v113, v45, v5
	v_min_f32_e32 v5, v45, v5
	v_max_f32_e32 v110, v92, v54
	v_min_f32_e32 v54, v92, v54
	v_max_f32_e32 v98, v52, v15
	v_min_f32_e32 v15, v52, v15
	v_max_f32_e32 v151, v150, v99
	v_min_f32_e32 v99, v150, v99
	v_max_f32_e32 v252, v23, v16
	v_min_f32_e32 v16, v23, v16
	v_max_f32_e32 v112, v107, v11
	v_min_f32_e32 v11, v107, v11
	v_max_f32_e32 v147, v46, v34
	v_min_f32_e32 v34, v46, v34
	v_max_f32_e32 v253, v108, v113
	v_min_f32_e32 v113, v108, v113
	v_max_f32_e32 v4, v123, v5
	v_min_f32_e32 v5, v123, v5
	v_max_f32_e32 v31, v110, v98
	v_min_f32_e32 v98, v110, v98
	v_max_f32_e32 v105, v54, v15
	v_min_f32_e32 v15, v54, v15
	v_mov_b32_e32 v120, v151
	v_mov_b32_e32 v126, v99
	v_mov_b32_e32 v70, v252
	v_mov_b32_e32 v115, v16
	v_mov_b32_e32 v71, v112
	v_mov_b32_e32 v75, v11
	v_mov_b32_e32 v72, v147
	v_mov_b32_e32 v85, v34
	v_mov_b32_e32 v17, v253
	v_mov_b32_e32 v81, v113
	v_mov_b32_e32 v64, v4
	v_mov_b32_e32 v76, v5
	v_mov_b32_e32 v73, v31
	v_mov_b32_e32 v69, v98
	v_mov_b32_e32 v74, v105
	v_mov_b32_e32 v82, v15
	s_nop 1
	v_permlane32_swap_b32_e32 v151, v120
	v_permlane32_swap_b32_e32 v99, v126
	v_permlane32_swap_b32_e32 v252, v70
	v_permlane32_swap_b32_e32 v16, v115
	v_permlane32_swap_b32_e32 v112, v71
	v_permlane32_swap_b32_e32 v11, v75
	v_permlane32_swap_b32_e32 v147, v72
	v_permlane32_swap_b32_e32 v34, v85
	v_permlane32_swap_b32_e32 v253, v17
	v_permlane32_swap_b32_e32 v113, v81
	v_permlane32_swap_b32_e32 v4, v64
	v_permlane32_swap_b32_e32 v5, v76
	v_permlane32_swap_b32_e32 v31, v73
	v_permlane32_swap_b32_e32 v98, v69
	v_permlane32_swap_b32_e32 v105, v74
	v_permlane32_swap_b32_e32 v15, v82
	s_nop 1
	v_max_f32_e32 v151, v151, v82
	v_max_f32_e32 v99, v99, v74
	v_max_f32_e32 v252, v252, v69
	v_max_f32_e32 v16, v16, v73
	v_max_f32_e32 v112, v112, v76
	v_max_f32_e32 v11, v11, v64
	v_max_f32_e32 v147, v147, v81
	v_max_f32_e32 v34, v34, v17
	v_max_f32_e32 v253, v253, v85
	v_max_f32_e32 v113, v113, v72
	v_max_f32_e32 v4, v4, v75
	v_max_f32_e32 v5, v5, v71
	v_max_f32_e32 v31, v31, v115
	v_max_f32_e32 v98, v98, v70
	v_max_f32_e32 v105, v105, v126
	v_max_f32_e32 v15, v15, v120
	v_max_f32_e32 v78, v151, v253
	v_min_f32_e32 v253, v151, v253
	v_max_f32_e32 v91, v99, v113
	v_min_f32_e32 v113, v99, v113
	v_max_f32_e32 v26, v252, v4
	v_min_f32_e32 v4, v252, v4
	v_max_f32_e32 v3, v16, v5
	v_min_f32_e32 v5, v16, v5
	v_max_f32_e32 v28, v112, v31
	v_min_f32_e32 v31, v112, v31
	v_max_f32_e32 v111, v11, v98
	v_min_f32_e32 v98, v11, v98
	v_max_f32_e32 v119, v147, v105
	v_min_f32_e32 v105, v147, v105
	v_max_f32_e32 v90, v34, v15
	v_min_f32_e32 v15, v34, v15
	v_max_f32_e32 v30, v78, v28
	v_min_f32_e32 v28, v78, v28
	v_max_f32_e32 v87, v91, v111
	v_min_f32_e32 v111, v91, v111
	v_max_f32_e32 v93, v26, v119
	v_min_f32_e32 v119, v26, v119
	v_max_f32_e32 v49, v3, v90
	v_min_f32_e32 v90, v3, v90
	v_max_f32_e32 v7, v253, v31
	v_min_f32_e32 v31, v253, v31
	v_max_f32_e32 v51, v113, v98
	v_min_f32_e32 v98, v113, v98
	v_max_f32_e32 v104, v4, v105
	v_min_f32_e32 v105, v4, v105
	v_max_f32_e32 v37, v5, v15
	v_min_f32_e32 v15, v5, v15
	v_max_f32_e32 v124, v30, v93
	v_min_f32_e32 v93, v30, v93
	v_max_f32_e32 v117, v87, v49
	v_min_f32_e32 v49, v87, v49
	v_max_f32_e32 v25, v28, v119
	v_min_f32_e32 v119, v28, v119
	v_max_f32_e32 v43, v111, v90
	v_min_f32_e32 v90, v111, v90
	v_max_f32_e32 v77, v7, v104
	v_min_f32_e32 v104, v7, v104
	v_max_f32_e32 v24, v51, v37
	v_min_f32_e32 v37, v51, v37
	v_max_f32_e32 v79, v31, v105
	v_min_f32_e32 v105, v31, v105
	v_max_f32_e32 v67, v98, v15
	v_min_f32_e32 v15, v98, v15
	v_max_f32_e32 v125, v124, v117
	v_min_f32_e32 v117, v124, v117
	v_max_f32_e32 v102, v93, v49
	v_min_f32_e32 v49, v93, v49
	v_max_f32_e32 v22, v25, v43
	v_min_f32_e32 v43, v25, v43
	v_max_f32_e32 v96, v119, v90
	v_min_f32_e32 v90, v119, v90
	v_max_f32_e32 v66, v77, v24
	v_min_f32_e32 v24, v77, v24
	v_max_f32_e32 v36, v104, v37
	v_min_f32_e32 v37, v104, v37
	v_max_f32_e32 v63, v79, v67
	v_min_f32_e32 v67, v79, v67
	v_max_f32_e32 v21, v105, v15
	v_min_f32_e32 v15, v105, v15
	s_waitcnt vmcnt(0)
	v_pk_mul_f32 v[160:161], v[160:161], v[176:177]
	v_pk_mul_f32 v[162:163], v[162:163], v[178:179]
	v_pk_mul_f32 v[164:165], v[164:165], v[180:181]
	v_pk_mul_f32 v[166:167], v[166:167], v[182:183]
	v_pk_mul_f32 v[168:169], v[168:169], v[184:185]
	v_pk_mul_f32 v[170:171], v[170:171], v[186:187]
	v_pk_mul_f32 v[172:173], v[172:173], v[188:189]
	v_pk_mul_f32 v[174:175], v[174:175], v[190:191]
	v_max3_f32 v192, |v160|, |v161|, |v162|
	v_max3_f32 v192, |v163|, |v164|, v192
	v_max3_f32 v192, |v165|, |v166|, v192
	v_max3_f32 v192, |v167|, |v168|, v192
	v_max3_f32 v192, |v169|, |v170|, v192
	v_max3_f32 v192, |v171|, |v172|, v192
	v_max3_f32 v192, |v173|, |v174|, v192
	v_max_f32_e64 v192, |v175|, v192
	s_nop 1
	v_mov_b32_dpp v193, v192 quad_perm:[1,0,3,2] row_mask:0xf bank_mask:0xf bound_ctrl:1
	v_max_f32_e32 v192, v192, v193
	s_nop 1
	v_mov_b32_dpp v193, v192 quad_perm:[2,3,0,1] row_mask:0xf bank_mask:0xf bound_ctrl:1
	v_max_f32_e32 v192, v192, v193
	s_nop 1
	v_mov_b32_dpp v193, v192 row_half_mirror row_mask:0xf bank_mask:0xf bound_ctrl:1
	v_max_f32_e32 v192, v192, v193
	s_nop 1
	v_mov_b32_dpp v193, v192 row_mirror row_mask:0xf bank_mask:0xf bound_ctrl:1
	v_max_f32_e32 v192, v192, v193
	v_mov_b32_e32 v193, v192
	s_nop 1
	v_permlane16_swap_b32_e32 v192, v193
	s_nop 1
	v_max_f32_e32 v192, v192, v193
	v_mov_b32_e32 v193, v192
	s_nop 1
	v_permlane32_swap_b32_e32 v192, v193
	s_nop 1
	v_max_f32_e32 v192, v192, v193
	v_max_f32_e32 v192, 0xda24260, v192
	v_mul_f32_e32 v194, 0x3e2aaaab, v192
	global_store_dword v214, v194, s[12:13]
	v_div_scale_f32 v195, s[26:27], v194, v194, 1.0
	v_rcp_f32_e32 v196, v195
	v_div_scale_f32 v204, vcc, 1.0, v194, 1.0
	v_fma_f32 v205, -v195, v196, 1.0
	v_fmac_f32_e32 v196, v205, v196
	v_mul_f32_e32 v205, v204, v196
	v_fma_f32 v206, -v195, v205, v204
	v_fmac_f32_e32 v205, v206, v196
	v_fma_f32 v195, -v195, v205, v204
	s_nop 0
	v_div_fmas_f32 v195, v195, v196, v205
	v_div_fixup_f32 v207, v195, v194, 1.0
	v_mul_f32_e32 v160, v207, v160
	v_mul_f32_e32 v161, v207, v161
	v_mul_f32_e32 v162, v207, v162
	v_mul_f32_e32 v163, v207, v163
	v_mul_f32_e32 v164, v207, v164
	v_mul_f32_e32 v165, v207, v165
	v_mul_f32_e32 v166, v207, v166
	v_mul_f32_e32 v167, v207, v167
	v_mul_f32_e32 v168, v207, v168
	v_mul_f32_e32 v169, v207, v169
	v_mul_f32_e32 v170, v207, v170
	v_mul_f32_e32 v171, v207, v171
	v_mul_f32_e32 v172, v207, v172
	v_mul_f32_e32 v173, v207, v173
	v_mul_f32_e32 v174, v207, v174
	v_mul_f32_e32 v175, v207, v175
	v_mov_b32_e32 v208, 0
	v_mov_b32_e32 v209, 0
	v_mov_b32_e32 v210, 0
	v_mov_b32_e32 v193, 0
	v_cvt_scalef32_pk_fp4_f32 v208, v160, v161, 1.0
	v_cvt_scalef32_pk_fp4_f32 v209, v164, v165, 1.0
	v_cvt_scalef32_pk_fp4_f32 v210, v168, v169, 1.0
	v_cvt_scalef32_pk_fp4_f32 v193, v172, v173, 1.0
	v_cvt_scalef32_pk_fp4_f32 v208, v162, v163, 1.0 op_sel:[0,0,1,0]
	v_cvt_scalef32_pk_fp4_f32 v209, v166, v167, 1.0 op_sel:[0,0,1,0]
	v_cvt_scalef32_pk_fp4_f32 v210, v170, v171, 1.0 op_sel:[0,0,1,0]
	v_cvt_scalef32_pk_fp4_f32 v193, v174, v175, 1.0 op_sel:[0,0,1,0]
	global_store_short v213, v208, s[10:11] nt
	s_add_u32 s14, s10, 0x200000
	s_addc_u32 s15, s11, 0
	global_store_short v213, v209, s[14:15] nt
	s_add_u32 s14, s10, 0x400000
	s_addc_u32 s15, s11, 0
	global_store_short v213, v210, s[14:15] nt
	s_add_u32 s14, s10, 0x600000
	s_addc_u32 s15, s11, 0
	global_store_short v213, v193, s[14:15] nt
	s_add_u32 s10, s10, 0x20000
	s_addc_u32 s11, s11, 0
	s_add_u32 s12, s12, 0x2000
	s_addc_u32 s13, s13, 0
	global_load_dwordx4 v[160:163], v212, s[8:9] offset:0 nt
	global_load_dwordx4 v[164:167], v212, s[8:9] offset:1024 nt
	global_load_dwordx4 v[168:171], v212, s[8:9] offset:2048 nt
	global_load_dwordx4 v[172:175], v212, s[8:9] offset:3072 nt
	s_add_u32 s8, s8, 0x800000
	s_addc_u32 s9, s9, 0
	ds_write_b8 v240, v125 offset:512
	ds_write_b8 v240, v117 offset:513
	ds_write_b8 v240, v102 offset:514
	ds_write_b8 v240, v49 offset:515
	ds_write_b8 v240, v22 offset:516
	ds_write_b8 v240, v43 offset:517
	ds_write_b8 v240, v96 offset:518
	ds_write_b8 v240, v90 offset:519
	ds_write_b8 v240, v66 offset:520
	ds_write_b8 v240, v24 offset:521
	ds_write_b8 v240, v36 offset:522
	ds_write_b8 v240, v37 offset:523
	ds_write_b8 v240, v63 offset:524
	ds_write_b8 v240, v67 offset:525
	ds_write_b8 v240, v21 offset:526
	ds_write_b8 v240, v15 offset:527
	v_cndmask_b32_e64 v0, v128, v125, s[4:5]
	v_cndmask_b32_e64 v17, v125, v128, s[4:5]
	v_cndmask_b32_e64 v1, v129, v117, s[4:5]
	v_cndmask_b32_e64 v18, v117, v129, s[4:5]
	v_cndmask_b32_e64 v2, v130, v102, s[4:5]
	v_cndmask_b32_e64 v19, v102, v130, s[4:5]
	v_cndmask_b32_e64 v3, v131, v49, s[4:5]
	v_cndmask_b32_e64 v20, v49, v131, s[4:5]
	v_cndmask_b32_e64 v4, v132, v22, s[4:5]
	v_cndmask_b32_e64 v23, v22, v132, s[4:5]
	v_cndmask_b32_e64 v5, v133, v43, s[4:5]
	v_cndmask_b32_e64 v25, v43, v133, s[4:5]
	v_cndmask_b32_e64 v6, v134, v96, s[4:5]
	v_cndmask_b32_e64 v26, v96, v134, s[4:5]
	v_cndmask_b32_e64 v7, v135, v90, s[4:5]
	v_cndmask_b32_e64 v27, v90, v135, s[4:5]
	v_cndmask_b32_e64 v8, v136, v66, s[4:5]
	v_cndmask_b32_e64 v28, v66, v136, s[4:5]
	v_cndmask_b32_e64 v9, v137, v24, s[4:5]
	v_cndmask_b32_e64 v29, v24, v137, s[4:5]
	v_cndmask_b32_e64 v10, v138, v36, s[4:5]
	v_cndmask_b32_e64 v30, v36, v138, s[4:5]
	v_cndmask_b32_e64 v11, v139, v37, s[4:5]
	v_cndmask_b32_e64 v31, v37, v139, s[4:5]
	v_cndmask_b32_e64 v12, v140, v63, s[4:5]
	v_cndmask_b32_e64 v32, v63, v140, s[4:5]
	v_cndmask_b32_e64 v13, v141, v67, s[4:5]
	v_cndmask_b32_e64 v33, v67, v141, s[4:5]
	v_cndmask_b32_e64 v14, v142, v21, s[4:5]
	v_cndmask_b32_e64 v34, v21, v142, s[4:5]
	v_cndmask_b32_e64 v16, v143, v15, s[4:5]
	v_cndmask_b32_e64 v35, v15, v143, s[4:5]
	v_and_b32_e32 v0, s6, v0
	v_and_b32_e32 v17, s6, v17
	v_and_b32_e32 v1, s6, v1
	v_and_b32_e32 v18, s6, v18
	v_and_b32_e32 v2, s6, v2
	v_and_b32_e32 v19, s6, v19
	v_and_b32_e32 v3, s6, v3
	v_and_b32_e32 v20, s6, v20
	v_and_b32_e32 v4, s6, v4
	v_and_b32_e32 v23, s6, v23
	v_and_b32_e32 v5, s6, v5
	v_and_b32_e32 v25, s6, v25
	v_and_b32_e32 v6, s6, v6
	v_and_b32_e32 v26, s6, v26
	v_and_b32_e32 v7, s6, v7
	v_and_b32_e32 v27, s6, v27
	v_and_b32_e32 v8, s6, v8
	v_and_b32_e32 v28, s6, v28
	v_and_b32_e32 v9, s6, v9
	v_and_b32_e32 v29, s6, v29
	v_and_b32_e32 v10, s6, v10
	v_and_b32_e32 v30, s6, v30
	v_and_b32_e32 v11, s6, v11
	v_and_b32_e32 v31, s6, v31
	v_and_b32_e32 v12, s6, v12
	v_and_b32_e32 v32, s6, v32
	v_and_b32_e32 v13, s6, v13
	v_and_b32_e32 v33, s6, v33
	v_and_b32_e32 v14, s6, v14
	v_and_b32_e32 v34, s6, v34
	v_and_b32_e32 v16, s6, v16
	v_and_b32_e32 v35, s6, v35
	v_add_f32_e32 v38, v0, v18
	v_and_or_b32 v38, v38, s7, 0
	v_add_f32_e32 v39, v0, v19
	v_and_or_b32 v39, v39, s7, 2
	v_add_f32_e32 v40, v0, v20
	v_and_or_b32 v40, v40, s7, 4
	v_add_f32_e32 v41, v0, v23
	v_and_or_b32 v41, v41, s7, 6
	v_add_f32_e32 v42, v0, v25
	v_and_or_b32 v42, v42, s7, 8
	v_add_f32_e32 v44, v0, v26
	v_and_or_b32 v44, v44, s7, 10
	v_add_f32_e32 v45, v0, v27
	v_and_or_b32 v45, v45, s7, 12
	v_add_f32_e32 v46, v0, v28
	v_and_or_b32 v46, v46, s7, 14
	v_add_f32_e32 v47, v0, v29
	v_and_or_b32 v47, v47, s7, 16
	v_add_f32_e32 v48, v0, v30
	v_and_or_b32 v48, v48, s7, 18
	v_add_f32_e32 v50, v0, v31
	v_and_or_b32 v50, v50, s7, 20
	v_add_f32_e32 v51, v0, v32
	v_and_or_b32 v51, v51, s7, 22
	v_add_f32_e32 v52, v0, v33
	v_and_or_b32 v52, v52, s7, 24
	v_add_f32_e32 v53, v0, v34
	v_and_or_b32 v53, v53, s7, 26
	v_add_f32_e32 v54, v0, v35
	v_and_or_b32 v54, v54, s7, 28
	v_add_f32_e32 v55, v1, v19
	v_and_or_b32 v55, v55, s7, 30
	v_add_f32_e32 v56, v1, v20
	v_and_or_b32 v56, v56, s7, 32
	v_add_f32_e32 v57, v1, v23
	v_and_or_b32 v57, v57, s7, 34
	v_add_f32_e32 v58, v1, v25
	v_and_or_b32 v58, v58, s7, 36
	v_add_f32_e32 v59, v1, v26
	v_and_or_b32 v59, v59, s7, 38
	v_add_f32_e32 v60, v1, v27
	v_and_or_b32 v60, v60, s7, 40
	v_add_f32_e32 v61, v2, v20
	v_and_or_b32 v61, v61, s7, 42
	v_add_f32_e32 v62, v2, v23
	v_and_or_b32 v62, v62, s7, 44
	v_add_f32_e32 v64, v0, v17
	v_and_or_b32 v64, v64, s7, 46
	v_cndmask_b32_e64 v64, v64, v244, s[4:5]
	v_add_f32_e32 v65, v1, v18
	v_and_or_b32 v65, v65, s7, 48
	v_cndmask_b32_e64 v65, v65, v244, s[4:5]
	v_add_f32_e32 v68, v2, v19
	v_and_or_b32 v68, v68, s7, 50
	v_cndmask_b32_e64 v68, v68, v244, s[4:5]
	v_add_f32_e32 v69, v3, v20
	v_and_or_b32 v69, v69, s7, 52
	v_cndmask_b32_e64 v69, v69, v244, s[4:5]
	v_max_f32_e32 v70, v38, v53
	v_min_f32_e32 v53, v38, v53
	v_max_f32_e32 v71, v39, v52
	v_min_f32_e32 v52, v39, v52
	v_max_f32_e32 v72, v40, v55
	v_min_f32_e32 v55, v40, v55
	v_max_f32_e32 v73, v41, v54
	v_min_f32_e32 v54, v41, v54
	v_max_f32_e32 v74, v42, v47
	v_min_f32_e32 v47, v42, v47
	v_max_f32_e32 v75, v44, v45
	v_min_f32_e32 v45, v44, v45
	v_max_f32_e32 v76, v46, v51
	v_min_f32_e32 v51, v46, v51
	v_max_f32_e32 v77, v48, v50
	v_min_f32_e32 v50, v48, v50
	v_max_f32_e32 v78, v70, v75
	v_min_f32_e32 v75, v70, v75
	v_max_f32_e32 v79, v71, v76
	v_min_f32_e32 v76, v71, v76
	v_max_f32_e32 v80, v72, v77
	v_min_f32_e32 v77, v72, v77
	v_max_f32_e32 v81, v73, v74
	v_min_f32_e32 v74, v73, v74
	v_max_f32_e32 v82, v45, v53
	v_min_f32_e32 v53, v45, v53
	v_max_f32_e32 v83, v47, v54
	v_min_f32_e32 v54, v47, v54
	v_max_f32_e32 v84, v50, v55
	v_min_f32_e32 v55, v50, v55
	v_max_f32_e32 v85, v51, v52
	v_min_f32_e32 v52, v51, v52
	v_max_f32_e32 v86, v78, v79
	v_min_f32_e32 v79, v78, v79
	v_max_f32_e32 v87, v80, v81
	v_min_f32_e32 v81, v80, v81
	v_max_f32_e32 v88, v74, v75
	v_min_f32_e32 v75, v74, v75
	v_max_f32_e32 v89, v82, v83
	v_min_f32_e32 v83, v82, v83
	v_max_f32_e32 v91, v76, v77
	v_min_f32_e32 v77, v76, v77
	v_max_f32_e32 v92, v84, v85
	v_min_f32_e32 v85, v84, v85
	v_max_f32_e32 v93, v52, v53
	v_min_f32_e32 v53, v52, v53
	v_max_f32_e32 v94, v54, v55
	v_min_f32_e32 v55, v54, v55
	v_max_f32_e32 v95, v86, v87
	v_min_f32_e32 v87, v86, v87
	v_max_f32_e32 v97, v79, v81
	v_min_f32_e32 v81, v79, v81
	v_max_f32_e32 v98, v88, v92
	v_min_f32_e32 v92, v88, v92
	v_max_f32_e32 v99, v75, v85
	v_min_f32_e32 v85, v75, v85
	v_max_f32_e32 v100, v89, v91
	v_min_f32_e32 v91, v89, v91
	v_max_f32_e32 v101, v83, v77
	v_min_f32_e32 v77, v83, v77
	v_max_f32_e32 v103, v93, v94
	v_min_f32_e32 v94, v93, v94
	v_max_f32_e32 v104, v53, v55
	v_min_f32_e32 v55, v53, v55
	v_max_f32_e32 v105, v97, v87
	v_min_f32_e32 v87, v97, v87
	v_max_f32_e32 v106, v81, v103
	v_min_f32_e32 v103, v81, v103
	v_max_f32_e32 v107, v98, v100
	v_min_f32_e32 v100, v98, v100
	v_max_f32_e32 v108, v99, v91
	v_min_f32_e32 v91, v99, v91
	v_max_f32_e32 v109, v101, v92
	v_min_f32_e32 v92, v101, v92
	v_max_f32_e32 v110, v77, v85
	v_min_f32_e32 v85, v77, v85
	v_max_f32_e32 v111, v104, v94
	v_min_f32_e32 v94, v104, v94
	v_max_f32_e32 v112, v105, v107
	v_min_f32_e32 v107, v105, v107
	v_max_f32_e32 v113, v87, v100
	v_min_f32_e32 v100, v87, v100
	v_max_f32_e32 v114, v108, v109
	v_min_f32_e32 v109, v108, v109
	v_max_f32_e32 v115, v91, v92
	v_min_f32_e32 v92, v91, v92
	v_max_f32_e32 v116, v110, v111
	v_min_f32_e32 v111, v110, v111
	v_max_f32_e32 v118, v85, v94
	v_min_f32_e32 v94, v85, v94
	v_max_f32_e32 v119, v113, v107
	v_min_f32_e32 v107, v113, v107
	v_max_f32_e32 v120, v106, v100
	v_min_f32_e32 v100, v106, v100
	v_max_f32_e32 v121, v116, v103
	v_min_f32_e32 v103, v116, v103
	v_max_f32_e32 v122, v118, v111
	v_min_f32_e32 v111, v118, v111
	v_max_f32_e32 v123, v120, v114
	v_min_f32_e32 v114, v120, v114
	v_max_f32_e32 v124, v100, v109
	v_min_f32_e32 v109, v100, v109
	v_max_f32_e32 v126, v115, v121
	v_min_f32_e32 v121, v115, v121
	v_max_f32_e32 v127, v92, v103
	v_min_f32_e32 v103, v92, v103
	v_max_f32_e32 v144, v123, v107
	v_min_f32_e32 v107, v123, v107
	v_max_f32_e32 v145, v114, v124
	v_min_f32_e32 v124, v114, v124
	v_max_f32_e32 v146, v126, v109
	v_min_f32_e32 v109, v126, v109
	v_max_f32_e32 v147, v121, v127
	v_min_f32_e32 v127, v121, v127
	v_max_f32_e32 v148, v122, v103
	v_min_f32_e32 v103, v122, v103
	v_max_f32_e32 v149, v124, v146
	v_min_f32_e32 v146, v124, v146
	v_max_f32_e32 v150, v109, v147
	v_min_f32_e32 v147, v109, v147
	v_max_f32_e32 v151, v60, v65
	v_min_f32_e32 v65, v60, v65
	v_max_f32_e32 v249, v61, v62
	v_min_f32_e32 v62, v61, v62
	v_max_f32_e32 v250, v68, v69
	v_min_f32_e32 v69, v68, v69
	v_max_f32_e32 v251, v56, v249
	v_min_f32_e32 v249, v56, v249
	v_max_f32_e32 v252, v57, v64
	v_min_f32_e32 v64, v57, v64
	v_max_f32_e32 v253, v58, v250
	v_min_f32_e32 v250, v58, v250
	v_max_f32_e32 v254, v59, v151
	v_min_f32_e32 v151, v59, v151
	v_max_f32_e32 v255, v251, v252
	v_min_f32_e32 v252, v251, v252
	v_max_f32_e32 v128, v253, v254
	v_min_f32_e32 v254, v253, v254
	v_max_f32_e32 v129, v151, v249
	v_min_f32_e32 v249, v151, v249
	v_max_f32_e32 v130, v62, v65
	v_min_f32_e32 v65, v62, v65
	v_max_f32_e32 v131, v64, v250
	v_min_f32_e32 v250, v64, v250
	v_max_f32_e32 v132, v255, v128
	v_min_f32_e32 v128, v255, v128
	v_max_f32_e32 v133, v252, v254
	v_min_f32_e32 v254, v252, v254
	v_max_f32_e32 v134, v129, v69
	v_min_f32_e32 v69, v129, v69
	v_max_f32_e32 v135, v130, v131
	v_min_f32_e32 v131, v130, v131
	v_max_f32_e32 v136, v65, v250
	v_min_f32_e32 v250, v65, v250
	v_max_f32_e32 v137, v133, v128
	v_min_f32_e32 v128, v133, v128
	v_max_f32_e32 v138, v134, v135
	v_min_f32_e32 v135, v134, v135
	v_max_f32_e32 v139, v249, v131
	v_min_f32_e32 v131, v249, v131
	v_max_f32_e32 v140, v136, v69
	v_min_f32_e32 v69, v136, v69
	v_max_f32_e32 v141, v137, v138
	v_min_f32_e32 v138, v137, v138
	v_max_f32_e32 v142, v128, v135
	v_min_f32_e32 v135, v128, v135
	v_max_f32_e32 v143, v139, v140
	v_min_f32_e32 v140, v139, v140
	v_max_f32_e32 v125, v131, v69
	v_min_f32_e32 v69, v131, v69
	v_max_f32_e32 v117, v142, v138
	v_min_f32_e32 v138, v142, v138
	v_max_f32_e32 v102, v254, v135
	v_min_f32_e32 v135, v254, v135
	v_max_f32_e32 v49, v102, v143
	v_min_f32_e32 v143, v102, v143
	v_max_f32_e32 v22, v135, v140
	v_min_f32_e32 v140, v135, v140
	v_max_f32_e32 v43, v125, v250
	v_min_f32_e32 v250, v125, v250
	v_max_f32_e32 v96, v49, v138
	v_min_f32_e32 v138, v49, v138
	v_max_f32_e32 v90, v143, v22
	v_min_f32_e32 v22, v143, v22
	v_max_f32_e32 v66, v43, v140
	v_min_f32_e32 v140, v43, v140
	v_max_f32_e32 v24, v250, v69
	v_min_f32_e32 v69, v250, v69
	v_max_f32_e32 v36, v22, v66
	v_min_f32_e32 v66, v22, v66
	v_max_f32_e32 v37, v140, v24
	v_min_f32_e32 v24, v140, v24
	s_waitcnt vmcnt(0)
	v_pk_mul_f32 v[160:161], v[160:161], v[176:177]
	v_pk_mul_f32 v[162:163], v[162:163], v[178:179]
	v_pk_mul_f32 v[164:165], v[164:165], v[180:181]
	v_pk_mul_f32 v[166:167], v[166:167], v[182:183]
	v_pk_mul_f32 v[168:169], v[168:169], v[184:185]
	v_pk_mul_f32 v[170:171], v[170:171], v[186:187]
	v_pk_mul_f32 v[172:173], v[172:173], v[188:189]
	v_pk_mul_f32 v[174:175], v[174:175], v[190:191]
	v_max3_f32 v192, |v160|, |v161|, |v162|
	v_max3_f32 v192, |v163|, |v164|, v192
	v_max3_f32 v192, |v165|, |v166|, v192
	v_max3_f32 v192, |v167|, |v168|, v192
	v_max3_f32 v192, |v169|, |v170|, v192
	v_max3_f32 v192, |v171|, |v172|, v192
	v_max3_f32 v192, |v173|, |v174|, v192
	v_max_f32_e64 v192, |v175|, v192
	s_nop 1
	v_mov_b32_dpp v193, v192 quad_perm:[1,0,3,2] row_mask:0xf bank_mask:0xf bound_ctrl:1
	v_max_f32_e32 v192, v192, v193
	s_nop 1
	v_mov_b32_dpp v193, v192 quad_perm:[2,3,0,1] row_mask:0xf bank_mask:0xf bound_ctrl:1
	v_max_f32_e32 v192, v192, v193
	s_nop 1
	v_mov_b32_dpp v193, v192 row_half_mirror row_mask:0xf bank_mask:0xf bound_ctrl:1
	v_max_f32_e32 v192, v192, v193
	s_nop 1
	v_mov_b32_dpp v193, v192 row_mirror row_mask:0xf bank_mask:0xf bound_ctrl:1
	v_max_f32_e32 v192, v192, v193
	v_mov_b32_e32 v193, v192
	s_nop 1
	v_permlane16_swap_b32_e32 v192, v193
	s_nop 1
	v_max_f32_e32 v192, v192, v193
	v_mov_b32_e32 v193, v192
	s_nop 1
	v_permlane32_swap_b32_e32 v192, v193
	s_nop 1
	v_max_f32_e32 v192, v192, v193
	v_max_f32_e32 v192, 0xda24260, v192
	v_mul_f32_e32 v194, 0x3e2aaaab, v192
	global_store_dword v214, v194, s[12:13]
	v_div_scale_f32 v195, s[26:27], v194, v194, 1.0
	v_rcp_f32_e32 v196, v195
	v_div_scale_f32 v204, vcc, 1.0, v194, 1.0
	v_fma_f32 v205, -v195, v196, 1.0
	v_fmac_f32_e32 v196, v205, v196
	v_mul_f32_e32 v205, v204, v196
	v_fma_f32 v206, -v195, v205, v204
	v_fmac_f32_e32 v205, v206, v196
	v_fma_f32 v195, -v195, v205, v204
	s_nop 0
	v_div_fmas_f32 v195, v195, v196, v205
	v_div_fixup_f32 v207, v195, v194, 1.0
	v_mul_f32_e32 v160, v207, v160
	v_mul_f32_e32 v161, v207, v161
	v_mul_f32_e32 v162, v207, v162
	v_mul_f32_e32 v163, v207, v163
	v_mul_f32_e32 v164, v207, v164
	v_mul_f32_e32 v165, v207, v165
	v_mul_f32_e32 v166, v207, v166
	v_mul_f32_e32 v167, v207, v167
	v_mul_f32_e32 v168, v207, v168
	v_mul_f32_e32 v169, v207, v169
	v_mul_f32_e32 v170, v207, v170
	v_mul_f32_e32 v171, v207, v171
	v_mul_f32_e32 v172, v207, v172
	v_mul_f32_e32 v173, v207, v173
	v_mul_f32_e32 v174, v207, v174
	v_mul_f32_e32 v175, v207, v175
	v_mov_b32_e32 v208, 0
	v_mov_b32_e32 v209, 0
	v_mov_b32_e32 v210, 0
	v_mov_b32_e32 v193, 0
	v_cvt_scalef32_pk_fp4_f32 v208, v160, v161, 1.0
	v_cvt_scalef32_pk_fp4_f32 v209, v164, v165, 1.0
	v_cvt_scalef32_pk_fp4_f32 v210, v168, v169, 1.0
	v_cvt_scalef32_pk_fp4_f32 v193, v172, v173, 1.0
	v_cvt_scalef32_pk_fp4_f32 v208, v162, v163, 1.0 op_sel:[0,0,1,0]
	v_cvt_scalef32_pk_fp4_f32 v209, v166, v167, 1.0 op_sel:[0,0,1,0]
	v_cvt_scalef32_pk_fp4_f32 v210, v170, v171, 1.0 op_sel:[0,0,1,0]
	v_cvt_scalef32_pk_fp4_f32 v193, v174, v175, 1.0 op_sel:[0,0,1,0]
	global_store_short v213, v208, s[10:11] nt
	s_add_u32 s14, s10, 0x200000
	s_addc_u32 s15, s11, 0
	global_store_short v213, v209, s[14:15] nt
	s_add_u32 s14, s10, 0x400000
	s_addc_u32 s15, s11, 0
	global_store_short v213, v210, s[14:15] nt
	s_add_u32 s14, s10, 0x600000
	s_addc_u32 s15, s11, 0
	global_store_short v213, v193, s[14:15] nt
	s_add_u32 s10, s10, 0x20000
	s_addc_u32 s11, s11, 0
	s_add_u32 s12, s12, 0x2000
	s_addc_u32 s13, s13, 0
	global_load_dwordx4 v[160:163], v212, s[8:9] offset:0 nt
	global_load_dwordx4 v[164:167], v212, s[8:9] offset:1024 nt
	global_load_dwordx4 v[168:171], v212, s[8:9] offset:2048 nt
	global_load_dwordx4 v[172:175], v212, s[8:9] offset:3072 nt
	s_add_u32 s8, s8, 0x800000
	s_addc_u32 s9, s9, 0
	v_max_f32_e32 v145, v145, v69
	v_max_f32_e32 v149, v149, v24
	v_max_f32_e32 v146, v146, v37
	v_max_f32_e32 v150, v150, v66
	v_max_f32_e32 v147, v147, v36
	v_max_f32_e32 v127, v127, v90
	v_max_f32_e32 v148, v148, v138
	v_max_f32_e32 v103, v103, v96
	v_max_f32_e32 v111, v111, v117
	v_max_f32_e32 v94, v94, v141
	v_max_f32_e32 v55, v55, v132
	v_max_f32_e32 v63, v95, v150
	v_min_f32_e32 v150, v95, v150
	v_max_f32_e32 v67, v112, v147
	v_min_f32_e32 v147, v112, v147
	v_max_f32_e32 v21, v119, v127
	v_min_f32_e32 v127, v119, v127
	v_max_f32_e32 v15, v144, v148
	v_min_f32_e32 v148, v144, v148
	v_max_f32_e32 v0, v107, v103
	v_min_f32_e32 v103, v107, v103
	v_max_f32_e32 v1, v145, v111
	v_min_f32_e32 v111, v145, v111
	v_max_f32_e32 v2, v149, v94
	v_min_f32_e32 v94, v149, v94
	v_max_f32_e32 v3, v146, v55
	v_min_f32_e32 v55, v146, v55
	v_max_f32_e32 v4, v63, v0
	v_min_f32_e32 v0, v63, v0
	v_max_f32_e32 v5, v67, v1
	v_min_f32_e32 v1, v67, v1
	v_max_f32_e32 v6, v21, v2
	v_min_f32_e32 v2, v21, v2
	v_max_f32_e32 v7, v15, v3
	v_min_f32_e32 v3, v15, v3
	v_max_f32_e32 v8, v150, v103
	v_min_f32_e32 v103, v150, v103
	v_max_f32_e32 v9, v147, v111
	v_min_f32_e32 v111, v147, v111
	v_max_f32_e32 v10, v127, v94
	v_min_f32_e32 v94, v127, v94
	v_max_f32_e32 v11, v148, v55
	v_min_f32_e32 v55, v148, v55
	v_max_f32_e32 v12, v4, v6
	v_min_f32_e32 v6, v4, v6
	v_max_f32_e32 v13, v5, v7
	v_min_f32_e32 v7, v5, v7
	v_max_f32_e32 v14, v0, v2
	v_min_f32_e32 v2, v0, v2
	v_max_f32_e32 v16, v1, v3
	v_min_f32_e32 v3, v1, v3
	v_max_f32_e32 v17, v8, v10
	v_min_f32_e32 v10, v8, v10
	v_max_f32_e32 v18, v9, v11
	v_min_f32_e32 v11, v9, v11
	v_max_f32_e32 v19, v103, v94
	v_min_f32_e32 v94, v103, v94
	v_max_f32_e32 v20, v111, v55
	v_min_f32_e32 v55, v111, v55
	v_max_f32_e32 v23, v12, v13
	v_min_f32_e32 v13, v12, v13
	v_max_f32_e32 v25, v6, v7
	v_min_f32_e32 v7, v6, v7
	v_max_f32_e32 v26, v14, v16
	v_min_f32_e32 v16, v14, v16
	v_max_f32_e32 v27, v2, v3
	v_min_f32_e32 v3, v2, v3
	v_max_f32_e32 v28, v17, v18
	v_min_f32_e32 v18, v17, v18
	v_max_f32_e32 v29, v10, v11
	v_min_f32_e32 v11, v10, v11
	v_max_f32_e32 v30, v19, v20
	v_min_f32_e32 v20, v19, v20
	v_max_f32_e32 v31, v94, v55
	v_min_f32_e32 v55, v94, v55
	v_or_b32_e32 v23, v23, v245
	v_or_b32_e32 v13, v13, v245
	v_or_b32_e32 v25, v25, v245
	v_or_b32_e32 v7, v7, v245
	v_or_b32_e32 v26, v26, v245
	v_or_b32_e32 v16, v16, v245
	v_or_b32_e32 v27, v27, v245
	v_or_b32_e32 v3, v3, v245
	v_or_b32_e32 v28, v28, v245
	v_or_b32_e32 v18, v18, v245
	v_or_b32_e32 v29, v29, v245
	v_or_b32_e32 v11, v11, v245
	v_or_b32_e32 v30, v30, v245
	v_or_b32_e32 v20, v20, v245
	v_or_b32_e32 v31, v31, v245
	v_or_b32_e32 v55, v55, v245
	v_mov_b32_e32 v32, v23
	v_mov_b32_e32 v33, v13
	v_mov_b32_e32 v34, v25
	v_mov_b32_e32 v35, v7
	v_mov_b32_e32 v38, v26
	v_mov_b32_e32 v39, v16
	v_mov_b32_e32 v40, v27
	v_mov_b32_e32 v41, v3
	v_mov_b32_e32 v42, v28
	v_mov_b32_e32 v44, v18
	v_mov_b32_e32 v46, v29
	v_mov_b32_e32 v48, v11
	v_mov_b32_e32 v70, v30
	v_mov_b32_e32 v71, v20
	v_mov_b32_e32 v72, v31
	v_mov_b32_e32 v73, v55
	s_nop 1
	v_permlane32_swap_b32_e32 v23, v32
	v_permlane32_swap_b32_e32 v13, v33
	v_permlane32_swap_b32_e32 v25, v34
	v_permlane32_swap_b32_e32 v7, v35
	v_permlane32_swap_b32_e32 v26, v38
	v_permlane32_swap_b32_e32 v16, v39
	v_permlane32_swap_b32_e32 v27, v40
	v_permlane32_swap_b32_e32 v3, v41
	v_permlane32_swap_b32_e32 v28, v42
	v_permlane32_swap_b32_e32 v18, v44
	v_permlane32_swap_b32_e32 v29, v46
	v_permlane32_swap_b32_e32 v11, v48
	v_permlane32_swap_b32_e32 v30, v70
	v_permlane32_swap_b32_e32 v20, v71
	v_permlane32_swap_b32_e32 v31, v72
	v_permlane32_swap_b32_e32 v55, v73
	s_nop 1
	v_max_f32_e32 v23, v23, v73
	v_max_f32_e32 v13, v13, v72
	v_max_f32_e32 v25, v25, v71
	v_max_f32_e32 v7, v7, v70
	v_max_f32_e32 v26, v26, v48
	v_max_f32_e32 v16, v16, v46
	v_max_f32_e32 v27, v27, v44
	v_max_f32_e32 v3, v3, v42
	v_max_f32_e32 v28, v28, v41
	v_max_f32_e32 v18, v18, v40
	v_max_f32_e32 v29, v29, v39
	v_max_f32_e32 v11, v11, v38
	v_max_f32_e32 v30, v30, v35
	v_max_f32_e32 v20, v20, v34
	v_max_f32_e32 v31, v31, v33
	v_max_f32_e32 v55, v55, v32
	v_max_f32_e32 v45, v23, v28
	v_min_f32_e32 v28, v23, v28
	v_max_f32_e32 v47, v13, v18
	v_min_f32_e32 v18, v13, v18
	v_max_f32_e32 v50, v25, v29
	v_min_f32_e32 v29, v25, v29
	v_max_f32_e32 v51, v7, v11
	v_min_f32_e32 v11, v7, v11
	v_max_f32_e32 v78, v26, v30
	v_min_f32_e32 v30, v26, v30
	v_max_f32_e32 v80, v16, v20
	v_min_f32_e32 v20, v16, v20
	v_max_f32_e32 v74, v27, v31
	v_min_f32_e32 v31, v27, v31
	v_max_f32_e32 v82, v3, v55
	v_min_f32_e32 v55, v3, v55
	v_max_f32_e32 v76, v45, v78
	v_min_f32_e32 v78, v45, v78
	v_max_f32_e32 v84, v47, v80
	v_min_f32_e32 v80, v47, v80
	v_max_f32_e32 v52, v50, v74
	v_min_f32_e32 v74, v50, v74
	v_max_f32_e32 v54, v51, v82
	v_min_f32_e32 v82, v51, v82
	v_max_f32_e32 v86, v28, v30
	v_min_f32_e32 v30, v28, v30
	v_max_f32_e32 v79, v18, v20
	v_min_f32_e32 v20, v18, v20
	v_max_f32_e32 v88, v29, v31
	v_min_f32_e32 v31, v29, v31
	v_max_f32_e32 v75, v11, v55
	v_min_f32_e32 v55, v11, v55
	v_max_f32_e32 v89, v76, v52
	v_min_f32_e32 v52, v76, v52
	v_max_f32_e32 v83, v84, v54
	v_min_f32_e32 v54, v84, v54
	v_max_f32_e32 v93, v78, v74
	v_min_f32_e32 v74, v78, v74
	v_max_f32_e32 v53, v80, v82
	v_min_f32_e32 v82, v80, v82
	v_max_f32_e32 v97, v86, v88
	v_min_f32_e32 v88, v86, v88
	v_max_f32_e32 v81, v79, v75
	v_min_f32_e32 v75, v79, v75
	v_max_f32_e32 v98, v30, v31
	v_min_f32_e32 v31, v30, v31
	v_max_f32_e32 v99, v20, v55
	v_min_f32_e32 v55, v20, v55
	v_max_f32_e32 v101, v89, v83
	v_min_f32_e32 v83, v89, v83
	v_max_f32_e32 v77, v52, v54
	v_min_f32_e32 v54, v52, v54
	v_max_f32_e32 v104, v93, v53
	v_min_f32_e32 v53, v93, v53
	v_max_f32_e32 v105, v74, v82
	v_min_f32_e32 v82, v74, v82
	v_max_f32_e32 v87, v97, v81
	v_min_f32_e32 v81, v97, v81
	v_max_f32_e32 v108, v88, v75
	v_min_f32_e32 v75, v88, v75
	v_max_f32_e32 v91, v98, v99
	v_min_f32_e32 v99, v98, v99
	v_max_f32_e32 v110, v31, v55
	v_min_f32_e32 v55, v31, v55
	v_and_b32_e32 v85, s7, v101
	v_cndmask_b32_e64 v113, v101, v87, s[4:5]
	v_cndmask_b32_e64 v106, v83, v81, s[4:5]
	v_cndmask_b32_e64 v116, v77, v108, s[4:5]
	v_cndmask_b32_e64 v118, v54, v75, s[4:5]
	v_cndmask_b32_e64 v120, v104, v91, s[4:5]
	v_cndmask_b32_e64 v100, v53, v99, s[4:5]
	v_cndmask_b32_e64 v115, v105, v110, s[4:5]
	v_cndmask_b32_e64 v92, v82, v55, s[4:5]
	v_and_or_b32 v123, v113, 63, v246
	ds_read_u8 v123, v123
	v_and_or_b32 v114, v106, 63, v246
	ds_read_u8 v114, v114
	v_and_or_b32 v126, v116, 63, v246
	ds_read_u8 v126, v126
	v_and_or_b32 v121, v118, 63, v246
	ds_read_u8 v121, v121
	v_and_or_b32 v122, v120, 63, v246
	ds_read_u8 v122, v122
	v_and_or_b32 v124, v100, 63, v246
	ds_read_u8 v124, v124
	v_and_or_b32 v109, v115, 63, v246
	ds_read_u8 v109, v109
	v_and_or_b32 v60, v92, 63, v246
	ds_read_u8 v60, v60
	v_and_b32_e32 v113, s7, v113
	v_sub_f32_e32 v113, v113, v85
	v_mul_f32_e32 v113, 0x3fb8aa3b, v113
	v_exp_f32_e32 v113, v113
	v_and_b32_e32 v106, s7, v106
	v_sub_f32_e32 v106, v106, v85
	v_mul_f32_e32 v106, 0x3fb8aa3b, v106
	v_exp_f32_e32 v106, v106
	v_and_b32_e32 v116, s7, v116
	v_sub_f32_e32 v116, v116, v85
	v_mul_f32_e32 v116, 0x3fb8aa3b, v116
	v_exp_f32_e32 v116, v116
	v_and_b32_e32 v118, s7, v118
	v_sub_f32_e32 v118, v118, v85
	v_mul_f32_e32 v118, 0x3fb8aa3b, v118
	v_exp_f32_e32 v118, v118
	v_and_b32_e32 v120, s7, v120
	v_sub_f32_e32 v120, v120, v85
	v_mul_f32_e32 v120, 0x3fb8aa3b, v120
	v_exp_f32_e32 v120, v120
	v_and_b32_e32 v100, s7, v100
	v_sub_f32_e32 v100, v100, v85
	v_mul_f32_e32 v100, 0x3fb8aa3b, v100
	v_exp_f32_e32 v100, v100
	v_and_b32_e32 v115, s7, v115
	v_sub_f32_e32 v115, v115, v85
	v_mul_f32_e32 v115, 0x3fb8aa3b, v115
	v_exp_f32_e32 v115, v115
	v_and_b32_e32 v92, s7, v92
	v_sub_f32_e32 v92, v92, v85
	v_mul_f32_e32 v92, 0x3fb8aa3b, v92
	v_exp_f32_e32 v92, v92
	s_nop 0
	v_add_f32_e32 v85, v113, v106
	v_add_f32_e32 v85, v85, v116
	v_add_f32_e32 v85, v85, v118
	v_add_f32_e32 v85, v85, v120
	v_add_f32_e32 v85, v85, v100
	v_add_f32_e32 v85, v85, v115
	v_add_f32_e32 v85, v85, v92
	v_mov_b32_e32 v61, v85
	s_nop 1
	v_permlane32_swap_b32_e32 v85, v61
	s_nop 1
	v_add_f32_e32 v85, v85, v61
	s_waitcnt lgkmcnt(0)
	v_bfe_u32 v68, v123, 4, 4
	v_or_b32_e32 v68, v68, v240
	v_and_or_b32 v123, v123, 15, v240
	ds_read_u8 v68, v68
	ds_read_u8 v123, v123 offset:512
	v_bfe_u32 v56, v114, 4, 4
	v_or_b32_e32 v56, v56, v240
	v_and_or_b32 v114, v114, 15, v240
	ds_read_u8 v56, v56
	ds_read_u8 v114, v114 offset:512
	v_bfe_u32 v57, v126, 4, 4
	v_or_b32_e32 v57, v57, v240
	v_and_or_b32 v126, v126, 15, v240
	ds_read_u8 v57, v57
	ds_read_u8 v126, v126 offset:512
	v_bfe_u32 v58, v121, 4, 4
	v_or_b32_e32 v58, v58, v240
	v_and_or_b32 v121, v121, 15, v240
	ds_read_u8 v58, v58
	ds_read_u8 v121, v121 offset:512
	v_bfe_u32 v59, v122, 4, 4
	v_or_b32_e32 v59, v59, v240
	v_and_or_b32 v122, v122, 15, v240
	ds_read_u8 v59, v59
	ds_read_u8 v122, v122 offset:512
	v_bfe_u32 v251, v124, 4, 4
	v_or_b32_e32 v251, v251, v240
	v_and_or_b32 v124, v124, 15, v240
	ds_read_u8 v251, v251
	ds_read_u8 v124, v124 offset:512
	v_bfe_u32 v253, v109, 4, 4
	v_or_b32_e32 v253, v253, v240
	v_and_or_b32 v109, v109, 15, v240
	ds_read_u8 v253, v253
	ds_read_u8 v109, v109 offset:512
	v_bfe_u32 v151, v60, 4, 4
	v_or_b32_e32 v151, v151, v240
	v_and_or_b32 v60, v60, 15, v240
	ds_read_u8 v151, v151
	ds_read_u8 v60, v60 offset:512
	v_div_scale_f32 v134, s[26:27], v85, v85, v113
	v_rcp_f32_e32 v249, v134
	s_nop 0
	v_fma_f32 v136, -v134, v249, 1.0
	v_fmac_f32_e32 v249, v136, v249
	v_div_scale_f32 v136, vcc, v113, v85, v113
	v_mul_f32_e32 v137, v136, v249
	v_fma_f32 v62, -v134, v137, v136
	v_fmac_f32_e32 v137, v62, v249
	v_fma_f32 v136, -v134, v137, v136
	s_nop 0
	v_div_fmas_f32 v136, v136, v249, v137
	v_div_fixup_f32 v62, v136, v85, v113
	v_div_scale_f32 v134, s[26:27], v85, v85, v106
	v_rcp_f32_e32 v249, v134
	s_nop 0
	v_fma_f32 v136, -v134, v249, 1.0
	v_fmac_f32_e32 v249, v136, v249
	v_div_scale_f32 v136, vcc, v106, v85, v106
	v_mul_f32_e32 v137, v136, v249
	v_fma_f32 v64, -v134, v137, v136
	v_fmac_f32_e32 v137, v64, v249
	v_fma_f32 v136, -v134, v137, v136
	s_nop 0
	v_div_fmas_f32 v136, v136, v249, v137
	v_div_fixup_f32 v64, v136, v85, v106
	v_div_scale_f32 v134, s[26:27], v85, v85, v116
	v_rcp_f32_e32 v249, v134
	s_nop 0
	v_fma_f32 v136, -v134, v249, 1.0
	v_fmac_f32_e32 v249, v136, v249
	v_div_scale_f32 v136, vcc, v116, v85, v116
	v_mul_f32_e32 v137, v136, v249
	v_fma_f32 v255, -v134, v137, v136
	v_fmac_f32_e32 v137, v255, v249
	v_fma_f32 v136, -v134, v137, v136
	s_nop 0
	v_div_fmas_f32 v136, v136, v249, v137
	v_div_fixup_f32 v255, v136, v85, v116
	v_div_scale_f32 v134, s[26:27], v85, v85, v118
	v_rcp_f32_e32 v249, v134
	s_nop 0
	v_fma_f32 v136, -v134, v249, 1.0
	v_fmac_f32_e32 v249, v136, v249
	v_div_scale_f32 v136, vcc, v118, v85, v118
	v_mul_f32_e32 v137, v136, v249
	v_fma_f32 v252, -v134, v137, v136
	v_fmac_f32_e32 v137, v252, v249
	v_fma_f32 v136, -v134, v137, v136
	s_nop 0
	v_div_fmas_f32 v136, v136, v249, v137
	v_div_fixup_f32 v252, v136, v85, v118
	v_div_scale_f32 v134, s[26:27], v85, v85, v120
	v_rcp_f32_e32 v249, v134
	s_nop 0
	v_fma_f32 v136, -v134, v249, 1.0
	v_fmac_f32_e32 v249, v136, v249
	v_div_scale_f32 v136, vcc, v120, v85, v120
	v_mul_f32_e32 v137, v136, v249
	v_fma_f32 v129, -v134, v137, v136
	v_fmac_f32_e32 v137, v129, v249
	v_fma_f32 v136, -v134, v137, v136
	s_nop 0
	v_div_fmas_f32 v136, v136, v249, v137
	v_div_fixup_f32 v129, v136, v85, v120
	v_div_scale_f32 v134, s[26:27], v85, v85, v100
	v_rcp_f32_e32 v249, v134
	s_nop 0
	v_fma_f32 v136, -v134, v249, 1.0
	v_fmac_f32_e32 v249, v136, v249
	v_div_scale_f32 v136, vcc, v100, v85, v100
	v_mul_f32_e32 v137, v136, v249
	v_fma_f32 v130, -v134, v137, v136
	v_fmac_f32_e32 v137, v130, v249
	v_fma_f32 v136, -v134, v137, v136
	s_nop 0
	v_div_fmas_f32 v136, v136, v249, v137
	v_div_fixup_f32 v130, v136, v85, v100
	v_div_scale_f32 v134, s[26:27], v85, v85, v115
	v_rcp_f32_e32 v249, v134
	s_nop 0
	v_fma_f32 v136, -v134, v249, 1.0
	v_fmac_f32_e32 v249, v136, v249
	v_div_scale_f32 v136, vcc, v115, v85, v115
	v_mul_f32_e32 v137, v136, v249
	v_fma_f32 v65, -v134, v137, v136
	v_fmac_f32_e32 v137, v65, v249
	v_fma_f32 v136, -v134, v137, v136
	s_nop 0
	v_div_fmas_f32 v136, v136, v249, v137
	v_div_fixup_f32 v65, v136, v85, v115
	v_div_scale_f32 v134, s[26:27], v85, v85, v92
	v_rcp_f32_e32 v249, v134
	s_nop 0
	v_fma_f32 v136, -v134, v249, 1.0
	v_fmac_f32_e32 v249, v136, v249
	v_div_scale_f32 v136, vcc, v92, v85, v92
	v_mul_f32_e32 v137, v136, v249
	v_fma_f32 v133, -v134, v137, v136
	v_fmac_f32_e32 v137, v133, v249
	v_fma_f32 v136, -v134, v137, v136
	s_nop 0
	v_div_fmas_f32 v136, v136, v249, v137
	v_div_fixup_f32 v133, v136, v85, v92
	s_waitcnt lgkmcnt(0)
	v_and_b32_e32 v68, 0x7f, v68
	v_and_b32_e32 v123, 0x7f, v123
	v_lshl_or_b32 v68, v68, 7, v123
	v_xor_b32_e32 v68, 0x3fff, v68
	v_and_b32_e32 v56, 0x7f, v56
	v_and_b32_e32 v114, 0x7f, v114
	v_lshl_or_b32 v56, v56, 7, v114
	v_xor_b32_e32 v56, 0x3fff, v56
	v_and_b32_e32 v57, 0x7f, v57
	v_and_b32_e32 v126, 0x7f, v126
	v_lshl_or_b32 v57, v57, 7, v126
	v_xor_b32_e32 v57, 0x3fff, v57
	v_and_b32_e32 v58, 0x7f, v58
	v_and_b32_e32 v121, 0x7f, v121
	v_lshl_or_b32 v58, v58, 7, v121
	v_xor_b32_e32 v58, 0x3fff, v58
	v_and_b32_e32 v59, 0x7f, v59
	v_and_b32_e32 v122, 0x7f, v122
	v_lshl_or_b32 v59, v59, 7, v122
	v_xor_b32_e32 v59, 0x3fff, v59
	v_and_b32_e32 v251, 0x7f, v251
	v_and_b32_e32 v124, 0x7f, v124
	v_lshl_or_b32 v251, v251, 7, v124
	v_xor_b32_e32 v251, 0x3fff, v251
	v_and_b32_e32 v253, 0x7f, v253
	v_and_b32_e32 v109, 0x7f, v109
	v_lshl_or_b32 v253, v253, 7, v109
	v_xor_b32_e32 v253, 0x3fff, v253
	v_and_b32_e32 v151, 0x7f, v151
	v_and_b32_e32 v60, 0x7f, v60
	v_lshl_or_b32 v151, v151, 7, v60
	v_xor_b32_e32 v151, 0x3fff, v151
	s_waitcnt vmcnt(0)
	v_pk_mul_f32 v[160:161], v[160:161], v[176:177]
	v_pk_mul_f32 v[162:163], v[162:163], v[178:179]
	v_pk_mul_f32 v[164:165], v[164:165], v[180:181]
	v_pk_mul_f32 v[166:167], v[166:167], v[182:183]
	v_pk_mul_f32 v[168:169], v[168:169], v[184:185]
	v_pk_mul_f32 v[170:171], v[170:171], v[186:187]
	v_pk_mul_f32 v[172:173], v[172:173], v[188:189]
	v_pk_mul_f32 v[174:175], v[174:175], v[190:191]
	v_max3_f32 v192, |v160|, |v161|, |v162|
	v_max3_f32 v192, |v163|, |v164|, v192
	v_max3_f32 v192, |v165|, |v166|, v192
	v_max3_f32 v192, |v167|, |v168|, v192
	v_max3_f32 v192, |v169|, |v170|, v192
	v_max3_f32 v192, |v171|, |v172|, v192
	v_max3_f32 v192, |v173|, |v174|, v192
	v_max_f32_e64 v192, |v175|, v192
	s_nop 1
	v_mov_b32_dpp v193, v192 quad_perm:[1,0,3,2] row_mask:0xf bank_mask:0xf bound_ctrl:1
	v_max_f32_e32 v192, v192, v193
	s_nop 1
	v_mov_b32_dpp v193, v192 quad_perm:[2,3,0,1] row_mask:0xf bank_mask:0xf bound_ctrl:1
	v_max_f32_e32 v192, v192, v193
	s_nop 1
	v_mov_b32_dpp v193, v192 row_half_mirror row_mask:0xf bank_mask:0xf bound_ctrl:1
	v_max_f32_e32 v192, v192, v193
	s_nop 1
	v_mov_b32_dpp v193, v192 row_mirror row_mask:0xf bank_mask:0xf bound_ctrl:1
	v_max_f32_e32 v192, v192, v193
	v_mov_b32_e32 v193, v192
	s_nop 1
	v_permlane16_swap_b32_e32 v192, v193
	s_nop 1
	v_max_f32_e32 v192, v192, v193
	v_mov_b32_e32 v193, v192
	s_nop 1
	v_permlane32_swap_b32_e32 v192, v193
	s_nop 1
	v_max_f32_e32 v192, v192, v193
	v_max_f32_e32 v192, 0xda24260, v192
	v_mul_f32_e32 v194, 0x3e2aaaab, v192
	global_store_dword v214, v194, s[12:13]
	v_div_scale_f32 v195, s[26:27], v194, v194, 1.0
	v_rcp_f32_e32 v196, v195
	v_div_scale_f32 v204, vcc, 1.0, v194, 1.0
	v_fma_f32 v205, -v195, v196, 1.0
	v_fmac_f32_e32 v196, v205, v196
	v_mul_f32_e32 v205, v204, v196
	v_fma_f32 v206, -v195, v205, v204
	v_fmac_f32_e32 v205, v206, v196
	v_fma_f32 v195, -v195, v205, v204
	s_nop 0
	v_div_fmas_f32 v195, v195, v196, v205
	v_div_fixup_f32 v207, v195, v194, 1.0
	v_mul_f32_e32 v160, v207, v160
	v_mul_f32_e32 v161, v207, v161
	v_mul_f32_e32 v162, v207, v162
	v_mul_f32_e32 v163, v207, v163
	v_mul_f32_e32 v164, v207, v164
	v_mul_f32_e32 v165, v207, v165
	v_mul_f32_e32 v166, v207, v166
	v_mul_f32_e32 v167, v207, v167
	v_mul_f32_e32 v168, v207, v168
	v_mul_f32_e32 v169, v207, v169
	v_mul_f32_e32 v170, v207, v170
	v_mul_f32_e32 v171, v207, v171
	v_mul_f32_e32 v172, v207, v172
	v_mul_f32_e32 v173, v207, v173
	v_mul_f32_e32 v174, v207, v174
	v_mul_f32_e32 v175, v207, v175
	v_mov_b32_e32 v208, 0
	v_mov_b32_e32 v209, 0
	v_mov_b32_e32 v210, 0
	v_mov_b32_e32 v193, 0
	v_cvt_scalef32_pk_fp4_f32 v208, v160, v161, 1.0
	v_cvt_scalef32_pk_fp4_f32 v209, v164, v165, 1.0
	v_cvt_scalef32_pk_fp4_f32 v210, v168, v169, 1.0
	v_cvt_scalef32_pk_fp4_f32 v193, v172, v173, 1.0
	v_cvt_scalef32_pk_fp4_f32 v208, v162, v163, 1.0 op_sel:[0,0,1,0]
	v_cvt_scalef32_pk_fp4_f32 v209, v166, v167, 1.0 op_sel:[0,0,1,0]
	v_cvt_scalef32_pk_fp4_f32 v210, v170, v171, 1.0 op_sel:[0,0,1,0]
	v_cvt_scalef32_pk_fp4_f32 v193, v174, v175, 1.0 op_sel:[0,0,1,0]
	global_store_short v213, v208, s[10:11] nt
	s_add_u32 s14, s10, 0x200000
	s_addc_u32 s15, s11, 0
	global_store_short v213, v209, s[14:15] nt
	s_add_u32 s14, s10, 0x400000
	s_addc_u32 s15, s11, 0
	global_store_short v213, v210, s[14:15] nt
	s_add_u32 s14, s10, 0x600000
	s_addc_u32 s15, s11, 0
	global_store_short v213, v193, s[14:15] nt
	s_add_u32 s10, s10, 0x20000
	s_addc_u32 s11, s11, 0
	s_add_u32 s12, s12, 0x2000
	s_addc_u32 s13, s13, 0
	s_cmp_eq_u32 s22, 1
	s_cbranch_scc1 .Ltk1_noload7
	global_load_dwordx4 v[160:163], v212, s[8:9] offset:0 nt
	global_load_dwordx4 v[164:167], v212, s[8:9] offset:1024 nt
	global_load_dwordx4 v[168:171], v212, s[8:9] offset:2048 nt
	global_load_dwordx4 v[172:175], v212, s[8:9] offset:3072 nt
	s_add_u32 s8, s8, 0x800000
	s_addc_u32 s9, s9, 0

.LpgL1_group:
	v_mbcnt_lo_u32_b32 v249, -1, 0
	v_mbcnt_hi_u32_b32 v249, -1, v249
	v_and_b32_e32 v250, 15, v249
	v_lshrrev_b32_e32 v251, 4, v249
	v_and_b32_e32 v252, 3, v250
	v_cmp_eq_u32_e64 s[4:5], 1, v252
	v_cmp_eq_u32_e64 s[6:7], 2, v252
	v_cmp_eq_u32_e64 s[8:9], 3, v252
	v_cmp_eq_u32_e64 s[10:11], 0, v249
	s_add_u32 s12, s54, 0x29800000
	s_addc_u32 s13, s55, 0
	s_and_b32 s13, s13, 0xffff
	s_mov_b32 s14, 0x2000000
	s_mov_b32 s15, 0x20000
	s_add_u32 s16, s54, 0x10000000
	s_addc_u32 s17, s55, 0
	s_and_b32 s17, s17, 0xffff
	s_mov_b32 s18, 0x1000000
	s_mov_b32 s19, 0x20000
	s_add_u32 s20, s54, 0x14000000
	s_addc_u32 s21, s55, 0
	s_and_b32 s21, s21, 0xffff
	s_mov_b32 s22, 0x1000000
	s_mov_b32 s23, 0x20000
	s_add_u32 s30, s54, 0xa0000
	s_addc_u32 s31, s55, 0
	s_add_u32 s34, s54, 0xe0000
	s_addc_u32 s35, s55, 0
	s_mov_b32 s94, 0xc3e00000
	s_mov_b32 s96, 0x800000
	s_mov_b32 s81, 0x1010101
	v_lshrrev_b32_e32 v253, 2, v250
	v_lshrrev_b32_e32 v254, 1, v251
	v_lshl_add_u32 v255, v253, 1, v254
	v_lshl_add_u32 v237, v255, 2, s91
	v_and_b32_e32 v255, 1, v251
	v_lshl_add_u32 v236, v255, 2, v252
	v_lshlrev_b32_e32 v236, 4, v236
	v_lshlrev_b32_e32 v254, 7, v254
	v_lshl_add_u32 v254, v252, 5, v254
	v_lshl_add_u32 v254, v255, 4, v254
	v_and_b32_e32 v253, 1, v253
	v_mov_b32_e32 v255, 0x7fff0000
	v_cmp_eq_u32_e32 vcc, 0, v253
	s_nop 1
	v_cndmask_b32_e32 v238, v255, v254, vcc
	v_cndmask_b32_e32 v239, v254, v255, vcc
	v_mov_b32_e32 v240, 0x7f7f7f7f
	v_mov_b32_e32 v255, 0x20202020
	v_cmp_gt_u32_e32 vcc, 8, v250
	s_nop 1
	v_cndmask_b32_e32 v241, v255, v240, vcc
	v_cndmask_b32_e32 v242, v240, v255, vcc
	v_lshrrev_b32_e32 v254, 3, v250
	v_lshl_add_u32 v254, v252, 1, v254
	v_lshl_add_u32 v255, v251, 1, v253
	v_lshl_add_u32 v244, v254, 3, v255
	v_lshlrev_b32_e32 v244, 2, v244
	v_add_u32_e32 v243, s91, v244
	v_and_b32_e32 v253, 3, v255
	v_lshrrev_b32_e32 v255, 2, v255
	v_lshl_add_u32 v253, v253, 1, v255
	v_lshl_add_u32 v253, v254, 3, v253
	v_lshlrev_b32_e32 v253, 2, v253
	v_add_u32_e32 v245, s91, v253
	v_add_u32_e32 v245, 0x1000, v245
	v_mov_b32_e32 v246, 0
	s_lshl_b32 s64, s63, 12
	s_add_u32 s24, s54, 0x28000000
	s_addc_u32 s25, s55, 0
	s_add_u32 s24, s24, s64
	s_addc_u32 s25, s25, 0
	s_lshl_b32 s64, s63, 12
	s_add_u32 s26, s54, 0x28800000
	s_addc_u32 s27, s55, 0
	s_add_u32 s26, s26, s64
	s_addc_u32 s27, s27, 0
	s_lshl_b32 s64, s63, 15
	s_add_u32 s28, s54, 0x18000000
	s_addc_u32 s29, s55, 0
	s_add_u32 s28, s28, s64
	s_addc_u32 s29, s29, 0
	s_lshl_b32 s64, s63, 5
	s_add_u32 s40, s54, 0x60000
	s_addc_u32 s41, s55, 0
	s_add_u32 s40, s40, s64
	s_addc_u32 s41, s41, 0
	s_lshl_b32 s64, s63, 5
	s_add_u32 s44, s54, 0x70000
	s_addc_u32 s45, s55, 0
	s_add_u32 s44, s44, s64
	s_addc_u32 s45, s45, 0
	s_lshl_b32 s64, s63, 16
	s_mov_b32 s46, s52
	s_mov_b32 s47, s53
	s_add_u32 s46, s46, s64
	s_addc_u32 s47, s47, 0
	s_lshl_b32 s61, s63, 14
	s_add_u32 s62, s61, 0x100
	v_mbcnt_lo_u32_b32 v253, -1, 0
	v_mbcnt_hi_u32_b32 v253, -1, v253
	v_lshlrev_b32_e32 v253, 2, v253
	global_load_dword v0, v253, s[24:25] offset:0 nt
	global_load_dword v1, v253, s[24:25] offset:256 nt
	global_load_dword v2, v253, s[24:25] offset:512 nt
	global_load_dword v3, v253, s[24:25] offset:768 nt
	global_load_dword v4, v253, s[24:25] offset:1024 nt
	global_load_dword v5, v253, s[24:25] offset:1280 nt
	global_load_dword v6, v253, s[24:25] offset:1536 nt
	global_load_dword v7, v253, s[24:25] offset:1792 nt
	global_load_dword v8, v253, s[24:25] offset:2048 nt
	global_load_dword v9, v253, s[24:25] offset:2304 nt
	global_load_dword v10, v253, s[24:25] offset:2560 nt
	global_load_dword v11, v253, s[24:25] offset:2816 nt
	global_load_dword v12, v253, s[24:25] offset:3072 nt
	global_load_dword v13, v253, s[24:25] offset:3328 nt
	global_load_dword v14, v253, s[24:25] offset:3584 nt
	global_load_dword v15, v253, s[24:25] offset:3840 nt
	v_add_u32_e32 v254, s91, v253
	s_waitcnt vmcnt(0)
	ds_write_b32 v254, v0 offset:0
	ds_write_b32 v254, v1 offset:256
	ds_write_b32 v254, v2 offset:512
	ds_write_b32 v254, v3 offset:768
	ds_write_b32 v254, v4 offset:1024
	ds_write_b32 v254, v5 offset:1280
	ds_write_b32 v254, v6 offset:1536
	ds_write_b32 v254, v7 offset:1792
	ds_write_b32 v254, v8 offset:2048
	ds_write_b32 v254, v9 offset:2304
	ds_write_b32 v254, v10 offset:2560
	ds_write_b32 v254, v11 offset:2816
	ds_write_b32 v254, v12 offset:3072
	ds_write_b32 v254, v13 offset:3328
	ds_write_b32 v254, v14 offset:3584
	ds_write_b32 v254, v15 offset:3840
	s_waitcnt lgkmcnt(0)
	s_lshl_b32 s61, s63, 14
	s_add_u32 s62, s61, 0x100
	v_mov_b32_e32 v204, 0
	v_mov_b32_e32 v205, 0
	v_mov_b32_e32 v206, 0
	v_mov_b32_e32 v207, 0
	v_mov_b32_e32 v208, 0
	v_mov_b32_e32 v209, 0
	v_mov_b32_e32 v210, 0
	v_mov_b32_e32 v211, 0
	v_mov_b32_e32 v212, 0
	v_mov_b32_e32 v213, 0
	v_mov_b32_e32 v214, 0
	v_mov_b32_e32 v215, 0
	v_mov_b32_e32 v216, 0
	v_mov_b32_e32 v217, 0
	v_mov_b32_e32 v218, 0
	v_mov_b32_e32 v219, 0
	v_mov_b32_e32 v176, 0
	v_mov_b32_e32 v177, 0
	v_mov_b32_e32 v178, 0
	v_mov_b32_e32 v179, 0
	v_mov_b32_e32 v180, 0
	v_mov_b32_e32 v181, 0
	v_mov_b32_e32 v182, 0
	v_mov_b32_e32 v183, 0
	v_mov_b32_e32 v184, 0
	v_mov_b32_e32 v185, 0
	v_mov_b32_e32 v186, 0
	v_mov_b32_e32 v187, 0
	v_mov_b32_e32 v188, 0
	v_mov_b32_e32 v189, 0
	v_mov_b32_e32 v190, 0
	v_mov_b32_e32 v191, 0
	s_mov_b32 s0, 0
	s_mov_b32 s1, 0
	s_mov_b32 s60, 0x200000
	ds_read_b32 v144, v237 offset:0
	ds_read_b32 v145, v237 offset:32
	ds_read_b32 v146, v237 offset:64
	ds_read_b32 v147, v237 offset:96
	ds_read_b32 v148, v237 offset:128
	ds_read_b32 v149, v237 offset:160
	ds_read_b32 v150, v237 offset:192
	ds_read_b32 v151, v237 offset:224
	s_waitcnt lgkmcnt(0)
	v_lshl_or_b32 v144, v144, 7, v236
	v_lshl_or_b32 v145, v145, 7, v236
	v_lshl_or_b32 v146, v146, 7, v236
	v_lshl_or_b32 v147, v147, 7, v236
	v_lshl_or_b32 v148, v148, 7, v236
	v_lshl_or_b32 v149, v149, 7, v236
	v_lshl_or_b32 v150, v150, 7, v236
	v_lshl_or_b32 v151, v151, 7, v236
	buffer_load_dwordx4 v[0:3], v144, s[16:19], s1 offen
	buffer_load_dwordx4 v[4:7], v145, s[16:19], s1 offen
	buffer_load_dwordx4 v[8:11], v146, s[16:19], s1 offen
	buffer_load_dwordx4 v[12:15], v147, s[16:19], s1 offen
	buffer_load_dwordx4 v[16:19], v148, s[16:19], s1 offen
	buffer_load_dwordx4 v[20:23], v149, s[16:19], s1 offen
	buffer_load_dwordx4 v[24:27], v150, s[16:19], s1 offen
	buffer_load_dwordx4 v[28:31], v151, s[16:19], s1 offen
	ds_read_b32 v144, v237 offset:256
	ds_read_b32 v145, v237 offset:288
	ds_read_b32 v146, v237 offset:320
	ds_read_b32 v147, v237 offset:352
	ds_read_b32 v148, v237 offset:384
	ds_read_b32 v149, v237 offset:416
	ds_read_b32 v150, v237 offset:448
	ds_read_b32 v151, v237 offset:480
	s_add_u32 s80, s61, 0x0
	buffer_load_dwordx4 v[128:131], v238, s[12:15], s80 offen nt
	buffer_load_dwordx4 v[132:135], v239, s[12:15], s80 offen nt
	s_waitcnt lgkmcnt(0)
	v_lshl_or_b32 v144, v144, 7, v236
	v_lshl_or_b32 v145, v145, 7, v236
	v_lshl_or_b32 v146, v146, 7, v236
	v_lshl_or_b32 v147, v147, 7, v236
	v_lshl_or_b32 v148, v148, 7, v236
	v_lshl_or_b32 v149, v149, 7, v236
	v_lshl_or_b32 v150, v150, 7, v236
	v_lshl_or_b32 v151, v151, 7, v236
	buffer_load_dwordx4 v[32:35], v144, s[16:19], s1 offen
	buffer_load_dwordx4 v[36:39], v145, s[16:19], s1 offen
	buffer_load_dwordx4 v[40:43], v146, s[16:19], s1 offen
	buffer_load_dwordx4 v[44:47], v147, s[16:19], s1 offen
	buffer_load_dwordx4 v[48:51], v148, s[16:19], s1 offen
	buffer_load_dwordx4 v[52:55], v149, s[16:19], s1 offen
	buffer_load_dwordx4 v[56:59], v150, s[16:19], s1 offen
	buffer_load_dwordx4 v[60:63], v151, s[16:19], s1 offen
	ds_read_b32 v144, v237 offset:512
	ds_read_b32 v145, v237 offset:544
	ds_read_b32 v146, v237 offset:576
	ds_read_b32 v147, v237 offset:608
	ds_read_b32 v148, v237 offset:640
	ds_read_b32 v149, v237 offset:672
	ds_read_b32 v150, v237 offset:704
	ds_read_b32 v151, v237 offset:736
	s_waitcnt lgkmcnt(0)
	v_lshl_or_b32 v144, v144, 7, v236
	v_lshl_or_b32 v145, v145, 7, v236
	v_lshl_or_b32 v146, v146, 7, v236
	v_lshl_or_b32 v147, v147, 7, v236
	v_lshl_or_b32 v148, v148, 7, v236
	v_lshl_or_b32 v149, v149, 7, v236
	v_lshl_or_b32 v150, v150, 7, v236
	v_lshl_or_b32 v151, v151, 7, v236
	buffer_load_dwordx4 v[64:67], v144, s[16:19], s1 offen
	buffer_load_dwordx4 v[68:71], v145, s[16:19], s1 offen
	buffer_load_dwordx4 v[72:75], v146, s[16:19], s1 offen
	buffer_load_dwordx4 v[76:79], v147, s[16:19], s1 offen
	buffer_load_dwordx4 v[80:83], v148, s[16:19], s1 offen
	buffer_load_dwordx4 v[84:87], v149, s[16:19], s1 offen
	buffer_load_dwordx4 v[88:91], v150, s[16:19], s1 offen
	buffer_load_dwordx4 v[92:95], v151, s[16:19], s1 offen
	ds_read_b32 v144, v237 offset:768
	ds_read_b32 v145, v237 offset:800
	ds_read_b32 v146, v237 offset:832
	ds_read_b32 v147, v237 offset:864
	ds_read_b32 v148, v237 offset:896
	ds_read_b32 v149, v237 offset:928
	ds_read_b32 v150, v237 offset:960
	ds_read_b32 v151, v237 offset:992
